# row phases: row sums by DPP adds and row broadcasts instead of 12 ds_bpermute round trips per row
# speedup vs baseline: 1.0038x; 1.0038x over previous
; DI const float* modp(const Frame& F, int l, int mr, int which) { return (const float*)(F.ws + WS_MOD) + ((size_t)(l * 9 + mr) * 6 + which) * 1024; }
; DI void ln_row_v(const Frame& F, f32x4 (&v)[4], float* xout, const float* g, const float* b, const float* sh, const float* sc, bf16_t* hout, const float* slab, const float* gres, float* stat = nullptr) {
;     ...
; #pragma unroll
;         for (int j = 0; j < 4; ++j) { s += (v[j][0] + v[j][1]) + (v[j][2] + v[j][3]); s2 += (v[j][0] * v[j][0] + v[j][1] * v[j][1]) + (v[j][2] * v[j][2] + v[j][3] * v[j][3]); }
;         wave_sum2(s, s2, F.lane);
; DI void ln_phase(const Frame& F, int which) {
;     const int gw = F.vcu * 8 + F.wave, NGW = F.G * 8; const int l = F.l;
;     const int nrows = (l == NL - 1) ? ML : MT;
;     bf16_t* H = (bf16_t*)(F.ws + WS_HB);
;     const float* g = pin(F, which == 0 ? I_LN1G : I_LN2G) + l * 1024; const float* b = pin(F, which == 0 ? I_LN1B : I_LN2B) + l * 1024;
;     const bool wh = !(which == 1 && l == NL - 1);
;     f32x4 vc[4], vn[4];
;     if (gw < nrows) ln_load(F, xrow_ptr(F, gw), vc);
;     for (int row = gw; row < nrows; row += NGW) {
;         if (row + NGW < nrows) ln_load(F, xrow_ptr(F, row + NGW), vn);
;         const int mr = row < ML ? (row >> 11) : 8;
;         const float* sh = which == 0 ? modp(F, l, mr, 3) : modp(F, l + 1 < NL ? l + 1 : l, mr, 0);
;         const float* sc = which == 0 ? modp(F, l, mr, 4) : modp(F, l + 1 < NL ? l + 1 : l, mr, 1);
;         const bool sl = (which == 1 && row >= ML);
;         const bool st_only = row < ML && !(which == 1 && l == NL - 1);
;         float* stp = st_only ? (float*)(F.ws + (which == 0 ? WS_ST1 : WS_ST2)) + 2 * (size_t)row : nullptr;
;         ln_row_v(F, vc, st_only ? nullptr : xrow_ptr(F, row), g, b, sh, sc, wh ? H + (size_t)row * D : nullptr, sl ? (const float*)(F.ws + WS_KN) + (size_t)(row - ML) * 1024 : nullptr, modp(F, l, mr, 5), stp);
.LBB0_107:
	s_cmp_gt_i32 s28, 4
	s_mov_b64 s[2:3], -1
	s_cbranch_scc0 .LBB0_125
	v_readlane_b32 s2, v255, 29
	s_lshl_b32 s2, s2, 3
	v_readlane_b32 s3, v255, 31
	s_add_i32 s16, s3, s2
	v_lshlrev_b32_e32 v0, 4, v186
	v_lshlrev_b32_e32 v1, 3, v186
	v_lshlrev_b32_e32 v96, 2, v186
	v_xor_b32_e32 v3, 4, v96
	v_xor_b32_e32 v4, 8, v96
	v_xor_b32_e32 v5, 16, v96
	v_xor_b32_e32 v6, 32, v96
	v_xor_b32_e32 v7, 64, v96
	v_xor_b32_e32 v8, 128, v96
	s_load_dwordx4 s[4:7], s[62:63], 0x98
	v_readlane_b32 s22, v255, 35
	v_readlane_b32 s8, v255, 17
	v_readlane_b32 s9, v255, 18
	s_add_u32 s20, s94, 0x3600000
	s_addc_u32 s21, s95, 0
	s_lshl_b32 s2, s16, 12
	s_lshl_b32 s3, s16, 15
	s_add_u32 s8, s8, s3
	s_addc_u32 s9, s9, 0
	s_add_u32 s20, s20, s2
	s_addc_u32 s21, s21, 0
	s_lshl_b32 s2, s16, 14
	s_add_u32 s10, s94, s2
	s_addc_u32 s11, s95, 0
	s_add_u32 s10, s10, 0x3e00000
	s_addc_u32 s11, s11, 0
	s_lshl_b32 s2, s16, 6
	s_add_u32 s12, s94, s2
	s_addc_u32 s13, s95, 0
	s_add_u32 s12, s12, 0x480000
	s_addc_u32 s13, s13, 0
	s_mov_b32 s3, s22
	s_mul_i32 s3, s3, 0x36000
	s_add_u32 s14, s94, s3
	s_addc_u32 s15, s95, 0
	s_add_u32 s14, s14, 0x103000
	s_addc_u32 s15, s15, 0
	s_add_u32 s18, s14, 0x1000
	s_addc_u32 s19, s15, 0
	s_lshl_b32 s2, s22, 12
	s_waitcnt lgkmcnt(0)
	s_add_u32 s4, s4, s2
	s_addc_u32 s5, s5, 0
	s_add_u32 s6, s6, s2
	s_addc_u32 s7, s7, 0
	global_load_dwordx4 v[10:13], v0, s[4:5]
	global_load_dwordx4 v[14:17], v0, s[4:5] offset:1024
	global_load_dwordx4 v[18:21], v0, s[4:5] offset:2048
	global_load_dwordx4 v[22:25], v0, s[4:5] offset:3072
	global_load_dwordx4 v[26:29], v0, s[6:7]
	global_load_dwordx4 v[30:33], v0, s[6:7] offset:1024
	global_load_dwordx4 v[34:37], v0, s[6:7] offset:2048
	global_load_dwordx4 v[38:41], v0, s[6:7] offset:3072
	s_add_u32 s2, s8, 0x0
	s_addc_u32 s3, s9, 0
	global_load_dwordx4 v[42:45], v0, s[2:3]
	global_load_dwordx4 v[46:49], v0, s[2:3] offset:1024
	global_load_dwordx4 v[50:53], v0, s[2:3] offset:2048
	global_load_dwordx4 v[54:57], v0, s[2:3] offset:3072
	s_lshr_b32 s23, s16, 8
	s_mul_i32 s23, s23, 0x6000
	s_add_u32 s2, s14, s23
	s_addc_u32 s3, s15, 0
	global_load_dwordx4 v[114:117], v0, s[2:3]
	global_load_dwordx4 v[118:121], v0, s[2:3] offset:1024
	global_load_dwordx4 v[122:125], v0, s[2:3] offset:2048
	global_load_dwordx4 v[126:129], v0, s[2:3] offset:3072
	s_add_u32 s2, s18, s23
	s_addc_u32 s3, s19, 0
	global_load_dwordx4 v[130:133], v0, s[2:3]
	global_load_dwordx4 v[134:137], v0, s[2:3] offset:1024
	global_load_dwordx4 v[138:141], v0, s[2:3] offset:2048
	global_load_dwordx4 v[142:145], v0, s[2:3] offset:3072
	s_add_u32 s2, s8, 0x1000
	s_addc_u32 s3, s9, 0
	global_load_dwordx4 v[58:61], v0, s[2:3]
	global_load_dwordx4 v[62:65], v0, s[2:3] offset:1024
	global_load_dwordx4 v[66:69], v0, s[2:3] offset:2048
	global_load_dwordx4 v[70:73], v0, s[2:3] offset:3072
	s_mov_b32 s23, 0x30000
	s_add_u32 s2, s14, s23
	s_addc_u32 s3, s15, 0
	global_load_dwordx4 v[146:149], v0, s[2:3]
	global_load_dwordx4 v[150:153], v0, s[2:3] offset:1024
	global_load_dwordx4 v[154:157], v0, s[2:3] offset:2048
	global_load_dwordx4 v[158:161], v0, s[2:3] offset:3072
	s_add_u32 s2, s18, s23
	s_addc_u32 s3, s19, 0
	global_load_dwordx4 v[162:165], v0, s[2:3]
	global_load_dwordx4 v[166:169], v0, s[2:3] offset:1024
	global_load_dwordx4 v[170:173], v0, s[2:3] offset:2048
	global_load_dwordx4 v[174:177], v0, s[2:3] offset:3072
	s_add_u32 s2, s8, 0x2000
	s_addc_u32 s3, s9, 0
	global_load_dwordx4 v[74:77], v0, s[2:3]
	global_load_dwordx4 v[78:81], v0, s[2:3] offset:1024
	global_load_dwordx4 v[82:85], v0, s[2:3] offset:2048
	global_load_dwordx4 v[86:89], v0, s[2:3] offset:3072
	s_add_u32 s2, s8, 0x3000
	s_addc_u32 s3, s9, 0
	global_load_dwordx4 v[98:101], v0, s[2:3]
	global_load_dwordx4 v[102:105], v0, s[2:3] offset:1024
	global_load_dwordx4 v[106:109], v0, s[2:3] offset:2048
	global_load_dwordx4 v[110:113], v0, s[2:3] offset:3072
	s_waitcnt vmcnt(28)
	v_add_f32_e32 v9, v42, v43
	v_add_f32_e32 v91, v44, v45
	v_mul_f32_e32 v90, v42, v42
	v_mul_f32_e32 v92, v43, v43
	v_add_f32_e32 v9, v9, v46
	v_add_f32_e32 v91, v91, v47
	v_add_f32_e32 v9, v9, v48
	v_add_f32_e32 v91, v91, v49
	v_add_f32_e32 v9, v9, v50
	v_add_f32_e32 v91, v91, v51
	v_add_f32_e32 v9, v9, v52
	v_add_f32_e32 v91, v91, v53
	v_add_f32_e32 v9, v9, v54
	v_add_f32_e32 v91, v91, v55
	v_add_f32_e32 v9, v9, v56
	v_add_f32_e32 v91, v91, v57
	v_fmac_f32_e32 v90, v44, v44
	v_fmac_f32_e32 v92, v45, v45
	v_fmac_f32_e32 v90, v46, v46
	v_fmac_f32_e32 v92, v47, v47
	v_fmac_f32_e32 v90, v48, v48
	v_fmac_f32_e32 v92, v49, v49
	v_fmac_f32_e32 v90, v50, v50
	v_fmac_f32_e32 v92, v51, v51
	v_fmac_f32_e32 v90, v52, v52
	v_fmac_f32_e32 v92, v53, v53
	v_fmac_f32_e32 v90, v54, v54
	v_fmac_f32_e32 v92, v55, v55
	v_fmac_f32_e32 v90, v56, v56
	v_fmac_f32_e32 v92, v57, v57
	v_add_f32_e32 v9, v9, v91
	v_add_f32_e32 v90, v90, v92
	s_nop 1
	v_add_f32_dpp v9, v9, v9 quad_perm:[1,0,3,2] row_mask:0xf bank_mask:0xf
	v_add_f32_dpp v90, v90, v90 quad_perm:[1,0,3,2] row_mask:0xf bank_mask:0xf
	s_nop 0
	v_add_f32_dpp v9, v9, v9 quad_perm:[2,3,0,1] row_mask:0xf bank_mask:0xf
	v_add_f32_dpp v90, v90, v90 quad_perm:[2,3,0,1] row_mask:0xf bank_mask:0xf
	s_nop 0
	v_add_f32_dpp v9, v9, v9 row_half_mirror row_mask:0xf bank_mask:0xf
	v_add_f32_dpp v90, v90, v90 row_half_mirror row_mask:0xf bank_mask:0xf
	s_nop 0
	v_add_f32_dpp v9, v9, v9 row_mirror row_mask:0xf bank_mask:0xf
	v_add_f32_dpp v90, v90, v90 row_mirror row_mask:0xf bank_mask:0xf
	s_nop 0
	v_add_f32_dpp v9, v9, v9 row_bcast:15 row_mask:0xa bank_mask:0xf
	v_add_f32_dpp v90, v90, v90 row_bcast:15 row_mask:0xa bank_mask:0xf
	s_nop 0
	v_add_f32_dpp v9, v9, v9 row_bcast:31 row_mask:0xc bank_mask:0xf
; DI void ln_row_v(const Frame& F, f32x4 (&v)[4], float* xout, const float* g, const float* b, const float* sh, const float* sc, bf16_t* hout, const float* slab, const float* gres, float* stat = nullptr) {
;     ...
;         wave_sum2(s, s2, F.lane);
;         const float mean = s * (1.f / D); const float rstd = 1.f / sqrtf(fmaxf(s2 * (1.f / D) - mean * mean, 0.f) + EPS);
;         if (stat && F.lane == 0) { f32x2 sv = {mean, rstd}; *(f32x2*)stat = sv; }
; #pragma unroll
;         for (int j = 0; j < 4; ++j) { const f32x4 gg = ((const f32x4*)g)[F.lane + 64 * j], bb = ((const f32x4*)b)[F.lane + 64 * j];
;             v[j] = (v[j] - mean) * rstd * gg + bb; if (xout) ((f32x4*)xout)[F.lane + 64 * j] = v[j]; }
;     }
;     if (hout) {
;         float s = 0.f, s2 = 0.f;
; #pragma unroll
;         for (int j = 0; j < 4; ++j) { s += (v[j][0] + v[j][1]) + (v[j][2] + v[j][3]); s2 += (v[j][0] * v[j][0] + v[j][1] * v[j][1]) + (v[j][2] * v[j][2] + v[j][3] * v[j][3]); }
;         wave_sum2(s, s2, F.lane);
;         const float mean = s * (1.f / D); const float rstd = 1.f / sqrtf(fmaxf(s2 * (1.f / D) - mean * mean, 0.f) + EPS);
	v_add_f32_dpp v90, v90, v90 row_bcast:31 row_mask:0xc bank_mask:0xf
	s_nop 0
	v_readlane_b32 s2, v9, 63
	v_readlane_b32 s3, v90, 63
	s_nop 1
	v_mov_b32_e32 v9, s2
	v_mov_b32_e32 v90, s3
	v_mul_f32_e32 v93, 0x3a800000, v9
	v_mul_f32_e32 v91, 0x3a800000, v90
	v_fma_f32 v91, -v93, v93, v91
	v_max_f32_e32 v91, 0, v91
	v_add_f32_e32 v91, 0x358637bd, v91
	v_rsq_f32_e32 v94, v91
	v_mul_f32_e32 v91, 0.5, v91
	v_mul_f32_e32 v92, v94, v94
	v_fma_f32 v92, -v91, v92, 0.5
	v_fma_f32 v94, v94, v92, v94
	s_add_u32 s2, s12, 0x0
	s_addc_u32 s3, s13, 0
	v_mov_b32_e32 v188, v93
	v_mov_b32_e32 v189, v94
	s_mov_b64 exec, 1
	global_store_dwordx2 v97, v[188:189], s[2:3]
	s_mov_b64 exec, -1
	v_sub_f32_e32 v42, v42, v93
	v_sub_f32_e32 v43, v43, v93
	v_sub_f32_e32 v44, v44, v93
	v_sub_f32_e32 v45, v45, v93
	v_sub_f32_e32 v46, v46, v93
	v_sub_f32_e32 v47, v47, v93
	v_sub_f32_e32 v48, v48, v93
	v_sub_f32_e32 v49, v49, v93
	v_sub_f32_e32 v50, v50, v93
	v_sub_f32_e32 v51, v51, v93
	v_sub_f32_e32 v52, v52, v93
	v_sub_f32_e32 v53, v53, v93
	v_sub_f32_e32 v54, v54, v93
	v_sub_f32_e32 v55, v55, v93
	v_sub_f32_e32 v56, v56, v93
	v_sub_f32_e32 v57, v57, v93
	v_mul_f32_e32 v42, v94, v42
	v_mul_f32_e32 v43, v94, v43
	v_mul_f32_e32 v44, v94, v44
	v_mul_f32_e32 v45, v94, v45
	v_mul_f32_e32 v46, v94, v46
	v_mul_f32_e32 v47, v94, v47
	v_mul_f32_e32 v48, v94, v48
	v_mul_f32_e32 v49, v94, v49
	v_mul_f32_e32 v50, v94, v50
	v_mul_f32_e32 v51, v94, v51
	v_mul_f32_e32 v52, v94, v52
	v_mul_f32_e32 v53, v94, v53
	v_mul_f32_e32 v54, v94, v54
	v_mul_f32_e32 v55, v94, v55
	v_mul_f32_e32 v56, v94, v56
	v_mul_f32_e32 v57, v94, v57
	v_fma_f32 v42, v42, v10, v26
	v_fma_f32 v43, v43, v11, v27
	v_fma_f32 v44, v44, v12, v28
	v_fma_f32 v45, v45, v13, v29
	v_fma_f32 v46, v46, v14, v30
	v_fma_f32 v47, v47, v15, v31
	v_fma_f32 v48, v48, v16, v32
	v_fma_f32 v49, v49, v17, v33
	v_fma_f32 v50, v50, v18, v34
	v_fma_f32 v51, v51, v19, v35
	v_fma_f32 v52, v52, v20, v36
	v_fma_f32 v53, v53, v21, v37
	v_fma_f32 v54, v54, v22, v38
	v_fma_f32 v55, v55, v23, v39
	v_fma_f32 v56, v56, v24, v40
	v_fma_f32 v57, v57, v25, v41
	v_add_f32_e32 v9, v42, v43
	v_add_f32_e32 v91, v44, v45
	v_mul_f32_e32 v90, v42, v42
	v_mul_f32_e32 v92, v43, v43
	v_add_f32_e32 v9, v9, v46
	v_add_f32_e32 v91, v91, v47
	v_add_f32_e32 v9, v9, v48
	v_add_f32_e32 v91, v91, v49
	v_add_f32_e32 v9, v9, v50
	v_add_f32_e32 v91, v91, v51
	v_add_f32_e32 v9, v9, v52
	v_add_f32_e32 v91, v91, v53
	v_add_f32_e32 v9, v9, v54
	v_add_f32_e32 v91, v91, v55
	v_add_f32_e32 v9, v9, v56
	v_add_f32_e32 v91, v91, v57
	v_fmac_f32_e32 v90, v44, v44
	v_fmac_f32_e32 v92, v45, v45
	v_fmac_f32_e32 v90, v46, v46
	v_fmac_f32_e32 v92, v47, v47
	v_fmac_f32_e32 v90, v48, v48
	v_fmac_f32_e32 v92, v49, v49
	v_fmac_f32_e32 v90, v50, v50
	v_fmac_f32_e32 v92, v51, v51
	v_fmac_f32_e32 v90, v52, v52
	v_fmac_f32_e32 v92, v53, v53
	v_fmac_f32_e32 v90, v54, v54
	v_fmac_f32_e32 v92, v55, v55
	v_fmac_f32_e32 v90, v56, v56
	v_fmac_f32_e32 v92, v57, v57
	v_add_f32_e32 v9, v9, v91
	v_add_f32_e32 v90, v90, v92
	s_nop 1
	v_add_f32_dpp v9, v9, v9 quad_perm:[1,0,3,2] row_mask:0xf bank_mask:0xf
	v_add_f32_dpp v90, v90, v90 quad_perm:[1,0,3,2] row_mask:0xf bank_mask:0xf
	s_nop 0
	v_add_f32_dpp v9, v9, v9 quad_perm:[2,3,0,1] row_mask:0xf bank_mask:0xf
	v_add_f32_dpp v90, v90, v90 quad_perm:[2,3,0,1] row_mask:0xf bank_mask:0xf
	s_nop 0
	v_add_f32_dpp v9, v9, v9 row_half_mirror row_mask:0xf bank_mask:0xf
	v_add_f32_dpp v90, v90, v90 row_half_mirror row_mask:0xf bank_mask:0xf
	s_nop 0
	v_add_f32_dpp v9, v9, v9 row_mirror row_mask:0xf bank_mask:0xf
	v_add_f32_dpp v90, v90, v90 row_mirror row_mask:0xf bank_mask:0xf
	s_nop 0
	v_add_f32_dpp v9, v9, v9 row_bcast:15 row_mask:0xa bank_mask:0xf
	v_add_f32_dpp v90, v90, v90 row_bcast:15 row_mask:0xa bank_mask:0xf
	s_nop 0
	v_add_f32_dpp v9, v9, v9 row_bcast:31 row_mask:0xc bank_mask:0xf
	v_add_f32_dpp v90, v90, v90 row_bcast:31 row_mask:0xc bank_mask:0xf
	s_nop 0
	v_readlane_b32 s2, v9, 63
	v_readlane_b32 s3, v90, 63
	s_nop 1
	v_mov_b32_e32 v9, s2
	v_mov_b32_e32 v90, s3
	v_mul_f32_e32 v93, 0x3a800000, v9
	v_mul_f32_e32 v91, 0x3a800000, v90
	v_fma_f32 v91, -v93, v93, v91
	v_max_f32_e32 v91, 0, v91
	v_add_f32_e32 v91, 0x358637bd, v91
	v_rsq_f32_e32 v94, v91
	v_mul_f32_e32 v91, 0.5, v91
	v_mul_f32_e32 v92, v94, v94
	v_fma_f32 v92, -v91, v92, 0.5
	v_fma_f32 v94, v94, v92, v94
	s_waitcnt vmcnt(21)
; DI unsigned pk2(float lo, float hi) { f32x2 v = {lo, hi}; bf16x2_t b = __builtin_convertvector(v, bf16x2_t); return __builtin_bit_cast(unsigned, b); }
; DI void ln_row_v(const Frame& F, f32x4 (&v)[4], float* xout, const float* g, const float* b, const float* sh, const float* sc, bf16_t* hout, const float* slab, const float* gres, float* stat = nullptr) {
;     ...
; #pragma unroll
;         for (int j = 0; j < 4; ++j) { s += (v[j][0] + v[j][1]) + (v[j][2] + v[j][3]); s2 += (v[j][0] * v[j][0] + v[j][1] * v[j][1]) + (v[j][2] * v[j][2] + v[j][3] * v[j][3]); }
;         wave_sum2(s, s2, F.lane);
;         const float mean = s * (1.f / D); const float rstd = 1.f / sqrtf(fmaxf(s2 * (1.f / D) - mean * mean, 0.f) + EPS);
;         if (stat && F.lane == 0) { f32x2 sv = {mean, rstd}; *(f32x2*)stat = sv; }
;     ...
;         const float mean = s * (1.f / D); const float rstd = 1.f / sqrtf(fmaxf(s2 * (1.f / D) - mean * mean, 0.f) + EPS);
; #pragma unroll
;         for (int j = 0; j < 4; ++j) { const f32x4 hh = ((const f32x4*)sh)[F.lane + 64 * j], cc = ((const f32x4*)sc)[F.lane + 64 * j];
;             const f32x4 o = (v[j] - mean) * rstd * (cc + 1.f) + hh; u32x2 wv; wv.x = pk2(o[0], o[1]); wv.y = pk2(o[2], o[3]);
;             ((u32x2*)hout)[F.lane + 64 * j] = wv; }
	v_sub_f32_e32 v42, v42, v93
	v_sub_f32_e32 v43, v43, v93
	v_sub_f32_e32 v44, v44, v93
	v_sub_f32_e32 v45, v45, v93
	v_sub_f32_e32 v46, v46, v93
	v_sub_f32_e32 v47, v47, v93
	v_sub_f32_e32 v48, v48, v93
	v_sub_f32_e32 v49, v49, v93
	v_sub_f32_e32 v50, v50, v93
	v_sub_f32_e32 v51, v51, v93
	v_sub_f32_e32 v52, v52, v93
	v_sub_f32_e32 v53, v53, v93
	v_sub_f32_e32 v54, v54, v93
	v_sub_f32_e32 v55, v55, v93
	v_sub_f32_e32 v56, v56, v93
	v_sub_f32_e32 v57, v57, v93
	v_add_f32_e32 v130, 1.0, v130
	v_add_f32_e32 v131, 1.0, v131
	v_add_f32_e32 v132, 1.0, v132
	v_add_f32_e32 v133, 1.0, v133
	v_add_f32_e32 v134, 1.0, v134
	v_add_f32_e32 v135, 1.0, v135
	v_add_f32_e32 v136, 1.0, v136
	v_add_f32_e32 v137, 1.0, v137
	v_add_f32_e32 v138, 1.0, v138
	v_add_f32_e32 v139, 1.0, v139
	v_add_f32_e32 v140, 1.0, v140
	v_add_f32_e32 v141, 1.0, v141
	v_add_f32_e32 v142, 1.0, v142
	v_add_f32_e32 v143, 1.0, v143
	v_add_f32_e32 v144, 1.0, v144
	v_add_f32_e32 v145, 1.0, v145
	v_mul_f32_e32 v42, v94, v42
	v_mul_f32_e32 v43, v94, v43
	v_mul_f32_e32 v44, v94, v44
	v_mul_f32_e32 v45, v94, v45
	v_mul_f32_e32 v46, v94, v46
	v_mul_f32_e32 v47, v94, v47
	v_mul_f32_e32 v48, v94, v48
	v_mul_f32_e32 v49, v94, v49
	v_mul_f32_e32 v50, v94, v50
	v_mul_f32_e32 v51, v94, v51
	v_mul_f32_e32 v52, v94, v52
	v_mul_f32_e32 v53, v94, v53
	v_mul_f32_e32 v54, v94, v54
	v_mul_f32_e32 v55, v94, v55
	v_mul_f32_e32 v56, v94, v56
	v_mul_f32_e32 v57, v94, v57
	v_fma_f32 v42, v42, v130, v114
	v_fma_f32 v43, v43, v131, v115
	v_fma_f32 v44, v44, v132, v116
	v_fma_f32 v45, v45, v133, v117
	v_fma_f32 v46, v46, v134, v118
	v_fma_f32 v47, v47, v135, v119
	v_fma_f32 v48, v48, v136, v120
	v_fma_f32 v49, v49, v137, v121
	v_fma_f32 v50, v50, v138, v122
	v_fma_f32 v51, v51, v139, v123
	v_fma_f32 v52, v52, v140, v124
	v_fma_f32 v53, v53, v141, v125
	v_fma_f32 v54, v54, v142, v126
	v_fma_f32 v55, v55, v143, v127
	v_fma_f32 v56, v56, v144, v128
	v_fma_f32 v57, v57, v145, v129
	v_cvt_pk_bf16_f32 v190, v42, v43
	v_cvt_pk_bf16_f32 v191, v44, v45
	v_cvt_pk_bf16_f32 v192, v46, v47
	v_cvt_pk_bf16_f32 v193, v48, v49
	v_cvt_pk_bf16_f32 v194, v50, v51
	v_cvt_pk_bf16_f32 v195, v52, v53
	v_cvt_pk_bf16_f32 v196, v54, v55
	v_cvt_pk_bf16_f32 v197, v56, v57
	s_add_u32 s2, s10, 0x0
	s_addc_u32 s3, s11, 0
	global_store_dwordx2 v1, v[190:191], s[2:3]
	global_store_dwordx2 v1, v[192:193], s[2:3] offset:512
	global_store_dwordx2 v1, v[194:195], s[2:3] offset:1024
	global_store_dwordx2 v1, v[196:197], s[2:3] offset:1536
	s_add_u32 s2, s8, 0x4000
	s_addc_u32 s3, s9, 0
	global_load_dwordx4 v[42:45], v0, s[2:3]
	global_load_dwordx4 v[46:49], v0, s[2:3] offset:1024
	global_load_dwordx4 v[50:53], v0, s[2:3] offset:2048
	global_load_dwordx4 v[54:57], v0, s[2:3] offset:3072
	s_waitcnt vmcnt(25)
	v_add_f32_e32 v9, v58, v59
	v_add_f32_e32 v91, v60, v61
	v_mul_f32_e32 v90, v58, v58
	v_mul_f32_e32 v92, v59, v59
	v_add_f32_e32 v9, v9, v62
	v_add_f32_e32 v91, v91, v63
	v_add_f32_e32 v9, v9, v64
	v_add_f32_e32 v91, v91, v65
	v_add_f32_e32 v9, v9, v66
	v_add_f32_e32 v91, v91, v67
	v_add_f32_e32 v9, v9, v68
	v_add_f32_e32 v91, v91, v69
	v_add_f32_e32 v9, v9, v70
	v_add_f32_e32 v91, v91, v71
	v_add_f32_e32 v9, v9, v72
	v_add_f32_e32 v91, v91, v73
	v_fmac_f32_e32 v90, v60, v60
	v_fmac_f32_e32 v92, v61, v61
	v_fmac_f32_e32 v90, v62, v62
	v_fmac_f32_e32 v92, v63, v63
	v_fmac_f32_e32 v90, v64, v64
	v_fmac_f32_e32 v92, v65, v65
	v_fmac_f32_e32 v90, v66, v66
	v_fmac_f32_e32 v92, v67, v67
	v_fmac_f32_e32 v90, v68, v68
	v_fmac_f32_e32 v92, v69, v69
	v_fmac_f32_e32 v90, v70, v70
	v_fmac_f32_e32 v92, v71, v71
	v_fmac_f32_e32 v90, v72, v72
	v_fmac_f32_e32 v92, v73, v73
	v_add_f32_e32 v9, v9, v91
	v_add_f32_e32 v90, v90, v92
	s_nop 1
	v_add_f32_dpp v9, v9, v9 quad_perm:[1,0,3,2] row_mask:0xf bank_mask:0xf
	v_add_f32_dpp v90, v90, v90 quad_perm:[1,0,3,2] row_mask:0xf bank_mask:0xf
	s_nop 0
	v_add_f32_dpp v9, v9, v9 quad_perm:[2,3,0,1] row_mask:0xf bank_mask:0xf
	v_add_f32_dpp v90, v90, v90 quad_perm:[2,3,0,1] row_mask:0xf bank_mask:0xf
	s_nop 0
	v_add_f32_dpp v9, v9, v9 row_half_mirror row_mask:0xf bank_mask:0xf
	v_add_f32_dpp v90, v90, v90 row_half_mirror row_mask:0xf bank_mask:0xf
	s_nop 0
	v_add_f32_dpp v9, v9, v9 row_mirror row_mask:0xf bank_mask:0xf
	v_add_f32_dpp v90, v90, v90 row_mirror row_mask:0xf bank_mask:0xf
	s_nop 0
	v_add_f32_dpp v9, v9, v9 row_bcast:15 row_mask:0xa bank_mask:0xf
	v_add_f32_dpp v90, v90, v90 row_bcast:15 row_mask:0xa bank_mask:0xf
	s_nop 0
	v_add_f32_dpp v9, v9, v9 row_bcast:31 row_mask:0xc bank_mask:0xf
	v_add_f32_dpp v90, v90, v90 row_bcast:31 row_mask:0xc bank_mask:0xf
	s_nop 0
	v_readlane_b32 s2, v9, 63
	v_readlane_b32 s3, v90, 63
	s_nop 1
	v_mov_b32_e32 v9, s2
	v_mov_b32_e32 v90, s3
	v_mul_f32_e32 v93, 0x3a800000, v9
	v_mul_f32_e32 v91, 0x3a800000, v90
	v_fma_f32 v91, -v93, v93, v91
	v_max_f32_e32 v91, 0, v91
	v_add_f32_e32 v91, 0x358637bd, v91
	v_rsq_f32_e32 v94, v91
	v_mul_f32_e32 v91, 0.5, v91
	v_mul_f32_e32 v92, v94, v94
	v_fma_f32 v92, -v91, v92, 0.5
	v_fma_f32 v94, v94, v92, v94
	s_add_u32 s2, s12, 0x8
	s_addc_u32 s3, s13, 0
	v_mov_b32_e32 v188, v93
	v_mov_b32_e32 v189, v94
	s_mov_b64 exec, 1
	global_store_dwordx2 v97, v[188:189], s[2:3]
	s_mov_b64 exec, -1
	v_sub_f32_e32 v58, v58, v93
	v_sub_f32_e32 v59, v59, v93
	v_sub_f32_e32 v60, v60, v93
	v_sub_f32_e32 v61, v61, v93
	v_sub_f32_e32 v62, v62, v93
	v_sub_f32_e32 v63, v63, v93
	v_sub_f32_e32 v64, v64, v93
	v_sub_f32_e32 v65, v65, v93
	v_sub_f32_e32 v66, v66, v93
	v_sub_f32_e32 v67, v67, v93
	v_sub_f32_e32 v68, v68, v93
	v_sub_f32_e32 v69, v69, v93
	v_sub_f32_e32 v70, v70, v93
	v_sub_f32_e32 v71, v71, v93
	v_sub_f32_e32 v72, v72, v93
	v_sub_f32_e32 v73, v73, v93
; DI unsigned pk2(float lo, float hi) { f32x2 v = {lo, hi}; bf16x2_t b = __builtin_convertvector(v, bf16x2_t); return __builtin_bit_cast(unsigned, b); }
; DI void ln_row_v(const Frame& F, f32x4 (&v)[4], float* xout, const float* g, const float* b, const float* sh, const float* sc, bf16_t* hout, const float* slab, const float* gres, float* stat = nullptr) {
;     ...
;         for (int j = 0; j < 4; ++j) { const f32x4 gg = ((const f32x4*)g)[F.lane + 64 * j], bb = ((const f32x4*)b)[F.lane + 64 * j];
;             v[j] = (v[j] - mean) * rstd * gg + bb; if (xout) ((f32x4*)xout)[F.lane + 64 * j] = v[j]; }
;     }
;     if (hout) {
;         float s = 0.f, s2 = 0.f;
; #pragma unroll
;         for (int j = 0; j < 4; ++j) { s += (v[j][0] + v[j][1]) + (v[j][2] + v[j][3]); s2 += (v[j][0] * v[j][0] + v[j][1] * v[j][1]) + (v[j][2] * v[j][2] + v[j][3] * v[j][3]); }
;         wave_sum2(s, s2, F.lane);
;         const float mean = s * (1.f / D); const float rstd = 1.f / sqrtf(fmaxf(s2 * (1.f / D) - mean * mean, 0.f) + EPS);
; #pragma unroll
;         for (int j = 0; j < 4; ++j) { const f32x4 hh = ((const f32x4*)sh)[F.lane + 64 * j], cc = ((const f32x4*)sc)[F.lane + 64 * j];
;             const f32x4 o = (v[j] - mean) * rstd * (cc + 1.f) + hh; u32x2 wv; wv.x = pk2(o[0], o[1]); wv.y = pk2(o[2], o[3]);
;             ((u32x2*)hout)[F.lane + 64 * j] = wv; }
	v_mul_f32_e32 v58, v94, v58
	v_mul_f32_e32 v59, v94, v59
	v_mul_f32_e32 v60, v94, v60
	v_mul_f32_e32 v61, v94, v61
	v_mul_f32_e32 v62, v94, v62
	v_mul_f32_e32 v63, v94, v63
	v_mul_f32_e32 v64, v94, v64
	v_mul_f32_e32 v65, v94, v65
	v_mul_f32_e32 v66, v94, v66
	v_mul_f32_e32 v67, v94, v67
	v_mul_f32_e32 v68, v94, v68
	v_mul_f32_e32 v69, v94, v69
	v_mul_f32_e32 v70, v94, v70
	v_mul_f32_e32 v71, v94, v71
	v_mul_f32_e32 v72, v94, v72
	v_mul_f32_e32 v73, v94, v73
	v_fma_f32 v58, v58, v10, v26
	v_fma_f32 v59, v59, v11, v27
	v_fma_f32 v60, v60, v12, v28
	v_fma_f32 v61, v61, v13, v29
	v_fma_f32 v62, v62, v14, v30
	v_fma_f32 v63, v63, v15, v31
	v_fma_f32 v64, v64, v16, v32
	v_fma_f32 v65, v65, v17, v33
	v_fma_f32 v66, v66, v18, v34
	v_fma_f32 v67, v67, v19, v35
	v_fma_f32 v68, v68, v20, v36
	v_fma_f32 v69, v69, v21, v37
	v_fma_f32 v70, v70, v22, v38
	v_fma_f32 v71, v71, v23, v39
	v_fma_f32 v72, v72, v24, v40
	v_fma_f32 v73, v73, v25, v41
	v_add_f32_e32 v9, v58, v59
	v_add_f32_e32 v91, v60, v61
	v_mul_f32_e32 v90, v58, v58
	v_mul_f32_e32 v92, v59, v59
	v_add_f32_e32 v9, v9, v62
	v_add_f32_e32 v91, v91, v63
	v_add_f32_e32 v9, v9, v64
	v_add_f32_e32 v91, v91, v65
	v_add_f32_e32 v9, v9, v66
	v_add_f32_e32 v91, v91, v67
	v_add_f32_e32 v9, v9, v68
	v_add_f32_e32 v91, v91, v69
	v_add_f32_e32 v9, v9, v70
	v_add_f32_e32 v91, v91, v71
	v_add_f32_e32 v9, v9, v72
	v_add_f32_e32 v91, v91, v73
	v_fmac_f32_e32 v90, v60, v60
	v_fmac_f32_e32 v92, v61, v61
	v_fmac_f32_e32 v90, v62, v62
	v_fmac_f32_e32 v92, v63, v63
	v_fmac_f32_e32 v90, v64, v64
	v_fmac_f32_e32 v92, v65, v65
	v_fmac_f32_e32 v90, v66, v66
	v_fmac_f32_e32 v92, v67, v67
	v_fmac_f32_e32 v90, v68, v68
	v_fmac_f32_e32 v92, v69, v69
	v_fmac_f32_e32 v90, v70, v70
	v_fmac_f32_e32 v92, v71, v71
	v_fmac_f32_e32 v90, v72, v72
	v_fmac_f32_e32 v92, v73, v73
	v_add_f32_e32 v9, v9, v91
	v_add_f32_e32 v90, v90, v92
	s_nop 1
	v_add_f32_dpp v9, v9, v9 quad_perm:[1,0,3,2] row_mask:0xf bank_mask:0xf
	v_add_f32_dpp v90, v90, v90 quad_perm:[1,0,3,2] row_mask:0xf bank_mask:0xf
	s_nop 0
	v_add_f32_dpp v9, v9, v9 quad_perm:[2,3,0,1] row_mask:0xf bank_mask:0xf
	v_add_f32_dpp v90, v90, v90 quad_perm:[2,3,0,1] row_mask:0xf bank_mask:0xf
	s_nop 0
	v_add_f32_dpp v9, v9, v9 row_half_mirror row_mask:0xf bank_mask:0xf
	v_add_f32_dpp v90, v90, v90 row_half_mirror row_mask:0xf bank_mask:0xf
	s_nop 0
	v_add_f32_dpp v9, v9, v9 row_mirror row_mask:0xf bank_mask:0xf
	v_add_f32_dpp v90, v90, v90 row_mirror row_mask:0xf bank_mask:0xf
	s_nop 0
	v_add_f32_dpp v9, v9, v9 row_bcast:15 row_mask:0xa bank_mask:0xf
	v_add_f32_dpp v90, v90, v90 row_bcast:15 row_mask:0xa bank_mask:0xf
	s_nop 0
	v_add_f32_dpp v9, v9, v9 row_bcast:31 row_mask:0xc bank_mask:0xf
	v_add_f32_dpp v90, v90, v90 row_bcast:31 row_mask:0xc bank_mask:0xf
	s_nop 0
	v_readlane_b32 s2, v9, 63
	v_readlane_b32 s3, v90, 63
	s_nop 1
	v_mov_b32_e32 v9, s2
	v_mov_b32_e32 v90, s3
	v_mul_f32_e32 v93, 0x3a800000, v9
	v_mul_f32_e32 v91, 0x3a800000, v90
	v_fma_f32 v91, -v93, v93, v91
	v_max_f32_e32 v91, 0, v91
	v_add_f32_e32 v91, 0x358637bd, v91
	v_rsq_f32_e32 v94, v91
	v_mul_f32_e32 v91, 0.5, v91
	v_mul_f32_e32 v92, v94, v94
	v_fma_f32 v92, -v91, v92, 0.5
	v_fma_f32 v94, v94, v92, v94
	v_sub_f32_e32 v58, v58, v93
	v_sub_f32_e32 v59, v59, v93
	v_sub_f32_e32 v60, v60, v93
	v_sub_f32_e32 v61, v61, v93
	v_sub_f32_e32 v62, v62, v93
	v_sub_f32_e32 v63, v63, v93
	v_sub_f32_e32 v64, v64, v93
	v_sub_f32_e32 v65, v65, v93
	v_sub_f32_e32 v66, v66, v93
	v_sub_f32_e32 v67, v67, v93
	v_sub_f32_e32 v68, v68, v93
	v_sub_f32_e32 v69, v69, v93
	v_sub_f32_e32 v70, v70, v93
	v_sub_f32_e32 v71, v71, v93
	v_sub_f32_e32 v72, v72, v93
	v_sub_f32_e32 v73, v73, v93
	v_mul_f32_e32 v58, v94, v58
	v_mul_f32_e32 v59, v94, v59
	v_mul_f32_e32 v60, v94, v60
	v_mul_f32_e32 v61, v94, v61
	v_mul_f32_e32 v62, v94, v62
	v_mul_f32_e32 v63, v94, v63
	v_mul_f32_e32 v64, v94, v64
	v_mul_f32_e32 v65, v94, v65
	v_mul_f32_e32 v66, v94, v66
	v_mul_f32_e32 v67, v94, v67
	v_mul_f32_e32 v68, v94, v68
	v_mul_f32_e32 v69, v94, v69
	v_mul_f32_e32 v70, v94, v70
	v_mul_f32_e32 v71, v94, v71
	v_mul_f32_e32 v72, v94, v72
	v_mul_f32_e32 v73, v94, v73
	v_fma_f32 v58, v58, v130, v114
	v_fma_f32 v59, v59, v131, v115
	v_fma_f32 v60, v60, v132, v116
	v_fma_f32 v61, v61, v133, v117
	v_fma_f32 v62, v62, v134, v118
	v_fma_f32 v63, v63, v135, v119
	v_fma_f32 v64, v64, v136, v120
	v_fma_f32 v65, v65, v137, v121
	v_fma_f32 v66, v66, v138, v122
	v_fma_f32 v67, v67, v139, v123
	v_fma_f32 v68, v68, v140, v124
	v_fma_f32 v69, v69, v141, v125
	v_fma_f32 v70, v70, v142, v126
	v_fma_f32 v71, v71, v143, v127
	v_fma_f32 v72, v72, v144, v128
	v_fma_f32 v73, v73, v145, v129
	v_cvt_pk_bf16_f32 v190, v58, v59
	v_cvt_pk_bf16_f32 v191, v60, v61
	v_cvt_pk_bf16_f32 v192, v62, v63
	v_cvt_pk_bf16_f32 v193, v64, v65
	v_cvt_pk_bf16_f32 v194, v66, v67
	v_cvt_pk_bf16_f32 v195, v68, v69
	v_cvt_pk_bf16_f32 v196, v70, v71
	v_cvt_pk_bf16_f32 v197, v72, v73
	s_add_u32 s2, s10, 0x800
	s_addc_u32 s3, s11, 0
	global_store_dwordx2 v1, v[190:191], s[2:3]
	global_store_dwordx2 v1, v[192:193], s[2:3] offset:512
	global_store_dwordx2 v1, v[194:195], s[2:3] offset:1024
	global_store_dwordx2 v1, v[196:197], s[2:3] offset:1536
	s_add_u32 s2, s8, 0x5000
	s_addc_u32 s3, s9, 0
	global_load_dwordx4 v[58:61], v0, s[2:3]
	global_load_dwordx4 v[62:65], v0, s[2:3] offset:1024
	global_load_dwordx4 v[66:69], v0, s[2:3] offset:2048
	global_load_dwordx4 v[70:73], v0, s[2:3] offset:3072
	s_waitcnt vmcnt(22)
; DI void ln_row_v(const Frame& F, f32x4 (&v)[4], float* xout, const float* g, const float* b, const float* sh, const float* sc, bf16_t* hout, const float* slab, const float* gres, float* stat = nullptr) {
;     ...
; #pragma unroll
;         for (int j = 0; j < 4; ++j) { s += (v[j][0] + v[j][1]) + (v[j][2] + v[j][3]); s2 += (v[j][0] * v[j][0] + v[j][1] * v[j][1]) + (v[j][2] * v[j][2] + v[j][3] * v[j][3]); }
;         wave_sum2(s, s2, F.lane);
;         const float mean = s * (1.f / D); const float rstd = 1.f / sqrtf(fmaxf(s2 * (1.f / D) - mean * mean, 0.f) + EPS);
;         if (stat && F.lane == 0) { f32x2 sv = {mean, rstd}; *(f32x2*)stat = sv; }
; #pragma unroll
;         for (int j = 0; j < 4; ++j) { const f32x4 gg = ((const f32x4*)g)[F.lane + 64 * j], bb = ((const f32x4*)b)[F.lane + 64 * j];
;             v[j] = (v[j] - mean) * rstd * gg + bb; if (xout) ((f32x4*)xout)[F.lane + 64 * j] = v[j]; }
;     }
;     if (hout) {
;         float s = 0.f, s2 = 0.f;
; #pragma unroll
;         for (int j = 0; j < 4; ++j) { s += (v[j][0] + v[j][1]) + (v[j][2] + v[j][3]); s2 += (v[j][0] * v[j][0] + v[j][1] * v[j][1]) + (v[j][2] * v[j][2] + v[j][3] * v[j][3]); }
;         wave_sum2(s, s2, F.lane);
	v_add_f32_e32 v9, v74, v75
	v_add_f32_e32 v91, v76, v77
	v_mul_f32_e32 v90, v74, v74
	v_mul_f32_e32 v92, v75, v75
	v_add_f32_e32 v9, v9, v78
	v_add_f32_e32 v91, v91, v79
	v_add_f32_e32 v9, v9, v80
	v_add_f32_e32 v91, v91, v81
	v_add_f32_e32 v9, v9, v82
	v_add_f32_e32 v91, v91, v83
	v_add_f32_e32 v9, v9, v84
	v_add_f32_e32 v91, v91, v85
	v_add_f32_e32 v9, v9, v86
	v_add_f32_e32 v91, v91, v87
	v_add_f32_e32 v9, v9, v88
	v_add_f32_e32 v91, v91, v89
	v_fmac_f32_e32 v90, v76, v76
	v_fmac_f32_e32 v92, v77, v77
	v_fmac_f32_e32 v90, v78, v78
	v_fmac_f32_e32 v92, v79, v79
	v_fmac_f32_e32 v90, v80, v80
	v_fmac_f32_e32 v92, v81, v81
	v_fmac_f32_e32 v90, v82, v82
	v_fmac_f32_e32 v92, v83, v83
	v_fmac_f32_e32 v90, v84, v84
	v_fmac_f32_e32 v92, v85, v85
	v_fmac_f32_e32 v90, v86, v86
	v_fmac_f32_e32 v92, v87, v87
	v_fmac_f32_e32 v90, v88, v88
	v_fmac_f32_e32 v92, v89, v89
	v_add_f32_e32 v9, v9, v91
	v_add_f32_e32 v90, v90, v92
	s_nop 1
	v_add_f32_dpp v9, v9, v9 quad_perm:[1,0,3,2] row_mask:0xf bank_mask:0xf
	v_add_f32_dpp v90, v90, v90 quad_perm:[1,0,3,2] row_mask:0xf bank_mask:0xf
	s_nop 0
	v_add_f32_dpp v9, v9, v9 quad_perm:[2,3,0,1] row_mask:0xf bank_mask:0xf
	v_add_f32_dpp v90, v90, v90 quad_perm:[2,3,0,1] row_mask:0xf bank_mask:0xf
	s_nop 0
	v_add_f32_dpp v9, v9, v9 row_half_mirror row_mask:0xf bank_mask:0xf
	v_add_f32_dpp v90, v90, v90 row_half_mirror row_mask:0xf bank_mask:0xf
	s_nop 0
	v_add_f32_dpp v9, v9, v9 row_mirror row_mask:0xf bank_mask:0xf
	v_add_f32_dpp v90, v90, v90 row_mirror row_mask:0xf bank_mask:0xf
	s_nop 0
	v_add_f32_dpp v9, v9, v9 row_bcast:15 row_mask:0xa bank_mask:0xf
	v_add_f32_dpp v90, v90, v90 row_bcast:15 row_mask:0xa bank_mask:0xf
	s_nop 0
	v_add_f32_dpp v9, v9, v9 row_bcast:31 row_mask:0xc bank_mask:0xf
	v_add_f32_dpp v90, v90, v90 row_bcast:31 row_mask:0xc bank_mask:0xf
	s_nop 0
	v_readlane_b32 s2, v9, 63
	v_readlane_b32 s3, v90, 63
	s_nop 1
	v_mov_b32_e32 v9, s2
	v_mov_b32_e32 v90, s3
	v_mul_f32_e32 v93, 0x3a800000, v9
	v_mul_f32_e32 v91, 0x3a800000, v90
	v_fma_f32 v91, -v93, v93, v91
	v_max_f32_e32 v91, 0, v91
	v_add_f32_e32 v91, 0x358637bd, v91
	v_rsq_f32_e32 v94, v91
	v_mul_f32_e32 v91, 0.5, v91
	v_mul_f32_e32 v92, v94, v94
	v_fma_f32 v92, -v91, v92, 0.5
	v_fma_f32 v94, v94, v92, v94
	s_add_u32 s2, s12, 0x10
	s_addc_u32 s3, s13, 0
	v_mov_b32_e32 v188, v93
	v_mov_b32_e32 v189, v94
	s_mov_b64 exec, 1
	global_store_dwordx2 v97, v[188:189], s[2:3]
	s_mov_b64 exec, -1
	v_sub_f32_e32 v74, v74, v93
	v_sub_f32_e32 v75, v75, v93
	v_sub_f32_e32 v76, v76, v93
	v_sub_f32_e32 v77, v77, v93
	v_sub_f32_e32 v78, v78, v93
	v_sub_f32_e32 v79, v79, v93
	v_sub_f32_e32 v80, v80, v93
	v_sub_f32_e32 v81, v81, v93
	v_sub_f32_e32 v82, v82, v93
	v_sub_f32_e32 v83, v83, v93
	v_sub_f32_e32 v84, v84, v93
	v_sub_f32_e32 v85, v85, v93
	v_sub_f32_e32 v86, v86, v93
	v_sub_f32_e32 v87, v87, v93
	v_sub_f32_e32 v88, v88, v93
	v_sub_f32_e32 v89, v89, v93
	v_mul_f32_e32 v74, v94, v74
	v_mul_f32_e32 v75, v94, v75
	v_mul_f32_e32 v76, v94, v76
	v_mul_f32_e32 v77, v94, v77
	v_mul_f32_e32 v78, v94, v78
	v_mul_f32_e32 v79, v94, v79
	v_mul_f32_e32 v80, v94, v80
	v_mul_f32_e32 v81, v94, v81
	v_mul_f32_e32 v82, v94, v82
	v_mul_f32_e32 v83, v94, v83
	v_mul_f32_e32 v84, v94, v84
	v_mul_f32_e32 v85, v94, v85
	v_mul_f32_e32 v86, v94, v86
	v_mul_f32_e32 v87, v94, v87
	v_mul_f32_e32 v88, v94, v88
	v_mul_f32_e32 v89, v94, v89
	v_fma_f32 v74, v74, v10, v26
	v_fma_f32 v75, v75, v11, v27
	v_fma_f32 v76, v76, v12, v28
	v_fma_f32 v77, v77, v13, v29
	v_fma_f32 v78, v78, v14, v30
	v_fma_f32 v79, v79, v15, v31
	v_fma_f32 v80, v80, v16, v32
	v_fma_f32 v81, v81, v17, v33
	v_fma_f32 v82, v82, v18, v34
	v_fma_f32 v83, v83, v19, v35
	v_fma_f32 v84, v84, v20, v36
	v_fma_f32 v85, v85, v21, v37
	v_fma_f32 v86, v86, v22, v38
	v_fma_f32 v87, v87, v23, v39
	v_fma_f32 v88, v88, v24, v40
	v_fma_f32 v89, v89, v25, v41
	v_add_f32_e32 v9, v74, v75
	v_add_f32_e32 v91, v76, v77
	v_mul_f32_e32 v90, v74, v74
	v_mul_f32_e32 v92, v75, v75
	v_add_f32_e32 v9, v9, v78
	v_add_f32_e32 v91, v91, v79
	v_add_f32_e32 v9, v9, v80
	v_add_f32_e32 v91, v91, v81
	v_add_f32_e32 v9, v9, v82
	v_add_f32_e32 v91, v91, v83
	v_add_f32_e32 v9, v9, v84
	v_add_f32_e32 v91, v91, v85
	v_add_f32_e32 v9, v9, v86
	v_add_f32_e32 v91, v91, v87
	v_add_f32_e32 v9, v9, v88
	v_add_f32_e32 v91, v91, v89
	v_fmac_f32_e32 v90, v76, v76
	v_fmac_f32_e32 v92, v77, v77
	v_fmac_f32_e32 v90, v78, v78
	v_fmac_f32_e32 v92, v79, v79
	v_fmac_f32_e32 v90, v80, v80
	v_fmac_f32_e32 v92, v81, v81
	v_fmac_f32_e32 v90, v82, v82
	v_fmac_f32_e32 v92, v83, v83
	v_fmac_f32_e32 v90, v84, v84
	v_fmac_f32_e32 v92, v85, v85
	v_fmac_f32_e32 v90, v86, v86
	v_fmac_f32_e32 v92, v87, v87
	v_fmac_f32_e32 v90, v88, v88
	v_fmac_f32_e32 v92, v89, v89
	v_add_f32_e32 v9, v9, v91
	v_add_f32_e32 v90, v90, v92
	s_nop 1
	v_add_f32_dpp v9, v9, v9 quad_perm:[1,0,3,2] row_mask:0xf bank_mask:0xf
	v_add_f32_dpp v90, v90, v90 quad_perm:[1,0,3,2] row_mask:0xf bank_mask:0xf
	s_nop 0
	v_add_f32_dpp v9, v9, v9 quad_perm:[2,3,0,1] row_mask:0xf bank_mask:0xf
	v_add_f32_dpp v90, v90, v90 quad_perm:[2,3,0,1] row_mask:0xf bank_mask:0xf
	s_nop 0
	v_add_f32_dpp v9, v9, v9 row_half_mirror row_mask:0xf bank_mask:0xf
	v_add_f32_dpp v90, v90, v90 row_half_mirror row_mask:0xf bank_mask:0xf
	s_nop 0
	v_add_f32_dpp v9, v9, v9 row_mirror row_mask:0xf bank_mask:0xf
	v_add_f32_dpp v90, v90, v90 row_mirror row_mask:0xf bank_mask:0xf
	s_nop 0
	v_add_f32_dpp v9, v9, v9 row_bcast:15 row_mask:0xa bank_mask:0xf
	v_add_f32_dpp v90, v90, v90 row_bcast:15 row_mask:0xa bank_mask:0xf
	s_nop 0
	v_add_f32_dpp v9, v9, v9 row_bcast:31 row_mask:0xc bank_mask:0xf
	v_add_f32_dpp v90, v90, v90 row_bcast:31 row_mask:0xc bank_mask:0xf
; DI unsigned pk2(float lo, float hi) { f32x2 v = {lo, hi}; bf16x2_t b = __builtin_convertvector(v, bf16x2_t); return __builtin_bit_cast(unsigned, b); }
; DI void ln_row_v(const Frame& F, f32x4 (&v)[4], float* xout, const float* g, const float* b, const float* sh, const float* sc, bf16_t* hout, const float* slab, const float* gres, float* stat = nullptr) {
;     ...
; #pragma unroll
;         for (int j = 0; j < 4; ++j) { s += (v[j][0] + v[j][1]) + (v[j][2] + v[j][3]); s2 += (v[j][0] * v[j][0] + v[j][1] * v[j][1]) + (v[j][2] * v[j][2] + v[j][3] * v[j][3]); }
;         wave_sum2(s, s2, F.lane);
;         const float mean = s * (1.f / D); const float rstd = 1.f / sqrtf(fmaxf(s2 * (1.f / D) - mean * mean, 0.f) + EPS);
;         if (stat && F.lane == 0) { f32x2 sv = {mean, rstd}; *(f32x2*)stat = sv; }
;     ...
;         const float mean = s * (1.f / D); const float rstd = 1.f / sqrtf(fmaxf(s2 * (1.f / D) - mean * mean, 0.f) + EPS);
; #pragma unroll
;         for (int j = 0; j < 4; ++j) { const f32x4 hh = ((const f32x4*)sh)[F.lane + 64 * j], cc = ((const f32x4*)sc)[F.lane + 64 * j];
;             const f32x4 o = (v[j] - mean) * rstd * (cc + 1.f) + hh; u32x2 wv; wv.x = pk2(o[0], o[1]); wv.y = pk2(o[2], o[3]);
;             ((u32x2*)hout)[F.lane + 64 * j] = wv; }
	s_nop 0
	v_readlane_b32 s2, v9, 63
	v_readlane_b32 s3, v90, 63
	s_nop 1
	v_mov_b32_e32 v9, s2
	v_mov_b32_e32 v90, s3
	v_mul_f32_e32 v93, 0x3a800000, v9
	v_mul_f32_e32 v91, 0x3a800000, v90
	v_fma_f32 v91, -v93, v93, v91
	v_max_f32_e32 v91, 0, v91
	v_add_f32_e32 v91, 0x358637bd, v91
	v_rsq_f32_e32 v94, v91
	v_mul_f32_e32 v91, 0.5, v91
	v_mul_f32_e32 v92, v94, v94
	v_fma_f32 v92, -v91, v92, 0.5
	v_fma_f32 v94, v94, v92, v94
	v_sub_f32_e32 v74, v74, v93
	v_sub_f32_e32 v75, v75, v93
	v_sub_f32_e32 v76, v76, v93
	v_sub_f32_e32 v77, v77, v93
	v_sub_f32_e32 v78, v78, v93
	v_sub_f32_e32 v79, v79, v93
	v_sub_f32_e32 v80, v80, v93
	v_sub_f32_e32 v81, v81, v93
	v_sub_f32_e32 v82, v82, v93
	v_sub_f32_e32 v83, v83, v93
	v_sub_f32_e32 v84, v84, v93
	v_sub_f32_e32 v85, v85, v93
	v_sub_f32_e32 v86, v86, v93
	v_sub_f32_e32 v87, v87, v93
	v_sub_f32_e32 v88, v88, v93
	v_sub_f32_e32 v89, v89, v93
	v_mul_f32_e32 v74, v94, v74
	v_mul_f32_e32 v75, v94, v75
	v_mul_f32_e32 v76, v94, v76
	v_mul_f32_e32 v77, v94, v77
	v_mul_f32_e32 v78, v94, v78
	v_mul_f32_e32 v79, v94, v79
	v_mul_f32_e32 v80, v94, v80
	v_mul_f32_e32 v81, v94, v81
	v_mul_f32_e32 v82, v94, v82
	v_mul_f32_e32 v83, v94, v83
	v_mul_f32_e32 v84, v94, v84
	v_mul_f32_e32 v85, v94, v85
	v_mul_f32_e32 v86, v94, v86
	v_mul_f32_e32 v87, v94, v87
	v_mul_f32_e32 v88, v94, v88
	v_mul_f32_e32 v89, v94, v89
	v_fma_f32 v74, v74, v130, v114
	v_fma_f32 v75, v75, v131, v115
	v_fma_f32 v76, v76, v132, v116
	v_fma_f32 v77, v77, v133, v117
	v_fma_f32 v78, v78, v134, v118
	v_fma_f32 v79, v79, v135, v119
	v_fma_f32 v80, v80, v136, v120
	v_fma_f32 v81, v81, v137, v121
	v_fma_f32 v82, v82, v138, v122
	v_fma_f32 v83, v83, v139, v123
	v_fma_f32 v84, v84, v140, v124
	v_fma_f32 v85, v85, v141, v125
	v_fma_f32 v86, v86, v142, v126
	v_fma_f32 v87, v87, v143, v127
	v_fma_f32 v88, v88, v144, v128
	v_fma_f32 v89, v89, v145, v129
	v_cvt_pk_bf16_f32 v190, v74, v75
	v_cvt_pk_bf16_f32 v191, v76, v77
	v_cvt_pk_bf16_f32 v192, v78, v79
	v_cvt_pk_bf16_f32 v193, v80, v81
	v_cvt_pk_bf16_f32 v194, v82, v83
	v_cvt_pk_bf16_f32 v195, v84, v85
	v_cvt_pk_bf16_f32 v196, v86, v87
	v_cvt_pk_bf16_f32 v197, v88, v89
	s_add_u32 s2, s10, 0x1000
	s_addc_u32 s3, s11, 0
	global_store_dwordx2 v1, v[190:191], s[2:3]
	global_store_dwordx2 v1, v[192:193], s[2:3] offset:512
	global_store_dwordx2 v1, v[194:195], s[2:3] offset:1024
	global_store_dwordx2 v1, v[196:197], s[2:3] offset:1536
	s_add_u32 s2, s8, 0x6000
	s_addc_u32 s3, s9, 0
	global_load_dwordx4 v[74:77], v0, s[2:3]
	global_load_dwordx4 v[78:81], v0, s[2:3] offset:1024
	global_load_dwordx4 v[82:85], v0, s[2:3] offset:2048
	global_load_dwordx4 v[86:89], v0, s[2:3] offset:3072
	s_waitcnt vmcnt(27)
	v_add_f32_e32 v9, v98, v99
	v_add_f32_e32 v91, v100, v101
	v_mul_f32_e32 v90, v98, v98
	v_mul_f32_e32 v92, v99, v99
	v_add_f32_e32 v9, v9, v102
	v_add_f32_e32 v91, v91, v103
	v_add_f32_e32 v9, v9, v104
	v_add_f32_e32 v91, v91, v105
	v_add_f32_e32 v9, v9, v106
	v_add_f32_e32 v91, v91, v107
	v_add_f32_e32 v9, v9, v108
	v_add_f32_e32 v91, v91, v109
	v_add_f32_e32 v9, v9, v110
	v_add_f32_e32 v91, v91, v111
	v_add_f32_e32 v9, v9, v112
	v_add_f32_e32 v91, v91, v113
	v_fmac_f32_e32 v90, v100, v100
	v_fmac_f32_e32 v92, v101, v101
	v_fmac_f32_e32 v90, v102, v102
	v_fmac_f32_e32 v92, v103, v103
	v_fmac_f32_e32 v90, v104, v104
	v_fmac_f32_e32 v92, v105, v105
	v_fmac_f32_e32 v90, v106, v106
	v_fmac_f32_e32 v92, v107, v107
	v_fmac_f32_e32 v90, v108, v108
	v_fmac_f32_e32 v92, v109, v109
	v_fmac_f32_e32 v90, v110, v110
	v_fmac_f32_e32 v92, v111, v111
	v_fmac_f32_e32 v90, v112, v112
	v_fmac_f32_e32 v92, v113, v113
	v_add_f32_e32 v9, v9, v91
	v_add_f32_e32 v90, v90, v92
	s_nop 1
	v_add_f32_dpp v9, v9, v9 quad_perm:[1,0,3,2] row_mask:0xf bank_mask:0xf
	v_add_f32_dpp v90, v90, v90 quad_perm:[1,0,3,2] row_mask:0xf bank_mask:0xf
	s_nop 0
	v_add_f32_dpp v9, v9, v9 quad_perm:[2,3,0,1] row_mask:0xf bank_mask:0xf
	v_add_f32_dpp v90, v90, v90 quad_perm:[2,3,0,1] row_mask:0xf bank_mask:0xf
	s_nop 0
	v_add_f32_dpp v9, v9, v9 row_half_mirror row_mask:0xf bank_mask:0xf
	v_add_f32_dpp v90, v90, v90 row_half_mirror row_mask:0xf bank_mask:0xf
	s_nop 0
	v_add_f32_dpp v9, v9, v9 row_mirror row_mask:0xf bank_mask:0xf
	v_add_f32_dpp v90, v90, v90 row_mirror row_mask:0xf bank_mask:0xf
	s_nop 0
	v_add_f32_dpp v9, v9, v9 row_bcast:15 row_mask:0xa bank_mask:0xf
	v_add_f32_dpp v90, v90, v90 row_bcast:15 row_mask:0xa bank_mask:0xf
	s_nop 0
	v_add_f32_dpp v9, v9, v9 row_bcast:31 row_mask:0xc bank_mask:0xf
	v_add_f32_dpp v90, v90, v90 row_bcast:31 row_mask:0xc bank_mask:0xf
	s_nop 0
	v_readlane_b32 s2, v9, 63
	v_readlane_b32 s3, v90, 63
	s_nop 1
	v_mov_b32_e32 v9, s2
	v_mov_b32_e32 v90, s3
	v_mul_f32_e32 v93, 0x3a800000, v9
	v_mul_f32_e32 v91, 0x3a800000, v90
	v_fma_f32 v91, -v93, v93, v91
	v_max_f32_e32 v91, 0, v91
	v_add_f32_e32 v91, 0x358637bd, v91
	v_rsq_f32_e32 v94, v91
	v_mul_f32_e32 v91, 0.5, v91
	v_mul_f32_e32 v92, v94, v94
	v_fma_f32 v92, -v91, v92, 0.5
	v_fma_f32 v94, v94, v92, v94
	s_add_u32 s2, s12, 0x18
	s_addc_u32 s3, s13, 0
	v_mov_b32_e32 v188, v93
	v_mov_b32_e32 v189, v94
	s_mov_b64 exec, 1
	global_store_dwordx2 v97, v[188:189], s[2:3]
	s_mov_b64 exec, -1
	v_sub_f32_e32 v98, v98, v93
	v_sub_f32_e32 v99, v99, v93
	v_sub_f32_e32 v100, v100, v93
	v_sub_f32_e32 v101, v101, v93
	v_sub_f32_e32 v102, v102, v93
	v_sub_f32_e32 v103, v103, v93
	v_sub_f32_e32 v104, v104, v93
	v_sub_f32_e32 v105, v105, v93
	v_sub_f32_e32 v106, v106, v93
	v_sub_f32_e32 v107, v107, v93
	v_sub_f32_e32 v108, v108, v93
	v_sub_f32_e32 v109, v109, v93
	v_sub_f32_e32 v110, v110, v93
	v_sub_f32_e32 v111, v111, v93
	v_sub_f32_e32 v112, v112, v93
	v_sub_f32_e32 v113, v113, v93
; DI unsigned pk2(float lo, float hi) { f32x2 v = {lo, hi}; bf16x2_t b = __builtin_convertvector(v, bf16x2_t); return __builtin_bit_cast(unsigned, b); }
; DI void ln_row_v(const Frame& F, f32x4 (&v)[4], float* xout, const float* g, const float* b, const float* sh, const float* sc, bf16_t* hout, const float* slab, const float* gres, float* stat = nullptr) {
;     ...
;         for (int j = 0; j < 4; ++j) { const f32x4 gg = ((const f32x4*)g)[F.lane + 64 * j], bb = ((const f32x4*)b)[F.lane + 64 * j];
;             v[j] = (v[j] - mean) * rstd * gg + bb; if (xout) ((f32x4*)xout)[F.lane + 64 * j] = v[j]; }
;     }
;     if (hout) {
;         float s = 0.f, s2 = 0.f;
; #pragma unroll
;         for (int j = 0; j < 4; ++j) { s += (v[j][0] + v[j][1]) + (v[j][2] + v[j][3]); s2 += (v[j][0] * v[j][0] + v[j][1] * v[j][1]) + (v[j][2] * v[j][2] + v[j][3] * v[j][3]); }
;         wave_sum2(s, s2, F.lane);
;         const float mean = s * (1.f / D); const float rstd = 1.f / sqrtf(fmaxf(s2 * (1.f / D) - mean * mean, 0.f) + EPS);
; #pragma unroll
;         for (int j = 0; j < 4; ++j) { const f32x4 hh = ((const f32x4*)sh)[F.lane + 64 * j], cc = ((const f32x4*)sc)[F.lane + 64 * j];
;             const f32x4 o = (v[j] - mean) * rstd * (cc + 1.f) + hh; u32x2 wv; wv.x = pk2(o[0], o[1]); wv.y = pk2(o[2], o[3]);
;             ((u32x2*)hout)[F.lane + 64 * j] = wv; }
	v_mul_f32_e32 v98, v94, v98
	v_mul_f32_e32 v99, v94, v99
	v_mul_f32_e32 v100, v94, v100
	v_mul_f32_e32 v101, v94, v101
	v_mul_f32_e32 v102, v94, v102
	v_mul_f32_e32 v103, v94, v103
	v_mul_f32_e32 v104, v94, v104
	v_mul_f32_e32 v105, v94, v105
	v_mul_f32_e32 v106, v94, v106
	v_mul_f32_e32 v107, v94, v107
	v_mul_f32_e32 v108, v94, v108
	v_mul_f32_e32 v109, v94, v109
	v_mul_f32_e32 v110, v94, v110
	v_mul_f32_e32 v111, v94, v111
	v_mul_f32_e32 v112, v94, v112
	v_mul_f32_e32 v113, v94, v113
	v_fma_f32 v98, v98, v10, v26
	v_fma_f32 v99, v99, v11, v27
	v_fma_f32 v100, v100, v12, v28
	v_fma_f32 v101, v101, v13, v29
	v_fma_f32 v102, v102, v14, v30
	v_fma_f32 v103, v103, v15, v31
	v_fma_f32 v104, v104, v16, v32
	v_fma_f32 v105, v105, v17, v33
	v_fma_f32 v106, v106, v18, v34
	v_fma_f32 v107, v107, v19, v35
	v_fma_f32 v108, v108, v20, v36
	v_fma_f32 v109, v109, v21, v37
	v_fma_f32 v110, v110, v22, v38
	v_fma_f32 v111, v111, v23, v39
	v_fma_f32 v112, v112, v24, v40
	v_fma_f32 v113, v113, v25, v41
	v_add_f32_e32 v9, v98, v99
	v_add_f32_e32 v91, v100, v101
	v_mul_f32_e32 v90, v98, v98
	v_mul_f32_e32 v92, v99, v99
	v_add_f32_e32 v9, v9, v102
	v_add_f32_e32 v91, v91, v103
	v_add_f32_e32 v9, v9, v104
	v_add_f32_e32 v91, v91, v105
	v_add_f32_e32 v9, v9, v106
	v_add_f32_e32 v91, v91, v107
	v_add_f32_e32 v9, v9, v108
	v_add_f32_e32 v91, v91, v109
	v_add_f32_e32 v9, v9, v110
	v_add_f32_e32 v91, v91, v111
	v_add_f32_e32 v9, v9, v112
	v_add_f32_e32 v91, v91, v113
	v_fmac_f32_e32 v90, v100, v100
	v_fmac_f32_e32 v92, v101, v101
	v_fmac_f32_e32 v90, v102, v102
	v_fmac_f32_e32 v92, v103, v103
	v_fmac_f32_e32 v90, v104, v104
	v_fmac_f32_e32 v92, v105, v105
	v_fmac_f32_e32 v90, v106, v106
	v_fmac_f32_e32 v92, v107, v107
	v_fmac_f32_e32 v90, v108, v108
	v_fmac_f32_e32 v92, v109, v109
	v_fmac_f32_e32 v90, v110, v110
	v_fmac_f32_e32 v92, v111, v111
	v_fmac_f32_e32 v90, v112, v112
	v_fmac_f32_e32 v92, v113, v113
	v_add_f32_e32 v9, v9, v91
	v_add_f32_e32 v90, v90, v92
	s_nop 1
	v_add_f32_dpp v9, v9, v9 quad_perm:[1,0,3,2] row_mask:0xf bank_mask:0xf
	v_add_f32_dpp v90, v90, v90 quad_perm:[1,0,3,2] row_mask:0xf bank_mask:0xf
	s_nop 0
	v_add_f32_dpp v9, v9, v9 quad_perm:[2,3,0,1] row_mask:0xf bank_mask:0xf
	v_add_f32_dpp v90, v90, v90 quad_perm:[2,3,0,1] row_mask:0xf bank_mask:0xf
	s_nop 0
	v_add_f32_dpp v9, v9, v9 row_half_mirror row_mask:0xf bank_mask:0xf
	v_add_f32_dpp v90, v90, v90 row_half_mirror row_mask:0xf bank_mask:0xf
	s_nop 0
	v_add_f32_dpp v9, v9, v9 row_mirror row_mask:0xf bank_mask:0xf
	v_add_f32_dpp v90, v90, v90 row_mirror row_mask:0xf bank_mask:0xf
	s_nop 0
	v_add_f32_dpp v9, v9, v9 row_bcast:15 row_mask:0xa bank_mask:0xf
	v_add_f32_dpp v90, v90, v90 row_bcast:15 row_mask:0xa bank_mask:0xf
	s_nop 0
	v_add_f32_dpp v9, v9, v9 row_bcast:31 row_mask:0xc bank_mask:0xf
	v_add_f32_dpp v90, v90, v90 row_bcast:31 row_mask:0xc bank_mask:0xf
	s_nop 0
	v_readlane_b32 s2, v9, 63
	v_readlane_b32 s3, v90, 63
	s_nop 1
	v_mov_b32_e32 v9, s2
	v_mov_b32_e32 v90, s3
	v_mul_f32_e32 v93, 0x3a800000, v9
	v_mul_f32_e32 v91, 0x3a800000, v90
	v_fma_f32 v91, -v93, v93, v91
	v_max_f32_e32 v91, 0, v91
	v_add_f32_e32 v91, 0x358637bd, v91
	v_rsq_f32_e32 v94, v91
	v_mul_f32_e32 v91, 0.5, v91
	v_mul_f32_e32 v92, v94, v94
	v_fma_f32 v92, -v91, v92, 0.5
	v_fma_f32 v94, v94, v92, v94
	v_sub_f32_e32 v98, v98, v93
	v_sub_f32_e32 v99, v99, v93
	v_sub_f32_e32 v100, v100, v93
	v_sub_f32_e32 v101, v101, v93
	v_sub_f32_e32 v102, v102, v93
	v_sub_f32_e32 v103, v103, v93
	v_sub_f32_e32 v104, v104, v93
	v_sub_f32_e32 v105, v105, v93
	v_sub_f32_e32 v106, v106, v93
	v_sub_f32_e32 v107, v107, v93
	v_sub_f32_e32 v108, v108, v93
	v_sub_f32_e32 v109, v109, v93
	v_sub_f32_e32 v110, v110, v93
	v_sub_f32_e32 v111, v111, v93
	v_sub_f32_e32 v112, v112, v93
	v_sub_f32_e32 v113, v113, v93
	v_mul_f32_e32 v98, v94, v98
	v_mul_f32_e32 v99, v94, v99
	v_mul_f32_e32 v100, v94, v100
	v_mul_f32_e32 v101, v94, v101
	v_mul_f32_e32 v102, v94, v102
	v_mul_f32_e32 v103, v94, v103
	v_mul_f32_e32 v104, v94, v104
	v_mul_f32_e32 v105, v94, v105
	v_mul_f32_e32 v106, v94, v106
	v_mul_f32_e32 v107, v94, v107
	v_mul_f32_e32 v108, v94, v108
	v_mul_f32_e32 v109, v94, v109
	v_mul_f32_e32 v110, v94, v110
	v_mul_f32_e32 v111, v94, v111
	v_mul_f32_e32 v112, v94, v112
	v_mul_f32_e32 v113, v94, v113
	v_fma_f32 v98, v98, v130, v114
	v_fma_f32 v99, v99, v131, v115
	v_fma_f32 v100, v100, v132, v116
	v_fma_f32 v101, v101, v133, v117
	v_fma_f32 v102, v102, v134, v118
	v_fma_f32 v103, v103, v135, v119
	v_fma_f32 v104, v104, v136, v120
	v_fma_f32 v105, v105, v137, v121
	v_fma_f32 v106, v106, v138, v122
	v_fma_f32 v107, v107, v139, v123
	v_fma_f32 v108, v108, v140, v124
	v_fma_f32 v109, v109, v141, v125
	v_fma_f32 v110, v110, v142, v126
	v_fma_f32 v111, v111, v143, v127
	v_fma_f32 v112, v112, v144, v128
	v_fma_f32 v113, v113, v145, v129
	v_cvt_pk_bf16_f32 v190, v98, v99
	v_cvt_pk_bf16_f32 v191, v100, v101
	v_cvt_pk_bf16_f32 v192, v102, v103
	v_cvt_pk_bf16_f32 v193, v104, v105
	v_cvt_pk_bf16_f32 v194, v106, v107
	v_cvt_pk_bf16_f32 v195, v108, v109
	v_cvt_pk_bf16_f32 v196, v110, v111
	v_cvt_pk_bf16_f32 v197, v112, v113
	s_add_u32 s2, s10, 0x1800
	s_addc_u32 s3, s11, 0
	global_store_dwordx2 v1, v[190:191], s[2:3]
	global_store_dwordx2 v1, v[192:193], s[2:3] offset:512
	global_store_dwordx2 v1, v[194:195], s[2:3] offset:1024
	global_store_dwordx2 v1, v[196:197], s[2:3] offset:1536
	s_add_u32 s2, s8, 0x7000
	s_addc_u32 s3, s9, 0
	global_load_dwordx4 v[98:101], v0, s[2:3]
	global_load_dwordx4 v[102:105], v0, s[2:3] offset:1024
	global_load_dwordx4 v[106:109], v0, s[2:3] offset:2048
	global_load_dwordx4 v[110:113], v0, s[2:3] offset:3072
	s_waitcnt vmcnt(27)
; DI void ln_row_v(const Frame& F, f32x4 (&v)[4], float* xout, const float* g, const float* b, const float* sh, const float* sc, bf16_t* hout, const float* slab, const float* gres, float* stat = nullptr) {
;     ...
; #pragma unroll
;         for (int j = 0; j < 4; ++j) { s += (v[j][0] + v[j][1]) + (v[j][2] + v[j][3]); s2 += (v[j][0] * v[j][0] + v[j][1] * v[j][1]) + (v[j][2] * v[j][2] + v[j][3] * v[j][3]); }
;         wave_sum2(s, s2, F.lane);
;         const float mean = s * (1.f / D); const float rstd = 1.f / sqrtf(fmaxf(s2 * (1.f / D) - mean * mean, 0.f) + EPS);
;         if (stat && F.lane == 0) { f32x2 sv = {mean, rstd}; *(f32x2*)stat = sv; }
; #pragma unroll
;         for (int j = 0; j < 4; ++j) { const f32x4 gg = ((const f32x4*)g)[F.lane + 64 * j], bb = ((const f32x4*)b)[F.lane + 64 * j];
;             v[j] = (v[j] - mean) * rstd * gg + bb; if (xout) ((f32x4*)xout)[F.lane + 64 * j] = v[j]; }
;     }
;     if (hout) {
;         float s = 0.f, s2 = 0.f;
; #pragma unroll
;         for (int j = 0; j < 4; ++j) { s += (v[j][0] + v[j][1]) + (v[j][2] + v[j][3]); s2 += (v[j][0] * v[j][0] + v[j][1] * v[j][1]) + (v[j][2] * v[j][2] + v[j][3] * v[j][3]); }
;         wave_sum2(s, s2, F.lane);
	v_add_f32_e32 v9, v42, v43
	v_add_f32_e32 v91, v44, v45
	v_mul_f32_e32 v90, v42, v42
	v_mul_f32_e32 v92, v43, v43
	v_add_f32_e32 v9, v9, v46
	v_add_f32_e32 v91, v91, v47
	v_add_f32_e32 v9, v9, v48
	v_add_f32_e32 v91, v91, v49
	v_add_f32_e32 v9, v9, v50
	v_add_f32_e32 v91, v91, v51
	v_add_f32_e32 v9, v9, v52
	v_add_f32_e32 v91, v91, v53
	v_add_f32_e32 v9, v9, v54
	v_add_f32_e32 v91, v91, v55
	v_add_f32_e32 v9, v9, v56
	v_add_f32_e32 v91, v91, v57
	v_fmac_f32_e32 v90, v44, v44
	v_fmac_f32_e32 v92, v45, v45
	v_fmac_f32_e32 v90, v46, v46
	v_fmac_f32_e32 v92, v47, v47
	v_fmac_f32_e32 v90, v48, v48
	v_fmac_f32_e32 v92, v49, v49
	v_fmac_f32_e32 v90, v50, v50
	v_fmac_f32_e32 v92, v51, v51
	v_fmac_f32_e32 v90, v52, v52
	v_fmac_f32_e32 v92, v53, v53
	v_fmac_f32_e32 v90, v54, v54
	v_fmac_f32_e32 v92, v55, v55
	v_fmac_f32_e32 v90, v56, v56
	v_fmac_f32_e32 v92, v57, v57
	v_add_f32_e32 v9, v9, v91
	v_add_f32_e32 v90, v90, v92
	s_nop 1
	v_add_f32_dpp v9, v9, v9 quad_perm:[1,0,3,2] row_mask:0xf bank_mask:0xf
	v_add_f32_dpp v90, v90, v90 quad_perm:[1,0,3,2] row_mask:0xf bank_mask:0xf
	s_nop 0
	v_add_f32_dpp v9, v9, v9 quad_perm:[2,3,0,1] row_mask:0xf bank_mask:0xf
	v_add_f32_dpp v90, v90, v90 quad_perm:[2,3,0,1] row_mask:0xf bank_mask:0xf
	s_nop 0
	v_add_f32_dpp v9, v9, v9 row_half_mirror row_mask:0xf bank_mask:0xf
	v_add_f32_dpp v90, v90, v90 row_half_mirror row_mask:0xf bank_mask:0xf
	s_nop 0
	v_add_f32_dpp v9, v9, v9 row_mirror row_mask:0xf bank_mask:0xf
	v_add_f32_dpp v90, v90, v90 row_mirror row_mask:0xf bank_mask:0xf
	s_nop 0
	v_add_f32_dpp v9, v9, v9 row_bcast:15 row_mask:0xa bank_mask:0xf
	v_add_f32_dpp v90, v90, v90 row_bcast:15 row_mask:0xa bank_mask:0xf
	s_nop 0
	v_add_f32_dpp v9, v9, v9 row_bcast:31 row_mask:0xc bank_mask:0xf
	v_add_f32_dpp v90, v90, v90 row_bcast:31 row_mask:0xc bank_mask:0xf
	s_nop 0
	v_readlane_b32 s2, v9, 63
	v_readlane_b32 s3, v90, 63
	s_nop 1
	v_mov_b32_e32 v9, s2
	v_mov_b32_e32 v90, s3
	v_mul_f32_e32 v93, 0x3a800000, v9
	v_mul_f32_e32 v91, 0x3a800000, v90
	v_fma_f32 v91, -v93, v93, v91
	v_max_f32_e32 v91, 0, v91
	v_add_f32_e32 v91, 0x358637bd, v91
	v_rsq_f32_e32 v94, v91
	v_mul_f32_e32 v91, 0.5, v91
	v_mul_f32_e32 v92, v94, v94
	v_fma_f32 v92, -v91, v92, 0.5
	v_fma_f32 v94, v94, v92, v94
	s_add_u32 s2, s12, 0x20
	s_addc_u32 s3, s13, 0
	v_mov_b32_e32 v188, v93
	v_mov_b32_e32 v189, v94
	s_mov_b64 exec, 1
	global_store_dwordx2 v97, v[188:189], s[2:3]
	s_mov_b64 exec, -1
	v_sub_f32_e32 v42, v42, v93
	v_sub_f32_e32 v43, v43, v93
	v_sub_f32_e32 v44, v44, v93
	v_sub_f32_e32 v45, v45, v93
	v_sub_f32_e32 v46, v46, v93
	v_sub_f32_e32 v47, v47, v93
	v_sub_f32_e32 v48, v48, v93
	v_sub_f32_e32 v49, v49, v93
	v_sub_f32_e32 v50, v50, v93
	v_sub_f32_e32 v51, v51, v93
	v_sub_f32_e32 v52, v52, v93
	v_sub_f32_e32 v53, v53, v93
	v_sub_f32_e32 v54, v54, v93
	v_sub_f32_e32 v55, v55, v93
	v_sub_f32_e32 v56, v56, v93
	v_sub_f32_e32 v57, v57, v93
	v_mul_f32_e32 v42, v94, v42
	v_mul_f32_e32 v43, v94, v43
	v_mul_f32_e32 v44, v94, v44
	v_mul_f32_e32 v45, v94, v45
	v_mul_f32_e32 v46, v94, v46
	v_mul_f32_e32 v47, v94, v47
	v_mul_f32_e32 v48, v94, v48
	v_mul_f32_e32 v49, v94, v49
	v_mul_f32_e32 v50, v94, v50
	v_mul_f32_e32 v51, v94, v51
	v_mul_f32_e32 v52, v94, v52
	v_mul_f32_e32 v53, v94, v53
	v_mul_f32_e32 v54, v94, v54
	v_mul_f32_e32 v55, v94, v55
	v_mul_f32_e32 v56, v94, v56
	v_mul_f32_e32 v57, v94, v57
	v_fma_f32 v42, v42, v10, v26
	v_fma_f32 v43, v43, v11, v27
	v_fma_f32 v44, v44, v12, v28
	v_fma_f32 v45, v45, v13, v29
	v_fma_f32 v46, v46, v14, v30
	v_fma_f32 v47, v47, v15, v31
	v_fma_f32 v48, v48, v16, v32
	v_fma_f32 v49, v49, v17, v33
	v_fma_f32 v50, v50, v18, v34
	v_fma_f32 v51, v51, v19, v35
	v_fma_f32 v52, v52, v20, v36
	v_fma_f32 v53, v53, v21, v37
	v_fma_f32 v54, v54, v22, v38
	v_fma_f32 v55, v55, v23, v39
	v_fma_f32 v56, v56, v24, v40
	v_fma_f32 v57, v57, v25, v41
	v_add_f32_e32 v9, v42, v43
	v_add_f32_e32 v91, v44, v45
	v_mul_f32_e32 v90, v42, v42
	v_mul_f32_e32 v92, v43, v43
	v_add_f32_e32 v9, v9, v46
	v_add_f32_e32 v91, v91, v47
	v_add_f32_e32 v9, v9, v48
	v_add_f32_e32 v91, v91, v49
	v_add_f32_e32 v9, v9, v50
	v_add_f32_e32 v91, v91, v51
	v_add_f32_e32 v9, v9, v52
	v_add_f32_e32 v91, v91, v53
	v_add_f32_e32 v9, v9, v54
	v_add_f32_e32 v91, v91, v55
	v_add_f32_e32 v9, v9, v56
	v_add_f32_e32 v91, v91, v57
	v_fmac_f32_e32 v90, v44, v44
	v_fmac_f32_e32 v92, v45, v45
	v_fmac_f32_e32 v90, v46, v46
	v_fmac_f32_e32 v92, v47, v47
	v_fmac_f32_e32 v90, v48, v48
	v_fmac_f32_e32 v92, v49, v49
	v_fmac_f32_e32 v90, v50, v50
	v_fmac_f32_e32 v92, v51, v51
	v_fmac_f32_e32 v90, v52, v52
	v_fmac_f32_e32 v92, v53, v53
	v_fmac_f32_e32 v90, v54, v54
	v_fmac_f32_e32 v92, v55, v55
	v_fmac_f32_e32 v90, v56, v56
	v_fmac_f32_e32 v92, v57, v57
	v_add_f32_e32 v9, v9, v91
	v_add_f32_e32 v90, v90, v92
	s_nop 1
	v_add_f32_dpp v9, v9, v9 quad_perm:[1,0,3,2] row_mask:0xf bank_mask:0xf
	v_add_f32_dpp v90, v90, v90 quad_perm:[1,0,3,2] row_mask:0xf bank_mask:0xf
	s_nop 0
	v_add_f32_dpp v9, v9, v9 quad_perm:[2,3,0,1] row_mask:0xf bank_mask:0xf
	v_add_f32_dpp v90, v90, v90 quad_perm:[2,3,0,1] row_mask:0xf bank_mask:0xf
	s_nop 0
	v_add_f32_dpp v9, v9, v9 row_half_mirror row_mask:0xf bank_mask:0xf
	v_add_f32_dpp v90, v90, v90 row_half_mirror row_mask:0xf bank_mask:0xf
	s_nop 0
	v_add_f32_dpp v9, v9, v9 row_mirror row_mask:0xf bank_mask:0xf
	v_add_f32_dpp v90, v90, v90 row_mirror row_mask:0xf bank_mask:0xf
	s_nop 0
	v_add_f32_dpp v9, v9, v9 row_bcast:15 row_mask:0xa bank_mask:0xf
	v_add_f32_dpp v90, v90, v90 row_bcast:15 row_mask:0xa bank_mask:0xf
	s_nop 0
	v_add_f32_dpp v9, v9, v9 row_bcast:31 row_mask:0xc bank_mask:0xf
	v_add_f32_dpp v90, v90, v90 row_bcast:31 row_mask:0xc bank_mask:0xf
; DI unsigned pk2(float lo, float hi) { f32x2 v = {lo, hi}; bf16x2_t b = __builtin_convertvector(v, bf16x2_t); return __builtin_bit_cast(unsigned, b); }
; DI void ln_row_v(const Frame& F, f32x4 (&v)[4], float* xout, const float* g, const float* b, const float* sh, const float* sc, bf16_t* hout, const float* slab, const float* gres, float* stat = nullptr) {
;     ...
; #pragma unroll
;         for (int j = 0; j < 4; ++j) { s += (v[j][0] + v[j][1]) + (v[j][2] + v[j][3]); s2 += (v[j][0] * v[j][0] + v[j][1] * v[j][1]) + (v[j][2] * v[j][2] + v[j][3] * v[j][3]); }
;         wave_sum2(s, s2, F.lane);
;         const float mean = s * (1.f / D); const float rstd = 1.f / sqrtf(fmaxf(s2 * (1.f / D) - mean * mean, 0.f) + EPS);
;         if (stat && F.lane == 0) { f32x2 sv = {mean, rstd}; *(f32x2*)stat = sv; }
; #pragma unroll
;         for (int j = 0; j < 4; ++j) { const f32x4 gg = ((const f32x4*)g)[F.lane + 64 * j], bb = ((const f32x4*)b)[F.lane + 64 * j];
;             v[j] = (v[j] - mean) * rstd * gg + bb; if (xout) ((f32x4*)xout)[F.lane + 64 * j] = v[j]; }
;     }
;     if (hout) {
;         float s = 0.f, s2 = 0.f;
; #pragma unroll
;         for (int j = 0; j < 4; ++j) { s += (v[j][0] + v[j][1]) + (v[j][2] + v[j][3]); s2 += (v[j][0] * v[j][0] + v[j][1] * v[j][1]) + (v[j][2] * v[j][2] + v[j][3] * v[j][3]); }
;         wave_sum2(s, s2, F.lane);
;         const float mean = s * (1.f / D); const float rstd = 1.f / sqrtf(fmaxf(s2 * (1.f / D) - mean * mean, 0.f) + EPS);
; #pragma unroll
;         for (int j = 0; j < 4; ++j) { const f32x4 hh = ((const f32x4*)sh)[F.lane + 64 * j], cc = ((const f32x4*)sc)[F.lane + 64 * j];
;             const f32x4 o = (v[j] - mean) * rstd * (cc + 1.f) + hh; u32x2 wv; wv.x = pk2(o[0], o[1]); wv.y = pk2(o[2], o[3]);
;             ((u32x2*)hout)[F.lane + 64 * j] = wv; }
	s_nop 0
	v_readlane_b32 s2, v9, 63
	v_readlane_b32 s3, v90, 63
	s_nop 1
	v_mov_b32_e32 v9, s2
	v_mov_b32_e32 v90, s3
	v_mul_f32_e32 v93, 0x3a800000, v9
	v_mul_f32_e32 v91, 0x3a800000, v90
	v_fma_f32 v91, -v93, v93, v91
	v_max_f32_e32 v91, 0, v91
	v_add_f32_e32 v91, 0x358637bd, v91
	v_rsq_f32_e32 v94, v91
	v_mul_f32_e32 v91, 0.5, v91
	v_mul_f32_e32 v92, v94, v94
	v_fma_f32 v92, -v91, v92, 0.5
	v_fma_f32 v94, v94, v92, v94
	v_sub_f32_e32 v42, v42, v93
	v_sub_f32_e32 v43, v43, v93
	v_sub_f32_e32 v44, v44, v93
	v_sub_f32_e32 v45, v45, v93
	v_sub_f32_e32 v46, v46, v93
	v_sub_f32_e32 v47, v47, v93
	v_sub_f32_e32 v48, v48, v93
	v_sub_f32_e32 v49, v49, v93
	v_sub_f32_e32 v50, v50, v93
	v_sub_f32_e32 v51, v51, v93
	v_sub_f32_e32 v52, v52, v93
	v_sub_f32_e32 v53, v53, v93
	v_sub_f32_e32 v54, v54, v93
	v_sub_f32_e32 v55, v55, v93
	v_sub_f32_e32 v56, v56, v93
	v_sub_f32_e32 v57, v57, v93
	v_mul_f32_e32 v42, v94, v42
	v_mul_f32_e32 v43, v94, v43
	v_mul_f32_e32 v44, v94, v44
	v_mul_f32_e32 v45, v94, v45
	v_mul_f32_e32 v46, v94, v46
	v_mul_f32_e32 v47, v94, v47
	v_mul_f32_e32 v48, v94, v48
	v_mul_f32_e32 v49, v94, v49
	v_mul_f32_e32 v50, v94, v50
	v_mul_f32_e32 v51, v94, v51
	v_mul_f32_e32 v52, v94, v52
	v_mul_f32_e32 v53, v94, v53
	v_mul_f32_e32 v54, v94, v54
	v_mul_f32_e32 v55, v94, v55
	v_mul_f32_e32 v56, v94, v56
	v_mul_f32_e32 v57, v94, v57
	v_fma_f32 v42, v42, v130, v114
	v_fma_f32 v43, v43, v131, v115
	v_fma_f32 v44, v44, v132, v116
	v_fma_f32 v45, v45, v133, v117
	v_fma_f32 v46, v46, v134, v118
	v_fma_f32 v47, v47, v135, v119
	v_fma_f32 v48, v48, v136, v120
	v_fma_f32 v49, v49, v137, v121
	v_fma_f32 v50, v50, v138, v122
	v_fma_f32 v51, v51, v139, v123
	v_fma_f32 v52, v52, v140, v124
	v_fma_f32 v53, v53, v141, v125
	v_fma_f32 v54, v54, v142, v126
	v_fma_f32 v55, v55, v143, v127
	v_fma_f32 v56, v56, v144, v128
	v_fma_f32 v57, v57, v145, v129
	v_cvt_pk_bf16_f32 v190, v42, v43
	v_cvt_pk_bf16_f32 v191, v44, v45
	v_cvt_pk_bf16_f32 v192, v46, v47
	v_cvt_pk_bf16_f32 v193, v48, v49
	v_cvt_pk_bf16_f32 v194, v50, v51
	v_cvt_pk_bf16_f32 v195, v52, v53
	v_cvt_pk_bf16_f32 v196, v54, v55
	v_cvt_pk_bf16_f32 v197, v56, v57
	s_add_u32 s2, s10, 0x2000
	s_addc_u32 s3, s11, 0
	global_store_dwordx2 v1, v[190:191], s[2:3]
	global_store_dwordx2 v1, v[192:193], s[2:3] offset:512
	global_store_dwordx2 v1, v[194:195], s[2:3] offset:1024
	global_store_dwordx2 v1, v[196:197], s[2:3] offset:1536
	s_mov_b64 s[2:3], s[20:21]
	global_load_dwordx4 v[42:45], v0, s[2:3]
	global_load_dwordx4 v[46:49], v0, s[2:3] offset:1024
	global_load_dwordx4 v[50:53], v0, s[2:3] offset:2048
	global_load_dwordx4 v[54:57], v0, s[2:3] offset:3072
	s_waitcnt vmcnt(27)
	v_add_f32_e32 v9, v58, v59
	v_add_f32_e32 v91, v60, v61
	v_mul_f32_e32 v90, v58, v58
	v_mul_f32_e32 v92, v59, v59
	v_add_f32_e32 v9, v9, v62
	v_add_f32_e32 v91, v91, v63
	v_add_f32_e32 v9, v9, v64
	v_add_f32_e32 v91, v91, v65
	v_add_f32_e32 v9, v9, v66
	v_add_f32_e32 v91, v91, v67
	v_add_f32_e32 v9, v9, v68
	v_add_f32_e32 v91, v91, v69
	v_add_f32_e32 v9, v9, v70
	v_add_f32_e32 v91, v91, v71
	v_add_f32_e32 v9, v9, v72
	v_add_f32_e32 v91, v91, v73
	v_fmac_f32_e32 v90, v60, v60
	v_fmac_f32_e32 v92, v61, v61
	v_fmac_f32_e32 v90, v62, v62
	v_fmac_f32_e32 v92, v63, v63
	v_fmac_f32_e32 v90, v64, v64
	v_fmac_f32_e32 v92, v65, v65
	v_fmac_f32_e32 v90, v66, v66
	v_fmac_f32_e32 v92, v67, v67
	v_fmac_f32_e32 v90, v68, v68
	v_fmac_f32_e32 v92, v69, v69
	v_fmac_f32_e32 v90, v70, v70
	v_fmac_f32_e32 v92, v71, v71
	v_fmac_f32_e32 v90, v72, v72
	v_fmac_f32_e32 v92, v73, v73
	v_add_f32_e32 v9, v9, v91
	v_add_f32_e32 v90, v90, v92
	s_nop 1
	v_add_f32_dpp v9, v9, v9 quad_perm:[1,0,3,2] row_mask:0xf bank_mask:0xf
	v_add_f32_dpp v90, v90, v90 quad_perm:[1,0,3,2] row_mask:0xf bank_mask:0xf
	s_nop 0
	v_add_f32_dpp v9, v9, v9 quad_perm:[2,3,0,1] row_mask:0xf bank_mask:0xf
	v_add_f32_dpp v90, v90, v90 quad_perm:[2,3,0,1] row_mask:0xf bank_mask:0xf
	s_nop 0
	v_add_f32_dpp v9, v9, v9 row_half_mirror row_mask:0xf bank_mask:0xf
	v_add_f32_dpp v90, v90, v90 row_half_mirror row_mask:0xf bank_mask:0xf
	s_nop 0
	v_add_f32_dpp v9, v9, v9 row_mirror row_mask:0xf bank_mask:0xf
	v_add_f32_dpp v90, v90, v90 row_mirror row_mask:0xf bank_mask:0xf
	s_nop 0
	v_add_f32_dpp v9, v9, v9 row_bcast:15 row_mask:0xa bank_mask:0xf
	v_add_f32_dpp v90, v90, v90 row_bcast:15 row_mask:0xa bank_mask:0xf
	s_nop 0
	v_add_f32_dpp v9, v9, v9 row_bcast:31 row_mask:0xc bank_mask:0xf
	v_add_f32_dpp v90, v90, v90 row_bcast:31 row_mask:0xc bank_mask:0xf
	s_nop 0
	v_readlane_b32 s2, v9, 63
	v_readlane_b32 s3, v90, 63
	s_nop 1
	v_mov_b32_e32 v9, s2
	v_mov_b32_e32 v90, s3
	v_mul_f32_e32 v93, 0x3a800000, v9
	v_mul_f32_e32 v91, 0x3a800000, v90
	v_fma_f32 v91, -v93, v93, v91
	v_max_f32_e32 v91, 0, v91
	v_add_f32_e32 v91, 0x358637bd, v91
	v_rsq_f32_e32 v94, v91
	v_mul_f32_e32 v91, 0.5, v91
	v_mul_f32_e32 v92, v94, v94
	v_fma_f32 v92, -v91, v92, 0.5
	v_fma_f32 v94, v94, v92, v94
	s_add_u32 s2, s12, 0x28
	s_addc_u32 s3, s13, 0
	v_mov_b32_e32 v188, v93
	v_mov_b32_e32 v189, v94
	s_mov_b64 exec, 1
	global_store_dwordx2 v97, v[188:189], s[2:3]
	s_mov_b64 exec, -1
	v_sub_f32_e32 v58, v58, v93
	v_sub_f32_e32 v59, v59, v93
	v_sub_f32_e32 v60, v60, v93
	v_sub_f32_e32 v61, v61, v93
	v_sub_f32_e32 v62, v62, v93
	v_sub_f32_e32 v63, v63, v93
	v_sub_f32_e32 v64, v64, v93
	v_sub_f32_e32 v65, v65, v93
	v_sub_f32_e32 v66, v66, v93
	v_sub_f32_e32 v67, v67, v93
	v_sub_f32_e32 v68, v68, v93
	v_sub_f32_e32 v69, v69, v93
	v_sub_f32_e32 v70, v70, v93
	v_sub_f32_e32 v71, v71, v93
	v_sub_f32_e32 v72, v72, v93
	v_sub_f32_e32 v73, v73, v93
	v_mul_f32_e32 v58, v94, v58
	v_mul_f32_e32 v59, v94, v59
	v_mul_f32_e32 v60, v94, v60
; DI unsigned pk2(float lo, float hi) { f32x2 v = {lo, hi}; bf16x2_t b = __builtin_convertvector(v, bf16x2_t); return __builtin_bit_cast(unsigned, b); }
; DI void ln_row_v(const Frame& F, f32x4 (&v)[4], float* xout, const float* g, const float* b, const float* sh, const float* sc, bf16_t* hout, const float* slab, const float* gres, float* stat = nullptr) {
;     ...
;         for (int j = 0; j < 4; ++j) { const f32x4 gg = ((const f32x4*)g)[F.lane + 64 * j], bb = ((const f32x4*)b)[F.lane + 64 * j];
;             v[j] = (v[j] - mean) * rstd * gg + bb; if (xout) ((f32x4*)xout)[F.lane + 64 * j] = v[j]; }
;     }
;     if (hout) {
;         float s = 0.f, s2 = 0.f;
; #pragma unroll
;         for (int j = 0; j < 4; ++j) { s += (v[j][0] + v[j][1]) + (v[j][2] + v[j][3]); s2 += (v[j][0] * v[j][0] + v[j][1] * v[j][1]) + (v[j][2] * v[j][2] + v[j][3] * v[j][3]); }
;         wave_sum2(s, s2, F.lane);
;         const float mean = s * (1.f / D); const float rstd = 1.f / sqrtf(fmaxf(s2 * (1.f / D) - mean * mean, 0.f) + EPS);
; #pragma unroll
;         for (int j = 0; j < 4; ++j) { const f32x4 hh = ((const f32x4*)sh)[F.lane + 64 * j], cc = ((const f32x4*)sc)[F.lane + 64 * j];
;             const f32x4 o = (v[j] - mean) * rstd * (cc + 1.f) + hh; u32x2 wv; wv.x = pk2(o[0], o[1]); wv.y = pk2(o[2], o[3]);
;             ((u32x2*)hout)[F.lane + 64 * j] = wv; }
	v_mul_f32_e32 v61, v94, v61
	v_mul_f32_e32 v62, v94, v62
	v_mul_f32_e32 v63, v94, v63
	v_mul_f32_e32 v64, v94, v64
	v_mul_f32_e32 v65, v94, v65
	v_mul_f32_e32 v66, v94, v66
	v_mul_f32_e32 v67, v94, v67
	v_mul_f32_e32 v68, v94, v68
	v_mul_f32_e32 v69, v94, v69
	v_mul_f32_e32 v70, v94, v70
	v_mul_f32_e32 v71, v94, v71
	v_mul_f32_e32 v72, v94, v72
	v_mul_f32_e32 v73, v94, v73
	v_fma_f32 v58, v58, v10, v26
	v_fma_f32 v59, v59, v11, v27
	v_fma_f32 v60, v60, v12, v28
	v_fma_f32 v61, v61, v13, v29
	v_fma_f32 v62, v62, v14, v30
	v_fma_f32 v63, v63, v15, v31
	v_fma_f32 v64, v64, v16, v32
	v_fma_f32 v65, v65, v17, v33
	v_fma_f32 v66, v66, v18, v34
	v_fma_f32 v67, v67, v19, v35
	v_fma_f32 v68, v68, v20, v36
	v_fma_f32 v69, v69, v21, v37
	v_fma_f32 v70, v70, v22, v38
	v_fma_f32 v71, v71, v23, v39
	v_fma_f32 v72, v72, v24, v40
	v_fma_f32 v73, v73, v25, v41
	v_add_f32_e32 v9, v58, v59
	v_add_f32_e32 v91, v60, v61
	v_mul_f32_e32 v90, v58, v58
	v_mul_f32_e32 v92, v59, v59
	v_add_f32_e32 v9, v9, v62
	v_add_f32_e32 v91, v91, v63
	v_add_f32_e32 v9, v9, v64
	v_add_f32_e32 v91, v91, v65
	v_add_f32_e32 v9, v9, v66
	v_add_f32_e32 v91, v91, v67
	v_add_f32_e32 v9, v9, v68
	v_add_f32_e32 v91, v91, v69
	v_add_f32_e32 v9, v9, v70
	v_add_f32_e32 v91, v91, v71
	v_add_f32_e32 v9, v9, v72
	v_add_f32_e32 v91, v91, v73
	v_fmac_f32_e32 v90, v60, v60
	v_fmac_f32_e32 v92, v61, v61
	v_fmac_f32_e32 v90, v62, v62
	v_fmac_f32_e32 v92, v63, v63
	v_fmac_f32_e32 v90, v64, v64
	v_fmac_f32_e32 v92, v65, v65
	v_fmac_f32_e32 v90, v66, v66
	v_fmac_f32_e32 v92, v67, v67
	v_fmac_f32_e32 v90, v68, v68
	v_fmac_f32_e32 v92, v69, v69
	v_fmac_f32_e32 v90, v70, v70
	v_fmac_f32_e32 v92, v71, v71
	v_fmac_f32_e32 v90, v72, v72
	v_fmac_f32_e32 v92, v73, v73
	v_add_f32_e32 v9, v9, v91
	v_add_f32_e32 v90, v90, v92
	s_nop 1
	v_add_f32_dpp v9, v9, v9 quad_perm:[1,0,3,2] row_mask:0xf bank_mask:0xf
	v_add_f32_dpp v90, v90, v90 quad_perm:[1,0,3,2] row_mask:0xf bank_mask:0xf
	s_nop 0
	v_add_f32_dpp v9, v9, v9 quad_perm:[2,3,0,1] row_mask:0xf bank_mask:0xf
	v_add_f32_dpp v90, v90, v90 quad_perm:[2,3,0,1] row_mask:0xf bank_mask:0xf
	s_nop 0
	v_add_f32_dpp v9, v9, v9 row_half_mirror row_mask:0xf bank_mask:0xf
	v_add_f32_dpp v90, v90, v90 row_half_mirror row_mask:0xf bank_mask:0xf
	s_nop 0
	v_add_f32_dpp v9, v9, v9 row_mirror row_mask:0xf bank_mask:0xf
	v_add_f32_dpp v90, v90, v90 row_mirror row_mask:0xf bank_mask:0xf
	s_nop 0
	v_add_f32_dpp v9, v9, v9 row_bcast:15 row_mask:0xa bank_mask:0xf
	v_add_f32_dpp v90, v90, v90 row_bcast:15 row_mask:0xa bank_mask:0xf
	s_nop 0
	v_add_f32_dpp v9, v9, v9 row_bcast:31 row_mask:0xc bank_mask:0xf
	v_add_f32_dpp v90, v90, v90 row_bcast:31 row_mask:0xc bank_mask:0xf
	s_nop 0
	v_readlane_b32 s2, v9, 63
	v_readlane_b32 s3, v90, 63
	s_nop 1
	v_mov_b32_e32 v9, s2
	v_mov_b32_e32 v90, s3
	v_mul_f32_e32 v93, 0x3a800000, v9
	v_mul_f32_e32 v91, 0x3a800000, v90
	v_fma_f32 v91, -v93, v93, v91
	v_max_f32_e32 v91, 0, v91
	v_add_f32_e32 v91, 0x358637bd, v91
	v_rsq_f32_e32 v94, v91
	v_mul_f32_e32 v91, 0.5, v91
	v_mul_f32_e32 v92, v94, v94
	v_fma_f32 v92, -v91, v92, 0.5
	v_fma_f32 v94, v94, v92, v94
	v_sub_f32_e32 v58, v58, v93
	v_sub_f32_e32 v59, v59, v93
	v_sub_f32_e32 v60, v60, v93
	v_sub_f32_e32 v61, v61, v93
	v_sub_f32_e32 v62, v62, v93
	v_sub_f32_e32 v63, v63, v93
	v_sub_f32_e32 v64, v64, v93
	v_sub_f32_e32 v65, v65, v93
	v_sub_f32_e32 v66, v66, v93
	v_sub_f32_e32 v67, v67, v93
	v_sub_f32_e32 v68, v68, v93
	v_sub_f32_e32 v69, v69, v93
	v_sub_f32_e32 v70, v70, v93
	v_sub_f32_e32 v71, v71, v93
	v_sub_f32_e32 v72, v72, v93
	v_sub_f32_e32 v73, v73, v93
	v_mul_f32_e32 v58, v94, v58
	v_mul_f32_e32 v59, v94, v59
	v_mul_f32_e32 v60, v94, v60
	v_mul_f32_e32 v61, v94, v61
	v_mul_f32_e32 v62, v94, v62
	v_mul_f32_e32 v63, v94, v63
	v_mul_f32_e32 v64, v94, v64
	v_mul_f32_e32 v65, v94, v65
	v_mul_f32_e32 v66, v94, v66
	v_mul_f32_e32 v67, v94, v67
	v_mul_f32_e32 v68, v94, v68
	v_mul_f32_e32 v69, v94, v69
	v_mul_f32_e32 v70, v94, v70
	v_mul_f32_e32 v71, v94, v71
	v_mul_f32_e32 v72, v94, v72
	v_mul_f32_e32 v73, v94, v73
	v_fma_f32 v58, v58, v130, v114
	v_fma_f32 v59, v59, v131, v115
	v_fma_f32 v60, v60, v132, v116
	v_fma_f32 v61, v61, v133, v117
	v_fma_f32 v62, v62, v134, v118
	v_fma_f32 v63, v63, v135, v119
	v_fma_f32 v64, v64, v136, v120
	v_fma_f32 v65, v65, v137, v121
	v_fma_f32 v66, v66, v138, v122
	v_fma_f32 v67, v67, v139, v123
	v_fma_f32 v68, v68, v140, v124
	v_fma_f32 v69, v69, v141, v125
	v_fma_f32 v70, v70, v142, v126
	v_fma_f32 v71, v71, v143, v127
	v_fma_f32 v72, v72, v144, v128
	v_fma_f32 v73, v73, v145, v129
	v_cvt_pk_bf16_f32 v190, v58, v59
	v_cvt_pk_bf16_f32 v191, v60, v61
	v_cvt_pk_bf16_f32 v192, v62, v63
	v_cvt_pk_bf16_f32 v193, v64, v65
	v_cvt_pk_bf16_f32 v194, v66, v67
	v_cvt_pk_bf16_f32 v195, v68, v69
	v_cvt_pk_bf16_f32 v196, v70, v71
	v_cvt_pk_bf16_f32 v197, v72, v73
	s_add_u32 s2, s10, 0x2800
	s_addc_u32 s3, s11, 0
	global_store_dwordx2 v1, v[190:191], s[2:3]
	global_store_dwordx2 v1, v[192:193], s[2:3] offset:512
	global_store_dwordx2 v1, v[194:195], s[2:3] offset:1024
	global_store_dwordx2 v1, v[196:197], s[2:3] offset:1536
	s_waitcnt vmcnt(23)
; DI void ln_row_v(const Frame& F, f32x4 (&v)[4], float* xout, const float* g, const float* b, const float* sh, const float* sc, bf16_t* hout, const float* slab, const float* gres, float* stat = nullptr) {
;     ...
; #pragma unroll
;         for (int j = 0; j < 4; ++j) { s += (v[j][0] + v[j][1]) + (v[j][2] + v[j][3]); s2 += (v[j][0] * v[j][0] + v[j][1] * v[j][1]) + (v[j][2] * v[j][2] + v[j][3] * v[j][3]); }
;         wave_sum2(s, s2, F.lane);
;         const float mean = s * (1.f / D); const float rstd = 1.f / sqrtf(fmaxf(s2 * (1.f / D) - mean * mean, 0.f) + EPS);
;         if (stat && F.lane == 0) { f32x2 sv = {mean, rstd}; *(f32x2*)stat = sv; }
; #pragma unroll
;         for (int j = 0; j < 4; ++j) { const f32x4 gg = ((const f32x4*)g)[F.lane + 64 * j], bb = ((const f32x4*)b)[F.lane + 64 * j];
;             v[j] = (v[j] - mean) * rstd * gg + bb; if (xout) ((f32x4*)xout)[F.lane + 64 * j] = v[j]; }
;     }
;     if (hout) {
;         float s = 0.f, s2 = 0.f;
; #pragma unroll
;         for (int j = 0; j < 4; ++j) { s += (v[j][0] + v[j][1]) + (v[j][2] + v[j][3]); s2 += (v[j][0] * v[j][0] + v[j][1] * v[j][1]) + (v[j][2] * v[j][2] + v[j][3] * v[j][3]); }
;         wave_sum2(s, s2, F.lane);
	v_add_f32_e32 v9, v74, v75
	v_add_f32_e32 v91, v76, v77
	v_mul_f32_e32 v90, v74, v74
	v_mul_f32_e32 v92, v75, v75
	v_add_f32_e32 v9, v9, v78
	v_add_f32_e32 v91, v91, v79
	v_add_f32_e32 v9, v9, v80
	v_add_f32_e32 v91, v91, v81
	v_add_f32_e32 v9, v9, v82
	v_add_f32_e32 v91, v91, v83
	v_add_f32_e32 v9, v9, v84
	v_add_f32_e32 v91, v91, v85
	v_add_f32_e32 v9, v9, v86
	v_add_f32_e32 v91, v91, v87
	v_add_f32_e32 v9, v9, v88
	v_add_f32_e32 v91, v91, v89
	v_fmac_f32_e32 v90, v76, v76
	v_fmac_f32_e32 v92, v77, v77
	v_fmac_f32_e32 v90, v78, v78
	v_fmac_f32_e32 v92, v79, v79
	v_fmac_f32_e32 v90, v80, v80
	v_fmac_f32_e32 v92, v81, v81
	v_fmac_f32_e32 v90, v82, v82
	v_fmac_f32_e32 v92, v83, v83
	v_fmac_f32_e32 v90, v84, v84
	v_fmac_f32_e32 v92, v85, v85
	v_fmac_f32_e32 v90, v86, v86
	v_fmac_f32_e32 v92, v87, v87
	v_fmac_f32_e32 v90, v88, v88
	v_fmac_f32_e32 v92, v89, v89
	v_add_f32_e32 v9, v9, v91
	v_add_f32_e32 v90, v90, v92
	s_nop 1
	v_add_f32_dpp v9, v9, v9 quad_perm:[1,0,3,2] row_mask:0xf bank_mask:0xf
	v_add_f32_dpp v90, v90, v90 quad_perm:[1,0,3,2] row_mask:0xf bank_mask:0xf
	s_nop 0
	v_add_f32_dpp v9, v9, v9 quad_perm:[2,3,0,1] row_mask:0xf bank_mask:0xf
	v_add_f32_dpp v90, v90, v90 quad_perm:[2,3,0,1] row_mask:0xf bank_mask:0xf
	s_nop 0
	v_add_f32_dpp v9, v9, v9 row_half_mirror row_mask:0xf bank_mask:0xf
	v_add_f32_dpp v90, v90, v90 row_half_mirror row_mask:0xf bank_mask:0xf
	s_nop 0
	v_add_f32_dpp v9, v9, v9 row_mirror row_mask:0xf bank_mask:0xf
	v_add_f32_dpp v90, v90, v90 row_mirror row_mask:0xf bank_mask:0xf
	s_nop 0
	v_add_f32_dpp v9, v9, v9 row_bcast:15 row_mask:0xa bank_mask:0xf
	v_add_f32_dpp v90, v90, v90 row_bcast:15 row_mask:0xa bank_mask:0xf
	s_nop 0
	v_add_f32_dpp v9, v9, v9 row_bcast:31 row_mask:0xc bank_mask:0xf
	v_add_f32_dpp v90, v90, v90 row_bcast:31 row_mask:0xc bank_mask:0xf
	s_nop 0
	v_readlane_b32 s2, v9, 63
	v_readlane_b32 s3, v90, 63
	s_nop 1
	v_mov_b32_e32 v9, s2
	v_mov_b32_e32 v90, s3
	v_mul_f32_e32 v93, 0x3a800000, v9
	v_mul_f32_e32 v91, 0x3a800000, v90
	v_fma_f32 v91, -v93, v93, v91
	v_max_f32_e32 v91, 0, v91
	v_add_f32_e32 v91, 0x358637bd, v91
	v_rsq_f32_e32 v94, v91
	v_mul_f32_e32 v91, 0.5, v91
	v_mul_f32_e32 v92, v94, v94
	v_fma_f32 v92, -v91, v92, 0.5
	v_fma_f32 v94, v94, v92, v94
	s_add_u32 s2, s12, 0x30
	s_addc_u32 s3, s13, 0
	v_mov_b32_e32 v188, v93
	v_mov_b32_e32 v189, v94
	s_mov_b64 exec, 1
	global_store_dwordx2 v97, v[188:189], s[2:3]
	s_mov_b64 exec, -1
	v_sub_f32_e32 v74, v74, v93
	v_sub_f32_e32 v75, v75, v93
	v_sub_f32_e32 v76, v76, v93
	v_sub_f32_e32 v77, v77, v93
	v_sub_f32_e32 v78, v78, v93
	v_sub_f32_e32 v79, v79, v93
	v_sub_f32_e32 v80, v80, v93
	v_sub_f32_e32 v81, v81, v93
	v_sub_f32_e32 v82, v82, v93
	v_sub_f32_e32 v83, v83, v93
	v_sub_f32_e32 v84, v84, v93
	v_sub_f32_e32 v85, v85, v93
	v_sub_f32_e32 v86, v86, v93
	v_sub_f32_e32 v87, v87, v93
	v_sub_f32_e32 v88, v88, v93
	v_sub_f32_e32 v89, v89, v93
	v_mul_f32_e32 v74, v94, v74
	v_mul_f32_e32 v75, v94, v75
	v_mul_f32_e32 v76, v94, v76
	v_mul_f32_e32 v77, v94, v77
	v_mul_f32_e32 v78, v94, v78
	v_mul_f32_e32 v79, v94, v79
	v_mul_f32_e32 v80, v94, v80
	v_mul_f32_e32 v81, v94, v81
	v_mul_f32_e32 v82, v94, v82
	v_mul_f32_e32 v83, v94, v83
	v_mul_f32_e32 v84, v94, v84
	v_mul_f32_e32 v85, v94, v85
	v_mul_f32_e32 v86, v94, v86
	v_mul_f32_e32 v87, v94, v87
	v_mul_f32_e32 v88, v94, v88
	v_mul_f32_e32 v89, v94, v89
	v_fma_f32 v74, v74, v10, v26
	v_fma_f32 v75, v75, v11, v27
	v_fma_f32 v76, v76, v12, v28
	v_fma_f32 v77, v77, v13, v29
	v_fma_f32 v78, v78, v14, v30
	v_fma_f32 v79, v79, v15, v31
	v_fma_f32 v80, v80, v16, v32
	v_fma_f32 v81, v81, v17, v33
	v_fma_f32 v82, v82, v18, v34
	v_fma_f32 v83, v83, v19, v35
	v_fma_f32 v84, v84, v20, v36
	v_fma_f32 v85, v85, v21, v37
	v_fma_f32 v86, v86, v22, v38
	v_fma_f32 v87, v87, v23, v39
	v_fma_f32 v88, v88, v24, v40
	v_fma_f32 v89, v89, v25, v41
	v_add_f32_e32 v9, v74, v75
	v_add_f32_e32 v91, v76, v77
	v_mul_f32_e32 v90, v74, v74
	v_mul_f32_e32 v92, v75, v75
	v_add_f32_e32 v9, v9, v78
	v_add_f32_e32 v91, v91, v79
	v_add_f32_e32 v9, v9, v80
	v_add_f32_e32 v91, v91, v81
	v_add_f32_e32 v9, v9, v82
	v_add_f32_e32 v91, v91, v83
	v_add_f32_e32 v9, v9, v84
	v_add_f32_e32 v91, v91, v85
	v_add_f32_e32 v9, v9, v86
	v_add_f32_e32 v91, v91, v87
	v_add_f32_e32 v9, v9, v88
	v_add_f32_e32 v91, v91, v89
	v_fmac_f32_e32 v90, v76, v76
	v_fmac_f32_e32 v92, v77, v77
	v_fmac_f32_e32 v90, v78, v78
	v_fmac_f32_e32 v92, v79, v79
	v_fmac_f32_e32 v90, v80, v80
	v_fmac_f32_e32 v92, v81, v81
	v_fmac_f32_e32 v90, v82, v82
	v_fmac_f32_e32 v92, v83, v83
	v_fmac_f32_e32 v90, v84, v84
	v_fmac_f32_e32 v92, v85, v85
	v_fmac_f32_e32 v90, v86, v86
	v_fmac_f32_e32 v92, v87, v87
	v_fmac_f32_e32 v90, v88, v88
	v_fmac_f32_e32 v92, v89, v89
	v_add_f32_e32 v9, v9, v91
	v_add_f32_e32 v90, v90, v92
	s_nop 1
	v_add_f32_dpp v9, v9, v9 quad_perm:[1,0,3,2] row_mask:0xf bank_mask:0xf
	v_add_f32_dpp v90, v90, v90 quad_perm:[1,0,3,2] row_mask:0xf bank_mask:0xf
	s_nop 0
	v_add_f32_dpp v9, v9, v9 quad_perm:[2,3,0,1] row_mask:0xf bank_mask:0xf
	v_add_f32_dpp v90, v90, v90 quad_perm:[2,3,0,1] row_mask:0xf bank_mask:0xf
	s_nop 0
	v_add_f32_dpp v9, v9, v9 row_half_mirror row_mask:0xf bank_mask:0xf
	v_add_f32_dpp v90, v90, v90 row_half_mirror row_mask:0xf bank_mask:0xf
	s_nop 0
	v_add_f32_dpp v9, v9, v9 row_mirror row_mask:0xf bank_mask:0xf
	v_add_f32_dpp v90, v90, v90 row_mirror row_mask:0xf bank_mask:0xf
	s_nop 0
	v_add_f32_dpp v9, v9, v9 row_bcast:15 row_mask:0xa bank_mask:0xf
	v_add_f32_dpp v90, v90, v90 row_bcast:15 row_mask:0xa bank_mask:0xf
	s_nop 0
	v_add_f32_dpp v9, v9, v9 row_bcast:31 row_mask:0xc bank_mask:0xf
	v_add_f32_dpp v90, v90, v90 row_bcast:31 row_mask:0xc bank_mask:0xf
; DI unsigned pk2(float lo, float hi) { f32x2 v = {lo, hi}; bf16x2_t b = __builtin_convertvector(v, bf16x2_t); return __builtin_bit_cast(unsigned, b); }
; DI void ln_row_v(const Frame& F, f32x4 (&v)[4], float* xout, const float* g, const float* b, const float* sh, const float* sc, bf16_t* hout, const float* slab, const float* gres, float* stat = nullptr) {
;     ...
; #pragma unroll
;         for (int j = 0; j < 4; ++j) { s += (v[j][0] + v[j][1]) + (v[j][2] + v[j][3]); s2 += (v[j][0] * v[j][0] + v[j][1] * v[j][1]) + (v[j][2] * v[j][2] + v[j][3] * v[j][3]); }
;         wave_sum2(s, s2, F.lane);
;         const float mean = s * (1.f / D); const float rstd = 1.f / sqrtf(fmaxf(s2 * (1.f / D) - mean * mean, 0.f) + EPS);
;         if (stat && F.lane == 0) { f32x2 sv = {mean, rstd}; *(f32x2*)stat = sv; }
; #pragma unroll
;         for (int j = 0; j < 4; ++j) { const f32x4 gg = ((const f32x4*)g)[F.lane + 64 * j], bb = ((const f32x4*)b)[F.lane + 64 * j];
;             v[j] = (v[j] - mean) * rstd * gg + bb; if (xout) ((f32x4*)xout)[F.lane + 64 * j] = v[j]; }
;     ...
;         const float mean = s * (1.f / D); const float rstd = 1.f / sqrtf(fmaxf(s2 * (1.f / D) - mean * mean, 0.f) + EPS);
; #pragma unroll
;         for (int j = 0; j < 4; ++j) { const f32x4 hh = ((const f32x4*)sh)[F.lane + 64 * j], cc = ((const f32x4*)sc)[F.lane + 64 * j];
;             const f32x4 o = (v[j] - mean) * rstd * (cc + 1.f) + hh; u32x2 wv; wv.x = pk2(o[0], o[1]); wv.y = pk2(o[2], o[3]);
;             ((u32x2*)hout)[F.lane + 64 * j] = wv; }
	s_nop 0
	v_readlane_b32 s2, v9, 63
	v_readlane_b32 s3, v90, 63
	s_nop 1
	v_mov_b32_e32 v9, s2
	v_mov_b32_e32 v90, s3
	v_mul_f32_e32 v93, 0x3a800000, v9
	v_mul_f32_e32 v91, 0x3a800000, v90
	v_fma_f32 v91, -v93, v93, v91
	v_max_f32_e32 v91, 0, v91
	v_add_f32_e32 v91, 0x358637bd, v91
	v_rsq_f32_e32 v94, v91
	v_mul_f32_e32 v91, 0.5, v91
	v_mul_f32_e32 v92, v94, v94
	v_fma_f32 v92, -v91, v92, 0.5
	v_fma_f32 v94, v94, v92, v94
	v_sub_f32_e32 v74, v74, v93
	v_sub_f32_e32 v75, v75, v93
	v_sub_f32_e32 v76, v76, v93
	v_sub_f32_e32 v77, v77, v93
	v_sub_f32_e32 v78, v78, v93
	v_sub_f32_e32 v79, v79, v93
	v_sub_f32_e32 v80, v80, v93
	v_sub_f32_e32 v81, v81, v93
	v_sub_f32_e32 v82, v82, v93
	v_sub_f32_e32 v83, v83, v93
	v_sub_f32_e32 v84, v84, v93
	v_sub_f32_e32 v85, v85, v93
	v_sub_f32_e32 v86, v86, v93
	v_sub_f32_e32 v87, v87, v93
	v_sub_f32_e32 v88, v88, v93
	v_sub_f32_e32 v89, v89, v93
	v_mul_f32_e32 v74, v94, v74
	v_mul_f32_e32 v75, v94, v75
	v_mul_f32_e32 v76, v94, v76
	v_mul_f32_e32 v77, v94, v77
	v_mul_f32_e32 v78, v94, v78
	v_mul_f32_e32 v79, v94, v79
	v_mul_f32_e32 v80, v94, v80
	v_mul_f32_e32 v81, v94, v81
	v_mul_f32_e32 v82, v94, v82
	v_mul_f32_e32 v83, v94, v83
	v_mul_f32_e32 v84, v94, v84
	v_mul_f32_e32 v85, v94, v85
	v_mul_f32_e32 v86, v94, v86
	v_mul_f32_e32 v87, v94, v87
	v_mul_f32_e32 v88, v94, v88
	v_mul_f32_e32 v89, v94, v89
	v_fma_f32 v74, v74, v130, v114
	v_fma_f32 v75, v75, v131, v115
	v_fma_f32 v76, v76, v132, v116
	v_fma_f32 v77, v77, v133, v117
	v_fma_f32 v78, v78, v134, v118
	v_fma_f32 v79, v79, v135, v119
	v_fma_f32 v80, v80, v136, v120
	v_fma_f32 v81, v81, v137, v121
	v_fma_f32 v82, v82, v138, v122
	v_fma_f32 v83, v83, v139, v123
	v_fma_f32 v84, v84, v140, v124
	v_fma_f32 v85, v85, v141, v125
	v_fma_f32 v86, v86, v142, v126
	v_fma_f32 v87, v87, v143, v127
	v_fma_f32 v88, v88, v144, v128
	v_fma_f32 v89, v89, v145, v129
	v_cvt_pk_bf16_f32 v190, v74, v75
	v_cvt_pk_bf16_f32 v191, v76, v77
	v_cvt_pk_bf16_f32 v192, v78, v79
	v_cvt_pk_bf16_f32 v193, v80, v81
	v_cvt_pk_bf16_f32 v194, v82, v83
	v_cvt_pk_bf16_f32 v195, v84, v85
	v_cvt_pk_bf16_f32 v196, v86, v87
	v_cvt_pk_bf16_f32 v197, v88, v89
	s_add_u32 s2, s10, 0x3000
	s_addc_u32 s3, s11, 0
	global_store_dwordx2 v1, v[190:191], s[2:3]
	global_store_dwordx2 v1, v[192:193], s[2:3] offset:512
	global_store_dwordx2 v1, v[194:195], s[2:3] offset:1024
	global_store_dwordx2 v1, v[196:197], s[2:3] offset:1536
	s_waitcnt vmcnt(19)
	v_add_f32_e32 v9, v98, v99
	v_add_f32_e32 v91, v100, v101
	v_mul_f32_e32 v90, v98, v98
	v_mul_f32_e32 v92, v99, v99
	v_add_f32_e32 v9, v9, v102
	v_add_f32_e32 v91, v91, v103
	v_add_f32_e32 v9, v9, v104
	v_add_f32_e32 v91, v91, v105
	v_add_f32_e32 v9, v9, v106
	v_add_f32_e32 v91, v91, v107
	v_add_f32_e32 v9, v9, v108
	v_add_f32_e32 v91, v91, v109
	v_add_f32_e32 v9, v9, v110
	v_add_f32_e32 v91, v91, v111
	v_add_f32_e32 v9, v9, v112
	v_add_f32_e32 v91, v91, v113
	v_fmac_f32_e32 v90, v100, v100
	v_fmac_f32_e32 v92, v101, v101
	v_fmac_f32_e32 v90, v102, v102
	v_fmac_f32_e32 v92, v103, v103
	v_fmac_f32_e32 v90, v104, v104
	v_fmac_f32_e32 v92, v105, v105
	v_fmac_f32_e32 v90, v106, v106
	v_fmac_f32_e32 v92, v107, v107
	v_fmac_f32_e32 v90, v108, v108
	v_fmac_f32_e32 v92, v109, v109
	v_fmac_f32_e32 v90, v110, v110
	v_fmac_f32_e32 v92, v111, v111
	v_fmac_f32_e32 v90, v112, v112
	v_fmac_f32_e32 v92, v113, v113
	v_add_f32_e32 v9, v9, v91
	v_add_f32_e32 v90, v90, v92
	s_nop 1
	v_add_f32_dpp v9, v9, v9 quad_perm:[1,0,3,2] row_mask:0xf bank_mask:0xf
	v_add_f32_dpp v90, v90, v90 quad_perm:[1,0,3,2] row_mask:0xf bank_mask:0xf
	s_nop 0
	v_add_f32_dpp v9, v9, v9 quad_perm:[2,3,0,1] row_mask:0xf bank_mask:0xf
	v_add_f32_dpp v90, v90, v90 quad_perm:[2,3,0,1] row_mask:0xf bank_mask:0xf
	s_nop 0
	v_add_f32_dpp v9, v9, v9 row_half_mirror row_mask:0xf bank_mask:0xf
	v_add_f32_dpp v90, v90, v90 row_half_mirror row_mask:0xf bank_mask:0xf
	s_nop 0
	v_add_f32_dpp v9, v9, v9 row_mirror row_mask:0xf bank_mask:0xf
	v_add_f32_dpp v90, v90, v90 row_mirror row_mask:0xf bank_mask:0xf
	s_nop 0
	v_add_f32_dpp v9, v9, v9 row_bcast:15 row_mask:0xa bank_mask:0xf
	v_add_f32_dpp v90, v90, v90 row_bcast:15 row_mask:0xa bank_mask:0xf
	s_nop 0
	v_add_f32_dpp v9, v9, v9 row_bcast:31 row_mask:0xc bank_mask:0xf
	v_add_f32_dpp v90, v90, v90 row_bcast:31 row_mask:0xc bank_mask:0xf
	s_nop 0
	v_readlane_b32 s2, v9, 63
	v_readlane_b32 s3, v90, 63
	s_nop 1
	v_mov_b32_e32 v9, s2
	v_mov_b32_e32 v90, s3
	v_mul_f32_e32 v93, 0x3a800000, v9
	v_mul_f32_e32 v91, 0x3a800000, v90
	v_fma_f32 v91, -v93, v93, v91
	v_max_f32_e32 v91, 0, v91
	v_add_f32_e32 v91, 0x358637bd, v91
	v_rsq_f32_e32 v94, v91
	v_mul_f32_e32 v91, 0.5, v91
	v_mul_f32_e32 v92, v94, v94
	v_fma_f32 v92, -v91, v92, 0.5
	v_fma_f32 v94, v94, v92, v94
	s_add_u32 s2, s12, 0x38
	s_addc_u32 s3, s13, 0
	v_mov_b32_e32 v188, v93
	v_mov_b32_e32 v189, v94
	s_mov_b64 exec, 1
	global_store_dwordx2 v97, v[188:189], s[2:3]
	s_mov_b64 exec, -1
	v_sub_f32_e32 v98, v98, v93
	v_sub_f32_e32 v99, v99, v93
	v_sub_f32_e32 v100, v100, v93
	v_sub_f32_e32 v101, v101, v93
	v_sub_f32_e32 v102, v102, v93
	v_sub_f32_e32 v103, v103, v93
	v_sub_f32_e32 v104, v104, v93
	v_sub_f32_e32 v105, v105, v93
	v_sub_f32_e32 v106, v106, v93
	v_sub_f32_e32 v107, v107, v93
	v_sub_f32_e32 v108, v108, v93
	v_sub_f32_e32 v109, v109, v93
	v_sub_f32_e32 v110, v110, v93
	v_sub_f32_e32 v111, v111, v93
	v_sub_f32_e32 v112, v112, v93
	v_sub_f32_e32 v113, v113, v93
	v_mul_f32_e32 v98, v94, v98
	v_mul_f32_e32 v99, v94, v99
	v_mul_f32_e32 v100, v94, v100
	v_mul_f32_e32 v101, v94, v101
	v_mul_f32_e32 v102, v94, v102
	v_mul_f32_e32 v103, v94, v103
	v_mul_f32_e32 v104, v94, v104
	v_mul_f32_e32 v105, v94, v105
; DI unsigned pk2(float lo, float hi) { f32x2 v = {lo, hi}; bf16x2_t b = __builtin_convertvector(v, bf16x2_t); return __builtin_bit_cast(unsigned, b); }
; DI void ln_row_v(const Frame& F, f32x4 (&v)[4], float* xout, const float* g, const float* b, const float* sh, const float* sc, bf16_t* hout, const float* slab, const float* gres, float* stat = nullptr) {
;     ...
;         for (int j = 0; j < 4; ++j) { const f32x4 gg = ((const f32x4*)g)[F.lane + 64 * j], bb = ((const f32x4*)b)[F.lane + 64 * j];
;             v[j] = (v[j] - mean) * rstd * gg + bb; if (xout) ((f32x4*)xout)[F.lane + 64 * j] = v[j]; }
;     }
;     if (hout) {
;         float s = 0.f, s2 = 0.f;
; #pragma unroll
;         for (int j = 0; j < 4; ++j) { s += (v[j][0] + v[j][1]) + (v[j][2] + v[j][3]); s2 += (v[j][0] * v[j][0] + v[j][1] * v[j][1]) + (v[j][2] * v[j][2] + v[j][3] * v[j][3]); }
;         wave_sum2(s, s2, F.lane);
;         const float mean = s * (1.f / D); const float rstd = 1.f / sqrtf(fmaxf(s2 * (1.f / D) - mean * mean, 0.f) + EPS);
; #pragma unroll
;         for (int j = 0; j < 4; ++j) { const f32x4 hh = ((const f32x4*)sh)[F.lane + 64 * j], cc = ((const f32x4*)sc)[F.lane + 64 * j];
;             const f32x4 o = (v[j] - mean) * rstd * (cc + 1.f) + hh; u32x2 wv; wv.x = pk2(o[0], o[1]); wv.y = pk2(o[2], o[3]);
;             ((u32x2*)hout)[F.lane + 64 * j] = wv; }
;     }
	v_mul_f32_e32 v106, v94, v106
	v_mul_f32_e32 v107, v94, v107
	v_mul_f32_e32 v108, v94, v108
	v_mul_f32_e32 v109, v94, v109
	v_mul_f32_e32 v110, v94, v110
	v_mul_f32_e32 v111, v94, v111
	v_mul_f32_e32 v112, v94, v112
	v_mul_f32_e32 v113, v94, v113
	v_fma_f32 v98, v98, v10, v26
	v_fma_f32 v99, v99, v11, v27
	v_fma_f32 v100, v100, v12, v28
	v_fma_f32 v101, v101, v13, v29
	v_fma_f32 v102, v102, v14, v30
	v_fma_f32 v103, v103, v15, v31
	v_fma_f32 v104, v104, v16, v32
	v_fma_f32 v105, v105, v17, v33
	v_fma_f32 v106, v106, v18, v34
	v_fma_f32 v107, v107, v19, v35
	v_fma_f32 v108, v108, v20, v36
	v_fma_f32 v109, v109, v21, v37
	v_fma_f32 v110, v110, v22, v38
	v_fma_f32 v111, v111, v23, v39
	v_fma_f32 v112, v112, v24, v40
	v_fma_f32 v113, v113, v25, v41
	v_add_f32_e32 v9, v98, v99
	v_add_f32_e32 v91, v100, v101
	v_mul_f32_e32 v90, v98, v98
	v_mul_f32_e32 v92, v99, v99
	v_add_f32_e32 v9, v9, v102
	v_add_f32_e32 v91, v91, v103
	v_add_f32_e32 v9, v9, v104
	v_add_f32_e32 v91, v91, v105
	v_add_f32_e32 v9, v9, v106
	v_add_f32_e32 v91, v91, v107
	v_add_f32_e32 v9, v9, v108
	v_add_f32_e32 v91, v91, v109
	v_add_f32_e32 v9, v9, v110
	v_add_f32_e32 v91, v91, v111
	v_add_f32_e32 v9, v9, v112
	v_add_f32_e32 v91, v91, v113
	v_fmac_f32_e32 v90, v100, v100
	v_fmac_f32_e32 v92, v101, v101
	v_fmac_f32_e32 v90, v102, v102
	v_fmac_f32_e32 v92, v103, v103
	v_fmac_f32_e32 v90, v104, v104
	v_fmac_f32_e32 v92, v105, v105
	v_fmac_f32_e32 v90, v106, v106
	v_fmac_f32_e32 v92, v107, v107
	v_fmac_f32_e32 v90, v108, v108
	v_fmac_f32_e32 v92, v109, v109
	v_fmac_f32_e32 v90, v110, v110
	v_fmac_f32_e32 v92, v111, v111
	v_fmac_f32_e32 v90, v112, v112
	v_fmac_f32_e32 v92, v113, v113
	v_add_f32_e32 v9, v9, v91
	v_add_f32_e32 v90, v90, v92
	s_nop 1
	v_add_f32_dpp v9, v9, v9 quad_perm:[1,0,3,2] row_mask:0xf bank_mask:0xf
	v_add_f32_dpp v90, v90, v90 quad_perm:[1,0,3,2] row_mask:0xf bank_mask:0xf
	s_nop 0
	v_add_f32_dpp v9, v9, v9 quad_perm:[2,3,0,1] row_mask:0xf bank_mask:0xf
	v_add_f32_dpp v90, v90, v90 quad_perm:[2,3,0,1] row_mask:0xf bank_mask:0xf
	s_nop 0
	v_add_f32_dpp v9, v9, v9 row_half_mirror row_mask:0xf bank_mask:0xf
	v_add_f32_dpp v90, v90, v90 row_half_mirror row_mask:0xf bank_mask:0xf
	s_nop 0
	v_add_f32_dpp v9, v9, v9 row_mirror row_mask:0xf bank_mask:0xf
	v_add_f32_dpp v90, v90, v90 row_mirror row_mask:0xf bank_mask:0xf
	s_nop 0
	v_add_f32_dpp v9, v9, v9 row_bcast:15 row_mask:0xa bank_mask:0xf
	v_add_f32_dpp v90, v90, v90 row_bcast:15 row_mask:0xa bank_mask:0xf
	s_nop 0
	v_add_f32_dpp v9, v9, v9 row_bcast:31 row_mask:0xc bank_mask:0xf
	v_add_f32_dpp v90, v90, v90 row_bcast:31 row_mask:0xc bank_mask:0xf
	s_nop 0
	v_readlane_b32 s2, v9, 63
	v_readlane_b32 s3, v90, 63
	s_nop 1
	v_mov_b32_e32 v9, s2
	v_mov_b32_e32 v90, s3
	v_mul_f32_e32 v93, 0x3a800000, v9
	v_mul_f32_e32 v91, 0x3a800000, v90
	v_fma_f32 v91, -v93, v93, v91
	v_max_f32_e32 v91, 0, v91
	v_add_f32_e32 v91, 0x358637bd, v91
	v_rsq_f32_e32 v94, v91
	v_mul_f32_e32 v91, 0.5, v91
	v_mul_f32_e32 v92, v94, v94
	v_fma_f32 v92, -v91, v92, 0.5
	v_fma_f32 v94, v94, v92, v94
	v_sub_f32_e32 v98, v98, v93
	v_sub_f32_e32 v99, v99, v93
	v_sub_f32_e32 v100, v100, v93
	v_sub_f32_e32 v101, v101, v93
	v_sub_f32_e32 v102, v102, v93
	v_sub_f32_e32 v103, v103, v93
	v_sub_f32_e32 v104, v104, v93
	v_sub_f32_e32 v105, v105, v93
	v_sub_f32_e32 v106, v106, v93
	v_sub_f32_e32 v107, v107, v93
	v_sub_f32_e32 v108, v108, v93
	v_sub_f32_e32 v109, v109, v93
	v_sub_f32_e32 v110, v110, v93
	v_sub_f32_e32 v111, v111, v93
	v_sub_f32_e32 v112, v112, v93
	v_sub_f32_e32 v113, v113, v93
	v_mul_f32_e32 v98, v94, v98
	v_mul_f32_e32 v99, v94, v99
	v_mul_f32_e32 v100, v94, v100
	v_mul_f32_e32 v101, v94, v101
	v_mul_f32_e32 v102, v94, v102
	v_mul_f32_e32 v103, v94, v103
	v_mul_f32_e32 v104, v94, v104
	v_mul_f32_e32 v105, v94, v105
	v_mul_f32_e32 v106, v94, v106
	v_mul_f32_e32 v107, v94, v107
	v_mul_f32_e32 v108, v94, v108
	v_mul_f32_e32 v109, v94, v109
	v_mul_f32_e32 v110, v94, v110
	v_mul_f32_e32 v111, v94, v111
	v_mul_f32_e32 v112, v94, v112
	v_mul_f32_e32 v113, v94, v113
	v_fma_f32 v98, v98, v130, v114
	v_fma_f32 v99, v99, v131, v115
	v_fma_f32 v100, v100, v132, v116
	v_fma_f32 v101, v101, v133, v117
	v_fma_f32 v102, v102, v134, v118
	v_fma_f32 v103, v103, v135, v119
	v_fma_f32 v104, v104, v136, v120
	v_fma_f32 v105, v105, v137, v121
	v_fma_f32 v106, v106, v138, v122
	v_fma_f32 v107, v107, v139, v123
	v_fma_f32 v108, v108, v140, v124
	v_fma_f32 v109, v109, v141, v125
	v_fma_f32 v110, v110, v142, v126
	v_fma_f32 v111, v111, v143, v127
	v_fma_f32 v112, v112, v144, v128
	v_fma_f32 v113, v113, v145, v129
	v_cvt_pk_bf16_f32 v190, v98, v99
	v_cvt_pk_bf16_f32 v191, v100, v101
	v_cvt_pk_bf16_f32 v192, v102, v103
	v_cvt_pk_bf16_f32 v193, v104, v105
	v_cvt_pk_bf16_f32 v194, v106, v107
	v_cvt_pk_bf16_f32 v195, v108, v109
	v_cvt_pk_bf16_f32 v196, v110, v111
	v_cvt_pk_bf16_f32 v197, v112, v113
	s_add_u32 s2, s10, 0x3800
	s_addc_u32 s3, s11, 0
	global_store_dwordx2 v1, v[190:191], s[2:3]
	global_store_dwordx2 v1, v[192:193], s[2:3] offset:512
	global_store_dwordx2 v1, v[194:195], s[2:3] offset:1024
	global_store_dwordx2 v1, v[196:197], s[2:3] offset:1536
	s_cmp_eq_u32 s22, 3
	s_cbranch_scc1 .Lln_a_noctx
; DI unsigned pk2(float lo, float hi) { f32x2 v = {lo, hi}; bf16x2_t b = __builtin_convertvector(v, bf16x2_t); return __builtin_bit_cast(unsigned, b); }
; DI void ln_row_v(const Frame& F, f32x4 (&v)[4], float* xout, const float* g, const float* b, const float* sh, const float* sc, bf16_t* hout, const float* slab, const float* gres, float* stat = nullptr) {
;     ...
;     if (g) {
;         float s = 0.f, s2 = 0.f;
; #pragma unroll
;         for (int j = 0; j < 4; ++j) { s += (v[j][0] + v[j][1]) + (v[j][2] + v[j][3]); s2 += (v[j][0] * v[j][0] + v[j][1] * v[j][1]) + (v[j][2] * v[j][2] + v[j][3] * v[j][3]); }
;         wave_sum2(s, s2, F.lane);
;         const float mean = s * (1.f / D); const float rstd = 1.f / sqrtf(fmaxf(s2 * (1.f / D) - mean * mean, 0.f) + EPS);
;         if (stat && F.lane == 0) { f32x2 sv = {mean, rstd}; *(f32x2*)stat = sv; }
; #pragma unroll
;         for (int j = 0; j < 4; ++j) { const f32x4 gg = ((const f32x4*)g)[F.lane + 64 * j], bb = ((const f32x4*)b)[F.lane + 64 * j];
;             v[j] = (v[j] - mean) * rstd * gg + bb; if (xout) ((f32x4*)xout)[F.lane + 64 * j] = v[j]; }
;     }
;     if (hout) {
;         float s = 0.f, s2 = 0.f;
; #pragma unroll
;         for (int j = 0; j < 4; ++j) { s += (v[j][0] + v[j][1]) + (v[j][2] + v[j][3]); s2 += (v[j][0] * v[j][0] + v[j][1] * v[j][1]) + (v[j][2] * v[j][2] + v[j][3] * v[j][3]); }
;         wave_sum2(s, s2, F.lane);
;         const float mean = s * (1.f / D); const float rstd = 1.f / sqrtf(fmaxf(s2 * (1.f / D) - mean * mean, 0.f) + EPS);
; #pragma unroll
;         for (int j = 0; j < 4; ++j) { const f32x4 hh = ((const f32x4*)sh)[F.lane + 64 * j], cc = ((const f32x4*)sc)[F.lane + 64 * j];
;             const f32x4 o = (v[j] - mean) * rstd * (cc + 1.f) + hh; u32x2 wv; wv.x = pk2(o[0], o[1]); wv.y = pk2(o[2], o[3]);
;             ((u32x2*)hout)[F.lane + 64 * j] = wv; }
;     }
	s_waitcnt vmcnt(15)
	v_add_f32_e32 v9, v42, v43
	v_add_f32_e32 v91, v44, v45
	v_mul_f32_e32 v90, v42, v42
	v_mul_f32_e32 v92, v43, v43
	v_add_f32_e32 v9, v9, v46
	v_add_f32_e32 v91, v91, v47
	v_add_f32_e32 v9, v9, v48
	v_add_f32_e32 v91, v91, v49
	v_add_f32_e32 v9, v9, v50
	v_add_f32_e32 v91, v91, v51
	v_add_f32_e32 v9, v9, v52
	v_add_f32_e32 v91, v91, v53
	v_add_f32_e32 v9, v9, v54
	v_add_f32_e32 v91, v91, v55
	v_add_f32_e32 v9, v9, v56
	v_add_f32_e32 v91, v91, v57
	v_fmac_f32_e32 v90, v44, v44
	v_fmac_f32_e32 v92, v45, v45
	v_fmac_f32_e32 v90, v46, v46
	v_fmac_f32_e32 v92, v47, v47
	v_fmac_f32_e32 v90, v48, v48
	v_fmac_f32_e32 v92, v49, v49
	v_fmac_f32_e32 v90, v50, v50
	v_fmac_f32_e32 v92, v51, v51
	v_fmac_f32_e32 v90, v52, v52
	v_fmac_f32_e32 v92, v53, v53
	v_fmac_f32_e32 v90, v54, v54
	v_fmac_f32_e32 v92, v55, v55
	v_fmac_f32_e32 v90, v56, v56
	v_fmac_f32_e32 v92, v57, v57
	v_add_f32_e32 v9, v9, v91
	v_add_f32_e32 v90, v90, v92
	s_nop 1
	v_add_f32_dpp v9, v9, v9 quad_perm:[1,0,3,2] row_mask:0xf bank_mask:0xf
	v_add_f32_dpp v90, v90, v90 quad_perm:[1,0,3,2] row_mask:0xf bank_mask:0xf
	s_nop 0
	v_add_f32_dpp v9, v9, v9 quad_perm:[2,3,0,1] row_mask:0xf bank_mask:0xf
	v_add_f32_dpp v90, v90, v90 quad_perm:[2,3,0,1] row_mask:0xf bank_mask:0xf
	s_nop 0
	v_add_f32_dpp v9, v9, v9 row_half_mirror row_mask:0xf bank_mask:0xf
	v_add_f32_dpp v90, v90, v90 row_half_mirror row_mask:0xf bank_mask:0xf
	s_nop 0
	v_add_f32_dpp v9, v9, v9 row_mirror row_mask:0xf bank_mask:0xf
	v_add_f32_dpp v90, v90, v90 row_mirror row_mask:0xf bank_mask:0xf
	s_nop 0
	v_add_f32_dpp v9, v9, v9 row_bcast:15 row_mask:0xa bank_mask:0xf
	v_add_f32_dpp v90, v90, v90 row_bcast:15 row_mask:0xa bank_mask:0xf
	s_nop 0
	v_add_f32_dpp v9, v9, v9 row_bcast:31 row_mask:0xc bank_mask:0xf
	v_add_f32_dpp v90, v90, v90 row_bcast:31 row_mask:0xc bank_mask:0xf
	s_nop 0
	v_readlane_b32 s2, v9, 63
	v_readlane_b32 s3, v90, 63
	s_nop 1
	v_mov_b32_e32 v9, s2
	v_mov_b32_e32 v90, s3
	v_mul_f32_e32 v93, 0x3a800000, v9
	v_mul_f32_e32 v91, 0x3a800000, v90
	v_fma_f32 v91, -v93, v93, v91
	v_max_f32_e32 v91, 0, v91
	v_add_f32_e32 v91, 0x358637bd, v91
	v_rsq_f32_e32 v94, v91
	v_mul_f32_e32 v91, 0.5, v91
	v_mul_f32_e32 v92, v94, v94
	v_fma_f32 v92, -v91, v92, 0.5
	v_fma_f32 v94, v94, v92, v94
	v_sub_f32_e32 v42, v42, v93
	v_sub_f32_e32 v43, v43, v93
	v_sub_f32_e32 v44, v44, v93
	v_sub_f32_e32 v45, v45, v93
	v_sub_f32_e32 v46, v46, v93
	v_sub_f32_e32 v47, v47, v93
	v_sub_f32_e32 v48, v48, v93
	v_sub_f32_e32 v49, v49, v93
	v_sub_f32_e32 v50, v50, v93
	v_sub_f32_e32 v51, v51, v93
	v_sub_f32_e32 v52, v52, v93
	v_sub_f32_e32 v53, v53, v93
	v_sub_f32_e32 v54, v54, v93
	v_sub_f32_e32 v55, v55, v93
	v_sub_f32_e32 v56, v56, v93
	v_sub_f32_e32 v57, v57, v93
	v_mul_f32_e32 v42, v94, v42
	v_mul_f32_e32 v43, v94, v43
	v_mul_f32_e32 v44, v94, v44
	v_mul_f32_e32 v45, v94, v45
	v_mul_f32_e32 v46, v94, v46
	v_mul_f32_e32 v47, v94, v47
	v_mul_f32_e32 v48, v94, v48
	v_mul_f32_e32 v49, v94, v49
	v_mul_f32_e32 v50, v94, v50
	v_mul_f32_e32 v51, v94, v51
	v_mul_f32_e32 v52, v94, v52
	v_mul_f32_e32 v53, v94, v53
	v_mul_f32_e32 v54, v94, v54
	v_mul_f32_e32 v55, v94, v55
	v_mul_f32_e32 v56, v94, v56
	v_mul_f32_e32 v57, v94, v57
	v_fma_f32 v42, v42, v10, v26
	v_fma_f32 v43, v43, v11, v27
	v_fma_f32 v44, v44, v12, v28
	v_fma_f32 v45, v45, v13, v29
	v_fma_f32 v46, v46, v14, v30
	v_fma_f32 v47, v47, v15, v31
	v_fma_f32 v48, v48, v16, v32
	v_fma_f32 v49, v49, v17, v33
	v_fma_f32 v50, v50, v18, v34
	v_fma_f32 v51, v51, v19, v35
	v_fma_f32 v52, v52, v20, v36
	v_fma_f32 v53, v53, v21, v37
	v_fma_f32 v54, v54, v22, v38
	v_fma_f32 v55, v55, v23, v39
	v_fma_f32 v56, v56, v24, v40
	v_fma_f32 v57, v57, v25, v41
	s_mov_b64 s[2:3], s[20:21]
	global_store_dwordx4 v0, v[42:45], s[2:3]
	global_store_dwordx4 v0, v[46:49], s[2:3] offset:1024
	global_store_dwordx4 v0, v[50:53], s[2:3] offset:2048
	global_store_dwordx4 v0, v[54:57], s[2:3] offset:3072
	v_add_f32_e32 v9, v42, v43
	v_add_f32_e32 v91, v44, v45
	v_mul_f32_e32 v90, v42, v42
	v_mul_f32_e32 v92, v43, v43
	v_add_f32_e32 v9, v9, v46
	v_add_f32_e32 v91, v91, v47
	v_add_f32_e32 v9, v9, v48
	v_add_f32_e32 v91, v91, v49
	v_add_f32_e32 v9, v9, v50
	v_add_f32_e32 v91, v91, v51
	v_add_f32_e32 v9, v9, v52
	v_add_f32_e32 v91, v91, v53
	v_add_f32_e32 v9, v9, v54
	v_add_f32_e32 v91, v91, v55
	v_add_f32_e32 v9, v9, v56
	v_add_f32_e32 v91, v91, v57
; DI unsigned pk2(float lo, float hi) { f32x2 v = {lo, hi}; bf16x2_t b = __builtin_convertvector(v, bf16x2_t); return __builtin_bit_cast(unsigned, b); }
; DI void ln_row_v(const Frame& F, f32x4 (&v)[4], float* xout, const float* g, const float* b, const float* sh, const float* sc, bf16_t* hout, const float* slab, const float* gres, float* stat = nullptr) {
;     ...
;         float s = 0.f, s2 = 0.f;
; #pragma unroll
;         for (int j = 0; j < 4; ++j) { s += (v[j][0] + v[j][1]) + (v[j][2] + v[j][3]); s2 += (v[j][0] * v[j][0] + v[j][1] * v[j][1]) + (v[j][2] * v[j][2] + v[j][3] * v[j][3]); }
;         wave_sum2(s, s2, F.lane);
;         const float mean = s * (1.f / D); const float rstd = 1.f / sqrtf(fmaxf(s2 * (1.f / D) - mean * mean, 0.f) + EPS);
; #pragma unroll
;         for (int j = 0; j < 4; ++j) { const f32x4 hh = ((const f32x4*)sh)[F.lane + 64 * j], cc = ((const f32x4*)sc)[F.lane + 64 * j];
;             const f32x4 o = (v[j] - mean) * rstd * (cc + 1.f) + hh; u32x2 wv; wv.x = pk2(o[0], o[1]); wv.y = pk2(o[2], o[3]);
;             ((u32x2*)hout)[F.lane + 64 * j] = wv; }
;     }
	v_fmac_f32_e32 v90, v44, v44
	v_fmac_f32_e32 v92, v45, v45
	v_fmac_f32_e32 v90, v46, v46
	v_fmac_f32_e32 v92, v47, v47
	v_fmac_f32_e32 v90, v48, v48
	v_fmac_f32_e32 v92, v49, v49
	v_fmac_f32_e32 v90, v50, v50
	v_fmac_f32_e32 v92, v51, v51
	v_fmac_f32_e32 v90, v52, v52
	v_fmac_f32_e32 v92, v53, v53
	v_fmac_f32_e32 v90, v54, v54
	v_fmac_f32_e32 v92, v55, v55
	v_fmac_f32_e32 v90, v56, v56
	v_fmac_f32_e32 v92, v57, v57
	v_add_f32_e32 v9, v9, v91
	v_add_f32_e32 v90, v90, v92
	s_nop 1
	v_add_f32_dpp v9, v9, v9 quad_perm:[1,0,3,2] row_mask:0xf bank_mask:0xf
	v_add_f32_dpp v90, v90, v90 quad_perm:[1,0,3,2] row_mask:0xf bank_mask:0xf
	s_nop 0
	v_add_f32_dpp v9, v9, v9 quad_perm:[2,3,0,1] row_mask:0xf bank_mask:0xf
	v_add_f32_dpp v90, v90, v90 quad_perm:[2,3,0,1] row_mask:0xf bank_mask:0xf
	s_nop 0
	v_add_f32_dpp v9, v9, v9 row_half_mirror row_mask:0xf bank_mask:0xf
	v_add_f32_dpp v90, v90, v90 row_half_mirror row_mask:0xf bank_mask:0xf
	s_nop 0
	v_add_f32_dpp v9, v9, v9 row_mirror row_mask:0xf bank_mask:0xf
	v_add_f32_dpp v90, v90, v90 row_mirror row_mask:0xf bank_mask:0xf
	s_nop 0
	v_add_f32_dpp v9, v9, v9 row_bcast:15 row_mask:0xa bank_mask:0xf
	v_add_f32_dpp v90, v90, v90 row_bcast:15 row_mask:0xa bank_mask:0xf
	s_nop 0
	v_add_f32_dpp v9, v9, v9 row_bcast:31 row_mask:0xc bank_mask:0xf
	v_add_f32_dpp v90, v90, v90 row_bcast:31 row_mask:0xc bank_mask:0xf
	s_nop 0
	v_readlane_b32 s2, v9, 63
	v_readlane_b32 s3, v90, 63
	s_nop 1
	v_mov_b32_e32 v9, s2
	v_mov_b32_e32 v90, s3
	v_mul_f32_e32 v93, 0x3a800000, v9
	v_mul_f32_e32 v91, 0x3a800000, v90
	v_fma_f32 v91, -v93, v93, v91
	v_max_f32_e32 v91, 0, v91
	v_add_f32_e32 v91, 0x358637bd, v91
	v_rsq_f32_e32 v94, v91
	v_mul_f32_e32 v91, 0.5, v91
	v_mul_f32_e32 v92, v94, v94
	v_fma_f32 v92, -v91, v92, 0.5
	v_fma_f32 v94, v94, v92, v94
	v_sub_f32_e32 v42, v42, v93
	v_sub_f32_e32 v43, v43, v93
	v_sub_f32_e32 v44, v44, v93
	v_sub_f32_e32 v45, v45, v93
	v_sub_f32_e32 v46, v46, v93
	v_sub_f32_e32 v47, v47, v93
	v_sub_f32_e32 v48, v48, v93
	v_sub_f32_e32 v49, v49, v93
	v_sub_f32_e32 v50, v50, v93
	v_sub_f32_e32 v51, v51, v93
	v_sub_f32_e32 v52, v52, v93
	v_sub_f32_e32 v53, v53, v93
	v_sub_f32_e32 v54, v54, v93
	v_sub_f32_e32 v55, v55, v93
	v_sub_f32_e32 v56, v56, v93
	v_sub_f32_e32 v57, v57, v93
	v_add_f32_e32 v162, 1.0, v162
	v_add_f32_e32 v163, 1.0, v163
	v_add_f32_e32 v164, 1.0, v164
	v_add_f32_e32 v165, 1.0, v165
	v_add_f32_e32 v166, 1.0, v166
	v_add_f32_e32 v167, 1.0, v167
	v_add_f32_e32 v168, 1.0, v168
	v_add_f32_e32 v169, 1.0, v169
	v_add_f32_e32 v170, 1.0, v170
	v_add_f32_e32 v171, 1.0, v171
	v_add_f32_e32 v172, 1.0, v172
	v_add_f32_e32 v173, 1.0, v173
	v_add_f32_e32 v174, 1.0, v174
	v_add_f32_e32 v175, 1.0, v175
	v_add_f32_e32 v176, 1.0, v176
	v_add_f32_e32 v177, 1.0, v177
	v_mul_f32_e32 v42, v94, v42
	v_mul_f32_e32 v43, v94, v43
	v_mul_f32_e32 v44, v94, v44
	v_mul_f32_e32 v45, v94, v45
	v_mul_f32_e32 v46, v94, v46
	v_mul_f32_e32 v47, v94, v47
	v_mul_f32_e32 v48, v94, v48
	v_mul_f32_e32 v49, v94, v49
	v_mul_f32_e32 v50, v94, v50
	v_mul_f32_e32 v51, v94, v51
	v_mul_f32_e32 v52, v94, v52
	v_mul_f32_e32 v53, v94, v53
	v_mul_f32_e32 v54, v94, v54
	v_mul_f32_e32 v55, v94, v55
	v_mul_f32_e32 v56, v94, v56
	v_mul_f32_e32 v57, v94, v57
	v_fma_f32 v42, v42, v162, v146
	v_fma_f32 v43, v43, v163, v147
	v_fma_f32 v44, v44, v164, v148
	v_fma_f32 v45, v45, v165, v149
	v_fma_f32 v46, v46, v166, v150
	v_fma_f32 v47, v47, v167, v151
	v_fma_f32 v48, v48, v168, v152
	v_fma_f32 v49, v49, v169, v153
	v_fma_f32 v50, v50, v170, v154
	v_fma_f32 v51, v51, v171, v155
	v_fma_f32 v52, v52, v172, v156
	v_fma_f32 v53, v53, v173, v157
	v_fma_f32 v54, v54, v174, v158
	v_fma_f32 v55, v55, v175, v159
	v_fma_f32 v56, v56, v176, v160
	v_fma_f32 v57, v57, v177, v161
	v_cvt_pk_bf16_f32 v190, v42, v43
	v_cvt_pk_bf16_f32 v191, v44, v45
	v_cvt_pk_bf16_f32 v192, v46, v47
	v_cvt_pk_bf16_f32 v193, v48, v49
	v_cvt_pk_bf16_f32 v194, v50, v51
	v_cvt_pk_bf16_f32 v195, v52, v53
	v_cvt_pk_bf16_f32 v196, v54, v55
	v_cvt_pk_bf16_f32 v197, v56, v57
	s_lshl_b32 s2, s16, 11
	s_add_u32 s2, s94, s2
	s_addc_u32 s3, s95, 0
	s_add_u32 s2, s2, 0x5e00000
	s_addc_u32 s3, s3, 0
	global_store_dwordx2 v1, v[190:191], s[2:3]
	global_store_dwordx2 v1, v[192:193], s[2:3] offset:512
	global_store_dwordx2 v1, v[194:195], s[2:3] offset:1024
	global_store_dwordx2 v1, v[196:197], s[2:3] offset:1536

; DI const float* modp(const Frame& F, int l, int mr, int which) { return (const float*)(F.ws + WS_MOD) + ((size_t)(l * 9 + mr) * 6 + which) * 1024; }
; DI void ln_row_v(const Frame& F, f32x4 (&v)[4], float* xout, const float* g, const float* b, const float* sh, const float* sc, bf16_t* hout, const float* slab, const float* gres, float* stat = nullptr) {
;     ...
;     if (g) {
;         float s = 0.f, s2 = 0.f;
; #pragma unroll
;         for (int j = 0; j < 4; ++j) { s += (v[j][0] + v[j][1]) + (v[j][2] + v[j][3]); s2 += (v[j][0] * v[j][0] + v[j][1] * v[j][1]) + (v[j][2] * v[j][2] + v[j][3] * v[j][3]); }
;         wave_sum2(s, s2, F.lane);
;         const float mean = s * (1.f / D); const float rstd = 1.f / sqrtf(fmaxf(s2 * (1.f / D) - mean * mean, 0.f) + EPS);
; DI void ln_phase(const Frame& F, int which) {
;     const int gw = F.vcu * 8 + F.wave, NGW = F.G * 8; const int l = F.l;
;     const int nrows = (l == NL - 1) ? ML : MT;
;     bf16_t* H = (bf16_t*)(F.ws + WS_HB);
;     const float* g = pin(F, which == 0 ? I_LN1G : I_LN2G) + l * 1024; const float* b = pin(F, which == 0 ? I_LN1B : I_LN2B) + l * 1024;
;     const bool wh = !(which == 1 && l == NL - 1);
;     f32x4 vc[4], vn[4];
;     if (gw < nrows) ln_load(F, xrow_ptr(F, gw), vc);
;     for (int row = gw; row < nrows; row += NGW) {
;         if (row + NGW < nrows) ln_load(F, xrow_ptr(F, row + NGW), vn);
;         const int mr = row < ML ? (row >> 11) : 8;
;         const float* sh = which == 0 ? modp(F, l, mr, 3) : modp(F, l + 1 < NL ? l + 1 : l, mr, 0);
;         const float* sc = which == 0 ? modp(F, l, mr, 4) : modp(F, l + 1 < NL ? l + 1 : l, mr, 1);
;         const bool sl = (which == 1 && row >= ML);
;         const bool st_only = row < ML && !(which == 1 && l == NL - 1);
;         float* stp = st_only ? (float*)(F.ws + (which == 0 ? WS_ST1 : WS_ST2)) + 2 * (size_t)row : nullptr;
;         ln_row_v(F, vc, st_only ? nullptr : xrow_ptr(F, row), g, b, sh, sc, wh ? H + (size_t)row * D : nullptr, sl ? (const float*)(F.ws + WS_KN) + (size_t)(row - ML) * 1024 : nullptr, modp(F, l, mr, 5), stp);
.LBB0_513:
	s_and_b64 vcc, exec, s[2:3]
	s_cbranch_vccz .LBB0_537
	v_readlane_b32 s2, v255, 29
	s_lshl_b32 s2, s2, 3
	v_readlane_b32 s3, v255, 31
	s_add_i32 s16, s3, s2
	v_lshlrev_b32_e32 v0, 4, v186
	v_lshlrev_b32_e32 v1, 3, v186
	v_lshlrev_b32_e32 v96, 2, v186
	v_xor_b32_e32 v3, 4, v96
	v_xor_b32_e32 v4, 8, v96
	v_xor_b32_e32 v5, 16, v96
	v_xor_b32_e32 v6, 32, v96
	v_xor_b32_e32 v7, 64, v96
	v_xor_b32_e32 v8, 128, v96
	s_load_dwordx4 s[4:7], s[62:63], 0xb8
	v_readlane_b32 s22, v255, 35
	v_readlane_b32 s8, v255, 17
	v_readlane_b32 s9, v255, 18
	s_add_u32 s20, s94, 0x3600000
	s_addc_u32 s21, s95, 0
	s_lshl_b32 s2, s16, 12
	s_lshl_b32 s3, s16, 15
	s_add_u32 s8, s8, s3
	s_addc_u32 s9, s9, 0
	s_add_u32 s20, s20, s2
	s_addc_u32 s21, s21, 0
	s_lshl_b32 s2, s16, 14
	s_add_u32 s10, s94, s2
	s_addc_u32 s11, s95, 0
	s_add_u32 s10, s10, 0x3e00000
	s_addc_u32 s11, s11, 0
	s_lshl_b32 s2, s16, 6
	s_add_u32 s12, s94, s2
	s_addc_u32 s13, s95, 0
	s_add_u32 s12, s12, 0x4c0000
	s_addc_u32 s13, s13, 0
	s_add_i32 s3, s22, 1
	s_min_u32 s3, s3, 3
	s_mul_i32 s3, s3, 0x36000
	s_add_u32 s14, s94, s3
	s_addc_u32 s15, s95, 0
	s_add_u32 s14, s14, 0x100000
	s_addc_u32 s15, s15, 0
	s_add_u32 s18, s14, 0x1000
	s_addc_u32 s19, s15, 0
	s_lshl_b32 s2, s22, 12
	s_waitcnt lgkmcnt(0)
	s_add_u32 s4, s4, s2
	s_addc_u32 s5, s5, 0
	s_add_u32 s6, s6, s2
	s_addc_u32 s7, s7, 0
	s_lshl_b32 s2, s16, 12
	s_add_u32 s24, s94, s2
	s_addc_u32 s25, s95, 0
	s_add_u32 s24, s24, 0x9100000
	s_addc_u32 s25, s25, 0
	s_mul_i32 s2, s22, 0x36000
	s_add_u32 s26, s94, s2
	s_addc_u32 s27, s95, 0
	s_add_u32 s26, s26, 0x135000
	s_addc_u32 s27, s27, 0
	s_cmp_eq_u32 s22, 3
	s_cbranch_scc1 .Lln_b_final
	global_load_dwordx4 v[10:13], v0, s[4:5]
	global_load_dwordx4 v[14:17], v0, s[4:5] offset:1024
	global_load_dwordx4 v[18:21], v0, s[4:5] offset:2048
	global_load_dwordx4 v[22:25], v0, s[4:5] offset:3072
	global_load_dwordx4 v[26:29], v0, s[6:7]
	global_load_dwordx4 v[30:33], v0, s[6:7] offset:1024
	global_load_dwordx4 v[34:37], v0, s[6:7] offset:2048
	global_load_dwordx4 v[38:41], v0, s[6:7] offset:3072
	s_add_u32 s2, s8, 0x0
	s_addc_u32 s3, s9, 0
	global_load_dwordx4 v[42:45], v0, s[2:3]
	global_load_dwordx4 v[46:49], v0, s[2:3] offset:1024
	global_load_dwordx4 v[50:53], v0, s[2:3] offset:2048
	global_load_dwordx4 v[54:57], v0, s[2:3] offset:3072
	s_lshr_b32 s23, s16, 8
	s_mul_i32 s23, s23, 0x6000
	s_add_u32 s2, s14, s23
	s_addc_u32 s3, s15, 0
	global_load_dwordx4 v[114:117], v0, s[2:3]
	global_load_dwordx4 v[118:121], v0, s[2:3] offset:1024
	global_load_dwordx4 v[122:125], v0, s[2:3] offset:2048
	global_load_dwordx4 v[126:129], v0, s[2:3] offset:3072
	s_add_u32 s2, s18, s23
	s_addc_u32 s3, s19, 0
	global_load_dwordx4 v[130:133], v0, s[2:3]
	global_load_dwordx4 v[134:137], v0, s[2:3] offset:1024
	global_load_dwordx4 v[138:141], v0, s[2:3] offset:2048
	global_load_dwordx4 v[142:145], v0, s[2:3] offset:3072
	s_add_u32 s2, s8, 0x1000
	s_addc_u32 s3, s9, 0
	global_load_dwordx4 v[58:61], v0, s[2:3]
	global_load_dwordx4 v[62:65], v0, s[2:3] offset:1024
	global_load_dwordx4 v[66:69], v0, s[2:3] offset:2048
	global_load_dwordx4 v[70:73], v0, s[2:3] offset:3072
	s_add_u32 s2, s8, 0x2000
	s_addc_u32 s3, s9, 0
	global_load_dwordx4 v[74:77], v0, s[2:3]
	global_load_dwordx4 v[78:81], v0, s[2:3] offset:1024
	global_load_dwordx4 v[82:85], v0, s[2:3] offset:2048
	global_load_dwordx4 v[86:89], v0, s[2:3] offset:3072
	s_add_u32 s2, s8, 0x3000
	s_addc_u32 s3, s9, 0
	global_load_dwordx4 v[98:101], v0, s[2:3]
	global_load_dwordx4 v[102:105], v0, s[2:3] offset:1024
	global_load_dwordx4 v[106:109], v0, s[2:3] offset:2048
	global_load_dwordx4 v[110:113], v0, s[2:3] offset:3072
	s_waitcnt vmcnt(20)
	v_add_f32_e32 v9, v42, v43
	v_add_f32_e32 v91, v44, v45
	v_mul_f32_e32 v90, v42, v42
	v_mul_f32_e32 v92, v43, v43
	v_add_f32_e32 v9, v9, v46
	v_add_f32_e32 v91, v91, v47
	v_add_f32_e32 v9, v9, v48
	v_add_f32_e32 v91, v91, v49
	v_add_f32_e32 v9, v9, v50
	v_add_f32_e32 v91, v91, v51
	v_add_f32_e32 v9, v9, v52
	v_add_f32_e32 v91, v91, v53
	v_add_f32_e32 v9, v9, v54
	v_add_f32_e32 v91, v91, v55
	v_add_f32_e32 v9, v9, v56
	v_add_f32_e32 v91, v91, v57
	v_fmac_f32_e32 v90, v44, v44
	v_fmac_f32_e32 v92, v45, v45
	v_fmac_f32_e32 v90, v46, v46
	v_fmac_f32_e32 v92, v47, v47
	v_fmac_f32_e32 v90, v48, v48
	v_fmac_f32_e32 v92, v49, v49
	v_fmac_f32_e32 v90, v50, v50
	v_fmac_f32_e32 v92, v51, v51
	v_fmac_f32_e32 v90, v52, v52
	v_fmac_f32_e32 v92, v53, v53
	v_fmac_f32_e32 v90, v54, v54
	v_fmac_f32_e32 v92, v55, v55
	v_fmac_f32_e32 v90, v56, v56
	v_fmac_f32_e32 v92, v57, v57
	v_add_f32_e32 v9, v9, v91
	v_add_f32_e32 v90, v90, v92
	s_nop 1
	v_add_f32_dpp v9, v9, v9 quad_perm:[1,0,3,2] row_mask:0xf bank_mask:0xf
	v_add_f32_dpp v90, v90, v90 quad_perm:[1,0,3,2] row_mask:0xf bank_mask:0xf
	s_nop 0
	v_add_f32_dpp v9, v9, v9 quad_perm:[2,3,0,1] row_mask:0xf bank_mask:0xf
	v_add_f32_dpp v90, v90, v90 quad_perm:[2,3,0,1] row_mask:0xf bank_mask:0xf
	s_nop 0
	v_add_f32_dpp v9, v9, v9 row_half_mirror row_mask:0xf bank_mask:0xf
	v_add_f32_dpp v90, v90, v90 row_half_mirror row_mask:0xf bank_mask:0xf
	s_nop 0
	v_add_f32_dpp v9, v9, v9 row_mirror row_mask:0xf bank_mask:0xf
	v_add_f32_dpp v90, v90, v90 row_mirror row_mask:0xf bank_mask:0xf
	s_nop 0
	v_add_f32_dpp v9, v9, v9 row_bcast:15 row_mask:0xa bank_mask:0xf
	v_add_f32_dpp v90, v90, v90 row_bcast:15 row_mask:0xa bank_mask:0xf
	s_nop 0
	v_add_f32_dpp v9, v9, v9 row_bcast:31 row_mask:0xc bank_mask:0xf
	v_add_f32_dpp v90, v90, v90 row_bcast:31 row_mask:0xc bank_mask:0xf
	s_nop 0
	v_readlane_b32 s2, v9, 63
	v_readlane_b32 s3, v90, 63
	s_nop 1
	v_mov_b32_e32 v9, s2
	v_mov_b32_e32 v90, s3
	v_mul_f32_e32 v93, 0x3a800000, v9
; DI unsigned pk2(float lo, float hi) { f32x2 v = {lo, hi}; bf16x2_t b = __builtin_convertvector(v, bf16x2_t); return __builtin_bit_cast(unsigned, b); }
; DI void ln_row_v(const Frame& F, f32x4 (&v)[4], float* xout, const float* g, const float* b, const float* sh, const float* sc, bf16_t* hout, const float* slab, const float* gres, float* stat = nullptr) {
;     ...
;     if (g) {
;         float s = 0.f, s2 = 0.f;
; #pragma unroll
;         for (int j = 0; j < 4; ++j) { s += (v[j][0] + v[j][1]) + (v[j][2] + v[j][3]); s2 += (v[j][0] * v[j][0] + v[j][1] * v[j][1]) + (v[j][2] * v[j][2] + v[j][3] * v[j][3]); }
;         wave_sum2(s, s2, F.lane);
;         const float mean = s * (1.f / D); const float rstd = 1.f / sqrtf(fmaxf(s2 * (1.f / D) - mean * mean, 0.f) + EPS);
;         if (stat && F.lane == 0) { f32x2 sv = {mean, rstd}; *(f32x2*)stat = sv; }
; #pragma unroll
;         for (int j = 0; j < 4; ++j) { const f32x4 gg = ((const f32x4*)g)[F.lane + 64 * j], bb = ((const f32x4*)b)[F.lane + 64 * j];
;             v[j] = (v[j] - mean) * rstd * gg + bb; if (xout) ((f32x4*)xout)[F.lane + 64 * j] = v[j]; }
;     }
;     if (hout) {
;         float s = 0.f, s2 = 0.f;
; #pragma unroll
;         for (int j = 0; j < 4; ++j) { s += (v[j][0] + v[j][1]) + (v[j][2] + v[j][3]); s2 += (v[j][0] * v[j][0] + v[j][1] * v[j][1]) + (v[j][2] * v[j][2] + v[j][3] * v[j][3]); }
;         wave_sum2(s, s2, F.lane);
;         const float mean = s * (1.f / D); const float rstd = 1.f / sqrtf(fmaxf(s2 * (1.f / D) - mean * mean, 0.f) + EPS);
; #pragma unroll
;         for (int j = 0; j < 4; ++j) { const f32x4 hh = ((const f32x4*)sh)[F.lane + 64 * j], cc = ((const f32x4*)sc)[F.lane + 64 * j];
;             const f32x4 o = (v[j] - mean) * rstd * (cc + 1.f) + hh; u32x2 wv; wv.x = pk2(o[0], o[1]); wv.y = pk2(o[2], o[3]);
;             ((u32x2*)hout)[F.lane + 64 * j] = wv; }
;     }
	v_mul_f32_e32 v91, 0x3a800000, v90
	v_fma_f32 v91, -v93, v93, v91
	v_max_f32_e32 v91, 0, v91
	v_add_f32_e32 v91, 0x358637bd, v91
	v_rsq_f32_e32 v94, v91
	v_mul_f32_e32 v91, 0.5, v91
	v_mul_f32_e32 v92, v94, v94
	v_fma_f32 v92, -v91, v92, 0.5
	v_fma_f32 v94, v94, v92, v94
	s_add_u32 s2, s12, 0x0
	s_addc_u32 s3, s13, 0
	v_mov_b32_e32 v188, v93
	v_mov_b32_e32 v189, v94
	s_mov_b64 exec, 1
	global_store_dwordx2 v97, v[188:189], s[2:3]
	s_mov_b64 exec, -1
	v_sub_f32_e32 v42, v42, v93
	v_sub_f32_e32 v43, v43, v93
	v_sub_f32_e32 v44, v44, v93
	v_sub_f32_e32 v45, v45, v93
	v_sub_f32_e32 v46, v46, v93
	v_sub_f32_e32 v47, v47, v93
	v_sub_f32_e32 v48, v48, v93
	v_sub_f32_e32 v49, v49, v93
	v_sub_f32_e32 v50, v50, v93
	v_sub_f32_e32 v51, v51, v93
	v_sub_f32_e32 v52, v52, v93
	v_sub_f32_e32 v53, v53, v93
	v_sub_f32_e32 v54, v54, v93
	v_sub_f32_e32 v55, v55, v93
	v_sub_f32_e32 v56, v56, v93
	v_sub_f32_e32 v57, v57, v93
	v_mul_f32_e32 v42, v94, v42
	v_mul_f32_e32 v43, v94, v43
	v_mul_f32_e32 v44, v94, v44
	v_mul_f32_e32 v45, v94, v45
	v_mul_f32_e32 v46, v94, v46
	v_mul_f32_e32 v47, v94, v47
	v_mul_f32_e32 v48, v94, v48
	v_mul_f32_e32 v49, v94, v49
	v_mul_f32_e32 v50, v94, v50
	v_mul_f32_e32 v51, v94, v51
	v_mul_f32_e32 v52, v94, v52
	v_mul_f32_e32 v53, v94, v53
	v_mul_f32_e32 v54, v94, v54
	v_mul_f32_e32 v55, v94, v55
	v_mul_f32_e32 v56, v94, v56
	v_mul_f32_e32 v57, v94, v57
	v_fma_f32 v42, v42, v10, v26
	v_fma_f32 v43, v43, v11, v27
	v_fma_f32 v44, v44, v12, v28
	v_fma_f32 v45, v45, v13, v29
	v_fma_f32 v46, v46, v14, v30
	v_fma_f32 v47, v47, v15, v31
	v_fma_f32 v48, v48, v16, v32
	v_fma_f32 v49, v49, v17, v33
	v_fma_f32 v50, v50, v18, v34
	v_fma_f32 v51, v51, v19, v35
	v_fma_f32 v52, v52, v20, v36
	v_fma_f32 v53, v53, v21, v37
	v_fma_f32 v54, v54, v22, v38
	v_fma_f32 v55, v55, v23, v39
	v_fma_f32 v56, v56, v24, v40
	v_fma_f32 v57, v57, v25, v41
	v_add_f32_e32 v9, v42, v43
	v_add_f32_e32 v91, v44, v45
	v_mul_f32_e32 v90, v42, v42
	v_mul_f32_e32 v92, v43, v43
	v_add_f32_e32 v9, v9, v46
	v_add_f32_e32 v91, v91, v47
	v_add_f32_e32 v9, v9, v48
	v_add_f32_e32 v91, v91, v49
	v_add_f32_e32 v9, v9, v50
	v_add_f32_e32 v91, v91, v51
	v_add_f32_e32 v9, v9, v52
	v_add_f32_e32 v91, v91, v53
	v_add_f32_e32 v9, v9, v54
	v_add_f32_e32 v91, v91, v55
	v_add_f32_e32 v9, v9, v56
	v_add_f32_e32 v91, v91, v57
	v_fmac_f32_e32 v90, v44, v44
	v_fmac_f32_e32 v92, v45, v45
	v_fmac_f32_e32 v90, v46, v46
	v_fmac_f32_e32 v92, v47, v47
	v_fmac_f32_e32 v90, v48, v48
	v_fmac_f32_e32 v92, v49, v49
	v_fmac_f32_e32 v90, v50, v50
	v_fmac_f32_e32 v92, v51, v51
	v_fmac_f32_e32 v90, v52, v52
	v_fmac_f32_e32 v92, v53, v53
	v_fmac_f32_e32 v90, v54, v54
	v_fmac_f32_e32 v92, v55, v55
	v_fmac_f32_e32 v90, v56, v56
	v_fmac_f32_e32 v92, v57, v57
	v_add_f32_e32 v9, v9, v91
	v_add_f32_e32 v90, v90, v92
	s_nop 1
	v_add_f32_dpp v9, v9, v9 quad_perm:[1,0,3,2] row_mask:0xf bank_mask:0xf
	v_add_f32_dpp v90, v90, v90 quad_perm:[1,0,3,2] row_mask:0xf bank_mask:0xf
	s_nop 0
	v_add_f32_dpp v9, v9, v9 quad_perm:[2,3,0,1] row_mask:0xf bank_mask:0xf
	v_add_f32_dpp v90, v90, v90 quad_perm:[2,3,0,1] row_mask:0xf bank_mask:0xf
	s_nop 0
	v_add_f32_dpp v9, v9, v9 row_half_mirror row_mask:0xf bank_mask:0xf
	v_add_f32_dpp v90, v90, v90 row_half_mirror row_mask:0xf bank_mask:0xf
	s_nop 0
	v_add_f32_dpp v9, v9, v9 row_mirror row_mask:0xf bank_mask:0xf
	v_add_f32_dpp v90, v90, v90 row_mirror row_mask:0xf bank_mask:0xf
	s_nop 0
	v_add_f32_dpp v9, v9, v9 row_bcast:15 row_mask:0xa bank_mask:0xf
	v_add_f32_dpp v90, v90, v90 row_bcast:15 row_mask:0xa bank_mask:0xf
	s_nop 0
	v_add_f32_dpp v9, v9, v9 row_bcast:31 row_mask:0xc bank_mask:0xf
	v_add_f32_dpp v90, v90, v90 row_bcast:31 row_mask:0xc bank_mask:0xf
	s_nop 0
	v_readlane_b32 s2, v9, 63
	v_readlane_b32 s3, v90, 63
	s_nop 1
	v_mov_b32_e32 v9, s2
	v_mov_b32_e32 v90, s3
	v_mul_f32_e32 v93, 0x3a800000, v9
	v_mul_f32_e32 v91, 0x3a800000, v90
	v_fma_f32 v91, -v93, v93, v91
	v_max_f32_e32 v91, 0, v91
	v_add_f32_e32 v91, 0x358637bd, v91
	v_rsq_f32_e32 v94, v91
	v_mul_f32_e32 v91, 0.5, v91
	v_mul_f32_e32 v92, v94, v94
	v_fma_f32 v92, -v91, v92, 0.5
	v_fma_f32 v94, v94, v92, v94
	s_waitcnt vmcnt(13)
	v_sub_f32_e32 v42, v42, v93
	v_sub_f32_e32 v43, v43, v93
	v_sub_f32_e32 v44, v44, v93
	v_sub_f32_e32 v45, v45, v93
	v_sub_f32_e32 v46, v46, v93
	v_sub_f32_e32 v47, v47, v93
	v_sub_f32_e32 v48, v48, v93
	v_sub_f32_e32 v49, v49, v93
	v_sub_f32_e32 v50, v50, v93
	v_sub_f32_e32 v51, v51, v93
	v_sub_f32_e32 v52, v52, v93
	v_sub_f32_e32 v53, v53, v93
	v_sub_f32_e32 v54, v54, v93
	v_sub_f32_e32 v55, v55, v93
	v_sub_f32_e32 v56, v56, v93
	v_sub_f32_e32 v57, v57, v93
	v_add_f32_e32 v130, 1.0, v130
	v_add_f32_e32 v131, 1.0, v131
	v_add_f32_e32 v132, 1.0, v132
	v_add_f32_e32 v133, 1.0, v133
	v_add_f32_e32 v134, 1.0, v134
	v_add_f32_e32 v135, 1.0, v135
	v_add_f32_e32 v136, 1.0, v136
	v_add_f32_e32 v137, 1.0, v137
	v_add_f32_e32 v138, 1.0, v138
	v_add_f32_e32 v139, 1.0, v139
	v_add_f32_e32 v140, 1.0, v140
	v_add_f32_e32 v141, 1.0, v141
	v_add_f32_e32 v142, 1.0, v142
	v_add_f32_e32 v143, 1.0, v143
	v_add_f32_e32 v144, 1.0, v144
	v_add_f32_e32 v145, 1.0, v145
	v_mul_f32_e32 v42, v94, v42
	v_mul_f32_e32 v43, v94, v43
	v_mul_f32_e32 v44, v94, v44
	v_mul_f32_e32 v45, v94, v45
	v_mul_f32_e32 v46, v94, v46
	v_mul_f32_e32 v47, v94, v47
	v_mul_f32_e32 v48, v94, v48
	v_mul_f32_e32 v49, v94, v49
	v_mul_f32_e32 v50, v94, v50
	v_mul_f32_e32 v51, v94, v51
	v_mul_f32_e32 v52, v94, v52
	v_mul_f32_e32 v53, v94, v53
	v_mul_f32_e32 v54, v94, v54
	v_mul_f32_e32 v55, v94, v55
	v_mul_f32_e32 v56, v94, v56
	v_mul_f32_e32 v57, v94, v57
	v_fma_f32 v42, v42, v130, v114
	v_fma_f32 v43, v43, v131, v115
	v_fma_f32 v44, v44, v132, v116
	v_fma_f32 v45, v45, v133, v117
	v_fma_f32 v46, v46, v134, v118
	v_fma_f32 v47, v47, v135, v119
	v_fma_f32 v48, v48, v136, v120
	v_fma_f32 v49, v49, v137, v121
	v_fma_f32 v50, v50, v138, v122
	v_fma_f32 v51, v51, v139, v123
	v_fma_f32 v52, v52, v140, v124
	v_fma_f32 v53, v53, v141, v125
	v_fma_f32 v54, v54, v142, v126
	v_fma_f32 v55, v55, v143, v127
	v_fma_f32 v56, v56, v144, v128
	v_fma_f32 v57, v57, v145, v129
	v_cvt_pk_bf16_f32 v190, v42, v43
	v_cvt_pk_bf16_f32 v191, v44, v45
	v_cvt_pk_bf16_f32 v192, v46, v47
	v_cvt_pk_bf16_f32 v193, v48, v49
	v_cvt_pk_bf16_f32 v194, v50, v51
	v_cvt_pk_bf16_f32 v195, v52, v53
	v_cvt_pk_bf16_f32 v196, v54, v55
	v_cvt_pk_bf16_f32 v197, v56, v57
	s_add_u32 s2, s10, 0x0
	s_addc_u32 s3, s11, 0
	global_store_dwordx2 v1, v[190:191], s[2:3]
	global_store_dwordx2 v1, v[192:193], s[2:3] offset:512
	global_store_dwordx2 v1, v[194:195], s[2:3] offset:1024
	global_store_dwordx2 v1, v[196:197], s[2:3] offset:1536
	s_add_u32 s2, s8, 0x4000
	s_addc_u32 s3, s9, 0
	global_load_dwordx4 v[42:45], v0, s[2:3]
	global_load_dwordx4 v[46:49], v0, s[2:3] offset:1024
	global_load_dwordx4 v[50:53], v0, s[2:3] offset:2048
	global_load_dwordx4 v[54:57], v0, s[2:3] offset:3072
	s_waitcnt vmcnt(17)
; DI void ln_row_v(const Frame& F, f32x4 (&v)[4], float* xout, const float* g, const float* b, const float* sh, const float* sc, bf16_t* hout, const float* slab, const float* gres, float* stat = nullptr) {
;     ...
;     if (g) {
;         float s = 0.f, s2 = 0.f;
; #pragma unroll
;         for (int j = 0; j < 4; ++j) { s += (v[j][0] + v[j][1]) + (v[j][2] + v[j][3]); s2 += (v[j][0] * v[j][0] + v[j][1] * v[j][1]) + (v[j][2] * v[j][2] + v[j][3] * v[j][3]); }
;         wave_sum2(s, s2, F.lane);
;         const float mean = s * (1.f / D); const float rstd = 1.f / sqrtf(fmaxf(s2 * (1.f / D) - mean * mean, 0.f) + EPS);
;         if (stat && F.lane == 0) { f32x2 sv = {mean, rstd}; *(f32x2*)stat = sv; }
; #pragma unroll
;         for (int j = 0; j < 4; ++j) { const f32x4 gg = ((const f32x4*)g)[F.lane + 64 * j], bb = ((const f32x4*)b)[F.lane + 64 * j];
;             v[j] = (v[j] - mean) * rstd * gg + bb; if (xout) ((f32x4*)xout)[F.lane + 64 * j] = v[j]; }
;     }
;     if (hout) {
;         float s = 0.f, s2 = 0.f;
; #pragma unroll
;         for (int j = 0; j < 4; ++j) { s += (v[j][0] + v[j][1]) + (v[j][2] + v[j][3]); s2 += (v[j][0] * v[j][0] + v[j][1] * v[j][1]) + (v[j][2] * v[j][2] + v[j][3] * v[j][3]); }
;         wave_sum2(s, s2, F.lane);
;         const float mean = s * (1.f / D); const float rstd = 1.f / sqrtf(fmaxf(s2 * (1.f / D) - mean * mean, 0.f) + EPS);
	v_add_f32_e32 v9, v58, v59
	v_add_f32_e32 v91, v60, v61
	v_mul_f32_e32 v90, v58, v58
	v_mul_f32_e32 v92, v59, v59
	v_add_f32_e32 v9, v9, v62
	v_add_f32_e32 v91, v91, v63
	v_add_f32_e32 v9, v9, v64
	v_add_f32_e32 v91, v91, v65
	v_add_f32_e32 v9, v9, v66
	v_add_f32_e32 v91, v91, v67
	v_add_f32_e32 v9, v9, v68
	v_add_f32_e32 v91, v91, v69
	v_add_f32_e32 v9, v9, v70
	v_add_f32_e32 v91, v91, v71
	v_add_f32_e32 v9, v9, v72
	v_add_f32_e32 v91, v91, v73
	v_fmac_f32_e32 v90, v60, v60
	v_fmac_f32_e32 v92, v61, v61
	v_fmac_f32_e32 v90, v62, v62
	v_fmac_f32_e32 v92, v63, v63
	v_fmac_f32_e32 v90, v64, v64
	v_fmac_f32_e32 v92, v65, v65
	v_fmac_f32_e32 v90, v66, v66
	v_fmac_f32_e32 v92, v67, v67
	v_fmac_f32_e32 v90, v68, v68
	v_fmac_f32_e32 v92, v69, v69
	v_fmac_f32_e32 v90, v70, v70
	v_fmac_f32_e32 v92, v71, v71
	v_fmac_f32_e32 v90, v72, v72
	v_fmac_f32_e32 v92, v73, v73
	v_add_f32_e32 v9, v9, v91
	v_add_f32_e32 v90, v90, v92
	s_nop 1
	v_add_f32_dpp v9, v9, v9 quad_perm:[1,0,3,2] row_mask:0xf bank_mask:0xf
	v_add_f32_dpp v90, v90, v90 quad_perm:[1,0,3,2] row_mask:0xf bank_mask:0xf
	s_nop 0
	v_add_f32_dpp v9, v9, v9 quad_perm:[2,3,0,1] row_mask:0xf bank_mask:0xf
	v_add_f32_dpp v90, v90, v90 quad_perm:[2,3,0,1] row_mask:0xf bank_mask:0xf
	s_nop 0
	v_add_f32_dpp v9, v9, v9 row_half_mirror row_mask:0xf bank_mask:0xf
	v_add_f32_dpp v90, v90, v90 row_half_mirror row_mask:0xf bank_mask:0xf
	s_nop 0
	v_add_f32_dpp v9, v9, v9 row_mirror row_mask:0xf bank_mask:0xf
	v_add_f32_dpp v90, v90, v90 row_mirror row_mask:0xf bank_mask:0xf
	s_nop 0
	v_add_f32_dpp v9, v9, v9 row_bcast:15 row_mask:0xa bank_mask:0xf
	v_add_f32_dpp v90, v90, v90 row_bcast:15 row_mask:0xa bank_mask:0xf
	s_nop 0
	v_add_f32_dpp v9, v9, v9 row_bcast:31 row_mask:0xc bank_mask:0xf
	v_add_f32_dpp v90, v90, v90 row_bcast:31 row_mask:0xc bank_mask:0xf
	s_nop 0
	v_readlane_b32 s2, v9, 63
	v_readlane_b32 s3, v90, 63
	s_nop 1
	v_mov_b32_e32 v9, s2
	v_mov_b32_e32 v90, s3
	v_mul_f32_e32 v93, 0x3a800000, v9
	v_mul_f32_e32 v91, 0x3a800000, v90
	v_fma_f32 v91, -v93, v93, v91
	v_max_f32_e32 v91, 0, v91
	v_add_f32_e32 v91, 0x358637bd, v91
	v_rsq_f32_e32 v94, v91
	v_mul_f32_e32 v91, 0.5, v91
	v_mul_f32_e32 v92, v94, v94
	v_fma_f32 v92, -v91, v92, 0.5
	v_fma_f32 v94, v94, v92, v94
	s_add_u32 s2, s12, 0x8
	s_addc_u32 s3, s13, 0
	v_mov_b32_e32 v188, v93
	v_mov_b32_e32 v189, v94
	s_mov_b64 exec, 1
	global_store_dwordx2 v97, v[188:189], s[2:3]
	s_mov_b64 exec, -1
	v_sub_f32_e32 v58, v58, v93
	v_sub_f32_e32 v59, v59, v93
	v_sub_f32_e32 v60, v60, v93
	v_sub_f32_e32 v61, v61, v93
	v_sub_f32_e32 v62, v62, v93
	v_sub_f32_e32 v63, v63, v93
	v_sub_f32_e32 v64, v64, v93
	v_sub_f32_e32 v65, v65, v93
	v_sub_f32_e32 v66, v66, v93
	v_sub_f32_e32 v67, v67, v93
	v_sub_f32_e32 v68, v68, v93
	v_sub_f32_e32 v69, v69, v93
	v_sub_f32_e32 v70, v70, v93
	v_sub_f32_e32 v71, v71, v93
	v_sub_f32_e32 v72, v72, v93
	v_sub_f32_e32 v73, v73, v93
	v_mul_f32_e32 v58, v94, v58
	v_mul_f32_e32 v59, v94, v59
	v_mul_f32_e32 v60, v94, v60
	v_mul_f32_e32 v61, v94, v61
	v_mul_f32_e32 v62, v94, v62
	v_mul_f32_e32 v63, v94, v63
	v_mul_f32_e32 v64, v94, v64
	v_mul_f32_e32 v65, v94, v65
	v_mul_f32_e32 v66, v94, v66
	v_mul_f32_e32 v67, v94, v67
	v_mul_f32_e32 v68, v94, v68
	v_mul_f32_e32 v69, v94, v69
	v_mul_f32_e32 v70, v94, v70
	v_mul_f32_e32 v71, v94, v71
	v_mul_f32_e32 v72, v94, v72
	v_mul_f32_e32 v73, v94, v73
	v_fma_f32 v58, v58, v10, v26
	v_fma_f32 v59, v59, v11, v27
	v_fma_f32 v60, v60, v12, v28
	v_fma_f32 v61, v61, v13, v29
	v_fma_f32 v62, v62, v14, v30
	v_fma_f32 v63, v63, v15, v31
	v_fma_f32 v64, v64, v16, v32
	v_fma_f32 v65, v65, v17, v33
	v_fma_f32 v66, v66, v18, v34
	v_fma_f32 v67, v67, v19, v35
	v_fma_f32 v68, v68, v20, v36
	v_fma_f32 v69, v69, v21, v37
	v_fma_f32 v70, v70, v22, v38
	v_fma_f32 v71, v71, v23, v39
	v_fma_f32 v72, v72, v24, v40
	v_fma_f32 v73, v73, v25, v41
	v_add_f32_e32 v9, v58, v59
	v_add_f32_e32 v91, v60, v61
	v_mul_f32_e32 v90, v58, v58
	v_mul_f32_e32 v92, v59, v59
	v_add_f32_e32 v9, v9, v62
	v_add_f32_e32 v91, v91, v63
	v_add_f32_e32 v9, v9, v64
	v_add_f32_e32 v91, v91, v65
	v_add_f32_e32 v9, v9, v66
	v_add_f32_e32 v91, v91, v67
	v_add_f32_e32 v9, v9, v68
	v_add_f32_e32 v91, v91, v69
	v_add_f32_e32 v9, v9, v70
	v_add_f32_e32 v91, v91, v71
	v_add_f32_e32 v9, v9, v72
	v_add_f32_e32 v91, v91, v73
	v_fmac_f32_e32 v90, v60, v60
	v_fmac_f32_e32 v92, v61, v61
	v_fmac_f32_e32 v90, v62, v62
	v_fmac_f32_e32 v92, v63, v63
	v_fmac_f32_e32 v90, v64, v64
	v_fmac_f32_e32 v92, v65, v65
	v_fmac_f32_e32 v90, v66, v66
	v_fmac_f32_e32 v92, v67, v67
	v_fmac_f32_e32 v90, v68, v68
	v_fmac_f32_e32 v92, v69, v69
	v_fmac_f32_e32 v90, v70, v70
	v_fmac_f32_e32 v92, v71, v71
	v_fmac_f32_e32 v90, v72, v72
	v_fmac_f32_e32 v92, v73, v73
	v_add_f32_e32 v9, v9, v91
	v_add_f32_e32 v90, v90, v92
	s_nop 1
	v_add_f32_dpp v9, v9, v9 quad_perm:[1,0,3,2] row_mask:0xf bank_mask:0xf
	v_add_f32_dpp v90, v90, v90 quad_perm:[1,0,3,2] row_mask:0xf bank_mask:0xf
	s_nop 0
	v_add_f32_dpp v9, v9, v9 quad_perm:[2,3,0,1] row_mask:0xf bank_mask:0xf
	v_add_f32_dpp v90, v90, v90 quad_perm:[2,3,0,1] row_mask:0xf bank_mask:0xf
	s_nop 0
	v_add_f32_dpp v9, v9, v9 row_half_mirror row_mask:0xf bank_mask:0xf
	v_add_f32_dpp v90, v90, v90 row_half_mirror row_mask:0xf bank_mask:0xf
	s_nop 0
	v_add_f32_dpp v9, v9, v9 row_mirror row_mask:0xf bank_mask:0xf
	v_add_f32_dpp v90, v90, v90 row_mirror row_mask:0xf bank_mask:0xf
	s_nop 0
	v_add_f32_dpp v9, v9, v9 row_bcast:15 row_mask:0xa bank_mask:0xf
	v_add_f32_dpp v90, v90, v90 row_bcast:15 row_mask:0xa bank_mask:0xf
	s_nop 0
	v_add_f32_dpp v9, v9, v9 row_bcast:31 row_mask:0xc bank_mask:0xf
	v_add_f32_dpp v90, v90, v90 row_bcast:31 row_mask:0xc bank_mask:0xf
; DI unsigned pk2(float lo, float hi) { f32x2 v = {lo, hi}; bf16x2_t b = __builtin_convertvector(v, bf16x2_t); return __builtin_bit_cast(unsigned, b); }
; DI void ln_row_v(const Frame& F, f32x4 (&v)[4], float* xout, const float* g, const float* b, const float* sh, const float* sc, bf16_t* hout, const float* slab, const float* gres, float* stat = nullptr) {
;     ...
;     if (g) {
;         float s = 0.f, s2 = 0.f;
; #pragma unroll
;         for (int j = 0; j < 4; ++j) { s += (v[j][0] + v[j][1]) + (v[j][2] + v[j][3]); s2 += (v[j][0] * v[j][0] + v[j][1] * v[j][1]) + (v[j][2] * v[j][2] + v[j][3] * v[j][3]); }
;         wave_sum2(s, s2, F.lane);
;         const float mean = s * (1.f / D); const float rstd = 1.f / sqrtf(fmaxf(s2 * (1.f / D) - mean * mean, 0.f) + EPS);
;     ...
;         wave_sum2(s, s2, F.lane);
;         const float mean = s * (1.f / D); const float rstd = 1.f / sqrtf(fmaxf(s2 * (1.f / D) - mean * mean, 0.f) + EPS);
; #pragma unroll
;         for (int j = 0; j < 4; ++j) { const f32x4 hh = ((const f32x4*)sh)[F.lane + 64 * j], cc = ((const f32x4*)sc)[F.lane + 64 * j];
;             const f32x4 o = (v[j] - mean) * rstd * (cc + 1.f) + hh; u32x2 wv; wv.x = pk2(o[0], o[1]); wv.y = pk2(o[2], o[3]);
;             ((u32x2*)hout)[F.lane + 64 * j] = wv; }
;     }
	s_nop 0
	v_readlane_b32 s2, v9, 63
	v_readlane_b32 s3, v90, 63
	s_nop 1
	v_mov_b32_e32 v9, s2
	v_mov_b32_e32 v90, s3
	v_mul_f32_e32 v93, 0x3a800000, v9
	v_mul_f32_e32 v91, 0x3a800000, v90
	v_fma_f32 v91, -v93, v93, v91
	v_max_f32_e32 v91, 0, v91
	v_add_f32_e32 v91, 0x358637bd, v91
	v_rsq_f32_e32 v94, v91
	v_mul_f32_e32 v91, 0.5, v91
	v_mul_f32_e32 v92, v94, v94
	v_fma_f32 v92, -v91, v92, 0.5
	v_fma_f32 v94, v94, v92, v94
	v_sub_f32_e32 v58, v58, v93
	v_sub_f32_e32 v59, v59, v93
	v_sub_f32_e32 v60, v60, v93
	v_sub_f32_e32 v61, v61, v93
	v_sub_f32_e32 v62, v62, v93
	v_sub_f32_e32 v63, v63, v93
	v_sub_f32_e32 v64, v64, v93
	v_sub_f32_e32 v65, v65, v93
	v_sub_f32_e32 v66, v66, v93
	v_sub_f32_e32 v67, v67, v93
	v_sub_f32_e32 v68, v68, v93
	v_sub_f32_e32 v69, v69, v93
	v_sub_f32_e32 v70, v70, v93
	v_sub_f32_e32 v71, v71, v93
	v_sub_f32_e32 v72, v72, v93
	v_sub_f32_e32 v73, v73, v93
	v_mul_f32_e32 v58, v94, v58
	v_mul_f32_e32 v59, v94, v59
	v_mul_f32_e32 v60, v94, v60
	v_mul_f32_e32 v61, v94, v61
	v_mul_f32_e32 v62, v94, v62
	v_mul_f32_e32 v63, v94, v63
	v_mul_f32_e32 v64, v94, v64
	v_mul_f32_e32 v65, v94, v65
	v_mul_f32_e32 v66, v94, v66
	v_mul_f32_e32 v67, v94, v67
	v_mul_f32_e32 v68, v94, v68
	v_mul_f32_e32 v69, v94, v69
	v_mul_f32_e32 v70, v94, v70
	v_mul_f32_e32 v71, v94, v71
	v_mul_f32_e32 v72, v94, v72
	v_mul_f32_e32 v73, v94, v73
	v_fma_f32 v58, v58, v130, v114
	v_fma_f32 v59, v59, v131, v115
	v_fma_f32 v60, v60, v132, v116
	v_fma_f32 v61, v61, v133, v117
	v_fma_f32 v62, v62, v134, v118
	v_fma_f32 v63, v63, v135, v119
	v_fma_f32 v64, v64, v136, v120
	v_fma_f32 v65, v65, v137, v121
	v_fma_f32 v66, v66, v138, v122
	v_fma_f32 v67, v67, v139, v123
	v_fma_f32 v68, v68, v140, v124
	v_fma_f32 v69, v69, v141, v125
	v_fma_f32 v70, v70, v142, v126
	v_fma_f32 v71, v71, v143, v127
	v_fma_f32 v72, v72, v144, v128
	v_fma_f32 v73, v73, v145, v129
	v_cvt_pk_bf16_f32 v190, v58, v59
	v_cvt_pk_bf16_f32 v191, v60, v61
	v_cvt_pk_bf16_f32 v192, v62, v63
	v_cvt_pk_bf16_f32 v193, v64, v65
	v_cvt_pk_bf16_f32 v194, v66, v67
	v_cvt_pk_bf16_f32 v195, v68, v69
	v_cvt_pk_bf16_f32 v196, v70, v71
	v_cvt_pk_bf16_f32 v197, v72, v73
	s_add_u32 s2, s10, 0x800
	s_addc_u32 s3, s11, 0
	global_store_dwordx2 v1, v[190:191], s[2:3]
	global_store_dwordx2 v1, v[192:193], s[2:3] offset:512
	global_store_dwordx2 v1, v[194:195], s[2:3] offset:1024
	global_store_dwordx2 v1, v[196:197], s[2:3] offset:1536
	s_add_u32 s2, s8, 0x5000
	s_addc_u32 s3, s9, 0
	global_load_dwordx4 v[58:61], v0, s[2:3]
	global_load_dwordx4 v[62:65], v0, s[2:3] offset:1024
	global_load_dwordx4 v[66:69], v0, s[2:3] offset:2048
	global_load_dwordx4 v[70:73], v0, s[2:3] offset:3072
	s_waitcnt vmcnt(22)
	v_add_f32_e32 v9, v74, v75
	v_add_f32_e32 v91, v76, v77
	v_mul_f32_e32 v90, v74, v74
	v_mul_f32_e32 v92, v75, v75
	v_add_f32_e32 v9, v9, v78
	v_add_f32_e32 v91, v91, v79
	v_add_f32_e32 v9, v9, v80
	v_add_f32_e32 v91, v91, v81
	v_add_f32_e32 v9, v9, v82
	v_add_f32_e32 v91, v91, v83
	v_add_f32_e32 v9, v9, v84
	v_add_f32_e32 v91, v91, v85
	v_add_f32_e32 v9, v9, v86
	v_add_f32_e32 v91, v91, v87
	v_add_f32_e32 v9, v9, v88
	v_add_f32_e32 v91, v91, v89
	v_fmac_f32_e32 v90, v76, v76
	v_fmac_f32_e32 v92, v77, v77
	v_fmac_f32_e32 v90, v78, v78
	v_fmac_f32_e32 v92, v79, v79
	v_fmac_f32_e32 v90, v80, v80
	v_fmac_f32_e32 v92, v81, v81
	v_fmac_f32_e32 v90, v82, v82
	v_fmac_f32_e32 v92, v83, v83
	v_fmac_f32_e32 v90, v84, v84
	v_fmac_f32_e32 v92, v85, v85
	v_fmac_f32_e32 v90, v86, v86
	v_fmac_f32_e32 v92, v87, v87
	v_fmac_f32_e32 v90, v88, v88
	v_fmac_f32_e32 v92, v89, v89
	v_add_f32_e32 v9, v9, v91
	v_add_f32_e32 v90, v90, v92
	s_nop 1
	v_add_f32_dpp v9, v9, v9 quad_perm:[1,0,3,2] row_mask:0xf bank_mask:0xf
	v_add_f32_dpp v90, v90, v90 quad_perm:[1,0,3,2] row_mask:0xf bank_mask:0xf
	s_nop 0
	v_add_f32_dpp v9, v9, v9 quad_perm:[2,3,0,1] row_mask:0xf bank_mask:0xf
	v_add_f32_dpp v90, v90, v90 quad_perm:[2,3,0,1] row_mask:0xf bank_mask:0xf
	s_nop 0
	v_add_f32_dpp v9, v9, v9 row_half_mirror row_mask:0xf bank_mask:0xf
	v_add_f32_dpp v90, v90, v90 row_half_mirror row_mask:0xf bank_mask:0xf
	s_nop 0
	v_add_f32_dpp v9, v9, v9 row_mirror row_mask:0xf bank_mask:0xf
	v_add_f32_dpp v90, v90, v90 row_mirror row_mask:0xf bank_mask:0xf
	s_nop 0
	v_add_f32_dpp v9, v9, v9 row_bcast:15 row_mask:0xa bank_mask:0xf
	v_add_f32_dpp v90, v90, v90 row_bcast:15 row_mask:0xa bank_mask:0xf
	s_nop 0
	v_add_f32_dpp v9, v9, v9 row_bcast:31 row_mask:0xc bank_mask:0xf
	v_add_f32_dpp v90, v90, v90 row_bcast:31 row_mask:0xc bank_mask:0xf
	s_nop 0
	v_readlane_b32 s2, v9, 63
	v_readlane_b32 s3, v90, 63
	s_nop 1
	v_mov_b32_e32 v9, s2
	v_mov_b32_e32 v90, s3
	v_mul_f32_e32 v93, 0x3a800000, v9
	v_mul_f32_e32 v91, 0x3a800000, v90
	v_fma_f32 v91, -v93, v93, v91
	v_max_f32_e32 v91, 0, v91
	v_add_f32_e32 v91, 0x358637bd, v91
	v_rsq_f32_e32 v94, v91
	v_mul_f32_e32 v91, 0.5, v91
	v_mul_f32_e32 v92, v94, v94
	v_fma_f32 v92, -v91, v92, 0.5
	v_fma_f32 v94, v94, v92, v94
	s_add_u32 s2, s12, 0x10
	s_addc_u32 s3, s13, 0
	v_mov_b32_e32 v188, v93
	v_mov_b32_e32 v189, v94
	s_mov_b64 exec, 1
	global_store_dwordx2 v97, v[188:189], s[2:3]
	s_mov_b64 exec, -1
	v_sub_f32_e32 v74, v74, v93
	v_sub_f32_e32 v75, v75, v93
	v_sub_f32_e32 v76, v76, v93
	v_sub_f32_e32 v77, v77, v93
	v_sub_f32_e32 v78, v78, v93
	v_sub_f32_e32 v79, v79, v93
	v_sub_f32_e32 v80, v80, v93
	v_sub_f32_e32 v81, v81, v93
	v_sub_f32_e32 v82, v82, v93
	v_sub_f32_e32 v83, v83, v93
	v_sub_f32_e32 v84, v84, v93
	v_sub_f32_e32 v85, v85, v93
	v_sub_f32_e32 v86, v86, v93
	v_sub_f32_e32 v87, v87, v93
	v_sub_f32_e32 v88, v88, v93
	v_sub_f32_e32 v89, v89, v93
	v_mul_f32_e32 v74, v94, v74
	v_mul_f32_e32 v75, v94, v75
; DI unsigned pk2(float lo, float hi) { f32x2 v = {lo, hi}; bf16x2_t b = __builtin_convertvector(v, bf16x2_t); return __builtin_bit_cast(unsigned, b); }
; DI void ln_row_v(const Frame& F, f32x4 (&v)[4], float* xout, const float* g, const float* b, const float* sh, const float* sc, bf16_t* hout, const float* slab, const float* gres, float* stat = nullptr) {
;     ...
;         for (int j = 0; j < 4; ++j) { const f32x4 gg = ((const f32x4*)g)[F.lane + 64 * j], bb = ((const f32x4*)b)[F.lane + 64 * j];
;             v[j] = (v[j] - mean) * rstd * gg + bb; if (xout) ((f32x4*)xout)[F.lane + 64 * j] = v[j]; }
;     }
;     if (hout) {
;         float s = 0.f, s2 = 0.f;
; #pragma unroll
;         for (int j = 0; j < 4; ++j) { s += (v[j][0] + v[j][1]) + (v[j][2] + v[j][3]); s2 += (v[j][0] * v[j][0] + v[j][1] * v[j][1]) + (v[j][2] * v[j][2] + v[j][3] * v[j][3]); }
;         wave_sum2(s, s2, F.lane);
;         const float mean = s * (1.f / D); const float rstd = 1.f / sqrtf(fmaxf(s2 * (1.f / D) - mean * mean, 0.f) + EPS);
; #pragma unroll
;         for (int j = 0; j < 4; ++j) { const f32x4 hh = ((const f32x4*)sh)[F.lane + 64 * j], cc = ((const f32x4*)sc)[F.lane + 64 * j];
;             const f32x4 o = (v[j] - mean) * rstd * (cc + 1.f) + hh; u32x2 wv; wv.x = pk2(o[0], o[1]); wv.y = pk2(o[2], o[3]);
;             ((u32x2*)hout)[F.lane + 64 * j] = wv; }
;     }
	v_mul_f32_e32 v76, v94, v76
	v_mul_f32_e32 v77, v94, v77
	v_mul_f32_e32 v78, v94, v78
	v_mul_f32_e32 v79, v94, v79
	v_mul_f32_e32 v80, v94, v80
	v_mul_f32_e32 v81, v94, v81
	v_mul_f32_e32 v82, v94, v82
	v_mul_f32_e32 v83, v94, v83
	v_mul_f32_e32 v84, v94, v84
	v_mul_f32_e32 v85, v94, v85
	v_mul_f32_e32 v86, v94, v86
	v_mul_f32_e32 v87, v94, v87
	v_mul_f32_e32 v88, v94, v88
	v_mul_f32_e32 v89, v94, v89
	v_fma_f32 v74, v74, v10, v26
	v_fma_f32 v75, v75, v11, v27
	v_fma_f32 v76, v76, v12, v28
	v_fma_f32 v77, v77, v13, v29
	v_fma_f32 v78, v78, v14, v30
	v_fma_f32 v79, v79, v15, v31
	v_fma_f32 v80, v80, v16, v32
	v_fma_f32 v81, v81, v17, v33
	v_fma_f32 v82, v82, v18, v34
	v_fma_f32 v83, v83, v19, v35
	v_fma_f32 v84, v84, v20, v36
	v_fma_f32 v85, v85, v21, v37
	v_fma_f32 v86, v86, v22, v38
	v_fma_f32 v87, v87, v23, v39
	v_fma_f32 v88, v88, v24, v40
	v_fma_f32 v89, v89, v25, v41
	v_add_f32_e32 v9, v74, v75
	v_add_f32_e32 v91, v76, v77
	v_mul_f32_e32 v90, v74, v74
	v_mul_f32_e32 v92, v75, v75
	v_add_f32_e32 v9, v9, v78
	v_add_f32_e32 v91, v91, v79
	v_add_f32_e32 v9, v9, v80
	v_add_f32_e32 v91, v91, v81
	v_add_f32_e32 v9, v9, v82
	v_add_f32_e32 v91, v91, v83
	v_add_f32_e32 v9, v9, v84
	v_add_f32_e32 v91, v91, v85
	v_add_f32_e32 v9, v9, v86
	v_add_f32_e32 v91, v91, v87
	v_add_f32_e32 v9, v9, v88
	v_add_f32_e32 v91, v91, v89
	v_fmac_f32_e32 v90, v76, v76
	v_fmac_f32_e32 v92, v77, v77
	v_fmac_f32_e32 v90, v78, v78
	v_fmac_f32_e32 v92, v79, v79
	v_fmac_f32_e32 v90, v80, v80
	v_fmac_f32_e32 v92, v81, v81
	v_fmac_f32_e32 v90, v82, v82
	v_fmac_f32_e32 v92, v83, v83
	v_fmac_f32_e32 v90, v84, v84
	v_fmac_f32_e32 v92, v85, v85
	v_fmac_f32_e32 v90, v86, v86
	v_fmac_f32_e32 v92, v87, v87
	v_fmac_f32_e32 v90, v88, v88
	v_fmac_f32_e32 v92, v89, v89
	v_add_f32_e32 v9, v9, v91
	v_add_f32_e32 v90, v90, v92
	s_nop 1
	v_add_f32_dpp v9, v9, v9 quad_perm:[1,0,3,2] row_mask:0xf bank_mask:0xf
	v_add_f32_dpp v90, v90, v90 quad_perm:[1,0,3,2] row_mask:0xf bank_mask:0xf
	s_nop 0
	v_add_f32_dpp v9, v9, v9 quad_perm:[2,3,0,1] row_mask:0xf bank_mask:0xf
	v_add_f32_dpp v90, v90, v90 quad_perm:[2,3,0,1] row_mask:0xf bank_mask:0xf
	s_nop 0
	v_add_f32_dpp v9, v9, v9 row_half_mirror row_mask:0xf bank_mask:0xf
	v_add_f32_dpp v90, v90, v90 row_half_mirror row_mask:0xf bank_mask:0xf
	s_nop 0
	v_add_f32_dpp v9, v9, v9 row_mirror row_mask:0xf bank_mask:0xf
	v_add_f32_dpp v90, v90, v90 row_mirror row_mask:0xf bank_mask:0xf
	s_nop 0
	v_add_f32_dpp v9, v9, v9 row_bcast:15 row_mask:0xa bank_mask:0xf
	v_add_f32_dpp v90, v90, v90 row_bcast:15 row_mask:0xa bank_mask:0xf
	s_nop 0
	v_add_f32_dpp v9, v9, v9 row_bcast:31 row_mask:0xc bank_mask:0xf
	v_add_f32_dpp v90, v90, v90 row_bcast:31 row_mask:0xc bank_mask:0xf
	s_nop 0
	v_readlane_b32 s2, v9, 63
	v_readlane_b32 s3, v90, 63
	s_nop 1
	v_mov_b32_e32 v9, s2
	v_mov_b32_e32 v90, s3
	v_mul_f32_e32 v93, 0x3a800000, v9
	v_mul_f32_e32 v91, 0x3a800000, v90
	v_fma_f32 v91, -v93, v93, v91
	v_max_f32_e32 v91, 0, v91
	v_add_f32_e32 v91, 0x358637bd, v91
	v_rsq_f32_e32 v94, v91
	v_mul_f32_e32 v91, 0.5, v91
	v_mul_f32_e32 v92, v94, v94
	v_fma_f32 v92, -v91, v92, 0.5
	v_fma_f32 v94, v94, v92, v94
	v_sub_f32_e32 v74, v74, v93
	v_sub_f32_e32 v75, v75, v93
	v_sub_f32_e32 v76, v76, v93
	v_sub_f32_e32 v77, v77, v93
	v_sub_f32_e32 v78, v78, v93
	v_sub_f32_e32 v79, v79, v93
	v_sub_f32_e32 v80, v80, v93
	v_sub_f32_e32 v81, v81, v93
	v_sub_f32_e32 v82, v82, v93
	v_sub_f32_e32 v83, v83, v93
	v_sub_f32_e32 v84, v84, v93
	v_sub_f32_e32 v85, v85, v93
	v_sub_f32_e32 v86, v86, v93
	v_sub_f32_e32 v87, v87, v93
	v_sub_f32_e32 v88, v88, v93
	v_sub_f32_e32 v89, v89, v93
	v_mul_f32_e32 v74, v94, v74
	v_mul_f32_e32 v75, v94, v75
	v_mul_f32_e32 v76, v94, v76
	v_mul_f32_e32 v77, v94, v77
	v_mul_f32_e32 v78, v94, v78
	v_mul_f32_e32 v79, v94, v79
	v_mul_f32_e32 v80, v94, v80
	v_mul_f32_e32 v81, v94, v81
	v_mul_f32_e32 v82, v94, v82
	v_mul_f32_e32 v83, v94, v83
	v_mul_f32_e32 v84, v94, v84
	v_mul_f32_e32 v85, v94, v85
	v_mul_f32_e32 v86, v94, v86
	v_mul_f32_e32 v87, v94, v87
	v_mul_f32_e32 v88, v94, v88
	v_mul_f32_e32 v89, v94, v89
	v_fma_f32 v74, v74, v130, v114
	v_fma_f32 v75, v75, v131, v115
	v_fma_f32 v76, v76, v132, v116
	v_fma_f32 v77, v77, v133, v117
	v_fma_f32 v78, v78, v134, v118
	v_fma_f32 v79, v79, v135, v119
	v_fma_f32 v80, v80, v136, v120
	v_fma_f32 v81, v81, v137, v121
	v_fma_f32 v82, v82, v138, v122
	v_fma_f32 v83, v83, v139, v123
	v_fma_f32 v84, v84, v140, v124
	v_fma_f32 v85, v85, v141, v125
	v_fma_f32 v86, v86, v142, v126
	v_fma_f32 v87, v87, v143, v127
	v_fma_f32 v88, v88, v144, v128
	v_fma_f32 v89, v89, v145, v129
	v_cvt_pk_bf16_f32 v190, v74, v75
	v_cvt_pk_bf16_f32 v191, v76, v77
	v_cvt_pk_bf16_f32 v192, v78, v79
	v_cvt_pk_bf16_f32 v193, v80, v81
	v_cvt_pk_bf16_f32 v194, v82, v83
	v_cvt_pk_bf16_f32 v195, v84, v85
	v_cvt_pk_bf16_f32 v196, v86, v87
	v_cvt_pk_bf16_f32 v197, v88, v89
	s_add_u32 s2, s10, 0x1000
	s_addc_u32 s3, s11, 0
	global_store_dwordx2 v1, v[190:191], s[2:3]
	global_store_dwordx2 v1, v[192:193], s[2:3] offset:512
	global_store_dwordx2 v1, v[194:195], s[2:3] offset:1024
	global_store_dwordx2 v1, v[196:197], s[2:3] offset:1536
	s_add_u32 s2, s8, 0x6000
	s_addc_u32 s3, s9, 0
	global_load_dwordx4 v[74:77], v0, s[2:3]
	global_load_dwordx4 v[78:81], v0, s[2:3] offset:1024
	global_load_dwordx4 v[82:85], v0, s[2:3] offset:2048
	global_load_dwordx4 v[86:89], v0, s[2:3] offset:3072
	s_waitcnt vmcnt(27)
; DI void ln_row_v(const Frame& F, f32x4 (&v)[4], float* xout, const float* g, const float* b, const float* sh, const float* sc, bf16_t* hout, const float* slab, const float* gres, float* stat = nullptr) {
;     ...
;     if (g) {
;         float s = 0.f, s2 = 0.f;
; #pragma unroll
;         for (int j = 0; j < 4; ++j) { s += (v[j][0] + v[j][1]) + (v[j][2] + v[j][3]); s2 += (v[j][0] * v[j][0] + v[j][1] * v[j][1]) + (v[j][2] * v[j][2] + v[j][3] * v[j][3]); }
;         wave_sum2(s, s2, F.lane);
;         const float mean = s * (1.f / D); const float rstd = 1.f / sqrtf(fmaxf(s2 * (1.f / D) - mean * mean, 0.f) + EPS);
;         if (stat && F.lane == 0) { f32x2 sv = {mean, rstd}; *(f32x2*)stat = sv; }
; #pragma unroll
;         for (int j = 0; j < 4; ++j) { const f32x4 gg = ((const f32x4*)g)[F.lane + 64 * j], bb = ((const f32x4*)b)[F.lane + 64 * j];
;             v[j] = (v[j] - mean) * rstd * gg + bb; if (xout) ((f32x4*)xout)[F.lane + 64 * j] = v[j]; }
;     }
;     if (hout) {
;         float s = 0.f, s2 = 0.f;
; #pragma unroll
;         for (int j = 0; j < 4; ++j) { s += (v[j][0] + v[j][1]) + (v[j][2] + v[j][3]); s2 += (v[j][0] * v[j][0] + v[j][1] * v[j][1]) + (v[j][2] * v[j][2] + v[j][3] * v[j][3]); }
;         wave_sum2(s, s2, F.lane);
;         const float mean = s * (1.f / D); const float rstd = 1.f / sqrtf(fmaxf(s2 * (1.f / D) - mean * mean, 0.f) + EPS);
	v_add_f32_e32 v9, v98, v99
	v_add_f32_e32 v91, v100, v101
	v_mul_f32_e32 v90, v98, v98
	v_mul_f32_e32 v92, v99, v99
	v_add_f32_e32 v9, v9, v102
	v_add_f32_e32 v91, v91, v103
	v_add_f32_e32 v9, v9, v104
	v_add_f32_e32 v91, v91, v105
	v_add_f32_e32 v9, v9, v106
	v_add_f32_e32 v91, v91, v107
	v_add_f32_e32 v9, v9, v108
	v_add_f32_e32 v91, v91, v109
	v_add_f32_e32 v9, v9, v110
	v_add_f32_e32 v91, v91, v111
	v_add_f32_e32 v9, v9, v112
	v_add_f32_e32 v91, v91, v113
	v_fmac_f32_e32 v90, v100, v100
	v_fmac_f32_e32 v92, v101, v101
	v_fmac_f32_e32 v90, v102, v102
	v_fmac_f32_e32 v92, v103, v103
	v_fmac_f32_e32 v90, v104, v104
	v_fmac_f32_e32 v92, v105, v105
	v_fmac_f32_e32 v90, v106, v106
	v_fmac_f32_e32 v92, v107, v107
	v_fmac_f32_e32 v90, v108, v108
	v_fmac_f32_e32 v92, v109, v109
	v_fmac_f32_e32 v90, v110, v110
	v_fmac_f32_e32 v92, v111, v111
	v_fmac_f32_e32 v90, v112, v112
	v_fmac_f32_e32 v92, v113, v113
	v_add_f32_e32 v9, v9, v91
	v_add_f32_e32 v90, v90, v92
	s_nop 1
	v_add_f32_dpp v9, v9, v9 quad_perm:[1,0,3,2] row_mask:0xf bank_mask:0xf
	v_add_f32_dpp v90, v90, v90 quad_perm:[1,0,3,2] row_mask:0xf bank_mask:0xf
	s_nop 0
	v_add_f32_dpp v9, v9, v9 quad_perm:[2,3,0,1] row_mask:0xf bank_mask:0xf
	v_add_f32_dpp v90, v90, v90 quad_perm:[2,3,0,1] row_mask:0xf bank_mask:0xf
	s_nop 0
	v_add_f32_dpp v9, v9, v9 row_half_mirror row_mask:0xf bank_mask:0xf
	v_add_f32_dpp v90, v90, v90 row_half_mirror row_mask:0xf bank_mask:0xf
	s_nop 0
	v_add_f32_dpp v9, v9, v9 row_mirror row_mask:0xf bank_mask:0xf
	v_add_f32_dpp v90, v90, v90 row_mirror row_mask:0xf bank_mask:0xf
	s_nop 0
	v_add_f32_dpp v9, v9, v9 row_bcast:15 row_mask:0xa bank_mask:0xf
	v_add_f32_dpp v90, v90, v90 row_bcast:15 row_mask:0xa bank_mask:0xf
	s_nop 0
	v_add_f32_dpp v9, v9, v9 row_bcast:31 row_mask:0xc bank_mask:0xf
	v_add_f32_dpp v90, v90, v90 row_bcast:31 row_mask:0xc bank_mask:0xf
	s_nop 0
	v_readlane_b32 s2, v9, 63
	v_readlane_b32 s3, v90, 63
	s_nop 1
	v_mov_b32_e32 v9, s2
	v_mov_b32_e32 v90, s3
	v_mul_f32_e32 v93, 0x3a800000, v9
	v_mul_f32_e32 v91, 0x3a800000, v90
	v_fma_f32 v91, -v93, v93, v91
	v_max_f32_e32 v91, 0, v91
	v_add_f32_e32 v91, 0x358637bd, v91
	v_rsq_f32_e32 v94, v91
	v_mul_f32_e32 v91, 0.5, v91
	v_mul_f32_e32 v92, v94, v94
	v_fma_f32 v92, -v91, v92, 0.5
	v_fma_f32 v94, v94, v92, v94
	s_add_u32 s2, s12, 0x18
	s_addc_u32 s3, s13, 0
	v_mov_b32_e32 v188, v93
	v_mov_b32_e32 v189, v94
	s_mov_b64 exec, 1
	global_store_dwordx2 v97, v[188:189], s[2:3]
	s_mov_b64 exec, -1
	v_sub_f32_e32 v98, v98, v93
	v_sub_f32_e32 v99, v99, v93
	v_sub_f32_e32 v100, v100, v93
	v_sub_f32_e32 v101, v101, v93
	v_sub_f32_e32 v102, v102, v93
	v_sub_f32_e32 v103, v103, v93
	v_sub_f32_e32 v104, v104, v93
	v_sub_f32_e32 v105, v105, v93
	v_sub_f32_e32 v106, v106, v93
	v_sub_f32_e32 v107, v107, v93
	v_sub_f32_e32 v108, v108, v93
	v_sub_f32_e32 v109, v109, v93
	v_sub_f32_e32 v110, v110, v93
	v_sub_f32_e32 v111, v111, v93
	v_sub_f32_e32 v112, v112, v93
	v_sub_f32_e32 v113, v113, v93
	v_mul_f32_e32 v98, v94, v98
	v_mul_f32_e32 v99, v94, v99
	v_mul_f32_e32 v100, v94, v100
	v_mul_f32_e32 v101, v94, v101
	v_mul_f32_e32 v102, v94, v102
	v_mul_f32_e32 v103, v94, v103
	v_mul_f32_e32 v104, v94, v104
	v_mul_f32_e32 v105, v94, v105
	v_mul_f32_e32 v106, v94, v106
	v_mul_f32_e32 v107, v94, v107
	v_mul_f32_e32 v108, v94, v108
	v_mul_f32_e32 v109, v94, v109
	v_mul_f32_e32 v110, v94, v110
	v_mul_f32_e32 v111, v94, v111
	v_mul_f32_e32 v112, v94, v112
	v_mul_f32_e32 v113, v94, v113
	v_fma_f32 v98, v98, v10, v26
	v_fma_f32 v99, v99, v11, v27
	v_fma_f32 v100, v100, v12, v28
	v_fma_f32 v101, v101, v13, v29
	v_fma_f32 v102, v102, v14, v30
	v_fma_f32 v103, v103, v15, v31
	v_fma_f32 v104, v104, v16, v32
	v_fma_f32 v105, v105, v17, v33
	v_fma_f32 v106, v106, v18, v34
	v_fma_f32 v107, v107, v19, v35
	v_fma_f32 v108, v108, v20, v36
	v_fma_f32 v109, v109, v21, v37
	v_fma_f32 v110, v110, v22, v38
	v_fma_f32 v111, v111, v23, v39
	v_fma_f32 v112, v112, v24, v40
	v_fma_f32 v113, v113, v25, v41
	v_add_f32_e32 v9, v98, v99
	v_add_f32_e32 v91, v100, v101
	v_mul_f32_e32 v90, v98, v98
	v_mul_f32_e32 v92, v99, v99
	v_add_f32_e32 v9, v9, v102
	v_add_f32_e32 v91, v91, v103
	v_add_f32_e32 v9, v9, v104
	v_add_f32_e32 v91, v91, v105
	v_add_f32_e32 v9, v9, v106
	v_add_f32_e32 v91, v91, v107
	v_add_f32_e32 v9, v9, v108
	v_add_f32_e32 v91, v91, v109
	v_add_f32_e32 v9, v9, v110
	v_add_f32_e32 v91, v91, v111
	v_add_f32_e32 v9, v9, v112
	v_add_f32_e32 v91, v91, v113
	v_fmac_f32_e32 v90, v100, v100
	v_fmac_f32_e32 v92, v101, v101
	v_fmac_f32_e32 v90, v102, v102
	v_fmac_f32_e32 v92, v103, v103
	v_fmac_f32_e32 v90, v104, v104
	v_fmac_f32_e32 v92, v105, v105
	v_fmac_f32_e32 v90, v106, v106
	v_fmac_f32_e32 v92, v107, v107
	v_fmac_f32_e32 v90, v108, v108
	v_fmac_f32_e32 v92, v109, v109
	v_fmac_f32_e32 v90, v110, v110
	v_fmac_f32_e32 v92, v111, v111
	v_fmac_f32_e32 v90, v112, v112
	v_fmac_f32_e32 v92, v113, v113
	v_add_f32_e32 v9, v9, v91
	v_add_f32_e32 v90, v90, v92
	s_nop 1
	v_add_f32_dpp v9, v9, v9 quad_perm:[1,0,3,2] row_mask:0xf bank_mask:0xf
	v_add_f32_dpp v90, v90, v90 quad_perm:[1,0,3,2] row_mask:0xf bank_mask:0xf
	s_nop 0
	v_add_f32_dpp v9, v9, v9 quad_perm:[2,3,0,1] row_mask:0xf bank_mask:0xf
	v_add_f32_dpp v90, v90, v90 quad_perm:[2,3,0,1] row_mask:0xf bank_mask:0xf
	s_nop 0
	v_add_f32_dpp v9, v9, v9 row_half_mirror row_mask:0xf bank_mask:0xf
	v_add_f32_dpp v90, v90, v90 row_half_mirror row_mask:0xf bank_mask:0xf
	s_nop 0
	v_add_f32_dpp v9, v9, v9 row_mirror row_mask:0xf bank_mask:0xf
	v_add_f32_dpp v90, v90, v90 row_mirror row_mask:0xf bank_mask:0xf
	s_nop 0
	v_add_f32_dpp v9, v9, v9 row_bcast:15 row_mask:0xa bank_mask:0xf
; DI unsigned pk2(float lo, float hi) { f32x2 v = {lo, hi}; bf16x2_t b = __builtin_convertvector(v, bf16x2_t); return __builtin_bit_cast(unsigned, b); }
; DI void ln_row_v(const Frame& F, f32x4 (&v)[4], float* xout, const float* g, const float* b, const float* sh, const float* sc, bf16_t* hout, const float* slab, const float* gres, float* stat = nullptr) {
;     ...
;     if (g) {
;         float s = 0.f, s2 = 0.f;
; #pragma unroll
;         for (int j = 0; j < 4; ++j) { s += (v[j][0] + v[j][1]) + (v[j][2] + v[j][3]); s2 += (v[j][0] * v[j][0] + v[j][1] * v[j][1]) + (v[j][2] * v[j][2] + v[j][3] * v[j][3]); }
;         wave_sum2(s, s2, F.lane);
;         const float mean = s * (1.f / D); const float rstd = 1.f / sqrtf(fmaxf(s2 * (1.f / D) - mean * mean, 0.f) + EPS);
;         if (stat && F.lane == 0) { f32x2 sv = {mean, rstd}; *(f32x2*)stat = sv; }
;     ...
;         const float mean = s * (1.f / D); const float rstd = 1.f / sqrtf(fmaxf(s2 * (1.f / D) - mean * mean, 0.f) + EPS);
; #pragma unroll
;         for (int j = 0; j < 4; ++j) { const f32x4 hh = ((const f32x4*)sh)[F.lane + 64 * j], cc = ((const f32x4*)sc)[F.lane + 64 * j];
;             const f32x4 o = (v[j] - mean) * rstd * (cc + 1.f) + hh; u32x2 wv; wv.x = pk2(o[0], o[1]); wv.y = pk2(o[2], o[3]);
;             ((u32x2*)hout)[F.lane + 64 * j] = wv; }
;     }
	v_add_f32_dpp v90, v90, v90 row_bcast:15 row_mask:0xa bank_mask:0xf
	s_nop 0
	v_add_f32_dpp v9, v9, v9 row_bcast:31 row_mask:0xc bank_mask:0xf
	v_add_f32_dpp v90, v90, v90 row_bcast:31 row_mask:0xc bank_mask:0xf
	s_nop 0
	v_readlane_b32 s2, v9, 63
	v_readlane_b32 s3, v90, 63
	s_nop 1
	v_mov_b32_e32 v9, s2
	v_mov_b32_e32 v90, s3
	v_mul_f32_e32 v93, 0x3a800000, v9
	v_mul_f32_e32 v91, 0x3a800000, v90
	v_fma_f32 v91, -v93, v93, v91
	v_max_f32_e32 v91, 0, v91
	v_add_f32_e32 v91, 0x358637bd, v91
	v_rsq_f32_e32 v94, v91
	v_mul_f32_e32 v91, 0.5, v91
	v_mul_f32_e32 v92, v94, v94
	v_fma_f32 v92, -v91, v92, 0.5
	v_fma_f32 v94, v94, v92, v94
	v_sub_f32_e32 v98, v98, v93
	v_sub_f32_e32 v99, v99, v93
	v_sub_f32_e32 v100, v100, v93
	v_sub_f32_e32 v101, v101, v93
	v_sub_f32_e32 v102, v102, v93
	v_sub_f32_e32 v103, v103, v93
	v_sub_f32_e32 v104, v104, v93
	v_sub_f32_e32 v105, v105, v93
	v_sub_f32_e32 v106, v106, v93
	v_sub_f32_e32 v107, v107, v93
	v_sub_f32_e32 v108, v108, v93
	v_sub_f32_e32 v109, v109, v93
	v_sub_f32_e32 v110, v110, v93
	v_sub_f32_e32 v111, v111, v93
	v_sub_f32_e32 v112, v112, v93
	v_sub_f32_e32 v113, v113, v93
	v_mul_f32_e32 v98, v94, v98
	v_mul_f32_e32 v99, v94, v99
	v_mul_f32_e32 v100, v94, v100
	v_mul_f32_e32 v101, v94, v101
	v_mul_f32_e32 v102, v94, v102
	v_mul_f32_e32 v103, v94, v103
	v_mul_f32_e32 v104, v94, v104
	v_mul_f32_e32 v105, v94, v105
	v_mul_f32_e32 v106, v94, v106
	v_mul_f32_e32 v107, v94, v107
	v_mul_f32_e32 v108, v94, v108
	v_mul_f32_e32 v109, v94, v109
	v_mul_f32_e32 v110, v94, v110
	v_mul_f32_e32 v111, v94, v111
	v_mul_f32_e32 v112, v94, v112
	v_mul_f32_e32 v113, v94, v113
	v_fma_f32 v98, v98, v130, v114
	v_fma_f32 v99, v99, v131, v115
	v_fma_f32 v100, v100, v132, v116
	v_fma_f32 v101, v101, v133, v117
	v_fma_f32 v102, v102, v134, v118
	v_fma_f32 v103, v103, v135, v119
	v_fma_f32 v104, v104, v136, v120
	v_fma_f32 v105, v105, v137, v121
	v_fma_f32 v106, v106, v138, v122
	v_fma_f32 v107, v107, v139, v123
	v_fma_f32 v108, v108, v140, v124
	v_fma_f32 v109, v109, v141, v125
	v_fma_f32 v110, v110, v142, v126
	v_fma_f32 v111, v111, v143, v127
	v_fma_f32 v112, v112, v144, v128
	v_fma_f32 v113, v113, v145, v129
	v_cvt_pk_bf16_f32 v190, v98, v99
	v_cvt_pk_bf16_f32 v191, v100, v101
	v_cvt_pk_bf16_f32 v192, v102, v103
	v_cvt_pk_bf16_f32 v193, v104, v105
	v_cvt_pk_bf16_f32 v194, v106, v107
	v_cvt_pk_bf16_f32 v195, v108, v109
	v_cvt_pk_bf16_f32 v196, v110, v111
	v_cvt_pk_bf16_f32 v197, v112, v113
	s_add_u32 s2, s10, 0x1800
	s_addc_u32 s3, s11, 0
	global_store_dwordx2 v1, v[190:191], s[2:3]
	global_store_dwordx2 v1, v[192:193], s[2:3] offset:512
	global_store_dwordx2 v1, v[194:195], s[2:3] offset:1024
	global_store_dwordx2 v1, v[196:197], s[2:3] offset:1536
	s_add_u32 s2, s8, 0x7000
	s_addc_u32 s3, s9, 0
	global_load_dwordx4 v[98:101], v0, s[2:3]
	global_load_dwordx4 v[102:105], v0, s[2:3] offset:1024
	global_load_dwordx4 v[106:109], v0, s[2:3] offset:2048
	global_load_dwordx4 v[110:113], v0, s[2:3] offset:3072
	s_waitcnt vmcnt(27)
	v_add_f32_e32 v9, v42, v43
	v_add_f32_e32 v91, v44, v45
	v_mul_f32_e32 v90, v42, v42
	v_mul_f32_e32 v92, v43, v43
	v_add_f32_e32 v9, v9, v46
	v_add_f32_e32 v91, v91, v47
	v_add_f32_e32 v9, v9, v48
	v_add_f32_e32 v91, v91, v49
	v_add_f32_e32 v9, v9, v50
	v_add_f32_e32 v91, v91, v51
	v_add_f32_e32 v9, v9, v52
	v_add_f32_e32 v91, v91, v53
	v_add_f32_e32 v9, v9, v54
	v_add_f32_e32 v91, v91, v55
	v_add_f32_e32 v9, v9, v56
	v_add_f32_e32 v91, v91, v57
	v_fmac_f32_e32 v90, v44, v44
	v_fmac_f32_e32 v92, v45, v45
	v_fmac_f32_e32 v90, v46, v46
	v_fmac_f32_e32 v92, v47, v47
	v_fmac_f32_e32 v90, v48, v48
	v_fmac_f32_e32 v92, v49, v49
	v_fmac_f32_e32 v90, v50, v50
	v_fmac_f32_e32 v92, v51, v51
	v_fmac_f32_e32 v90, v52, v52
	v_fmac_f32_e32 v92, v53, v53
	v_fmac_f32_e32 v90, v54, v54
	v_fmac_f32_e32 v92, v55, v55
	v_fmac_f32_e32 v90, v56, v56
	v_fmac_f32_e32 v92, v57, v57
	v_add_f32_e32 v9, v9, v91
	v_add_f32_e32 v90, v90, v92
	s_nop 1
	v_add_f32_dpp v9, v9, v9 quad_perm:[1,0,3,2] row_mask:0xf bank_mask:0xf
	v_add_f32_dpp v90, v90, v90 quad_perm:[1,0,3,2] row_mask:0xf bank_mask:0xf
	s_nop 0
	v_add_f32_dpp v9, v9, v9 quad_perm:[2,3,0,1] row_mask:0xf bank_mask:0xf
	v_add_f32_dpp v90, v90, v90 quad_perm:[2,3,0,1] row_mask:0xf bank_mask:0xf
	s_nop 0
	v_add_f32_dpp v9, v9, v9 row_half_mirror row_mask:0xf bank_mask:0xf
	v_add_f32_dpp v90, v90, v90 row_half_mirror row_mask:0xf bank_mask:0xf
	s_nop 0
	v_add_f32_dpp v9, v9, v9 row_mirror row_mask:0xf bank_mask:0xf
	v_add_f32_dpp v90, v90, v90 row_mirror row_mask:0xf bank_mask:0xf
	s_nop 0
	v_add_f32_dpp v9, v9, v9 row_bcast:15 row_mask:0xa bank_mask:0xf
	v_add_f32_dpp v90, v90, v90 row_bcast:15 row_mask:0xa bank_mask:0xf
	s_nop 0
	v_add_f32_dpp v9, v9, v9 row_bcast:31 row_mask:0xc bank_mask:0xf
	v_add_f32_dpp v90, v90, v90 row_bcast:31 row_mask:0xc bank_mask:0xf
	s_nop 0
	v_readlane_b32 s2, v9, 63
	v_readlane_b32 s3, v90, 63
	s_nop 1
	v_mov_b32_e32 v9, s2
	v_mov_b32_e32 v90, s3
	v_mul_f32_e32 v93, 0x3a800000, v9
	v_mul_f32_e32 v91, 0x3a800000, v90
	v_fma_f32 v91, -v93, v93, v91
	v_max_f32_e32 v91, 0, v91
	v_add_f32_e32 v91, 0x358637bd, v91
	v_rsq_f32_e32 v94, v91
	v_mul_f32_e32 v91, 0.5, v91
	v_mul_f32_e32 v92, v94, v94
	v_fma_f32 v92, -v91, v92, 0.5
	v_fma_f32 v94, v94, v92, v94
	s_add_u32 s2, s12, 0x20
	s_addc_u32 s3, s13, 0
	v_mov_b32_e32 v188, v93
	v_mov_b32_e32 v189, v94
	s_mov_b64 exec, 1
	global_store_dwordx2 v97, v[188:189], s[2:3]
	s_mov_b64 exec, -1
	v_sub_f32_e32 v42, v42, v93
	v_sub_f32_e32 v43, v43, v93
	v_sub_f32_e32 v44, v44, v93
	v_sub_f32_e32 v45, v45, v93
	v_sub_f32_e32 v46, v46, v93
	v_sub_f32_e32 v47, v47, v93
	v_sub_f32_e32 v48, v48, v93
; DI unsigned pk2(float lo, float hi) { f32x2 v = {lo, hi}; bf16x2_t b = __builtin_convertvector(v, bf16x2_t); return __builtin_bit_cast(unsigned, b); }
; DI void ln_row_v(const Frame& F, f32x4 (&v)[4], float* xout, const float* g, const float* b, const float* sh, const float* sc, bf16_t* hout, const float* slab, const float* gres, float* stat = nullptr) {
;     ...
;         for (int j = 0; j < 4; ++j) { const f32x4 gg = ((const f32x4*)g)[F.lane + 64 * j], bb = ((const f32x4*)b)[F.lane + 64 * j];
;             v[j] = (v[j] - mean) * rstd * gg + bb; if (xout) ((f32x4*)xout)[F.lane + 64 * j] = v[j]; }
;     }
;     if (hout) {
;         float s = 0.f, s2 = 0.f;
; #pragma unroll
;         for (int j = 0; j < 4; ++j) { s += (v[j][0] + v[j][1]) + (v[j][2] + v[j][3]); s2 += (v[j][0] * v[j][0] + v[j][1] * v[j][1]) + (v[j][2] * v[j][2] + v[j][3] * v[j][3]); }
;         wave_sum2(s, s2, F.lane);
;         const float mean = s * (1.f / D); const float rstd = 1.f / sqrtf(fmaxf(s2 * (1.f / D) - mean * mean, 0.f) + EPS);
; #pragma unroll
;         for (int j = 0; j < 4; ++j) { const f32x4 hh = ((const f32x4*)sh)[F.lane + 64 * j], cc = ((const f32x4*)sc)[F.lane + 64 * j];
;             const f32x4 o = (v[j] - mean) * rstd * (cc + 1.f) + hh; u32x2 wv; wv.x = pk2(o[0], o[1]); wv.y = pk2(o[2], o[3]);
;             ((u32x2*)hout)[F.lane + 64 * j] = wv; }
;     }
	v_sub_f32_e32 v49, v49, v93
	v_sub_f32_e32 v50, v50, v93
	v_sub_f32_e32 v51, v51, v93
	v_sub_f32_e32 v52, v52, v93
	v_sub_f32_e32 v53, v53, v93
	v_sub_f32_e32 v54, v54, v93
	v_sub_f32_e32 v55, v55, v93
	v_sub_f32_e32 v56, v56, v93
	v_sub_f32_e32 v57, v57, v93
	v_mul_f32_e32 v42, v94, v42
	v_mul_f32_e32 v43, v94, v43
	v_mul_f32_e32 v44, v94, v44
	v_mul_f32_e32 v45, v94, v45
	v_mul_f32_e32 v46, v94, v46
	v_mul_f32_e32 v47, v94, v47
	v_mul_f32_e32 v48, v94, v48
	v_mul_f32_e32 v49, v94, v49
	v_mul_f32_e32 v50, v94, v50
	v_mul_f32_e32 v51, v94, v51
	v_mul_f32_e32 v52, v94, v52
	v_mul_f32_e32 v53, v94, v53
	v_mul_f32_e32 v54, v94, v54
	v_mul_f32_e32 v55, v94, v55
	v_mul_f32_e32 v56, v94, v56
	v_mul_f32_e32 v57, v94, v57
	v_fma_f32 v42, v42, v10, v26
	v_fma_f32 v43, v43, v11, v27
	v_fma_f32 v44, v44, v12, v28
	v_fma_f32 v45, v45, v13, v29
	v_fma_f32 v46, v46, v14, v30
	v_fma_f32 v47, v47, v15, v31
	v_fma_f32 v48, v48, v16, v32
	v_fma_f32 v49, v49, v17, v33
	v_fma_f32 v50, v50, v18, v34
	v_fma_f32 v51, v51, v19, v35
	v_fma_f32 v52, v52, v20, v36
	v_fma_f32 v53, v53, v21, v37
	v_fma_f32 v54, v54, v22, v38
	v_fma_f32 v55, v55, v23, v39
	v_fma_f32 v56, v56, v24, v40
	v_fma_f32 v57, v57, v25, v41
	v_add_f32_e32 v9, v42, v43
	v_add_f32_e32 v91, v44, v45
	v_mul_f32_e32 v90, v42, v42
	v_mul_f32_e32 v92, v43, v43
	v_add_f32_e32 v9, v9, v46
	v_add_f32_e32 v91, v91, v47
	v_add_f32_e32 v9, v9, v48
	v_add_f32_e32 v91, v91, v49
	v_add_f32_e32 v9, v9, v50
	v_add_f32_e32 v91, v91, v51
	v_add_f32_e32 v9, v9, v52
	v_add_f32_e32 v91, v91, v53
	v_add_f32_e32 v9, v9, v54
	v_add_f32_e32 v91, v91, v55
	v_add_f32_e32 v9, v9, v56
	v_add_f32_e32 v91, v91, v57
	v_fmac_f32_e32 v90, v44, v44
	v_fmac_f32_e32 v92, v45, v45
	v_fmac_f32_e32 v90, v46, v46
	v_fmac_f32_e32 v92, v47, v47
	v_fmac_f32_e32 v90, v48, v48
	v_fmac_f32_e32 v92, v49, v49
	v_fmac_f32_e32 v90, v50, v50
	v_fmac_f32_e32 v92, v51, v51
	v_fmac_f32_e32 v90, v52, v52
	v_fmac_f32_e32 v92, v53, v53
	v_fmac_f32_e32 v90, v54, v54
	v_fmac_f32_e32 v92, v55, v55
	v_fmac_f32_e32 v90, v56, v56
	v_fmac_f32_e32 v92, v57, v57
	v_add_f32_e32 v9, v9, v91
	v_add_f32_e32 v90, v90, v92
	s_nop 1
	v_add_f32_dpp v9, v9, v9 quad_perm:[1,0,3,2] row_mask:0xf bank_mask:0xf
	v_add_f32_dpp v90, v90, v90 quad_perm:[1,0,3,2] row_mask:0xf bank_mask:0xf
	s_nop 0
	v_add_f32_dpp v9, v9, v9 quad_perm:[2,3,0,1] row_mask:0xf bank_mask:0xf
	v_add_f32_dpp v90, v90, v90 quad_perm:[2,3,0,1] row_mask:0xf bank_mask:0xf
	s_nop 0
	v_add_f32_dpp v9, v9, v9 row_half_mirror row_mask:0xf bank_mask:0xf
	v_add_f32_dpp v90, v90, v90 row_half_mirror row_mask:0xf bank_mask:0xf
	s_nop 0
	v_add_f32_dpp v9, v9, v9 row_mirror row_mask:0xf bank_mask:0xf
	v_add_f32_dpp v90, v90, v90 row_mirror row_mask:0xf bank_mask:0xf
	s_nop 0
	v_add_f32_dpp v9, v9, v9 row_bcast:15 row_mask:0xa bank_mask:0xf
	v_add_f32_dpp v90, v90, v90 row_bcast:15 row_mask:0xa bank_mask:0xf
	s_nop 0
	v_add_f32_dpp v9, v9, v9 row_bcast:31 row_mask:0xc bank_mask:0xf
	v_add_f32_dpp v90, v90, v90 row_bcast:31 row_mask:0xc bank_mask:0xf
	s_nop 0
	v_readlane_b32 s2, v9, 63
	v_readlane_b32 s3, v90, 63
	s_nop 1
	v_mov_b32_e32 v9, s2
	v_mov_b32_e32 v90, s3
	v_mul_f32_e32 v93, 0x3a800000, v9
	v_mul_f32_e32 v91, 0x3a800000, v90
	v_fma_f32 v91, -v93, v93, v91
	v_max_f32_e32 v91, 0, v91
	v_add_f32_e32 v91, 0x358637bd, v91
	v_rsq_f32_e32 v94, v91
	v_mul_f32_e32 v91, 0.5, v91
	v_mul_f32_e32 v92, v94, v94
	v_fma_f32 v92, -v91, v92, 0.5
	v_fma_f32 v94, v94, v92, v94
	v_sub_f32_e32 v42, v42, v93
	v_sub_f32_e32 v43, v43, v93
	v_sub_f32_e32 v44, v44, v93
	v_sub_f32_e32 v45, v45, v93
	v_sub_f32_e32 v46, v46, v93
	v_sub_f32_e32 v47, v47, v93
	v_sub_f32_e32 v48, v48, v93
	v_sub_f32_e32 v49, v49, v93
	v_sub_f32_e32 v50, v50, v93
	v_sub_f32_e32 v51, v51, v93
	v_sub_f32_e32 v52, v52, v93
	v_sub_f32_e32 v53, v53, v93
	v_sub_f32_e32 v54, v54, v93
	v_sub_f32_e32 v55, v55, v93
	v_sub_f32_e32 v56, v56, v93
	v_sub_f32_e32 v57, v57, v93
	v_mul_f32_e32 v42, v94, v42
	v_mul_f32_e32 v43, v94, v43
	v_mul_f32_e32 v44, v94, v44
	v_mul_f32_e32 v45, v94, v45
	v_mul_f32_e32 v46, v94, v46
	v_mul_f32_e32 v47, v94, v47
	v_mul_f32_e32 v48, v94, v48
	v_mul_f32_e32 v49, v94, v49
	v_mul_f32_e32 v50, v94, v50
	v_mul_f32_e32 v51, v94, v51
	v_mul_f32_e32 v52, v94, v52
	v_mul_f32_e32 v53, v94, v53
	v_mul_f32_e32 v54, v94, v54
	v_mul_f32_e32 v55, v94, v55
	v_mul_f32_e32 v56, v94, v56
	v_mul_f32_e32 v57, v94, v57
	v_fma_f32 v42, v42, v130, v114
	v_fma_f32 v43, v43, v131, v115
	v_fma_f32 v44, v44, v132, v116
	v_fma_f32 v45, v45, v133, v117
	v_fma_f32 v46, v46, v134, v118
	v_fma_f32 v47, v47, v135, v119
	v_fma_f32 v48, v48, v136, v120
	v_fma_f32 v49, v49, v137, v121
	v_fma_f32 v50, v50, v138, v122
	v_fma_f32 v51, v51, v139, v123
	v_fma_f32 v52, v52, v140, v124
	v_fma_f32 v53, v53, v141, v125
	v_fma_f32 v54, v54, v142, v126
	v_fma_f32 v55, v55, v143, v127
	v_fma_f32 v56, v56, v144, v128
	v_fma_f32 v57, v57, v145, v129
	v_cvt_pk_bf16_f32 v190, v42, v43
	v_cvt_pk_bf16_f32 v191, v44, v45
	v_cvt_pk_bf16_f32 v192, v46, v47
	v_cvt_pk_bf16_f32 v193, v48, v49
	v_cvt_pk_bf16_f32 v194, v50, v51
	v_cvt_pk_bf16_f32 v195, v52, v53
	v_cvt_pk_bf16_f32 v196, v54, v55
	v_cvt_pk_bf16_f32 v197, v56, v57
	s_add_u32 s2, s10, 0x2000
	s_addc_u32 s3, s11, 0
	global_store_dwordx2 v1, v[190:191], s[2:3]
	global_store_dwordx2 v1, v[192:193], s[2:3] offset:512
	global_store_dwordx2 v1, v[194:195], s[2:3] offset:1024
	global_store_dwordx2 v1, v[196:197], s[2:3] offset:1536
	s_mov_b64 s[2:3], s[20:21]
	global_load_dwordx4 v[42:45], v0, s[2:3]
	global_load_dwordx4 v[46:49], v0, s[2:3] offset:1024
	global_load_dwordx4 v[50:53], v0, s[2:3] offset:2048
	global_load_dwordx4 v[54:57], v0, s[2:3] offset:3072
	s_waitcnt vmcnt(27)
; DI void ln_row_v(const Frame& F, f32x4 (&v)[4], float* xout, const float* g, const float* b, const float* sh, const float* sc, bf16_t* hout, const float* slab, const float* gres, float* stat = nullptr) {
;     ...
;     if (g) {
;         float s = 0.f, s2 = 0.f;
; #pragma unroll
;         for (int j = 0; j < 4; ++j) { s += (v[j][0] + v[j][1]) + (v[j][2] + v[j][3]); s2 += (v[j][0] * v[j][0] + v[j][1] * v[j][1]) + (v[j][2] * v[j][2] + v[j][3] * v[j][3]); }
;         wave_sum2(s, s2, F.lane);
;         const float mean = s * (1.f / D); const float rstd = 1.f / sqrtf(fmaxf(s2 * (1.f / D) - mean * mean, 0.f) + EPS);
;         if (stat && F.lane == 0) { f32x2 sv = {mean, rstd}; *(f32x2*)stat = sv; }
; #pragma unroll
;         for (int j = 0; j < 4; ++j) { const f32x4 gg = ((const f32x4*)g)[F.lane + 64 * j], bb = ((const f32x4*)b)[F.lane + 64 * j];
;             v[j] = (v[j] - mean) * rstd * gg + bb; if (xout) ((f32x4*)xout)[F.lane + 64 * j] = v[j]; }
;     }
;     if (hout) {
;         float s = 0.f, s2 = 0.f;
; #pragma unroll
;         for (int j = 0; j < 4; ++j) { s += (v[j][0] + v[j][1]) + (v[j][2] + v[j][3]); s2 += (v[j][0] * v[j][0] + v[j][1] * v[j][1]) + (v[j][2] * v[j][2] + v[j][3] * v[j][3]); }
;         wave_sum2(s, s2, F.lane);
;         const float mean = s * (1.f / D); const float rstd = 1.f / sqrtf(fmaxf(s2 * (1.f / D) - mean * mean, 0.f) + EPS);
	v_add_f32_e32 v9, v58, v59
	v_add_f32_e32 v91, v60, v61
	v_mul_f32_e32 v90, v58, v58
	v_mul_f32_e32 v92, v59, v59
	v_add_f32_e32 v9, v9, v62
	v_add_f32_e32 v91, v91, v63
	v_add_f32_e32 v9, v9, v64
	v_add_f32_e32 v91, v91, v65
	v_add_f32_e32 v9, v9, v66
	v_add_f32_e32 v91, v91, v67
	v_add_f32_e32 v9, v9, v68
	v_add_f32_e32 v91, v91, v69
	v_add_f32_e32 v9, v9, v70
	v_add_f32_e32 v91, v91, v71
	v_add_f32_e32 v9, v9, v72
	v_add_f32_e32 v91, v91, v73
	v_fmac_f32_e32 v90, v60, v60
	v_fmac_f32_e32 v92, v61, v61
	v_fmac_f32_e32 v90, v62, v62
	v_fmac_f32_e32 v92, v63, v63
	v_fmac_f32_e32 v90, v64, v64
	v_fmac_f32_e32 v92, v65, v65
	v_fmac_f32_e32 v90, v66, v66
	v_fmac_f32_e32 v92, v67, v67
	v_fmac_f32_e32 v90, v68, v68
	v_fmac_f32_e32 v92, v69, v69
	v_fmac_f32_e32 v90, v70, v70
	v_fmac_f32_e32 v92, v71, v71
	v_fmac_f32_e32 v90, v72, v72
	v_fmac_f32_e32 v92, v73, v73
	v_add_f32_e32 v9, v9, v91
	v_add_f32_e32 v90, v90, v92
	s_nop 1
	v_add_f32_dpp v9, v9, v9 quad_perm:[1,0,3,2] row_mask:0xf bank_mask:0xf
	v_add_f32_dpp v90, v90, v90 quad_perm:[1,0,3,2] row_mask:0xf bank_mask:0xf
	s_nop 0
	v_add_f32_dpp v9, v9, v9 quad_perm:[2,3,0,1] row_mask:0xf bank_mask:0xf
	v_add_f32_dpp v90, v90, v90 quad_perm:[2,3,0,1] row_mask:0xf bank_mask:0xf
	s_nop 0
	v_add_f32_dpp v9, v9, v9 row_half_mirror row_mask:0xf bank_mask:0xf
	v_add_f32_dpp v90, v90, v90 row_half_mirror row_mask:0xf bank_mask:0xf
	s_nop 0
	v_add_f32_dpp v9, v9, v9 row_mirror row_mask:0xf bank_mask:0xf
	v_add_f32_dpp v90, v90, v90 row_mirror row_mask:0xf bank_mask:0xf
	s_nop 0
	v_add_f32_dpp v9, v9, v9 row_bcast:15 row_mask:0xa bank_mask:0xf
	v_add_f32_dpp v90, v90, v90 row_bcast:15 row_mask:0xa bank_mask:0xf
	s_nop 0
	v_add_f32_dpp v9, v9, v9 row_bcast:31 row_mask:0xc bank_mask:0xf
	v_add_f32_dpp v90, v90, v90 row_bcast:31 row_mask:0xc bank_mask:0xf
	s_nop 0
	v_readlane_b32 s2, v9, 63
	v_readlane_b32 s3, v90, 63
	s_nop 1
	v_mov_b32_e32 v9, s2
	v_mov_b32_e32 v90, s3
	v_mul_f32_e32 v93, 0x3a800000, v9
	v_mul_f32_e32 v91, 0x3a800000, v90
	v_fma_f32 v91, -v93, v93, v91
	v_max_f32_e32 v91, 0, v91
	v_add_f32_e32 v91, 0x358637bd, v91
	v_rsq_f32_e32 v94, v91
	v_mul_f32_e32 v91, 0.5, v91
	v_mul_f32_e32 v92, v94, v94
	v_fma_f32 v92, -v91, v92, 0.5
	v_fma_f32 v94, v94, v92, v94
	s_add_u32 s2, s12, 0x28
	s_addc_u32 s3, s13, 0
	v_mov_b32_e32 v188, v93
	v_mov_b32_e32 v189, v94
	s_mov_b64 exec, 1
	global_store_dwordx2 v97, v[188:189], s[2:3]
	s_mov_b64 exec, -1
	v_sub_f32_e32 v58, v58, v93
	v_sub_f32_e32 v59, v59, v93
	v_sub_f32_e32 v60, v60, v93
	v_sub_f32_e32 v61, v61, v93
	v_sub_f32_e32 v62, v62, v93
	v_sub_f32_e32 v63, v63, v93
	v_sub_f32_e32 v64, v64, v93
	v_sub_f32_e32 v65, v65, v93
	v_sub_f32_e32 v66, v66, v93
	v_sub_f32_e32 v67, v67, v93
	v_sub_f32_e32 v68, v68, v93
	v_sub_f32_e32 v69, v69, v93
	v_sub_f32_e32 v70, v70, v93
	v_sub_f32_e32 v71, v71, v93
	v_sub_f32_e32 v72, v72, v93
	v_sub_f32_e32 v73, v73, v93
	v_mul_f32_e32 v58, v94, v58
	v_mul_f32_e32 v59, v94, v59
	v_mul_f32_e32 v60, v94, v60
	v_mul_f32_e32 v61, v94, v61
	v_mul_f32_e32 v62, v94, v62
	v_mul_f32_e32 v63, v94, v63
	v_mul_f32_e32 v64, v94, v64
	v_mul_f32_e32 v65, v94, v65
	v_mul_f32_e32 v66, v94, v66
	v_mul_f32_e32 v67, v94, v67
	v_mul_f32_e32 v68, v94, v68
	v_mul_f32_e32 v69, v94, v69
	v_mul_f32_e32 v70, v94, v70
	v_mul_f32_e32 v71, v94, v71
	v_mul_f32_e32 v72, v94, v72
	v_mul_f32_e32 v73, v94, v73
	v_fma_f32 v58, v58, v10, v26
	v_fma_f32 v59, v59, v11, v27
	v_fma_f32 v60, v60, v12, v28
	v_fma_f32 v61, v61, v13, v29
	v_fma_f32 v62, v62, v14, v30
	v_fma_f32 v63, v63, v15, v31
	v_fma_f32 v64, v64, v16, v32
	v_fma_f32 v65, v65, v17, v33
	v_fma_f32 v66, v66, v18, v34
	v_fma_f32 v67, v67, v19, v35
	v_fma_f32 v68, v68, v20, v36
	v_fma_f32 v69, v69, v21, v37
	v_fma_f32 v70, v70, v22, v38
	v_fma_f32 v71, v71, v23, v39
	v_fma_f32 v72, v72, v24, v40
	v_fma_f32 v73, v73, v25, v41
	v_add_f32_e32 v9, v58, v59
	v_add_f32_e32 v91, v60, v61
	v_mul_f32_e32 v90, v58, v58
	v_mul_f32_e32 v92, v59, v59
	v_add_f32_e32 v9, v9, v62
	v_add_f32_e32 v91, v91, v63
	v_add_f32_e32 v9, v9, v64
	v_add_f32_e32 v91, v91, v65
	v_add_f32_e32 v9, v9, v66
	v_add_f32_e32 v91, v91, v67
	v_add_f32_e32 v9, v9, v68
	v_add_f32_e32 v91, v91, v69
	v_add_f32_e32 v9, v9, v70
	v_add_f32_e32 v91, v91, v71
	v_add_f32_e32 v9, v9, v72
	v_add_f32_e32 v91, v91, v73
	v_fmac_f32_e32 v90, v60, v60
	v_fmac_f32_e32 v92, v61, v61
	v_fmac_f32_e32 v90, v62, v62
	v_fmac_f32_e32 v92, v63, v63
	v_fmac_f32_e32 v90, v64, v64
	v_fmac_f32_e32 v92, v65, v65
	v_fmac_f32_e32 v90, v66, v66
	v_fmac_f32_e32 v92, v67, v67
	v_fmac_f32_e32 v90, v68, v68
	v_fmac_f32_e32 v92, v69, v69
	v_fmac_f32_e32 v90, v70, v70
	v_fmac_f32_e32 v92, v71, v71
	v_fmac_f32_e32 v90, v72, v72
	v_fmac_f32_e32 v92, v73, v73
	v_add_f32_e32 v9, v9, v91
	v_add_f32_e32 v90, v90, v92
	s_nop 1
	v_add_f32_dpp v9, v9, v9 quad_perm:[1,0,3,2] row_mask:0xf bank_mask:0xf
	v_add_f32_dpp v90, v90, v90 quad_perm:[1,0,3,2] row_mask:0xf bank_mask:0xf
	s_nop 0
	v_add_f32_dpp v9, v9, v9 quad_perm:[2,3,0,1] row_mask:0xf bank_mask:0xf
	v_add_f32_dpp v90, v90, v90 quad_perm:[2,3,0,1] row_mask:0xf bank_mask:0xf
	s_nop 0
	v_add_f32_dpp v9, v9, v9 row_half_mirror row_mask:0xf bank_mask:0xf
	v_add_f32_dpp v90, v90, v90 row_half_mirror row_mask:0xf bank_mask:0xf
	s_nop 0
	v_add_f32_dpp v9, v9, v9 row_mirror row_mask:0xf bank_mask:0xf
	v_add_f32_dpp v90, v90, v90 row_mirror row_mask:0xf bank_mask:0xf
	s_nop 0
	v_add_f32_dpp v9, v9, v9 row_bcast:15 row_mask:0xa bank_mask:0xf
	v_add_f32_dpp v90, v90, v90 row_bcast:15 row_mask:0xa bank_mask:0xf
	s_nop 0
	v_add_f32_dpp v9, v9, v9 row_bcast:31 row_mask:0xc bank_mask:0xf
	v_add_f32_dpp v90, v90, v90 row_bcast:31 row_mask:0xc bank_mask:0xf
; DI unsigned pk2(float lo, float hi) { f32x2 v = {lo, hi}; bf16x2_t b = __builtin_convertvector(v, bf16x2_t); return __builtin_bit_cast(unsigned, b); }
; DI void ln_row_v(const Frame& F, f32x4 (&v)[4], float* xout, const float* g, const float* b, const float* sh, const float* sc, bf16_t* hout, const float* slab, const float* gres, float* stat = nullptr) {
;     ...
;     if (g) {
;         float s = 0.f, s2 = 0.f;
; #pragma unroll
;         for (int j = 0; j < 4; ++j) { s += (v[j][0] + v[j][1]) + (v[j][2] + v[j][3]); s2 += (v[j][0] * v[j][0] + v[j][1] * v[j][1]) + (v[j][2] * v[j][2] + v[j][3] * v[j][3]); }
;         wave_sum2(s, s2, F.lane);
;         const float mean = s * (1.f / D); const float rstd = 1.f / sqrtf(fmaxf(s2 * (1.f / D) - mean * mean, 0.f) + EPS);
;         if (stat && F.lane == 0) { f32x2 sv = {mean, rstd}; *(f32x2*)stat = sv; }
;     ...
;         const float mean = s * (1.f / D); const float rstd = 1.f / sqrtf(fmaxf(s2 * (1.f / D) - mean * mean, 0.f) + EPS);
; #pragma unroll
;         for (int j = 0; j < 4; ++j) { const f32x4 hh = ((const f32x4*)sh)[F.lane + 64 * j], cc = ((const f32x4*)sc)[F.lane + 64 * j];
;             const f32x4 o = (v[j] - mean) * rstd * (cc + 1.f) + hh; u32x2 wv; wv.x = pk2(o[0], o[1]); wv.y = pk2(o[2], o[3]);
;             ((u32x2*)hout)[F.lane + 64 * j] = wv; }
;     }
	s_nop 0
	v_readlane_b32 s2, v9, 63
	v_readlane_b32 s3, v90, 63
	s_nop 1
	v_mov_b32_e32 v9, s2
	v_mov_b32_e32 v90, s3
	v_mul_f32_e32 v93, 0x3a800000, v9
	v_mul_f32_e32 v91, 0x3a800000, v90
	v_fma_f32 v91, -v93, v93, v91
	v_max_f32_e32 v91, 0, v91
	v_add_f32_e32 v91, 0x358637bd, v91
	v_rsq_f32_e32 v94, v91
	v_mul_f32_e32 v91, 0.5, v91
	v_mul_f32_e32 v92, v94, v94
	v_fma_f32 v92, -v91, v92, 0.5
	v_fma_f32 v94, v94, v92, v94
	v_sub_f32_e32 v58, v58, v93
	v_sub_f32_e32 v59, v59, v93
	v_sub_f32_e32 v60, v60, v93
	v_sub_f32_e32 v61, v61, v93
	v_sub_f32_e32 v62, v62, v93
	v_sub_f32_e32 v63, v63, v93
	v_sub_f32_e32 v64, v64, v93
	v_sub_f32_e32 v65, v65, v93
	v_sub_f32_e32 v66, v66, v93
	v_sub_f32_e32 v67, v67, v93
	v_sub_f32_e32 v68, v68, v93
	v_sub_f32_e32 v69, v69, v93
	v_sub_f32_e32 v70, v70, v93
	v_sub_f32_e32 v71, v71, v93
	v_sub_f32_e32 v72, v72, v93
	v_sub_f32_e32 v73, v73, v93
	v_mul_f32_e32 v58, v94, v58
	v_mul_f32_e32 v59, v94, v59
	v_mul_f32_e32 v60, v94, v60
	v_mul_f32_e32 v61, v94, v61
	v_mul_f32_e32 v62, v94, v62
	v_mul_f32_e32 v63, v94, v63
	v_mul_f32_e32 v64, v94, v64
	v_mul_f32_e32 v65, v94, v65
	v_mul_f32_e32 v66, v94, v66
	v_mul_f32_e32 v67, v94, v67
	v_mul_f32_e32 v68, v94, v68
	v_mul_f32_e32 v69, v94, v69
	v_mul_f32_e32 v70, v94, v70
	v_mul_f32_e32 v71, v94, v71
	v_mul_f32_e32 v72, v94, v72
	v_mul_f32_e32 v73, v94, v73
	v_fma_f32 v58, v58, v130, v114
	v_fma_f32 v59, v59, v131, v115
	v_fma_f32 v60, v60, v132, v116
	v_fma_f32 v61, v61, v133, v117
	v_fma_f32 v62, v62, v134, v118
	v_fma_f32 v63, v63, v135, v119
	v_fma_f32 v64, v64, v136, v120
	v_fma_f32 v65, v65, v137, v121
	v_fma_f32 v66, v66, v138, v122
	v_fma_f32 v67, v67, v139, v123
	v_fma_f32 v68, v68, v140, v124
	v_fma_f32 v69, v69, v141, v125
	v_fma_f32 v70, v70, v142, v126
	v_fma_f32 v71, v71, v143, v127
	v_fma_f32 v72, v72, v144, v128
	v_fma_f32 v73, v73, v145, v129
	v_cvt_pk_bf16_f32 v190, v58, v59
	v_cvt_pk_bf16_f32 v191, v60, v61
	v_cvt_pk_bf16_f32 v192, v62, v63
	v_cvt_pk_bf16_f32 v193, v64, v65
	v_cvt_pk_bf16_f32 v194, v66, v67
	v_cvt_pk_bf16_f32 v195, v68, v69
	v_cvt_pk_bf16_f32 v196, v70, v71
	v_cvt_pk_bf16_f32 v197, v72, v73
	s_add_u32 s2, s10, 0x2800
	s_addc_u32 s3, s11, 0
	global_store_dwordx2 v1, v[190:191], s[2:3]
	global_store_dwordx2 v1, v[192:193], s[2:3] offset:512
	global_store_dwordx2 v1, v[194:195], s[2:3] offset:1024
	global_store_dwordx2 v1, v[196:197], s[2:3] offset:1536
	s_waitcnt vmcnt(23)
	v_add_f32_e32 v9, v74, v75
	v_add_f32_e32 v91, v76, v77
	v_mul_f32_e32 v90, v74, v74
	v_mul_f32_e32 v92, v75, v75
	v_add_f32_e32 v9, v9, v78
	v_add_f32_e32 v91, v91, v79
	v_add_f32_e32 v9, v9, v80
	v_add_f32_e32 v91, v91, v81
	v_add_f32_e32 v9, v9, v82
	v_add_f32_e32 v91, v91, v83
	v_add_f32_e32 v9, v9, v84
	v_add_f32_e32 v91, v91, v85
	v_add_f32_e32 v9, v9, v86
	v_add_f32_e32 v91, v91, v87
	v_add_f32_e32 v9, v9, v88
	v_add_f32_e32 v91, v91, v89
	v_fmac_f32_e32 v90, v76, v76
	v_fmac_f32_e32 v92, v77, v77
	v_fmac_f32_e32 v90, v78, v78
	v_fmac_f32_e32 v92, v79, v79
	v_fmac_f32_e32 v90, v80, v80
	v_fmac_f32_e32 v92, v81, v81
	v_fmac_f32_e32 v90, v82, v82
	v_fmac_f32_e32 v92, v83, v83
	v_fmac_f32_e32 v90, v84, v84
	v_fmac_f32_e32 v92, v85, v85
	v_fmac_f32_e32 v90, v86, v86
	v_fmac_f32_e32 v92, v87, v87
	v_fmac_f32_e32 v90, v88, v88
	v_fmac_f32_e32 v92, v89, v89
	v_add_f32_e32 v9, v9, v91
	v_add_f32_e32 v90, v90, v92
	s_nop 1
	v_add_f32_dpp v9, v9, v9 quad_perm:[1,0,3,2] row_mask:0xf bank_mask:0xf
	v_add_f32_dpp v90, v90, v90 quad_perm:[1,0,3,2] row_mask:0xf bank_mask:0xf
	s_nop 0
	v_add_f32_dpp v9, v9, v9 quad_perm:[2,3,0,1] row_mask:0xf bank_mask:0xf
	v_add_f32_dpp v90, v90, v90 quad_perm:[2,3,0,1] row_mask:0xf bank_mask:0xf
	s_nop 0
	v_add_f32_dpp v9, v9, v9 row_half_mirror row_mask:0xf bank_mask:0xf
	v_add_f32_dpp v90, v90, v90 row_half_mirror row_mask:0xf bank_mask:0xf
	s_nop 0
	v_add_f32_dpp v9, v9, v9 row_mirror row_mask:0xf bank_mask:0xf
	v_add_f32_dpp v90, v90, v90 row_mirror row_mask:0xf bank_mask:0xf
	s_nop 0
	v_add_f32_dpp v9, v9, v9 row_bcast:15 row_mask:0xa bank_mask:0xf
	v_add_f32_dpp v90, v90, v90 row_bcast:15 row_mask:0xa bank_mask:0xf
	s_nop 0
	v_add_f32_dpp v9, v9, v9 row_bcast:31 row_mask:0xc bank_mask:0xf
	v_add_f32_dpp v90, v90, v90 row_bcast:31 row_mask:0xc bank_mask:0xf
	s_nop 0
	v_readlane_b32 s2, v9, 63
	v_readlane_b32 s3, v90, 63
	s_nop 1
	v_mov_b32_e32 v9, s2
	v_mov_b32_e32 v90, s3
	v_mul_f32_e32 v93, 0x3a800000, v9
	v_mul_f32_e32 v91, 0x3a800000, v90
	v_fma_f32 v91, -v93, v93, v91
	v_max_f32_e32 v91, 0, v91
	v_add_f32_e32 v91, 0x358637bd, v91
	v_rsq_f32_e32 v94, v91
	v_mul_f32_e32 v91, 0.5, v91
	v_mul_f32_e32 v92, v94, v94
	v_fma_f32 v92, -v91, v92, 0.5
	v_fma_f32 v94, v94, v92, v94
	s_add_u32 s2, s12, 0x30
	s_addc_u32 s3, s13, 0
	v_mov_b32_e32 v188, v93
	v_mov_b32_e32 v189, v94
	s_mov_b64 exec, 1
	global_store_dwordx2 v97, v[188:189], s[2:3]
	s_mov_b64 exec, -1
	v_sub_f32_e32 v74, v74, v93
	v_sub_f32_e32 v75, v75, v93
	v_sub_f32_e32 v76, v76, v93
	v_sub_f32_e32 v77, v77, v93
	v_sub_f32_e32 v78, v78, v93
	v_sub_f32_e32 v79, v79, v93
	v_sub_f32_e32 v80, v80, v93
	v_sub_f32_e32 v81, v81, v93
	v_sub_f32_e32 v82, v82, v93
	v_sub_f32_e32 v83, v83, v93
	v_sub_f32_e32 v84, v84, v93
	v_sub_f32_e32 v85, v85, v93
	v_sub_f32_e32 v86, v86, v93
	v_sub_f32_e32 v87, v87, v93
	v_sub_f32_e32 v88, v88, v93
	v_sub_f32_e32 v89, v89, v93
	v_mul_f32_e32 v74, v94, v74
	v_mul_f32_e32 v75, v94, v75
	v_mul_f32_e32 v76, v94, v76
	v_mul_f32_e32 v77, v94, v77
	v_mul_f32_e32 v78, v94, v78
	v_mul_f32_e32 v79, v94, v79
	v_mul_f32_e32 v80, v94, v80
	v_mul_f32_e32 v81, v94, v81
	v_mul_f32_e32 v82, v94, v82
	v_mul_f32_e32 v83, v94, v83
	v_mul_f32_e32 v84, v94, v84
; DI unsigned pk2(float lo, float hi) { f32x2 v = {lo, hi}; bf16x2_t b = __builtin_convertvector(v, bf16x2_t); return __builtin_bit_cast(unsigned, b); }
; DI void ln_row_v(const Frame& F, f32x4 (&v)[4], float* xout, const float* g, const float* b, const float* sh, const float* sc, bf16_t* hout, const float* slab, const float* gres, float* stat = nullptr) {
;     ...
;         for (int j = 0; j < 4; ++j) { const f32x4 gg = ((const f32x4*)g)[F.lane + 64 * j], bb = ((const f32x4*)b)[F.lane + 64 * j];
;             v[j] = (v[j] - mean) * rstd * gg + bb; if (xout) ((f32x4*)xout)[F.lane + 64 * j] = v[j]; }
;     }
;     if (hout) {
;         float s = 0.f, s2 = 0.f;
; #pragma unroll
;         for (int j = 0; j < 4; ++j) { s += (v[j][0] + v[j][1]) + (v[j][2] + v[j][3]); s2 += (v[j][0] * v[j][0] + v[j][1] * v[j][1]) + (v[j][2] * v[j][2] + v[j][3] * v[j][3]); }
;         wave_sum2(s, s2, F.lane);
;         const float mean = s * (1.f / D); const float rstd = 1.f / sqrtf(fmaxf(s2 * (1.f / D) - mean * mean, 0.f) + EPS);
; #pragma unroll
;         for (int j = 0; j < 4; ++j) { const f32x4 hh = ((const f32x4*)sh)[F.lane + 64 * j], cc = ((const f32x4*)sc)[F.lane + 64 * j];
;             const f32x4 o = (v[j] - mean) * rstd * (cc + 1.f) + hh; u32x2 wv; wv.x = pk2(o[0], o[1]); wv.y = pk2(o[2], o[3]);
;             ((u32x2*)hout)[F.lane + 64 * j] = wv; }
;     }
	v_mul_f32_e32 v85, v94, v85
	v_mul_f32_e32 v86, v94, v86
	v_mul_f32_e32 v87, v94, v87
	v_mul_f32_e32 v88, v94, v88
	v_mul_f32_e32 v89, v94, v89
	v_fma_f32 v74, v74, v10, v26
	v_fma_f32 v75, v75, v11, v27
	v_fma_f32 v76, v76, v12, v28
	v_fma_f32 v77, v77, v13, v29
	v_fma_f32 v78, v78, v14, v30
	v_fma_f32 v79, v79, v15, v31
	v_fma_f32 v80, v80, v16, v32
	v_fma_f32 v81, v81, v17, v33
	v_fma_f32 v82, v82, v18, v34
	v_fma_f32 v83, v83, v19, v35
	v_fma_f32 v84, v84, v20, v36
	v_fma_f32 v85, v85, v21, v37
	v_fma_f32 v86, v86, v22, v38
	v_fma_f32 v87, v87, v23, v39
	v_fma_f32 v88, v88, v24, v40
	v_fma_f32 v89, v89, v25, v41
	v_add_f32_e32 v9, v74, v75
	v_add_f32_e32 v91, v76, v77
	v_mul_f32_e32 v90, v74, v74
	v_mul_f32_e32 v92, v75, v75
	v_add_f32_e32 v9, v9, v78
	v_add_f32_e32 v91, v91, v79
	v_add_f32_e32 v9, v9, v80
	v_add_f32_e32 v91, v91, v81
	v_add_f32_e32 v9, v9, v82
	v_add_f32_e32 v91, v91, v83
	v_add_f32_e32 v9, v9, v84
	v_add_f32_e32 v91, v91, v85
	v_add_f32_e32 v9, v9, v86
	v_add_f32_e32 v91, v91, v87
	v_add_f32_e32 v9, v9, v88
	v_add_f32_e32 v91, v91, v89
	v_fmac_f32_e32 v90, v76, v76
	v_fmac_f32_e32 v92, v77, v77
	v_fmac_f32_e32 v90, v78, v78
	v_fmac_f32_e32 v92, v79, v79
	v_fmac_f32_e32 v90, v80, v80
	v_fmac_f32_e32 v92, v81, v81
	v_fmac_f32_e32 v90, v82, v82
	v_fmac_f32_e32 v92, v83, v83
	v_fmac_f32_e32 v90, v84, v84
	v_fmac_f32_e32 v92, v85, v85
	v_fmac_f32_e32 v90, v86, v86
	v_fmac_f32_e32 v92, v87, v87
	v_fmac_f32_e32 v90, v88, v88
	v_fmac_f32_e32 v92, v89, v89
	v_add_f32_e32 v9, v9, v91
	v_add_f32_e32 v90, v90, v92
	s_nop 1
	v_add_f32_dpp v9, v9, v9 quad_perm:[1,0,3,2] row_mask:0xf bank_mask:0xf
	v_add_f32_dpp v90, v90, v90 quad_perm:[1,0,3,2] row_mask:0xf bank_mask:0xf
	s_nop 0
	v_add_f32_dpp v9, v9, v9 quad_perm:[2,3,0,1] row_mask:0xf bank_mask:0xf
	v_add_f32_dpp v90, v90, v90 quad_perm:[2,3,0,1] row_mask:0xf bank_mask:0xf
	s_nop 0
	v_add_f32_dpp v9, v9, v9 row_half_mirror row_mask:0xf bank_mask:0xf
	v_add_f32_dpp v90, v90, v90 row_half_mirror row_mask:0xf bank_mask:0xf
	s_nop 0
	v_add_f32_dpp v9, v9, v9 row_mirror row_mask:0xf bank_mask:0xf
	v_add_f32_dpp v90, v90, v90 row_mirror row_mask:0xf bank_mask:0xf
	s_nop 0
	v_add_f32_dpp v9, v9, v9 row_bcast:15 row_mask:0xa bank_mask:0xf
	v_add_f32_dpp v90, v90, v90 row_bcast:15 row_mask:0xa bank_mask:0xf
	s_nop 0
	v_add_f32_dpp v9, v9, v9 row_bcast:31 row_mask:0xc bank_mask:0xf
	v_add_f32_dpp v90, v90, v90 row_bcast:31 row_mask:0xc bank_mask:0xf
	s_nop 0
	v_readlane_b32 s2, v9, 63
	v_readlane_b32 s3, v90, 63
	s_nop 1
	v_mov_b32_e32 v9, s2
	v_mov_b32_e32 v90, s3
	v_mul_f32_e32 v93, 0x3a800000, v9
	v_mul_f32_e32 v91, 0x3a800000, v90
	v_fma_f32 v91, -v93, v93, v91
	v_max_f32_e32 v91, 0, v91
	v_add_f32_e32 v91, 0x358637bd, v91
	v_rsq_f32_e32 v94, v91
	v_mul_f32_e32 v91, 0.5, v91
	v_mul_f32_e32 v92, v94, v94
	v_fma_f32 v92, -v91, v92, 0.5
	v_fma_f32 v94, v94, v92, v94
	v_sub_f32_e32 v74, v74, v93
	v_sub_f32_e32 v75, v75, v93
	v_sub_f32_e32 v76, v76, v93
	v_sub_f32_e32 v77, v77, v93
	v_sub_f32_e32 v78, v78, v93
	v_sub_f32_e32 v79, v79, v93
	v_sub_f32_e32 v80, v80, v93
	v_sub_f32_e32 v81, v81, v93
	v_sub_f32_e32 v82, v82, v93
	v_sub_f32_e32 v83, v83, v93
	v_sub_f32_e32 v84, v84, v93
	v_sub_f32_e32 v85, v85, v93
	v_sub_f32_e32 v86, v86, v93
	v_sub_f32_e32 v87, v87, v93
	v_sub_f32_e32 v88, v88, v93
	v_sub_f32_e32 v89, v89, v93
	v_mul_f32_e32 v74, v94, v74
	v_mul_f32_e32 v75, v94, v75
	v_mul_f32_e32 v76, v94, v76
	v_mul_f32_e32 v77, v94, v77
	v_mul_f32_e32 v78, v94, v78
	v_mul_f32_e32 v79, v94, v79
	v_mul_f32_e32 v80, v94, v80
	v_mul_f32_e32 v81, v94, v81
	v_mul_f32_e32 v82, v94, v82
	v_mul_f32_e32 v83, v94, v83
	v_mul_f32_e32 v84, v94, v84
	v_mul_f32_e32 v85, v94, v85
	v_mul_f32_e32 v86, v94, v86
	v_mul_f32_e32 v87, v94, v87
	v_mul_f32_e32 v88, v94, v88
	v_mul_f32_e32 v89, v94, v89
	v_fma_f32 v74, v74, v130, v114
	v_fma_f32 v75, v75, v131, v115
	v_fma_f32 v76, v76, v132, v116
	v_fma_f32 v77, v77, v133, v117
	v_fma_f32 v78, v78, v134, v118
	v_fma_f32 v79, v79, v135, v119
	v_fma_f32 v80, v80, v136, v120
	v_fma_f32 v81, v81, v137, v121
	v_fma_f32 v82, v82, v138, v122
	v_fma_f32 v83, v83, v139, v123
	v_fma_f32 v84, v84, v140, v124
	v_fma_f32 v85, v85, v141, v125
	v_fma_f32 v86, v86, v142, v126
	v_fma_f32 v87, v87, v143, v127
	v_fma_f32 v88, v88, v144, v128
	v_fma_f32 v89, v89, v145, v129
	v_cvt_pk_bf16_f32 v190, v74, v75
	v_cvt_pk_bf16_f32 v191, v76, v77
	v_cvt_pk_bf16_f32 v192, v78, v79
	v_cvt_pk_bf16_f32 v193, v80, v81
	v_cvt_pk_bf16_f32 v194, v82, v83
	v_cvt_pk_bf16_f32 v195, v84, v85
	v_cvt_pk_bf16_f32 v196, v86, v87
	v_cvt_pk_bf16_f32 v197, v88, v89
	s_add_u32 s2, s10, 0x3000
	s_addc_u32 s3, s11, 0
	global_store_dwordx2 v1, v[190:191], s[2:3]
	global_store_dwordx2 v1, v[192:193], s[2:3] offset:512
	global_store_dwordx2 v1, v[194:195], s[2:3] offset:1024
	global_store_dwordx2 v1, v[196:197], s[2:3] offset:1536
	s_waitcnt vmcnt(19)
; DI void ln_row_v(const Frame& F, f32x4 (&v)[4], float* xout, const float* g, const float* b, const float* sh, const float* sc, bf16_t* hout, const float* slab, const float* gres, float* stat = nullptr) {
;     ...
;     if (g) {
;         float s = 0.f, s2 = 0.f;
; #pragma unroll
;         for (int j = 0; j < 4; ++j) { s += (v[j][0] + v[j][1]) + (v[j][2] + v[j][3]); s2 += (v[j][0] * v[j][0] + v[j][1] * v[j][1]) + (v[j][2] * v[j][2] + v[j][3] * v[j][3]); }
;         wave_sum2(s, s2, F.lane);
;         const float mean = s * (1.f / D); const float rstd = 1.f / sqrtf(fmaxf(s2 * (1.f / D) - mean * mean, 0.f) + EPS);
;         if (stat && F.lane == 0) { f32x2 sv = {mean, rstd}; *(f32x2*)stat = sv; }
; #pragma unroll
;         for (int j = 0; j < 4; ++j) { const f32x4 gg = ((const f32x4*)g)[F.lane + 64 * j], bb = ((const f32x4*)b)[F.lane + 64 * j];
;             v[j] = (v[j] - mean) * rstd * gg + bb; if (xout) ((f32x4*)xout)[F.lane + 64 * j] = v[j]; }
;     }
;     if (hout) {
;         float s = 0.f, s2 = 0.f;
; #pragma unroll
;         for (int j = 0; j < 4; ++j) { s += (v[j][0] + v[j][1]) + (v[j][2] + v[j][3]); s2 += (v[j][0] * v[j][0] + v[j][1] * v[j][1]) + (v[j][2] * v[j][2] + v[j][3] * v[j][3]); }
;         wave_sum2(s, s2, F.lane);
;         const float mean = s * (1.f / D); const float rstd = 1.f / sqrtf(fmaxf(s2 * (1.f / D) - mean * mean, 0.f) + EPS);
	v_add_f32_e32 v9, v98, v99
	v_add_f32_e32 v91, v100, v101
	v_mul_f32_e32 v90, v98, v98
	v_mul_f32_e32 v92, v99, v99
	v_add_f32_e32 v9, v9, v102
	v_add_f32_e32 v91, v91, v103
	v_add_f32_e32 v9, v9, v104
	v_add_f32_e32 v91, v91, v105
	v_add_f32_e32 v9, v9, v106
	v_add_f32_e32 v91, v91, v107
	v_add_f32_e32 v9, v9, v108
	v_add_f32_e32 v91, v91, v109
	v_add_f32_e32 v9, v9, v110
	v_add_f32_e32 v91, v91, v111
	v_add_f32_e32 v9, v9, v112
	v_add_f32_e32 v91, v91, v113
	v_fmac_f32_e32 v90, v100, v100
	v_fmac_f32_e32 v92, v101, v101
	v_fmac_f32_e32 v90, v102, v102
	v_fmac_f32_e32 v92, v103, v103
	v_fmac_f32_e32 v90, v104, v104
	v_fmac_f32_e32 v92, v105, v105
	v_fmac_f32_e32 v90, v106, v106
	v_fmac_f32_e32 v92, v107, v107
	v_fmac_f32_e32 v90, v108, v108
	v_fmac_f32_e32 v92, v109, v109
	v_fmac_f32_e32 v90, v110, v110
	v_fmac_f32_e32 v92, v111, v111
	v_fmac_f32_e32 v90, v112, v112
	v_fmac_f32_e32 v92, v113, v113
	v_add_f32_e32 v9, v9, v91
	v_add_f32_e32 v90, v90, v92
	s_nop 1
	v_add_f32_dpp v9, v9, v9 quad_perm:[1,0,3,2] row_mask:0xf bank_mask:0xf
	v_add_f32_dpp v90, v90, v90 quad_perm:[1,0,3,2] row_mask:0xf bank_mask:0xf
	s_nop 0
	v_add_f32_dpp v9, v9, v9 quad_perm:[2,3,0,1] row_mask:0xf bank_mask:0xf
	v_add_f32_dpp v90, v90, v90 quad_perm:[2,3,0,1] row_mask:0xf bank_mask:0xf
	s_nop 0
	v_add_f32_dpp v9, v9, v9 row_half_mirror row_mask:0xf bank_mask:0xf
	v_add_f32_dpp v90, v90, v90 row_half_mirror row_mask:0xf bank_mask:0xf
	s_nop 0
	v_add_f32_dpp v9, v9, v9 row_mirror row_mask:0xf bank_mask:0xf
	v_add_f32_dpp v90, v90, v90 row_mirror row_mask:0xf bank_mask:0xf
	s_nop 0
	v_add_f32_dpp v9, v9, v9 row_bcast:15 row_mask:0xa bank_mask:0xf
	v_add_f32_dpp v90, v90, v90 row_bcast:15 row_mask:0xa bank_mask:0xf
	s_nop 0
	v_add_f32_dpp v9, v9, v9 row_bcast:31 row_mask:0xc bank_mask:0xf
	v_add_f32_dpp v90, v90, v90 row_bcast:31 row_mask:0xc bank_mask:0xf
	s_nop 0
	v_readlane_b32 s2, v9, 63
	v_readlane_b32 s3, v90, 63
	s_nop 1
	v_mov_b32_e32 v9, s2
	v_mov_b32_e32 v90, s3
	v_mul_f32_e32 v93, 0x3a800000, v9
	v_mul_f32_e32 v91, 0x3a800000, v90
	v_fma_f32 v91, -v93, v93, v91
	v_max_f32_e32 v91, 0, v91
	v_add_f32_e32 v91, 0x358637bd, v91
	v_rsq_f32_e32 v94, v91
	v_mul_f32_e32 v91, 0.5, v91
	v_mul_f32_e32 v92, v94, v94
	v_fma_f32 v92, -v91, v92, 0.5
	v_fma_f32 v94, v94, v92, v94
	s_add_u32 s2, s12, 0x38
	s_addc_u32 s3, s13, 0
	v_mov_b32_e32 v188, v93
	v_mov_b32_e32 v189, v94
	s_mov_b64 exec, 1
	global_store_dwordx2 v97, v[188:189], s[2:3]
	s_mov_b64 exec, -1
	v_sub_f32_e32 v98, v98, v93
	v_sub_f32_e32 v99, v99, v93
	v_sub_f32_e32 v100, v100, v93
	v_sub_f32_e32 v101, v101, v93
	v_sub_f32_e32 v102, v102, v93
	v_sub_f32_e32 v103, v103, v93
	v_sub_f32_e32 v104, v104, v93
	v_sub_f32_e32 v105, v105, v93
	v_sub_f32_e32 v106, v106, v93
	v_sub_f32_e32 v107, v107, v93
	v_sub_f32_e32 v108, v108, v93
	v_sub_f32_e32 v109, v109, v93
	v_sub_f32_e32 v110, v110, v93
	v_sub_f32_e32 v111, v111, v93
	v_sub_f32_e32 v112, v112, v93
	v_sub_f32_e32 v113, v113, v93
	v_mul_f32_e32 v98, v94, v98
	v_mul_f32_e32 v99, v94, v99
	v_mul_f32_e32 v100, v94, v100
	v_mul_f32_e32 v101, v94, v101
	v_mul_f32_e32 v102, v94, v102
	v_mul_f32_e32 v103, v94, v103
	v_mul_f32_e32 v104, v94, v104
	v_mul_f32_e32 v105, v94, v105
	v_mul_f32_e32 v106, v94, v106
	v_mul_f32_e32 v107, v94, v107
	v_mul_f32_e32 v108, v94, v108
	v_mul_f32_e32 v109, v94, v109
	v_mul_f32_e32 v110, v94, v110
	v_mul_f32_e32 v111, v94, v111
	v_mul_f32_e32 v112, v94, v112
	v_mul_f32_e32 v113, v94, v113
	v_fma_f32 v98, v98, v10, v26
	v_fma_f32 v99, v99, v11, v27
	v_fma_f32 v100, v100, v12, v28
	v_fma_f32 v101, v101, v13, v29
	v_fma_f32 v102, v102, v14, v30
	v_fma_f32 v103, v103, v15, v31
	v_fma_f32 v104, v104, v16, v32
	v_fma_f32 v105, v105, v17, v33
	v_fma_f32 v106, v106, v18, v34
	v_fma_f32 v107, v107, v19, v35
	v_fma_f32 v108, v108, v20, v36
	v_fma_f32 v109, v109, v21, v37
	v_fma_f32 v110, v110, v22, v38
	v_fma_f32 v111, v111, v23, v39
	v_fma_f32 v112, v112, v24, v40
	v_fma_f32 v113, v113, v25, v41
	v_add_f32_e32 v9, v98, v99
	v_add_f32_e32 v91, v100, v101
	v_mul_f32_e32 v90, v98, v98
	v_mul_f32_e32 v92, v99, v99
	v_add_f32_e32 v9, v9, v102
	v_add_f32_e32 v91, v91, v103
	v_add_f32_e32 v9, v9, v104
	v_add_f32_e32 v91, v91, v105
	v_add_f32_e32 v9, v9, v106
	v_add_f32_e32 v91, v91, v107
	v_add_f32_e32 v9, v9, v108
	v_add_f32_e32 v91, v91, v109
	v_add_f32_e32 v9, v9, v110
	v_add_f32_e32 v91, v91, v111
	v_add_f32_e32 v9, v9, v112
	v_add_f32_e32 v91, v91, v113
	v_fmac_f32_e32 v90, v100, v100
	v_fmac_f32_e32 v92, v101, v101
	v_fmac_f32_e32 v90, v102, v102
	v_fmac_f32_e32 v92, v103, v103
	v_fmac_f32_e32 v90, v104, v104
	v_fmac_f32_e32 v92, v105, v105
	v_fmac_f32_e32 v90, v106, v106
	v_fmac_f32_e32 v92, v107, v107
	v_fmac_f32_e32 v90, v108, v108
	v_fmac_f32_e32 v92, v109, v109
	v_fmac_f32_e32 v90, v110, v110
	v_fmac_f32_e32 v92, v111, v111
	v_fmac_f32_e32 v90, v112, v112
	v_fmac_f32_e32 v92, v113, v113
	v_add_f32_e32 v9, v9, v91
	v_add_f32_e32 v90, v90, v92
	s_nop 1
	v_add_f32_dpp v9, v9, v9 quad_perm:[1,0,3,2] row_mask:0xf bank_mask:0xf
	v_add_f32_dpp v90, v90, v90 quad_perm:[1,0,3,2] row_mask:0xf bank_mask:0xf
	s_nop 0
	v_add_f32_dpp v9, v9, v9 quad_perm:[2,3,0,1] row_mask:0xf bank_mask:0xf
	v_add_f32_dpp v90, v90, v90 quad_perm:[2,3,0,1] row_mask:0xf bank_mask:0xf
	s_nop 0
	v_add_f32_dpp v9, v9, v9 row_half_mirror row_mask:0xf bank_mask:0xf
	v_add_f32_dpp v90, v90, v90 row_half_mirror row_mask:0xf bank_mask:0xf
	s_nop 0
	v_add_f32_dpp v9, v9, v9 row_mirror row_mask:0xf bank_mask:0xf
	v_add_f32_dpp v90, v90, v90 row_mirror row_mask:0xf bank_mask:0xf
	s_nop 0
	v_add_f32_dpp v9, v9, v9 row_bcast:15 row_mask:0xa bank_mask:0xf
; DI unsigned pk2(float lo, float hi) { f32x2 v = {lo, hi}; bf16x2_t b = __builtin_convertvector(v, bf16x2_t); return __builtin_bit_cast(unsigned, b); }
; DI void ln_row_v(const Frame& F, f32x4 (&v)[4], float* xout, const float* g, const float* b, const float* sh, const float* sc, bf16_t* hout, const float* slab, const float* gres, float* stat = nullptr) {
;     if (slab) {
; #pragma unroll
;         for (int j = 0; j < 4; ++j) { f32x4 a = ((const f32x4*)slab)[F.lane + 64 * j];
; #pragma unroll
;             for (int z = 1; z < 8; ++z) a += ((const f32x4*)(slab + (size_t)z * MC * 1024))[F.lane + 64 * j];
;             v[j] = v[j] * ALPHA + ((const f32x4*)gres)[F.lane + 64 * j] * a; }
;     ...
;         const float mean = s * (1.f / D); const float rstd = 1.f / sqrtf(fmaxf(s2 * (1.f / D) - mean * mean, 0.f) + EPS);
; #pragma unroll
;         for (int j = 0; j < 4; ++j) { const f32x4 hh = ((const f32x4*)sh)[F.lane + 64 * j], cc = ((const f32x4*)sc)[F.lane + 64 * j];
;             const f32x4 o = (v[j] - mean) * rstd * (cc + 1.f) + hh; u32x2 wv; wv.x = pk2(o[0], o[1]); wv.y = pk2(o[2], o[3]);
;             ((u32x2*)hout)[F.lane + 64 * j] = wv; }
;     }
	v_add_f32_dpp v90, v90, v90 row_bcast:15 row_mask:0xa bank_mask:0xf
	s_nop 0
	v_add_f32_dpp v9, v9, v9 row_bcast:31 row_mask:0xc bank_mask:0xf
	v_add_f32_dpp v90, v90, v90 row_bcast:31 row_mask:0xc bank_mask:0xf
	s_nop 0
	v_readlane_b32 s2, v9, 63
	v_readlane_b32 s3, v90, 63
	s_nop 1
	v_mov_b32_e32 v9, s2
	v_mov_b32_e32 v90, s3
	v_mul_f32_e32 v93, 0x3a800000, v9
	v_mul_f32_e32 v91, 0x3a800000, v90
	v_fma_f32 v91, -v93, v93, v91
	v_max_f32_e32 v91, 0, v91
	v_add_f32_e32 v91, 0x358637bd, v91
	v_rsq_f32_e32 v94, v91
	v_mul_f32_e32 v91, 0.5, v91
	v_mul_f32_e32 v92, v94, v94
	v_fma_f32 v92, -v91, v92, 0.5
	v_fma_f32 v94, v94, v92, v94
	v_sub_f32_e32 v98, v98, v93
	v_sub_f32_e32 v99, v99, v93
	v_sub_f32_e32 v100, v100, v93
	v_sub_f32_e32 v101, v101, v93
	v_sub_f32_e32 v102, v102, v93
	v_sub_f32_e32 v103, v103, v93
	v_sub_f32_e32 v104, v104, v93
	v_sub_f32_e32 v105, v105, v93
	v_sub_f32_e32 v106, v106, v93
	v_sub_f32_e32 v107, v107, v93
	v_sub_f32_e32 v108, v108, v93
	v_sub_f32_e32 v109, v109, v93
	v_sub_f32_e32 v110, v110, v93
	v_sub_f32_e32 v111, v111, v93
	v_sub_f32_e32 v112, v112, v93
	v_sub_f32_e32 v113, v113, v93
	v_mul_f32_e32 v98, v94, v98
	v_mul_f32_e32 v99, v94, v99
	v_mul_f32_e32 v100, v94, v100
	v_mul_f32_e32 v101, v94, v101
	v_mul_f32_e32 v102, v94, v102
	v_mul_f32_e32 v103, v94, v103
	v_mul_f32_e32 v104, v94, v104
	v_mul_f32_e32 v105, v94, v105
	v_mul_f32_e32 v106, v94, v106
	v_mul_f32_e32 v107, v94, v107
	v_mul_f32_e32 v108, v94, v108
	v_mul_f32_e32 v109, v94, v109
	v_mul_f32_e32 v110, v94, v110
	v_mul_f32_e32 v111, v94, v111
	v_mul_f32_e32 v112, v94, v112
	v_mul_f32_e32 v113, v94, v113
	v_fma_f32 v98, v98, v130, v114
	v_fma_f32 v99, v99, v131, v115
	v_fma_f32 v100, v100, v132, v116
	v_fma_f32 v101, v101, v133, v117
	v_fma_f32 v102, v102, v134, v118
	v_fma_f32 v103, v103, v135, v119
	v_fma_f32 v104, v104, v136, v120
	v_fma_f32 v105, v105, v137, v121
	v_fma_f32 v106, v106, v138, v122
	v_fma_f32 v107, v107, v139, v123
	v_fma_f32 v108, v108, v140, v124
	v_fma_f32 v109, v109, v141, v125
	v_fma_f32 v110, v110, v142, v126
	v_fma_f32 v111, v111, v143, v127
	v_fma_f32 v112, v112, v144, v128
	v_fma_f32 v113, v113, v145, v129
	v_cvt_pk_bf16_f32 v190, v98, v99
	v_cvt_pk_bf16_f32 v191, v100, v101
	v_cvt_pk_bf16_f32 v192, v102, v103
	v_cvt_pk_bf16_f32 v193, v104, v105
	v_cvt_pk_bf16_f32 v194, v106, v107
	v_cvt_pk_bf16_f32 v195, v108, v109
	v_cvt_pk_bf16_f32 v196, v110, v111
	v_cvt_pk_bf16_f32 v197, v112, v113
	s_add_u32 s2, s10, 0x3800
	s_addc_u32 s3, s11, 0
	global_store_dwordx2 v1, v[190:191], s[2:3]
	global_store_dwordx2 v1, v[192:193], s[2:3] offset:512
	global_store_dwordx2 v1, v[194:195], s[2:3] offset:1024
	global_store_dwordx2 v1, v[196:197], s[2:3] offset:1536
	s_cmp_eq_u32 s22, 3
	s_cbranch_scc1 .Lln_b_noctx
	s_add_u32 s2, s24, 0x0
	s_addc_u32 s3, s25, 0
	global_load_dwordx4 v[58:61], v0, s[2:3]
	global_load_dwordx4 v[62:65], v0, s[2:3] offset:1024
	global_load_dwordx4 v[66:69], v0, s[2:3] offset:2048
	global_load_dwordx4 v[70:73], v0, s[2:3] offset:3072
	s_add_u32 s2, s24, 0x800000
	s_addc_u32 s3, s25, 0
	global_load_dwordx4 v[74:77], v0, s[2:3]
	global_load_dwordx4 v[78:81], v0, s[2:3] offset:1024
	global_load_dwordx4 v[82:85], v0, s[2:3] offset:2048
	global_load_dwordx4 v[86:89], v0, s[2:3] offset:3072
	s_add_u32 s2, s24, 0x1000000
	s_addc_u32 s3, s25, 0
	global_load_dwordx4 v[98:101], v0, s[2:3]
	global_load_dwordx4 v[102:105], v0, s[2:3] offset:1024
	global_load_dwordx4 v[106:109], v0, s[2:3] offset:2048
	global_load_dwordx4 v[110:113], v0, s[2:3] offset:3072
	s_add_u32 s2, s24, 0x1800000
	s_addc_u32 s3, s25, 0
	global_load_dwordx4 v[146:149], v0, s[2:3]
	global_load_dwordx4 v[150:153], v0, s[2:3] offset:1024
	global_load_dwordx4 v[154:157], v0, s[2:3] offset:2048
	global_load_dwordx4 v[158:161], v0, s[2:3] offset:3072
	s_add_u32 s2, s24, 0x2000000
	s_addc_u32 s3, s25, 0
	global_load_dwordx4 v[162:165], v0, s[2:3]
	global_load_dwordx4 v[166:169], v0, s[2:3] offset:1024
	global_load_dwordx4 v[170:173], v0, s[2:3] offset:2048
	global_load_dwordx4 v[174:177], v0, s[2:3] offset:3072
	s_mov_b64 s[2:3], s[26:27]
	global_load_dwordx4 v[226:229], v0, s[2:3]
	global_load_dwordx4 v[230:233], v0, s[2:3] offset:1024
	global_load_dwordx4 v[234:237], v0, s[2:3] offset:2048
	global_load_dwordx4 v[238:241], v0, s[2:3] offset:3072
	s_waitcnt vmcnt(16)
	v_add_f32_e32 v58, v58, v74
	v_add_f32_e32 v59, v59, v75
	v_add_f32_e32 v60, v60, v76
	v_add_f32_e32 v61, v61, v77
	v_add_f32_e32 v62, v62, v78
	v_add_f32_e32 v63, v63, v79
	v_add_f32_e32 v64, v64, v80
	v_add_f32_e32 v65, v65, v81
	v_add_f32_e32 v66, v66, v82
	v_add_f32_e32 v67, v67, v83
	v_add_f32_e32 v68, v68, v84
	v_add_f32_e32 v69, v69, v85
	v_add_f32_e32 v70, v70, v86
	v_add_f32_e32 v71, v71, v87
	v_add_f32_e32 v72, v72, v88
	v_add_f32_e32 v73, v73, v89
	s_add_u32 s2, s24, 0x2800000
	s_addc_u32 s3, s25, 0
	global_load_dwordx4 v[74:77], v0, s[2:3]
	global_load_dwordx4 v[78:81], v0, s[2:3] offset:1024
	global_load_dwordx4 v[82:85], v0, s[2:3] offset:2048
	global_load_dwordx4 v[86:89], v0, s[2:3] offset:3072
	s_waitcnt vmcnt(16)
	v_add_f32_e32 v58, v58, v98
	v_add_f32_e32 v59, v59, v99
	v_add_f32_e32 v60, v60, v100
	v_add_f32_e32 v61, v61, v101
	v_add_f32_e32 v62, v62, v102
	v_add_f32_e32 v63, v63, v103
	v_add_f32_e32 v64, v64, v104
	v_add_f32_e32 v65, v65, v105
	v_add_f32_e32 v66, v66, v106
	v_add_f32_e32 v67, v67, v107
	v_add_f32_e32 v68, v68, v108
	v_add_f32_e32 v69, v69, v109
	v_add_f32_e32 v70, v70, v110
	v_add_f32_e32 v71, v71, v111
	v_add_f32_e32 v72, v72, v112
	v_add_f32_e32 v73, v73, v113
	s_add_u32 s2, s24, 0x3000000
	s_addc_u32 s3, s25, 0
	global_load_dwordx4 v[98:101], v0, s[2:3]
	global_load_dwordx4 v[102:105], v0, s[2:3] offset:1024
	global_load_dwordx4 v[106:109], v0, s[2:3] offset:2048
	global_load_dwordx4 v[110:113], v0, s[2:3] offset:3072
	s_waitcnt vmcnt(16)
; DI void ln_row_v(const Frame& F, f32x4 (&v)[4], float* xout, const float* g, const float* b, const float* sh, const float* sc, bf16_t* hout, const float* slab, const float* gres, float* stat = nullptr) {
;     if (slab) {
; #pragma unroll
;         for (int j = 0; j < 4; ++j) { f32x4 a = ((const f32x4*)slab)[F.lane + 64 * j];
; #pragma unroll
;             for (int z = 1; z < 8; ++z) a += ((const f32x4*)(slab + (size_t)z * MC * 1024))[F.lane + 64 * j];
;             v[j] = v[j] * ALPHA + ((const f32x4*)gres)[F.lane + 64 * j] * a; }
;     }
;     if (g) {
;         float s = 0.f, s2 = 0.f;
; #pragma unroll
;         for (int j = 0; j < 4; ++j) { s += (v[j][0] + v[j][1]) + (v[j][2] + v[j][3]); s2 += (v[j][0] * v[j][0] + v[j][1] * v[j][1]) + (v[j][2] * v[j][2] + v[j][3] * v[j][3]); }
;         wave_sum2(s, s2, F.lane);
;         const float mean = s * (1.f / D); const float rstd = 1.f / sqrtf(fmaxf(s2 * (1.f / D) - mean * mean, 0.f) + EPS);
	v_add_f32_e32 v58, v58, v146
	v_add_f32_e32 v59, v59, v147
	v_add_f32_e32 v60, v60, v148
	v_add_f32_e32 v61, v61, v149
	v_add_f32_e32 v62, v62, v150
	v_add_f32_e32 v63, v63, v151
	v_add_f32_e32 v64, v64, v152
	v_add_f32_e32 v65, v65, v153
	v_add_f32_e32 v66, v66, v154
	v_add_f32_e32 v67, v67, v155
	v_add_f32_e32 v68, v68, v156
	v_add_f32_e32 v69, v69, v157
	v_add_f32_e32 v70, v70, v158
	v_add_f32_e32 v71, v71, v159
	v_add_f32_e32 v72, v72, v160
	v_add_f32_e32 v73, v73, v161
	s_add_u32 s2, s24, 0x3800000
	s_addc_u32 s3, s25, 0
	global_load_dwordx4 v[146:149], v0, s[2:3]
	global_load_dwordx4 v[150:153], v0, s[2:3] offset:1024
	global_load_dwordx4 v[154:157], v0, s[2:3] offset:2048
	global_load_dwordx4 v[158:161], v0, s[2:3] offset:3072
	s_waitcnt vmcnt(16)
	v_add_f32_e32 v58, v58, v162
	v_add_f32_e32 v59, v59, v163
	v_add_f32_e32 v60, v60, v164
	v_add_f32_e32 v61, v61, v165
	v_add_f32_e32 v62, v62, v166
	v_add_f32_e32 v63, v63, v167
	v_add_f32_e32 v64, v64, v168
	v_add_f32_e32 v65, v65, v169
	v_add_f32_e32 v66, v66, v170
	v_add_f32_e32 v67, v67, v171
	v_add_f32_e32 v68, v68, v172
	v_add_f32_e32 v69, v69, v173
	v_add_f32_e32 v70, v70, v174
	v_add_f32_e32 v71, v71, v175
	v_add_f32_e32 v72, v72, v176
	v_add_f32_e32 v73, v73, v177
	s_waitcnt vmcnt(8)
	v_add_f32_e32 v58, v58, v74
	v_add_f32_e32 v59, v59, v75
	v_add_f32_e32 v60, v60, v76
	v_add_f32_e32 v61, v61, v77
	v_add_f32_e32 v62, v62, v78
	v_add_f32_e32 v63, v63, v79
	v_add_f32_e32 v64, v64, v80
	v_add_f32_e32 v65, v65, v81
	v_add_f32_e32 v66, v66, v82
	v_add_f32_e32 v67, v67, v83
	v_add_f32_e32 v68, v68, v84
	v_add_f32_e32 v69, v69, v85
	v_add_f32_e32 v70, v70, v86
	v_add_f32_e32 v71, v71, v87
	v_add_f32_e32 v72, v72, v88
	v_add_f32_e32 v73, v73, v89
	s_waitcnt vmcnt(4)
	v_add_f32_e32 v58, v58, v98
	v_add_f32_e32 v59, v59, v99
	v_add_f32_e32 v60, v60, v100
	v_add_f32_e32 v61, v61, v101
	v_add_f32_e32 v62, v62, v102
	v_add_f32_e32 v63, v63, v103
	v_add_f32_e32 v64, v64, v104
	v_add_f32_e32 v65, v65, v105
	v_add_f32_e32 v66, v66, v106
	v_add_f32_e32 v67, v67, v107
	v_add_f32_e32 v68, v68, v108
	v_add_f32_e32 v69, v69, v109
	v_add_f32_e32 v70, v70, v110
	v_add_f32_e32 v71, v71, v111
	v_add_f32_e32 v72, v72, v112
	v_add_f32_e32 v73, v73, v113
	s_waitcnt vmcnt(0)
	v_add_f32_e32 v58, v58, v146
	v_add_f32_e32 v59, v59, v147
	v_add_f32_e32 v60, v60, v148
	v_add_f32_e32 v61, v61, v149
	v_add_f32_e32 v62, v62, v150
	v_add_f32_e32 v63, v63, v151
	v_add_f32_e32 v64, v64, v152
	v_add_f32_e32 v65, v65, v153
	v_add_f32_e32 v66, v66, v154
	v_add_f32_e32 v67, v67, v155
	v_add_f32_e32 v68, v68, v156
	v_add_f32_e32 v69, v69, v157
	v_add_f32_e32 v70, v70, v158
	v_add_f32_e32 v71, v71, v159
	v_add_f32_e32 v72, v72, v160
	v_add_f32_e32 v73, v73, v161
	s_mov_b32 s23, 0x30000
	s_add_u32 s2, s14, s23
	s_addc_u32 s3, s15, 0
	global_load_dwordx4 v[146:149], v0, s[2:3]
	global_load_dwordx4 v[150:153], v0, s[2:3] offset:1024
	global_load_dwordx4 v[154:157], v0, s[2:3] offset:2048
	global_load_dwordx4 v[158:161], v0, s[2:3] offset:3072
	s_add_u32 s2, s18, s23
	s_addc_u32 s3, s19, 0
	global_load_dwordx4 v[162:165], v0, s[2:3]
	global_load_dwordx4 v[166:169], v0, s[2:3] offset:1024
	global_load_dwordx4 v[170:173], v0, s[2:3] offset:2048
	global_load_dwordx4 v[174:177], v0, s[2:3] offset:3072
	v_mul_f32_e32 v42, 0x3fd744fd, v42
	v_mul_f32_e32 v43, 0x3fd744fd, v43
	v_mul_f32_e32 v44, 0x3fd744fd, v44
	v_mul_f32_e32 v45, 0x3fd744fd, v45
	v_mul_f32_e32 v46, 0x3fd744fd, v46
	v_mul_f32_e32 v47, 0x3fd744fd, v47
	v_mul_f32_e32 v48, 0x3fd744fd, v48
	v_mul_f32_e32 v49, 0x3fd744fd, v49
	v_mul_f32_e32 v50, 0x3fd744fd, v50
	v_mul_f32_e32 v51, 0x3fd744fd, v51
	v_mul_f32_e32 v52, 0x3fd744fd, v52
	v_mul_f32_e32 v53, 0x3fd744fd, v53
	v_mul_f32_e32 v54, 0x3fd744fd, v54
	v_mul_f32_e32 v55, 0x3fd744fd, v55
	v_mul_f32_e32 v56, 0x3fd744fd, v56
	v_mul_f32_e32 v57, 0x3fd744fd, v57
	v_fmac_f32_e32 v42, v226, v58
	v_fmac_f32_e32 v43, v227, v59
	v_fmac_f32_e32 v44, v228, v60
	v_fmac_f32_e32 v45, v229, v61
	v_fmac_f32_e32 v46, v230, v62
	v_fmac_f32_e32 v47, v231, v63
	v_fmac_f32_e32 v48, v232, v64
	v_fmac_f32_e32 v49, v233, v65
	v_fmac_f32_e32 v50, v234, v66
	v_fmac_f32_e32 v51, v235, v67
	v_fmac_f32_e32 v52, v236, v68
	v_fmac_f32_e32 v53, v237, v69
	v_fmac_f32_e32 v54, v238, v70
	v_fmac_f32_e32 v55, v239, v71
	v_fmac_f32_e32 v56, v240, v72
	v_fmac_f32_e32 v57, v241, v73
	v_add_f32_e32 v9, v42, v43
	v_add_f32_e32 v91, v44, v45
	v_mul_f32_e32 v90, v42, v42
	v_mul_f32_e32 v92, v43, v43
	v_add_f32_e32 v9, v9, v46
	v_add_f32_e32 v91, v91, v47
	v_add_f32_e32 v9, v9, v48
	v_add_f32_e32 v91, v91, v49
	v_add_f32_e32 v9, v9, v50
	v_add_f32_e32 v91, v91, v51
	v_add_f32_e32 v9, v9, v52
	v_add_f32_e32 v91, v91, v53
	v_add_f32_e32 v9, v9, v54
	v_add_f32_e32 v91, v91, v55
	v_add_f32_e32 v9, v9, v56
	v_add_f32_e32 v91, v91, v57
	v_fmac_f32_e32 v90, v44, v44
	v_fmac_f32_e32 v92, v45, v45
	v_fmac_f32_e32 v90, v46, v46
	v_fmac_f32_e32 v92, v47, v47
	v_fmac_f32_e32 v90, v48, v48
	v_fmac_f32_e32 v92, v49, v49
	v_fmac_f32_e32 v90, v50, v50
	v_fmac_f32_e32 v92, v51, v51
	v_fmac_f32_e32 v90, v52, v52
	v_fmac_f32_e32 v92, v53, v53
	v_fmac_f32_e32 v90, v54, v54
	v_fmac_f32_e32 v92, v55, v55
	v_fmac_f32_e32 v90, v56, v56
	v_fmac_f32_e32 v92, v57, v57
	v_add_f32_e32 v9, v9, v91
	v_add_f32_e32 v90, v90, v92
	s_nop 1
	v_add_f32_dpp v9, v9, v9 quad_perm:[1,0,3,2] row_mask:0xf bank_mask:0xf
	v_add_f32_dpp v90, v90, v90 quad_perm:[1,0,3,2] row_mask:0xf bank_mask:0xf
	s_nop 0
	v_add_f32_dpp v9, v9, v9 quad_perm:[2,3,0,1] row_mask:0xf bank_mask:0xf
	v_add_f32_dpp v90, v90, v90 quad_perm:[2,3,0,1] row_mask:0xf bank_mask:0xf
	s_nop 0
	v_add_f32_dpp v9, v9, v9 row_half_mirror row_mask:0xf bank_mask:0xf
; DI void ln_row_v(const Frame& F, f32x4 (&v)[4], float* xout, const float* g, const float* b, const float* sh, const float* sc, bf16_t* hout, const float* slab, const float* gres, float* stat = nullptr) {
;     ...
;         const float mean = s * (1.f / D); const float rstd = 1.f / sqrtf(fmaxf(s2 * (1.f / D) - mean * mean, 0.f) + EPS);
;         if (stat && F.lane == 0) { f32x2 sv = {mean, rstd}; *(f32x2*)stat = sv; }
; #pragma unroll
;         for (int j = 0; j < 4; ++j) { const f32x4 gg = ((const f32x4*)g)[F.lane + 64 * j], bb = ((const f32x4*)b)[F.lane + 64 * j];
;             v[j] = (v[j] - mean) * rstd * gg + bb; if (xout) ((f32x4*)xout)[F.lane + 64 * j] = v[j]; }
;     }
;     if (hout) {
;         float s = 0.f, s2 = 0.f;
; #pragma unroll
;         for (int j = 0; j < 4; ++j) { s += (v[j][0] + v[j][1]) + (v[j][2] + v[j][3]); s2 += (v[j][0] * v[j][0] + v[j][1] * v[j][1]) + (v[j][2] * v[j][2] + v[j][3] * v[j][3]); }
;         wave_sum2(s, s2, F.lane);
;         const float mean = s * (1.f / D); const float rstd = 1.f / sqrtf(fmaxf(s2 * (1.f / D) - mean * mean, 0.f) + EPS);
	v_add_f32_dpp v90, v90, v90 row_half_mirror row_mask:0xf bank_mask:0xf
	s_nop 0
	v_add_f32_dpp v9, v9, v9 row_mirror row_mask:0xf bank_mask:0xf
	v_add_f32_dpp v90, v90, v90 row_mirror row_mask:0xf bank_mask:0xf
	s_nop 0
	v_add_f32_dpp v9, v9, v9 row_bcast:15 row_mask:0xa bank_mask:0xf
	v_add_f32_dpp v90, v90, v90 row_bcast:15 row_mask:0xa bank_mask:0xf
	s_nop 0
	v_add_f32_dpp v9, v9, v9 row_bcast:31 row_mask:0xc bank_mask:0xf
	v_add_f32_dpp v90, v90, v90 row_bcast:31 row_mask:0xc bank_mask:0xf
	s_nop 0
	v_readlane_b32 s2, v9, 63
	v_readlane_b32 s3, v90, 63
	s_nop 1
	v_mov_b32_e32 v9, s2
	v_mov_b32_e32 v90, s3
	v_mul_f32_e32 v93, 0x3a800000, v9
	v_mul_f32_e32 v91, 0x3a800000, v90
	v_fma_f32 v91, -v93, v93, v91
	v_max_f32_e32 v91, 0, v91
	v_add_f32_e32 v91, 0x358637bd, v91
	v_rsq_f32_e32 v94, v91
	v_mul_f32_e32 v91, 0.5, v91
	v_mul_f32_e32 v92, v94, v94
	v_fma_f32 v92, -v91, v92, 0.5
	v_fma_f32 v94, v94, v92, v94
	v_sub_f32_e32 v42, v42, v93
	v_sub_f32_e32 v43, v43, v93
	v_sub_f32_e32 v44, v44, v93
	v_sub_f32_e32 v45, v45, v93
	v_sub_f32_e32 v46, v46, v93
	v_sub_f32_e32 v47, v47, v93
	v_sub_f32_e32 v48, v48, v93
	v_sub_f32_e32 v49, v49, v93
	v_sub_f32_e32 v50, v50, v93
	v_sub_f32_e32 v51, v51, v93
	v_sub_f32_e32 v52, v52, v93
	v_sub_f32_e32 v53, v53, v93
	v_sub_f32_e32 v54, v54, v93
	v_sub_f32_e32 v55, v55, v93
	v_sub_f32_e32 v56, v56, v93
	v_sub_f32_e32 v57, v57, v93
	v_mul_f32_e32 v42, v94, v42
	v_mul_f32_e32 v43, v94, v43
	v_mul_f32_e32 v44, v94, v44
	v_mul_f32_e32 v45, v94, v45
	v_mul_f32_e32 v46, v94, v46
	v_mul_f32_e32 v47, v94, v47
	v_mul_f32_e32 v48, v94, v48
	v_mul_f32_e32 v49, v94, v49
	v_mul_f32_e32 v50, v94, v50
	v_mul_f32_e32 v51, v94, v51
	v_mul_f32_e32 v52, v94, v52
	v_mul_f32_e32 v53, v94, v53
	v_mul_f32_e32 v54, v94, v54
	v_mul_f32_e32 v55, v94, v55
	v_mul_f32_e32 v56, v94, v56
	v_mul_f32_e32 v57, v94, v57
	v_fma_f32 v42, v42, v10, v26
	v_fma_f32 v43, v43, v11, v27
	v_fma_f32 v44, v44, v12, v28
	v_fma_f32 v45, v45, v13, v29
	v_fma_f32 v46, v46, v14, v30
	v_fma_f32 v47, v47, v15, v31
	v_fma_f32 v48, v48, v16, v32
	v_fma_f32 v49, v49, v17, v33
	v_fma_f32 v50, v50, v18, v34
	v_fma_f32 v51, v51, v19, v35
	v_fma_f32 v52, v52, v20, v36
	v_fma_f32 v53, v53, v21, v37
	v_fma_f32 v54, v54, v22, v38
	v_fma_f32 v55, v55, v23, v39
	v_fma_f32 v56, v56, v24, v40
	v_fma_f32 v57, v57, v25, v41
	s_mov_b64 s[2:3], s[20:21]
	global_store_dwordx4 v0, v[42:45], s[2:3]
	global_store_dwordx4 v0, v[46:49], s[2:3] offset:1024
	global_store_dwordx4 v0, v[50:53], s[2:3] offset:2048
	global_store_dwordx4 v0, v[54:57], s[2:3] offset:3072
	v_add_f32_e32 v9, v42, v43
	v_add_f32_e32 v91, v44, v45
	v_mul_f32_e32 v90, v42, v42
	v_mul_f32_e32 v92, v43, v43
	v_add_f32_e32 v9, v9, v46
	v_add_f32_e32 v91, v91, v47
	v_add_f32_e32 v9, v9, v48
	v_add_f32_e32 v91, v91, v49
	v_add_f32_e32 v9, v9, v50
	v_add_f32_e32 v91, v91, v51
	v_add_f32_e32 v9, v9, v52
	v_add_f32_e32 v91, v91, v53
	v_add_f32_e32 v9, v9, v54
	v_add_f32_e32 v91, v91, v55
	v_add_f32_e32 v9, v9, v56
	v_add_f32_e32 v91, v91, v57
	v_fmac_f32_e32 v90, v44, v44
	v_fmac_f32_e32 v92, v45, v45
	v_fmac_f32_e32 v90, v46, v46
	v_fmac_f32_e32 v92, v47, v47
	v_fmac_f32_e32 v90, v48, v48
	v_fmac_f32_e32 v92, v49, v49
	v_fmac_f32_e32 v90, v50, v50
	v_fmac_f32_e32 v92, v51, v51
	v_fmac_f32_e32 v90, v52, v52
	v_fmac_f32_e32 v92, v53, v53
	v_fmac_f32_e32 v90, v54, v54
	v_fmac_f32_e32 v92, v55, v55
	v_fmac_f32_e32 v90, v56, v56
	v_fmac_f32_e32 v92, v57, v57
	v_add_f32_e32 v9, v9, v91
	v_add_f32_e32 v90, v90, v92
	s_nop 1
	v_add_f32_dpp v9, v9, v9 quad_perm:[1,0,3,2] row_mask:0xf bank_mask:0xf
	v_add_f32_dpp v90, v90, v90 quad_perm:[1,0,3,2] row_mask:0xf bank_mask:0xf
	s_nop 0
	v_add_f32_dpp v9, v9, v9 quad_perm:[2,3,0,1] row_mask:0xf bank_mask:0xf
	v_add_f32_dpp v90, v90, v90 quad_perm:[2,3,0,1] row_mask:0xf bank_mask:0xf
	s_nop 0
	v_add_f32_dpp v9, v9, v9 row_half_mirror row_mask:0xf bank_mask:0xf
	v_add_f32_dpp v90, v90, v90 row_half_mirror row_mask:0xf bank_mask:0xf
	s_nop 0
	v_add_f32_dpp v9, v9, v9 row_mirror row_mask:0xf bank_mask:0xf
	v_add_f32_dpp v90, v90, v90 row_mirror row_mask:0xf bank_mask:0xf
	s_nop 0
	v_add_f32_dpp v9, v9, v9 row_bcast:15 row_mask:0xa bank_mask:0xf
	v_add_f32_dpp v90, v90, v90 row_bcast:15 row_mask:0xa bank_mask:0xf
	s_nop 0
	v_add_f32_dpp v9, v9, v9 row_bcast:31 row_mask:0xc bank_mask:0xf
	v_add_f32_dpp v90, v90, v90 row_bcast:31 row_mask:0xc bank_mask:0xf
	s_nop 0
	v_readlane_b32 s2, v9, 63
	v_readlane_b32 s3, v90, 63
	s_nop 1
	v_mov_b32_e32 v9, s2
	v_mov_b32_e32 v90, s3
	v_mul_f32_e32 v93, 0x3a800000, v9
	v_mul_f32_e32 v91, 0x3a800000, v90
	v_fma_f32 v91, -v93, v93, v91
	v_max_f32_e32 v91, 0, v91
	v_add_f32_e32 v91, 0x358637bd, v91
	v_rsq_f32_e32 v94, v91
	v_mul_f32_e32 v91, 0.5, v91
	v_mul_f32_e32 v92, v94, v94
	v_fma_f32 v92, -v91, v92, 0.5
	v_fma_f32 v94, v94, v92, v94
	s_waitcnt vmcnt(4)
; DI unsigned pk2(float lo, float hi) { f32x2 v = {lo, hi}; bf16x2_t b = __builtin_convertvector(v, bf16x2_t); return __builtin_bit_cast(unsigned, b); }
; DI void ln_row_v(const Frame& F, f32x4 (&v)[4], float* xout, const float* g, const float* b, const float* sh, const float* sc, bf16_t* hout, const float* slab, const float* gres, float* stat = nullptr) {
;     ...
;         const float mean = s * (1.f / D); const float rstd = 1.f / sqrtf(fmaxf(s2 * (1.f / D) - mean * mean, 0.f) + EPS);
; #pragma unroll
;         for (int j = 0; j < 4; ++j) { const f32x4 hh = ((const f32x4*)sh)[F.lane + 64 * j], cc = ((const f32x4*)sc)[F.lane + 64 * j];
;             const f32x4 o = (v[j] - mean) * rstd * (cc + 1.f) + hh; u32x2 wv; wv.x = pk2(o[0], o[1]); wv.y = pk2(o[2], o[3]);
;             ((u32x2*)hout)[F.lane + 64 * j] = wv; }
;     }
	v_sub_f32_e32 v42, v42, v93
	v_sub_f32_e32 v43, v43, v93
	v_sub_f32_e32 v44, v44, v93
	v_sub_f32_e32 v45, v45, v93
	v_sub_f32_e32 v46, v46, v93
	v_sub_f32_e32 v47, v47, v93
	v_sub_f32_e32 v48, v48, v93
	v_sub_f32_e32 v49, v49, v93
	v_sub_f32_e32 v50, v50, v93
	v_sub_f32_e32 v51, v51, v93
	v_sub_f32_e32 v52, v52, v93
	v_sub_f32_e32 v53, v53, v93
	v_sub_f32_e32 v54, v54, v93
	v_sub_f32_e32 v55, v55, v93
	v_sub_f32_e32 v56, v56, v93
	v_sub_f32_e32 v57, v57, v93
	v_add_f32_e32 v162, 1.0, v162
	v_add_f32_e32 v163, 1.0, v163
	v_add_f32_e32 v164, 1.0, v164
	v_add_f32_e32 v165, 1.0, v165
	v_add_f32_e32 v166, 1.0, v166
	v_add_f32_e32 v167, 1.0, v167
	v_add_f32_e32 v168, 1.0, v168
	v_add_f32_e32 v169, 1.0, v169
	v_add_f32_e32 v170, 1.0, v170
	v_add_f32_e32 v171, 1.0, v171
	v_add_f32_e32 v172, 1.0, v172
	v_add_f32_e32 v173, 1.0, v173
	v_add_f32_e32 v174, 1.0, v174
	v_add_f32_e32 v175, 1.0, v175
	v_add_f32_e32 v176, 1.0, v176
	v_add_f32_e32 v177, 1.0, v177
	v_mul_f32_e32 v42, v94, v42
	v_mul_f32_e32 v43, v94, v43
	v_mul_f32_e32 v44, v94, v44
	v_mul_f32_e32 v45, v94, v45
	v_mul_f32_e32 v46, v94, v46
	v_mul_f32_e32 v47, v94, v47
	v_mul_f32_e32 v48, v94, v48
	v_mul_f32_e32 v49, v94, v49
	v_mul_f32_e32 v50, v94, v50
	v_mul_f32_e32 v51, v94, v51
	v_mul_f32_e32 v52, v94, v52
	v_mul_f32_e32 v53, v94, v53
	v_mul_f32_e32 v54, v94, v54
	v_mul_f32_e32 v55, v94, v55
	v_mul_f32_e32 v56, v94, v56
	v_mul_f32_e32 v57, v94, v57
	v_fma_f32 v42, v42, v162, v146
	v_fma_f32 v43, v43, v163, v147
	v_fma_f32 v44, v44, v164, v148
	v_fma_f32 v45, v45, v165, v149
	v_fma_f32 v46, v46, v166, v150
	v_fma_f32 v47, v47, v167, v151
	v_fma_f32 v48, v48, v168, v152
	v_fma_f32 v49, v49, v169, v153
	v_fma_f32 v50, v50, v170, v154
	v_fma_f32 v51, v51, v171, v155
	v_fma_f32 v52, v52, v172, v156
	v_fma_f32 v53, v53, v173, v157
	v_fma_f32 v54, v54, v174, v158
	v_fma_f32 v55, v55, v175, v159
	v_fma_f32 v56, v56, v176, v160
	v_fma_f32 v57, v57, v177, v161
	v_cvt_pk_bf16_f32 v190, v42, v43
	v_cvt_pk_bf16_f32 v191, v44, v45
	v_cvt_pk_bf16_f32 v192, v46, v47
	v_cvt_pk_bf16_f32 v193, v48, v49
	v_cvt_pk_bf16_f32 v194, v50, v51
	v_cvt_pk_bf16_f32 v195, v52, v53
	v_cvt_pk_bf16_f32 v196, v54, v55
	v_cvt_pk_bf16_f32 v197, v56, v57
	s_lshl_b32 s2, s16, 11
	s_add_u32 s2, s94, s2
	s_addc_u32 s3, s95, 0
	s_add_u32 s2, s2, 0x5e00000
	s_addc_u32 s3, s3, 0
	global_store_dwordx2 v1, v[190:191], s[2:3]
	global_store_dwordx2 v1, v[192:193], s[2:3] offset:512
	global_store_dwordx2 v1, v[194:195], s[2:3] offset:1024
	global_store_dwordx2 v1, v[196:197], s[2:3] offset:1536

; DI float shx(float v, int m, int lane) { return __int_as_float(__builtin_amdgcn_ds_bpermute((lane ^ m) << 2, __float_as_int(v))); }
; DI void wave_sum2(float& a, float& b, int lane) {
; #pragma unroll
;     for (int o = 1; o < 64; o <<= 1) { const float ta = shx(a, o, lane), tb = shx(b, o, lane); a += ta; b += tb; }
; }
; DI void ln_row_v(const Frame& F, f32x4 (&v)[4], float* xout, const float* g, const float* b, const float* sh, const float* sc, bf16_t* hout, const float* slab, const float* gres, float* stat = nullptr) {
;     ...
;     if (g) {
;         float s = 0.f, s2 = 0.f;
; #pragma unroll
;         for (int j = 0; j < 4; ++j) { s += (v[j][0] + v[j][1]) + (v[j][2] + v[j][3]); s2 += (v[j][0] * v[j][0] + v[j][1] * v[j][1]) + (v[j][2] * v[j][2] + v[j][3] * v[j][3]); }
;         wave_sum2(s, s2, F.lane);
;         const float mean = s * (1.f / D); const float rstd = 1.f / sqrtf(fmaxf(s2 * (1.f / D) - mean * mean, 0.f) + EPS);
;         if (stat && F.lane == 0) { f32x2 sv = {mean, rstd}; *(f32x2*)stat = sv; }
; #pragma unroll
;         for (int j = 0; j < 4; ++j) { const f32x4 gg = ((const f32x4*)g)[F.lane + 64 * j], bb = ((const f32x4*)b)[F.lane + 64 * j];
;             v[j] = (v[j] - mean) * rstd * gg + bb; if (xout) ((f32x4*)xout)[F.lane + 64 * j] = v[j]; }
;     }
.Lln_b_final:
	global_load_dwordx4 v[10:13], v0, s[4:5]
	global_load_dwordx4 v[14:17], v0, s[4:5] offset:1024
	global_load_dwordx4 v[18:21], v0, s[4:5] offset:2048
	global_load_dwordx4 v[22:25], v0, s[4:5] offset:3072
	global_load_dwordx4 v[26:29], v0, s[6:7]
	global_load_dwordx4 v[30:33], v0, s[6:7] offset:1024
	global_load_dwordx4 v[34:37], v0, s[6:7] offset:2048
	global_load_dwordx4 v[38:41], v0, s[6:7] offset:3072
	s_add_u32 s2, s8, 0x0
	s_addc_u32 s3, s9, 0
	global_load_dwordx4 v[42:45], v0, s[2:3]
	global_load_dwordx4 v[46:49], v0, s[2:3] offset:1024
	global_load_dwordx4 v[50:53], v0, s[2:3] offset:2048
	global_load_dwordx4 v[54:57], v0, s[2:3] offset:3072
	s_add_u32 s2, s8, 0x1000
	s_addc_u32 s3, s9, 0
	global_load_dwordx4 v[58:61], v0, s[2:3]
	global_load_dwordx4 v[62:65], v0, s[2:3] offset:1024
	global_load_dwordx4 v[66:69], v0, s[2:3] offset:2048
	global_load_dwordx4 v[70:73], v0, s[2:3] offset:3072
	s_add_u32 s2, s8, 0x2000
	s_addc_u32 s3, s9, 0
	global_load_dwordx4 v[74:77], v0, s[2:3]
	global_load_dwordx4 v[78:81], v0, s[2:3] offset:1024
	global_load_dwordx4 v[82:85], v0, s[2:3] offset:2048
	global_load_dwordx4 v[86:89], v0, s[2:3] offset:3072
	s_add_u32 s2, s8, 0x3000
	s_addc_u32 s3, s9, 0
	global_load_dwordx4 v[98:101], v0, s[2:3]
	global_load_dwordx4 v[102:105], v0, s[2:3] offset:1024
	global_load_dwordx4 v[106:109], v0, s[2:3] offset:2048
	global_load_dwordx4 v[110:113], v0, s[2:3] offset:3072
	s_waitcnt vmcnt(12)
	v_add_f32_e32 v9, v42, v43
	v_add_f32_e32 v91, v44, v45
	v_mul_f32_e32 v90, v42, v42
	v_mul_f32_e32 v92, v43, v43
	v_add_f32_e32 v9, v9, v46
	v_add_f32_e32 v91, v91, v47
	v_add_f32_e32 v9, v9, v48
	v_add_f32_e32 v91, v91, v49
	v_add_f32_e32 v9, v9, v50
	v_add_f32_e32 v91, v91, v51
	v_add_f32_e32 v9, v9, v52
	v_add_f32_e32 v91, v91, v53
	v_add_f32_e32 v9, v9, v54
	v_add_f32_e32 v91, v91, v55
	v_add_f32_e32 v9, v9, v56
	v_add_f32_e32 v91, v91, v57
	v_fmac_f32_e32 v90, v44, v44
	v_fmac_f32_e32 v92, v45, v45
	v_fmac_f32_e32 v90, v46, v46
	v_fmac_f32_e32 v92, v47, v47
	v_fmac_f32_e32 v90, v48, v48
	v_fmac_f32_e32 v92, v49, v49
	v_fmac_f32_e32 v90, v50, v50
	v_fmac_f32_e32 v92, v51, v51
	v_fmac_f32_e32 v90, v52, v52
	v_fmac_f32_e32 v92, v53, v53
	v_fmac_f32_e32 v90, v54, v54
	v_fmac_f32_e32 v92, v55, v55
	v_fmac_f32_e32 v90, v56, v56
	v_fmac_f32_e32 v92, v57, v57
	v_add_f32_e32 v9, v9, v91
	v_add_f32_e32 v90, v90, v92
	s_nop 1
	v_add_f32_dpp v9, v9, v9 quad_perm:[1,0,3,2] row_mask:0xf bank_mask:0xf
	v_add_f32_dpp v90, v90, v90 quad_perm:[1,0,3,2] row_mask:0xf bank_mask:0xf
	s_nop 0
	v_add_f32_dpp v9, v9, v9 quad_perm:[2,3,0,1] row_mask:0xf bank_mask:0xf
	v_add_f32_dpp v90, v90, v90 quad_perm:[2,3,0,1] row_mask:0xf bank_mask:0xf
	s_nop 0
	v_add_f32_dpp v9, v9, v9 row_half_mirror row_mask:0xf bank_mask:0xf
	v_add_f32_dpp v90, v90, v90 row_half_mirror row_mask:0xf bank_mask:0xf
	s_nop 0
	v_add_f32_dpp v9, v9, v9 row_mirror row_mask:0xf bank_mask:0xf
	v_add_f32_dpp v90, v90, v90 row_mirror row_mask:0xf bank_mask:0xf
	s_nop 0
	v_add_f32_dpp v9, v9, v9 row_bcast:15 row_mask:0xa bank_mask:0xf
	v_add_f32_dpp v90, v90, v90 row_bcast:15 row_mask:0xa bank_mask:0xf
	s_nop 0
	v_add_f32_dpp v9, v9, v9 row_bcast:31 row_mask:0xc bank_mask:0xf
	v_add_f32_dpp v90, v90, v90 row_bcast:31 row_mask:0xc bank_mask:0xf
	s_nop 0
	v_readlane_b32 s2, v9, 63
	v_readlane_b32 s3, v90, 63
	s_nop 1
	v_mov_b32_e32 v9, s2
	v_mov_b32_e32 v90, s3
	v_mul_f32_e32 v93, 0x3a800000, v9
	v_mul_f32_e32 v91, 0x3a800000, v90
	v_fma_f32 v91, -v93, v93, v91
	v_max_f32_e32 v91, 0, v91
	v_add_f32_e32 v91, 0x358637bd, v91
	v_rsq_f32_e32 v94, v91
	v_mul_f32_e32 v91, 0.5, v91
	v_mul_f32_e32 v92, v94, v94
	v_fma_f32 v92, -v91, v92, 0.5
	v_fma_f32 v94, v94, v92, v94
	v_sub_f32_e32 v42, v42, v93
	v_sub_f32_e32 v43, v43, v93
	v_sub_f32_e32 v44, v44, v93
	v_sub_f32_e32 v45, v45, v93
	v_sub_f32_e32 v46, v46, v93
	v_sub_f32_e32 v47, v47, v93
	v_sub_f32_e32 v48, v48, v93
	v_sub_f32_e32 v49, v49, v93
	v_sub_f32_e32 v50, v50, v93
	v_sub_f32_e32 v51, v51, v93
	v_sub_f32_e32 v52, v52, v93
	v_sub_f32_e32 v53, v53, v93
	v_sub_f32_e32 v54, v54, v93
	v_sub_f32_e32 v55, v55, v93
	v_sub_f32_e32 v56, v56, v93
	v_sub_f32_e32 v57, v57, v93
	v_mul_f32_e32 v42, v94, v42
	v_mul_f32_e32 v43, v94, v43
	v_mul_f32_e32 v44, v94, v44
	v_mul_f32_e32 v45, v94, v45
	v_mul_f32_e32 v46, v94, v46
	v_mul_f32_e32 v47, v94, v47
	v_mul_f32_e32 v48, v94, v48
	v_mul_f32_e32 v49, v94, v49
	v_mul_f32_e32 v50, v94, v50
	v_mul_f32_e32 v51, v94, v51
	v_mul_f32_e32 v52, v94, v52
	v_mul_f32_e32 v53, v94, v53
	v_mul_f32_e32 v54, v94, v54
	v_mul_f32_e32 v55, v94, v55
	v_mul_f32_e32 v56, v94, v56
	v_mul_f32_e32 v57, v94, v57
	v_fma_f32 v42, v42, v10, v26
	v_fma_f32 v43, v43, v11, v27
	v_fma_f32 v44, v44, v12, v28
	v_fma_f32 v45, v45, v13, v29
	v_fma_f32 v46, v46, v14, v30
	v_fma_f32 v47, v47, v15, v31
	v_fma_f32 v48, v48, v16, v32
	v_fma_f32 v49, v49, v17, v33
	v_fma_f32 v50, v50, v18, v34
	v_fma_f32 v51, v51, v19, v35
	v_fma_f32 v52, v52, v20, v36
	v_fma_f32 v53, v53, v21, v37
	v_fma_f32 v54, v54, v22, v38
	v_fma_f32 v55, v55, v23, v39
	v_fma_f32 v56, v56, v24, v40
	v_fma_f32 v57, v57, v25, v41
	s_add_u32 s2, s8, 0x0
	s_addc_u32 s3, s9, 0
	global_store_dwordx4 v0, v[42:45], s[2:3]
	global_store_dwordx4 v0, v[46:49], s[2:3] offset:1024
	global_store_dwordx4 v0, v[50:53], s[2:3] offset:2048
	global_store_dwordx4 v0, v[54:57], s[2:3] offset:3072
	s_add_u32 s2, s8, 0x4000
	s_addc_u32 s3, s9, 0
	global_load_dwordx4 v[42:45], v0, s[2:3]
	global_load_dwordx4 v[46:49], v0, s[2:3] offset:1024
	global_load_dwordx4 v[50:53], v0, s[2:3] offset:2048
	global_load_dwordx4 v[54:57], v0, s[2:3] offset:3072
	s_waitcnt vmcnt(16)
; DI float shx(float v, int m, int lane) { return __int_as_float(__builtin_amdgcn_ds_bpermute((lane ^ m) << 2, __float_as_int(v))); }
; DI void wave_sum2(float& a, float& b, int lane) {
; #pragma unroll
;     for (int o = 1; o < 64; o <<= 1) { const float ta = shx(a, o, lane), tb = shx(b, o, lane); a += ta; b += tb; }
; }
; DI void ln_row_v(const Frame& F, f32x4 (&v)[4], float* xout, const float* g, const float* b, const float* sh, const float* sc, bf16_t* hout, const float* slab, const float* gres, float* stat = nullptr) {
;     ...
;     if (g) {
;         float s = 0.f, s2 = 0.f;
; #pragma unroll
;         for (int j = 0; j < 4; ++j) { s += (v[j][0] + v[j][1]) + (v[j][2] + v[j][3]); s2 += (v[j][0] * v[j][0] + v[j][1] * v[j][1]) + (v[j][2] * v[j][2] + v[j][3] * v[j][3]); }
;         wave_sum2(s, s2, F.lane);
;         const float mean = s * (1.f / D); const float rstd = 1.f / sqrtf(fmaxf(s2 * (1.f / D) - mean * mean, 0.f) + EPS);
;         if (stat && F.lane == 0) { f32x2 sv = {mean, rstd}; *(f32x2*)stat = sv; }
; #pragma unroll
;         for (int j = 0; j < 4; ++j) { const f32x4 gg = ((const f32x4*)g)[F.lane + 64 * j], bb = ((const f32x4*)b)[F.lane + 64 * j];
;             v[j] = (v[j] - mean) * rstd * gg + bb; if (xout) ((f32x4*)xout)[F.lane + 64 * j] = v[j]; }
;     }
	v_add_f32_e32 v9, v58, v59
	v_add_f32_e32 v91, v60, v61
	v_mul_f32_e32 v90, v58, v58
	v_mul_f32_e32 v92, v59, v59
	v_add_f32_e32 v9, v9, v62
	v_add_f32_e32 v91, v91, v63
	v_add_f32_e32 v9, v9, v64
	v_add_f32_e32 v91, v91, v65
	v_add_f32_e32 v9, v9, v66
	v_add_f32_e32 v91, v91, v67
	v_add_f32_e32 v9, v9, v68
	v_add_f32_e32 v91, v91, v69
	v_add_f32_e32 v9, v9, v70
	v_add_f32_e32 v91, v91, v71
	v_add_f32_e32 v9, v9, v72
	v_add_f32_e32 v91, v91, v73
	v_fmac_f32_e32 v90, v60, v60
	v_fmac_f32_e32 v92, v61, v61
	v_fmac_f32_e32 v90, v62, v62
	v_fmac_f32_e32 v92, v63, v63
	v_fmac_f32_e32 v90, v64, v64
	v_fmac_f32_e32 v92, v65, v65
	v_fmac_f32_e32 v90, v66, v66
	v_fmac_f32_e32 v92, v67, v67
	v_fmac_f32_e32 v90, v68, v68
	v_fmac_f32_e32 v92, v69, v69
	v_fmac_f32_e32 v90, v70, v70
	v_fmac_f32_e32 v92, v71, v71
	v_fmac_f32_e32 v90, v72, v72
	v_fmac_f32_e32 v92, v73, v73
	v_add_f32_e32 v9, v9, v91
	v_add_f32_e32 v90, v90, v92
	s_nop 1
	v_add_f32_dpp v9, v9, v9 quad_perm:[1,0,3,2] row_mask:0xf bank_mask:0xf
	v_add_f32_dpp v90, v90, v90 quad_perm:[1,0,3,2] row_mask:0xf bank_mask:0xf
	s_nop 0
	v_add_f32_dpp v9, v9, v9 quad_perm:[2,3,0,1] row_mask:0xf bank_mask:0xf
	v_add_f32_dpp v90, v90, v90 quad_perm:[2,3,0,1] row_mask:0xf bank_mask:0xf
	s_nop 0
	v_add_f32_dpp v9, v9, v9 row_half_mirror row_mask:0xf bank_mask:0xf
	v_add_f32_dpp v90, v90, v90 row_half_mirror row_mask:0xf bank_mask:0xf
	s_nop 0
	v_add_f32_dpp v9, v9, v9 row_mirror row_mask:0xf bank_mask:0xf
	v_add_f32_dpp v90, v90, v90 row_mirror row_mask:0xf bank_mask:0xf
	s_nop 0
	v_add_f32_dpp v9, v9, v9 row_bcast:15 row_mask:0xa bank_mask:0xf
	v_add_f32_dpp v90, v90, v90 row_bcast:15 row_mask:0xa bank_mask:0xf
	s_nop 0
	v_add_f32_dpp v9, v9, v9 row_bcast:31 row_mask:0xc bank_mask:0xf
	v_add_f32_dpp v90, v90, v90 row_bcast:31 row_mask:0xc bank_mask:0xf
	s_nop 0
	v_readlane_b32 s2, v9, 63
	v_readlane_b32 s3, v90, 63
	s_nop 1
	v_mov_b32_e32 v9, s2
	v_mov_b32_e32 v90, s3
	v_mul_f32_e32 v93, 0x3a800000, v9
	v_mul_f32_e32 v91, 0x3a800000, v90
	v_fma_f32 v91, -v93, v93, v91
	v_max_f32_e32 v91, 0, v91
	v_add_f32_e32 v91, 0x358637bd, v91
	v_rsq_f32_e32 v94, v91
	v_mul_f32_e32 v91, 0.5, v91
	v_mul_f32_e32 v92, v94, v94
	v_fma_f32 v92, -v91, v92, 0.5
	v_fma_f32 v94, v94, v92, v94
	v_sub_f32_e32 v58, v58, v93
	v_sub_f32_e32 v59, v59, v93
	v_sub_f32_e32 v60, v60, v93
	v_sub_f32_e32 v61, v61, v93
	v_sub_f32_e32 v62, v62, v93
	v_sub_f32_e32 v63, v63, v93
	v_sub_f32_e32 v64, v64, v93
	v_sub_f32_e32 v65, v65, v93
	v_sub_f32_e32 v66, v66, v93
	v_sub_f32_e32 v67, v67, v93
	v_sub_f32_e32 v68, v68, v93
	v_sub_f32_e32 v69, v69, v93
	v_sub_f32_e32 v70, v70, v93
	v_sub_f32_e32 v71, v71, v93
	v_sub_f32_e32 v72, v72, v93
	v_sub_f32_e32 v73, v73, v93
	v_mul_f32_e32 v58, v94, v58
	v_mul_f32_e32 v59, v94, v59
	v_mul_f32_e32 v60, v94, v60
	v_mul_f32_e32 v61, v94, v61
	v_mul_f32_e32 v62, v94, v62
	v_mul_f32_e32 v63, v94, v63
	v_mul_f32_e32 v64, v94, v64
	v_mul_f32_e32 v65, v94, v65
	v_mul_f32_e32 v66, v94, v66
	v_mul_f32_e32 v67, v94, v67
	v_mul_f32_e32 v68, v94, v68
	v_mul_f32_e32 v69, v94, v69
	v_mul_f32_e32 v70, v94, v70
	v_mul_f32_e32 v71, v94, v71
	v_mul_f32_e32 v72, v94, v72
	v_mul_f32_e32 v73, v94, v73
	v_fma_f32 v58, v58, v10, v26
	v_fma_f32 v59, v59, v11, v27
	v_fma_f32 v60, v60, v12, v28
	v_fma_f32 v61, v61, v13, v29
	v_fma_f32 v62, v62, v14, v30
	v_fma_f32 v63, v63, v15, v31
	v_fma_f32 v64, v64, v16, v32
	v_fma_f32 v65, v65, v17, v33
	v_fma_f32 v66, v66, v18, v34
	v_fma_f32 v67, v67, v19, v35
	v_fma_f32 v68, v68, v20, v36
	v_fma_f32 v69, v69, v21, v37
	v_fma_f32 v70, v70, v22, v38
	v_fma_f32 v71, v71, v23, v39
	v_fma_f32 v72, v72, v24, v40
	v_fma_f32 v73, v73, v25, v41
	s_add_u32 s2, s8, 0x1000
	s_addc_u32 s3, s9, 0
	global_store_dwordx4 v0, v[58:61], s[2:3]
	global_store_dwordx4 v0, v[62:65], s[2:3] offset:1024
	global_store_dwordx4 v0, v[66:69], s[2:3] offset:2048
	global_store_dwordx4 v0, v[70:73], s[2:3] offset:3072
	s_add_u32 s2, s8, 0x5000
	s_addc_u32 s3, s9, 0
	global_load_dwordx4 v[58:61], v0, s[2:3]
	global_load_dwordx4 v[62:65], v0, s[2:3] offset:1024
	global_load_dwordx4 v[66:69], v0, s[2:3] offset:2048
	global_load_dwordx4 v[70:73], v0, s[2:3] offset:3072
	s_waitcnt vmcnt(20)
	v_add_f32_e32 v9, v74, v75
	v_add_f32_e32 v91, v76, v77
	v_mul_f32_e32 v90, v74, v74
	v_mul_f32_e32 v92, v75, v75
	v_add_f32_e32 v9, v9, v78
	v_add_f32_e32 v91, v91, v79
	v_add_f32_e32 v9, v9, v80
	v_add_f32_e32 v91, v91, v81
	v_add_f32_e32 v9, v9, v82
	v_add_f32_e32 v91, v91, v83
	v_add_f32_e32 v9, v9, v84
	v_add_f32_e32 v91, v91, v85
	v_add_f32_e32 v9, v9, v86
	v_add_f32_e32 v91, v91, v87
	v_add_f32_e32 v9, v9, v88
	v_add_f32_e32 v91, v91, v89
	v_fmac_f32_e32 v90, v76, v76
	v_fmac_f32_e32 v92, v77, v77
	v_fmac_f32_e32 v90, v78, v78
	v_fmac_f32_e32 v92, v79, v79
	v_fmac_f32_e32 v90, v80, v80
	v_fmac_f32_e32 v92, v81, v81
	v_fmac_f32_e32 v90, v82, v82
	v_fmac_f32_e32 v92, v83, v83
	v_fmac_f32_e32 v90, v84, v84
	v_fmac_f32_e32 v92, v85, v85
	v_fmac_f32_e32 v90, v86, v86
	v_fmac_f32_e32 v92, v87, v87
	v_fmac_f32_e32 v90, v88, v88
	v_fmac_f32_e32 v92, v89, v89
	v_add_f32_e32 v9, v9, v91
	v_add_f32_e32 v90, v90, v92
	s_nop 1
	v_add_f32_dpp v9, v9, v9 quad_perm:[1,0,3,2] row_mask:0xf bank_mask:0xf
	v_add_f32_dpp v90, v90, v90 quad_perm:[1,0,3,2] row_mask:0xf bank_mask:0xf
	s_nop 0
	v_add_f32_dpp v9, v9, v9 quad_perm:[2,3,0,1] row_mask:0xf bank_mask:0xf
	v_add_f32_dpp v90, v90, v90 quad_perm:[2,3,0,1] row_mask:0xf bank_mask:0xf
	s_nop 0
	v_add_f32_dpp v9, v9, v9 row_half_mirror row_mask:0xf bank_mask:0xf
	v_add_f32_dpp v90, v90, v90 row_half_mirror row_mask:0xf bank_mask:0xf
	s_nop 0
	v_add_f32_dpp v9, v9, v9 row_mirror row_mask:0xf bank_mask:0xf
; DI float shx(float v, int m, int lane) { return __int_as_float(__builtin_amdgcn_ds_bpermute((lane ^ m) << 2, __float_as_int(v))); }
; DI void wave_sum2(float& a, float& b, int lane) {
; #pragma unroll
;     for (int o = 1; o < 64; o <<= 1) { const float ta = shx(a, o, lane), tb = shx(b, o, lane); a += ta; b += tb; }
; }
; DI void ln_row_v(const Frame& F, f32x4 (&v)[4], float* xout, const float* g, const float* b, const float* sh, const float* sc, bf16_t* hout, const float* slab, const float* gres, float* stat = nullptr) {
;     ...
;     if (g) {
;         float s = 0.f, s2 = 0.f;
; #pragma unroll
;         for (int j = 0; j < 4; ++j) { s += (v[j][0] + v[j][1]) + (v[j][2] + v[j][3]); s2 += (v[j][0] * v[j][0] + v[j][1] * v[j][1]) + (v[j][2] * v[j][2] + v[j][3] * v[j][3]); }
;         wave_sum2(s, s2, F.lane);
;         const float mean = s * (1.f / D); const float rstd = 1.f / sqrtf(fmaxf(s2 * (1.f / D) - mean * mean, 0.f) + EPS);
;         if (stat && F.lane == 0) { f32x2 sv = {mean, rstd}; *(f32x2*)stat = sv; }
; #pragma unroll
;         for (int j = 0; j < 4; ++j) { const f32x4 gg = ((const f32x4*)g)[F.lane + 64 * j], bb = ((const f32x4*)b)[F.lane + 64 * j];
;             v[j] = (v[j] - mean) * rstd * gg + bb; if (xout) ((f32x4*)xout)[F.lane + 64 * j] = v[j]; }
;     }
	v_add_f32_dpp v90, v90, v90 row_mirror row_mask:0xf bank_mask:0xf
	s_nop 0
	v_add_f32_dpp v9, v9, v9 row_bcast:15 row_mask:0xa bank_mask:0xf
	v_add_f32_dpp v90, v90, v90 row_bcast:15 row_mask:0xa bank_mask:0xf
	s_nop 0
	v_add_f32_dpp v9, v9, v9 row_bcast:31 row_mask:0xc bank_mask:0xf
	v_add_f32_dpp v90, v90, v90 row_bcast:31 row_mask:0xc bank_mask:0xf
	s_nop 0
	v_readlane_b32 s2, v9, 63
	v_readlane_b32 s3, v90, 63
	s_nop 1
	v_mov_b32_e32 v9, s2
	v_mov_b32_e32 v90, s3
	v_mul_f32_e32 v93, 0x3a800000, v9
	v_mul_f32_e32 v91, 0x3a800000, v90
	v_fma_f32 v91, -v93, v93, v91
	v_max_f32_e32 v91, 0, v91
	v_add_f32_e32 v91, 0x358637bd, v91
	v_rsq_f32_e32 v94, v91
	v_mul_f32_e32 v91, 0.5, v91
	v_mul_f32_e32 v92, v94, v94
	v_fma_f32 v92, -v91, v92, 0.5
	v_fma_f32 v94, v94, v92, v94
	v_sub_f32_e32 v74, v74, v93
	v_sub_f32_e32 v75, v75, v93
	v_sub_f32_e32 v76, v76, v93
	v_sub_f32_e32 v77, v77, v93
	v_sub_f32_e32 v78, v78, v93
	v_sub_f32_e32 v79, v79, v93
	v_sub_f32_e32 v80, v80, v93
	v_sub_f32_e32 v81, v81, v93
	v_sub_f32_e32 v82, v82, v93
	v_sub_f32_e32 v83, v83, v93
	v_sub_f32_e32 v84, v84, v93
	v_sub_f32_e32 v85, v85, v93
	v_sub_f32_e32 v86, v86, v93
	v_sub_f32_e32 v87, v87, v93
	v_sub_f32_e32 v88, v88, v93
	v_sub_f32_e32 v89, v89, v93
	v_mul_f32_e32 v74, v94, v74
	v_mul_f32_e32 v75, v94, v75
	v_mul_f32_e32 v76, v94, v76
	v_mul_f32_e32 v77, v94, v77
	v_mul_f32_e32 v78, v94, v78
	v_mul_f32_e32 v79, v94, v79
	v_mul_f32_e32 v80, v94, v80
	v_mul_f32_e32 v81, v94, v81
	v_mul_f32_e32 v82, v94, v82
	v_mul_f32_e32 v83, v94, v83
	v_mul_f32_e32 v84, v94, v84
	v_mul_f32_e32 v85, v94, v85
	v_mul_f32_e32 v86, v94, v86
	v_mul_f32_e32 v87, v94, v87
	v_mul_f32_e32 v88, v94, v88
	v_mul_f32_e32 v89, v94, v89
	v_fma_f32 v74, v74, v10, v26
	v_fma_f32 v75, v75, v11, v27
	v_fma_f32 v76, v76, v12, v28
	v_fma_f32 v77, v77, v13, v29
	v_fma_f32 v78, v78, v14, v30
	v_fma_f32 v79, v79, v15, v31
	v_fma_f32 v80, v80, v16, v32
	v_fma_f32 v81, v81, v17, v33
	v_fma_f32 v82, v82, v18, v34
	v_fma_f32 v83, v83, v19, v35
	v_fma_f32 v84, v84, v20, v36
	v_fma_f32 v85, v85, v21, v37
	v_fma_f32 v86, v86, v22, v38
	v_fma_f32 v87, v87, v23, v39
	v_fma_f32 v88, v88, v24, v40
	v_fma_f32 v89, v89, v25, v41
	s_add_u32 s2, s8, 0x2000
	s_addc_u32 s3, s9, 0
	global_store_dwordx4 v0, v[74:77], s[2:3]
	global_store_dwordx4 v0, v[78:81], s[2:3] offset:1024
	global_store_dwordx4 v0, v[82:85], s[2:3] offset:2048
	global_store_dwordx4 v0, v[86:89], s[2:3] offset:3072
	s_add_u32 s2, s8, 0x6000
	s_addc_u32 s3, s9, 0
	global_load_dwordx4 v[74:77], v0, s[2:3]
	global_load_dwordx4 v[78:81], v0, s[2:3] offset:1024
	global_load_dwordx4 v[82:85], v0, s[2:3] offset:2048
	global_load_dwordx4 v[86:89], v0, s[2:3] offset:3072
	s_waitcnt vmcnt(24)
	v_add_f32_e32 v9, v98, v99
	v_add_f32_e32 v91, v100, v101
	v_mul_f32_e32 v90, v98, v98
	v_mul_f32_e32 v92, v99, v99
	v_add_f32_e32 v9, v9, v102
	v_add_f32_e32 v91, v91, v103
	v_add_f32_e32 v9, v9, v104
	v_add_f32_e32 v91, v91, v105
	v_add_f32_e32 v9, v9, v106
	v_add_f32_e32 v91, v91, v107
	v_add_f32_e32 v9, v9, v108
	v_add_f32_e32 v91, v91, v109
	v_add_f32_e32 v9, v9, v110
	v_add_f32_e32 v91, v91, v111
	v_add_f32_e32 v9, v9, v112
	v_add_f32_e32 v91, v91, v113
	v_fmac_f32_e32 v90, v100, v100
	v_fmac_f32_e32 v92, v101, v101
	v_fmac_f32_e32 v90, v102, v102
	v_fmac_f32_e32 v92, v103, v103
	v_fmac_f32_e32 v90, v104, v104
	v_fmac_f32_e32 v92, v105, v105
	v_fmac_f32_e32 v90, v106, v106
	v_fmac_f32_e32 v92, v107, v107
	v_fmac_f32_e32 v90, v108, v108
	v_fmac_f32_e32 v92, v109, v109
	v_fmac_f32_e32 v90, v110, v110
	v_fmac_f32_e32 v92, v111, v111
	v_fmac_f32_e32 v90, v112, v112
	v_fmac_f32_e32 v92, v113, v113
	v_add_f32_e32 v9, v9, v91
	v_add_f32_e32 v90, v90, v92
	s_nop 1
	v_add_f32_dpp v9, v9, v9 quad_perm:[1,0,3,2] row_mask:0xf bank_mask:0xf
	v_add_f32_dpp v90, v90, v90 quad_perm:[1,0,3,2] row_mask:0xf bank_mask:0xf
	s_nop 0
	v_add_f32_dpp v9, v9, v9 quad_perm:[2,3,0,1] row_mask:0xf bank_mask:0xf
	v_add_f32_dpp v90, v90, v90 quad_perm:[2,3,0,1] row_mask:0xf bank_mask:0xf
	s_nop 0
	v_add_f32_dpp v9, v9, v9 row_half_mirror row_mask:0xf bank_mask:0xf
	v_add_f32_dpp v90, v90, v90 row_half_mirror row_mask:0xf bank_mask:0xf
	s_nop 0
	v_add_f32_dpp v9, v9, v9 row_mirror row_mask:0xf bank_mask:0xf
	v_add_f32_dpp v90, v90, v90 row_mirror row_mask:0xf bank_mask:0xf
	s_nop 0
	v_add_f32_dpp v9, v9, v9 row_bcast:15 row_mask:0xa bank_mask:0xf
	v_add_f32_dpp v90, v90, v90 row_bcast:15 row_mask:0xa bank_mask:0xf
	s_nop 0
	v_add_f32_dpp v9, v9, v9 row_bcast:31 row_mask:0xc bank_mask:0xf
	v_add_f32_dpp v90, v90, v90 row_bcast:31 row_mask:0xc bank_mask:0xf
	s_nop 0
	v_readlane_b32 s2, v9, 63
	v_readlane_b32 s3, v90, 63
	s_nop 1
	v_mov_b32_e32 v9, s2
	v_mov_b32_e32 v90, s3
	v_mul_f32_e32 v93, 0x3a800000, v9
	v_mul_f32_e32 v91, 0x3a800000, v90
	v_fma_f32 v91, -v93, v93, v91
	v_max_f32_e32 v91, 0, v91
	v_add_f32_e32 v91, 0x358637bd, v91
	v_rsq_f32_e32 v94, v91
	v_mul_f32_e32 v91, 0.5, v91
	v_mul_f32_e32 v92, v94, v94
	v_fma_f32 v92, -v91, v92, 0.5
	v_fma_f32 v94, v94, v92, v94
	v_sub_f32_e32 v98, v98, v93
	v_sub_f32_e32 v99, v99, v93
	v_sub_f32_e32 v100, v100, v93
	v_sub_f32_e32 v101, v101, v93
	v_sub_f32_e32 v102, v102, v93
	v_sub_f32_e32 v103, v103, v93
	v_sub_f32_e32 v104, v104, v93
	v_sub_f32_e32 v105, v105, v93
	v_sub_f32_e32 v106, v106, v93
	v_sub_f32_e32 v107, v107, v93
	v_sub_f32_e32 v108, v108, v93
	v_sub_f32_e32 v109, v109, v93
	v_sub_f32_e32 v110, v110, v93
	v_sub_f32_e32 v111, v111, v93
	v_sub_f32_e32 v112, v112, v93
	v_sub_f32_e32 v113, v113, v93
	v_mul_f32_e32 v98, v94, v98
	v_mul_f32_e32 v99, v94, v99
	v_mul_f32_e32 v100, v94, v100
	v_mul_f32_e32 v101, v94, v101
	v_mul_f32_e32 v102, v94, v102
	v_mul_f32_e32 v103, v94, v103
	v_mul_f32_e32 v104, v94, v104
	v_mul_f32_e32 v105, v94, v105
	v_mul_f32_e32 v106, v94, v106
	v_mul_f32_e32 v107, v94, v107
	v_mul_f32_e32 v108, v94, v108
	v_mul_f32_e32 v109, v94, v109
	v_mul_f32_e32 v110, v94, v110
	v_mul_f32_e32 v111, v94, v111
	v_mul_f32_e32 v112, v94, v112
	v_mul_f32_e32 v113, v94, v113
	v_fma_f32 v98, v98, v10, v26
	v_fma_f32 v99, v99, v11, v27
	v_fma_f32 v100, v100, v12, v28
	v_fma_f32 v101, v101, v13, v29
	v_fma_f32 v102, v102, v14, v30
	v_fma_f32 v103, v103, v15, v31
	v_fma_f32 v104, v104, v16, v32
	v_fma_f32 v105, v105, v17, v33
	v_fma_f32 v106, v106, v18, v34
	v_fma_f32 v107, v107, v19, v35
	v_fma_f32 v108, v108, v20, v36
	v_fma_f32 v109, v109, v21, v37
	v_fma_f32 v110, v110, v22, v38
	v_fma_f32 v111, v111, v23, v39
	v_fma_f32 v112, v112, v24, v40
	v_fma_f32 v113, v113, v25, v41
	s_add_u32 s2, s8, 0x3000
	s_addc_u32 s3, s9, 0
	global_store_dwordx4 v0, v[98:101], s[2:3]
	global_store_dwordx4 v0, v[102:105], s[2:3] offset:1024
	global_store_dwordx4 v0, v[106:109], s[2:3] offset:2048
	global_store_dwordx4 v0, v[110:113], s[2:3] offset:3072
	s_add_u32 s2, s8, 0x7000
	s_addc_u32 s3, s9, 0
	global_load_dwordx4 v[98:101], v0, s[2:3]
	global_load_dwordx4 v[102:105], v0, s[2:3] offset:1024
	global_load_dwordx4 v[106:109], v0, s[2:3] offset:2048
	global_load_dwordx4 v[110:113], v0, s[2:3] offset:3072
	s_waitcnt vmcnt(24)
; DI float shx(float v, int m, int lane) { return __int_as_float(__builtin_amdgcn_ds_bpermute((lane ^ m) << 2, __float_as_int(v))); }
; DI void wave_sum2(float& a, float& b, int lane) {
; #pragma unroll
;     for (int o = 1; o < 64; o <<= 1) { const float ta = shx(a, o, lane), tb = shx(b, o, lane); a += ta; b += tb; }
; }
; DI void ln_row_v(const Frame& F, f32x4 (&v)[4], float* xout, const float* g, const float* b, const float* sh, const float* sc, bf16_t* hout, const float* slab, const float* gres, float* stat = nullptr) {
;     ...
;     if (g) {
;         float s = 0.f, s2 = 0.f;
; #pragma unroll
;         for (int j = 0; j < 4; ++j) { s += (v[j][0] + v[j][1]) + (v[j][2] + v[j][3]); s2 += (v[j][0] * v[j][0] + v[j][1] * v[j][1]) + (v[j][2] * v[j][2] + v[j][3] * v[j][3]); }
;         wave_sum2(s, s2, F.lane);
;         const float mean = s * (1.f / D); const float rstd = 1.f / sqrtf(fmaxf(s2 * (1.f / D) - mean * mean, 0.f) + EPS);
;         if (stat && F.lane == 0) { f32x2 sv = {mean, rstd}; *(f32x2*)stat = sv; }
; #pragma unroll
;         for (int j = 0; j < 4; ++j) { const f32x4 gg = ((const f32x4*)g)[F.lane + 64 * j], bb = ((const f32x4*)b)[F.lane + 64 * j];
;             v[j] = (v[j] - mean) * rstd * gg + bb; if (xout) ((f32x4*)xout)[F.lane + 64 * j] = v[j]; }
;     }
	v_add_f32_e32 v9, v42, v43
	v_add_f32_e32 v91, v44, v45
	v_mul_f32_e32 v90, v42, v42
	v_mul_f32_e32 v92, v43, v43
	v_add_f32_e32 v9, v9, v46
	v_add_f32_e32 v91, v91, v47
	v_add_f32_e32 v9, v9, v48
	v_add_f32_e32 v91, v91, v49
	v_add_f32_e32 v9, v9, v50
	v_add_f32_e32 v91, v91, v51
	v_add_f32_e32 v9, v9, v52
	v_add_f32_e32 v91, v91, v53
	v_add_f32_e32 v9, v9, v54
	v_add_f32_e32 v91, v91, v55
	v_add_f32_e32 v9, v9, v56
	v_add_f32_e32 v91, v91, v57
	v_fmac_f32_e32 v90, v44, v44
	v_fmac_f32_e32 v92, v45, v45
	v_fmac_f32_e32 v90, v46, v46
	v_fmac_f32_e32 v92, v47, v47
	v_fmac_f32_e32 v90, v48, v48
	v_fmac_f32_e32 v92, v49, v49
	v_fmac_f32_e32 v90, v50, v50
	v_fmac_f32_e32 v92, v51, v51
	v_fmac_f32_e32 v90, v52, v52
	v_fmac_f32_e32 v92, v53, v53
	v_fmac_f32_e32 v90, v54, v54
	v_fmac_f32_e32 v92, v55, v55
	v_fmac_f32_e32 v90, v56, v56
	v_fmac_f32_e32 v92, v57, v57
	v_add_f32_e32 v9, v9, v91
	v_add_f32_e32 v90, v90, v92
	s_nop 1
	v_add_f32_dpp v9, v9, v9 quad_perm:[1,0,3,2] row_mask:0xf bank_mask:0xf
	v_add_f32_dpp v90, v90, v90 quad_perm:[1,0,3,2] row_mask:0xf bank_mask:0xf
	s_nop 0
	v_add_f32_dpp v9, v9, v9 quad_perm:[2,3,0,1] row_mask:0xf bank_mask:0xf
	v_add_f32_dpp v90, v90, v90 quad_perm:[2,3,0,1] row_mask:0xf bank_mask:0xf
	s_nop 0
	v_add_f32_dpp v9, v9, v9 row_half_mirror row_mask:0xf bank_mask:0xf
	v_add_f32_dpp v90, v90, v90 row_half_mirror row_mask:0xf bank_mask:0xf
	s_nop 0
	v_add_f32_dpp v9, v9, v9 row_mirror row_mask:0xf bank_mask:0xf
	v_add_f32_dpp v90, v90, v90 row_mirror row_mask:0xf bank_mask:0xf
	s_nop 0
	v_add_f32_dpp v9, v9, v9 row_bcast:15 row_mask:0xa bank_mask:0xf
	v_add_f32_dpp v90, v90, v90 row_bcast:15 row_mask:0xa bank_mask:0xf
	s_nop 0
	v_add_f32_dpp v9, v9, v9 row_bcast:31 row_mask:0xc bank_mask:0xf
	v_add_f32_dpp v90, v90, v90 row_bcast:31 row_mask:0xc bank_mask:0xf
	s_nop 0
	v_readlane_b32 s2, v9, 63
	v_readlane_b32 s3, v90, 63
	s_nop 1
	v_mov_b32_e32 v9, s2
	v_mov_b32_e32 v90, s3
	v_mul_f32_e32 v93, 0x3a800000, v9
	v_mul_f32_e32 v91, 0x3a800000, v90
	v_fma_f32 v91, -v93, v93, v91
	v_max_f32_e32 v91, 0, v91
	v_add_f32_e32 v91, 0x358637bd, v91
	v_rsq_f32_e32 v94, v91
	v_mul_f32_e32 v91, 0.5, v91
	v_mul_f32_e32 v92, v94, v94
	v_fma_f32 v92, -v91, v92, 0.5
	v_fma_f32 v94, v94, v92, v94
	v_sub_f32_e32 v42, v42, v93
	v_sub_f32_e32 v43, v43, v93
	v_sub_f32_e32 v44, v44, v93
	v_sub_f32_e32 v45, v45, v93
	v_sub_f32_e32 v46, v46, v93
	v_sub_f32_e32 v47, v47, v93
	v_sub_f32_e32 v48, v48, v93
	v_sub_f32_e32 v49, v49, v93
	v_sub_f32_e32 v50, v50, v93
	v_sub_f32_e32 v51, v51, v93
	v_sub_f32_e32 v52, v52, v93
	v_sub_f32_e32 v53, v53, v93
	v_sub_f32_e32 v54, v54, v93
	v_sub_f32_e32 v55, v55, v93
	v_sub_f32_e32 v56, v56, v93
	v_sub_f32_e32 v57, v57, v93
	v_mul_f32_e32 v42, v94, v42
	v_mul_f32_e32 v43, v94, v43
	v_mul_f32_e32 v44, v94, v44
	v_mul_f32_e32 v45, v94, v45
	v_mul_f32_e32 v46, v94, v46
	v_mul_f32_e32 v47, v94, v47
	v_mul_f32_e32 v48, v94, v48
	v_mul_f32_e32 v49, v94, v49
	v_mul_f32_e32 v50, v94, v50
	v_mul_f32_e32 v51, v94, v51
	v_mul_f32_e32 v52, v94, v52
	v_mul_f32_e32 v53, v94, v53
	v_mul_f32_e32 v54, v94, v54
	v_mul_f32_e32 v55, v94, v55
	v_mul_f32_e32 v56, v94, v56
	v_mul_f32_e32 v57, v94, v57
	v_fma_f32 v42, v42, v10, v26
	v_fma_f32 v43, v43, v11, v27
	v_fma_f32 v44, v44, v12, v28
	v_fma_f32 v45, v45, v13, v29
	v_fma_f32 v46, v46, v14, v30
	v_fma_f32 v47, v47, v15, v31
	v_fma_f32 v48, v48, v16, v32
	v_fma_f32 v49, v49, v17, v33
	v_fma_f32 v50, v50, v18, v34
	v_fma_f32 v51, v51, v19, v35
	v_fma_f32 v52, v52, v20, v36
	v_fma_f32 v53, v53, v21, v37
	v_fma_f32 v54, v54, v22, v38
	v_fma_f32 v55, v55, v23, v39
	v_fma_f32 v56, v56, v24, v40
	v_fma_f32 v57, v57, v25, v41
	s_add_u32 s2, s8, 0x4000
	s_addc_u32 s3, s9, 0
	global_store_dwordx4 v0, v[42:45], s[2:3]
	global_store_dwordx4 v0, v[46:49], s[2:3] offset:1024
	global_store_dwordx4 v0, v[50:53], s[2:3] offset:2048
	global_store_dwordx4 v0, v[54:57], s[2:3] offset:3072
	s_waitcnt vmcnt(20)
	v_add_f32_e32 v9, v58, v59
	v_add_f32_e32 v91, v60, v61
	v_mul_f32_e32 v90, v58, v58
	v_mul_f32_e32 v92, v59, v59
	v_add_f32_e32 v9, v9, v62
	v_add_f32_e32 v91, v91, v63
	v_add_f32_e32 v9, v9, v64
	v_add_f32_e32 v91, v91, v65
	v_add_f32_e32 v9, v9, v66
	v_add_f32_e32 v91, v91, v67
	v_add_f32_e32 v9, v9, v68
	v_add_f32_e32 v91, v91, v69
	v_add_f32_e32 v9, v9, v70
	v_add_f32_e32 v91, v91, v71
	v_add_f32_e32 v9, v9, v72
	v_add_f32_e32 v91, v91, v73
	v_fmac_f32_e32 v90, v60, v60
	v_fmac_f32_e32 v92, v61, v61
	v_fmac_f32_e32 v90, v62, v62
	v_fmac_f32_e32 v92, v63, v63
	v_fmac_f32_e32 v90, v64, v64
	v_fmac_f32_e32 v92, v65, v65
	v_fmac_f32_e32 v90, v66, v66
	v_fmac_f32_e32 v92, v67, v67
	v_fmac_f32_e32 v90, v68, v68
	v_fmac_f32_e32 v92, v69, v69
	v_fmac_f32_e32 v90, v70, v70
	v_fmac_f32_e32 v92, v71, v71
	v_fmac_f32_e32 v90, v72, v72
	v_fmac_f32_e32 v92, v73, v73
	v_add_f32_e32 v9, v9, v91
	v_add_f32_e32 v90, v90, v92
	s_nop 1
	v_add_f32_dpp v9, v9, v9 quad_perm:[1,0,3,2] row_mask:0xf bank_mask:0xf
	v_add_f32_dpp v90, v90, v90 quad_perm:[1,0,3,2] row_mask:0xf bank_mask:0xf
	s_nop 0
	v_add_f32_dpp v9, v9, v9 quad_perm:[2,3,0,1] row_mask:0xf bank_mask:0xf
	v_add_f32_dpp v90, v90, v90 quad_perm:[2,3,0,1] row_mask:0xf bank_mask:0xf
	s_nop 0
	v_add_f32_dpp v9, v9, v9 row_half_mirror row_mask:0xf bank_mask:0xf
	v_add_f32_dpp v90, v90, v90 row_half_mirror row_mask:0xf bank_mask:0xf
	s_nop 0
	v_add_f32_dpp v9, v9, v9 row_mirror row_mask:0xf bank_mask:0xf
	v_add_f32_dpp v90, v90, v90 row_mirror row_mask:0xf bank_mask:0xf
	s_nop 0
	v_add_f32_dpp v9, v9, v9 row_bcast:15 row_mask:0xa bank_mask:0xf
	v_add_f32_dpp v90, v90, v90 row_bcast:15 row_mask:0xa bank_mask:0xf
	s_nop 0
; DI float shx(float v, int m, int lane) { return __int_as_float(__builtin_amdgcn_ds_bpermute((lane ^ m) << 2, __float_as_int(v))); }
; DI void wave_sum2(float& a, float& b, int lane) {
; #pragma unroll
;     for (int o = 1; o < 64; o <<= 1) { const float ta = shx(a, o, lane), tb = shx(b, o, lane); a += ta; b += tb; }
; }
; DI void ln_row_v(const Frame& F, f32x4 (&v)[4], float* xout, const float* g, const float* b, const float* sh, const float* sc, bf16_t* hout, const float* slab, const float* gres, float* stat = nullptr) {
;     ...
;     if (g) {
;         float s = 0.f, s2 = 0.f;
; #pragma unroll
;         for (int j = 0; j < 4; ++j) { s += (v[j][0] + v[j][1]) + (v[j][2] + v[j][3]); s2 += (v[j][0] * v[j][0] + v[j][1] * v[j][1]) + (v[j][2] * v[j][2] + v[j][3] * v[j][3]); }
;         wave_sum2(s, s2, F.lane);
;         const float mean = s * (1.f / D); const float rstd = 1.f / sqrtf(fmaxf(s2 * (1.f / D) - mean * mean, 0.f) + EPS);
;         if (stat && F.lane == 0) { f32x2 sv = {mean, rstd}; *(f32x2*)stat = sv; }
; #pragma unroll
;         for (int j = 0; j < 4; ++j) { const f32x4 gg = ((const f32x4*)g)[F.lane + 64 * j], bb = ((const f32x4*)b)[F.lane + 64 * j];
;             v[j] = (v[j] - mean) * rstd * gg + bb; if (xout) ((f32x4*)xout)[F.lane + 64 * j] = v[j]; }
;     }
	v_add_f32_dpp v9, v9, v9 row_bcast:31 row_mask:0xc bank_mask:0xf
	v_add_f32_dpp v90, v90, v90 row_bcast:31 row_mask:0xc bank_mask:0xf
	s_nop 0
	v_readlane_b32 s2, v9, 63
	v_readlane_b32 s3, v90, 63
	s_nop 1
	v_mov_b32_e32 v9, s2
	v_mov_b32_e32 v90, s3
	v_mul_f32_e32 v93, 0x3a800000, v9
	v_mul_f32_e32 v91, 0x3a800000, v90
	v_fma_f32 v91, -v93, v93, v91
	v_max_f32_e32 v91, 0, v91
	v_add_f32_e32 v91, 0x358637bd, v91
	v_rsq_f32_e32 v94, v91
	v_mul_f32_e32 v91, 0.5, v91
	v_mul_f32_e32 v92, v94, v94
	v_fma_f32 v92, -v91, v92, 0.5
	v_fma_f32 v94, v94, v92, v94
	v_sub_f32_e32 v58, v58, v93
	v_sub_f32_e32 v59, v59, v93
	v_sub_f32_e32 v60, v60, v93
	v_sub_f32_e32 v61, v61, v93
	v_sub_f32_e32 v62, v62, v93
	v_sub_f32_e32 v63, v63, v93
	v_sub_f32_e32 v64, v64, v93
	v_sub_f32_e32 v65, v65, v93
	v_sub_f32_e32 v66, v66, v93
	v_sub_f32_e32 v67, v67, v93
	v_sub_f32_e32 v68, v68, v93
	v_sub_f32_e32 v69, v69, v93
	v_sub_f32_e32 v70, v70, v93
	v_sub_f32_e32 v71, v71, v93
	v_sub_f32_e32 v72, v72, v93
	v_sub_f32_e32 v73, v73, v93
	v_mul_f32_e32 v58, v94, v58
	v_mul_f32_e32 v59, v94, v59
	v_mul_f32_e32 v60, v94, v60
	v_mul_f32_e32 v61, v94, v61
	v_mul_f32_e32 v62, v94, v62
	v_mul_f32_e32 v63, v94, v63
	v_mul_f32_e32 v64, v94, v64
	v_mul_f32_e32 v65, v94, v65
	v_mul_f32_e32 v66, v94, v66
	v_mul_f32_e32 v67, v94, v67
	v_mul_f32_e32 v68, v94, v68
	v_mul_f32_e32 v69, v94, v69
	v_mul_f32_e32 v70, v94, v70
	v_mul_f32_e32 v71, v94, v71
	v_mul_f32_e32 v72, v94, v72
	v_mul_f32_e32 v73, v94, v73
	v_fma_f32 v58, v58, v10, v26
	v_fma_f32 v59, v59, v11, v27
	v_fma_f32 v60, v60, v12, v28
	v_fma_f32 v61, v61, v13, v29
	v_fma_f32 v62, v62, v14, v30
	v_fma_f32 v63, v63, v15, v31
	v_fma_f32 v64, v64, v16, v32
	v_fma_f32 v65, v65, v17, v33
	v_fma_f32 v66, v66, v18, v34
	v_fma_f32 v67, v67, v19, v35
	v_fma_f32 v68, v68, v20, v36
	v_fma_f32 v69, v69, v21, v37
	v_fma_f32 v70, v70, v22, v38
	v_fma_f32 v71, v71, v23, v39
	v_fma_f32 v72, v72, v24, v40
	v_fma_f32 v73, v73, v25, v41
	s_add_u32 s2, s8, 0x5000
	s_addc_u32 s3, s9, 0
	global_store_dwordx4 v0, v[58:61], s[2:3]
	global_store_dwordx4 v0, v[62:65], s[2:3] offset:1024
	global_store_dwordx4 v0, v[66:69], s[2:3] offset:2048
	global_store_dwordx4 v0, v[70:73], s[2:3] offset:3072
	s_waitcnt vmcnt(16)
	v_add_f32_e32 v9, v74, v75
	v_add_f32_e32 v91, v76, v77
	v_mul_f32_e32 v90, v74, v74
	v_mul_f32_e32 v92, v75, v75
	v_add_f32_e32 v9, v9, v78
	v_add_f32_e32 v91, v91, v79
	v_add_f32_e32 v9, v9, v80
	v_add_f32_e32 v91, v91, v81
	v_add_f32_e32 v9, v9, v82
	v_add_f32_e32 v91, v91, v83
	v_add_f32_e32 v9, v9, v84
	v_add_f32_e32 v91, v91, v85
	v_add_f32_e32 v9, v9, v86
	v_add_f32_e32 v91, v91, v87
	v_add_f32_e32 v9, v9, v88
	v_add_f32_e32 v91, v91, v89
	v_fmac_f32_e32 v90, v76, v76
	v_fmac_f32_e32 v92, v77, v77
	v_fmac_f32_e32 v90, v78, v78
	v_fmac_f32_e32 v92, v79, v79
	v_fmac_f32_e32 v90, v80, v80
	v_fmac_f32_e32 v92, v81, v81
	v_fmac_f32_e32 v90, v82, v82
	v_fmac_f32_e32 v92, v83, v83
	v_fmac_f32_e32 v90, v84, v84
	v_fmac_f32_e32 v92, v85, v85
	v_fmac_f32_e32 v90, v86, v86
	v_fmac_f32_e32 v92, v87, v87
	v_fmac_f32_e32 v90, v88, v88
	v_fmac_f32_e32 v92, v89, v89
	v_add_f32_e32 v9, v9, v91
	v_add_f32_e32 v90, v90, v92
	s_nop 1
	v_add_f32_dpp v9, v9, v9 quad_perm:[1,0,3,2] row_mask:0xf bank_mask:0xf
	v_add_f32_dpp v90, v90, v90 quad_perm:[1,0,3,2] row_mask:0xf bank_mask:0xf
	s_nop 0
	v_add_f32_dpp v9, v9, v9 quad_perm:[2,3,0,1] row_mask:0xf bank_mask:0xf
	v_add_f32_dpp v90, v90, v90 quad_perm:[2,3,0,1] row_mask:0xf bank_mask:0xf
	s_nop 0
	v_add_f32_dpp v9, v9, v9 row_half_mirror row_mask:0xf bank_mask:0xf
	v_add_f32_dpp v90, v90, v90 row_half_mirror row_mask:0xf bank_mask:0xf
	s_nop 0
	v_add_f32_dpp v9, v9, v9 row_mirror row_mask:0xf bank_mask:0xf
	v_add_f32_dpp v90, v90, v90 row_mirror row_mask:0xf bank_mask:0xf
	s_nop 0
	v_add_f32_dpp v9, v9, v9 row_bcast:15 row_mask:0xa bank_mask:0xf
	v_add_f32_dpp v90, v90, v90 row_bcast:15 row_mask:0xa bank_mask:0xf
	s_nop 0
	v_add_f32_dpp v9, v9, v9 row_bcast:31 row_mask:0xc bank_mask:0xf
	v_add_f32_dpp v90, v90, v90 row_bcast:31 row_mask:0xc bank_mask:0xf
	s_nop 0
	v_readlane_b32 s2, v9, 63
	v_readlane_b32 s3, v90, 63
	s_nop 1
	v_mov_b32_e32 v9, s2
	v_mov_b32_e32 v90, s3
	v_mul_f32_e32 v93, 0x3a800000, v9
	v_mul_f32_e32 v91, 0x3a800000, v90
	v_fma_f32 v91, -v93, v93, v91
	v_max_f32_e32 v91, 0, v91
	v_add_f32_e32 v91, 0x358637bd, v91
	v_rsq_f32_e32 v94, v91
	v_mul_f32_e32 v91, 0.5, v91
	v_mul_f32_e32 v92, v94, v94
	v_fma_f32 v92, -v91, v92, 0.5
	v_fma_f32 v94, v94, v92, v94
	v_sub_f32_e32 v74, v74, v93
	v_sub_f32_e32 v75, v75, v93
	v_sub_f32_e32 v76, v76, v93
	v_sub_f32_e32 v77, v77, v93
	v_sub_f32_e32 v78, v78, v93
	v_sub_f32_e32 v79, v79, v93
	v_sub_f32_e32 v80, v80, v93
	v_sub_f32_e32 v81, v81, v93
	v_sub_f32_e32 v82, v82, v93
	v_sub_f32_e32 v83, v83, v93
	v_sub_f32_e32 v84, v84, v93
	v_sub_f32_e32 v85, v85, v93
	v_sub_f32_e32 v86, v86, v93
	v_sub_f32_e32 v87, v87, v93
	v_sub_f32_e32 v88, v88, v93
	v_sub_f32_e32 v89, v89, v93
	v_mul_f32_e32 v74, v94, v74
	v_mul_f32_e32 v75, v94, v75
	v_mul_f32_e32 v76, v94, v76
	v_mul_f32_e32 v77, v94, v77
	v_mul_f32_e32 v78, v94, v78
	v_mul_f32_e32 v79, v94, v79
	v_mul_f32_e32 v80, v94, v80
	v_mul_f32_e32 v81, v94, v81
	v_mul_f32_e32 v82, v94, v82
	v_mul_f32_e32 v83, v94, v83
	v_mul_f32_e32 v84, v94, v84
	v_mul_f32_e32 v85, v94, v85
	v_mul_f32_e32 v86, v94, v86
	v_mul_f32_e32 v87, v94, v87
	v_mul_f32_e32 v88, v94, v88
	v_mul_f32_e32 v89, v94, v89
	v_fma_f32 v74, v74, v10, v26
	v_fma_f32 v75, v75, v11, v27
	v_fma_f32 v76, v76, v12, v28
	v_fma_f32 v77, v77, v13, v29
	v_fma_f32 v78, v78, v14, v30
	v_fma_f32 v79, v79, v15, v31
	v_fma_f32 v80, v80, v16, v32
	v_fma_f32 v81, v81, v17, v33
	v_fma_f32 v82, v82, v18, v34
	v_fma_f32 v83, v83, v19, v35
	v_fma_f32 v84, v84, v20, v36
	v_fma_f32 v85, v85, v21, v37
	v_fma_f32 v86, v86, v22, v38
	v_fma_f32 v87, v87, v23, v39
	v_fma_f32 v88, v88, v24, v40
	v_fma_f32 v89, v89, v25, v41
	s_add_u32 s2, s8, 0x6000
	s_addc_u32 s3, s9, 0
	global_store_dwordx4 v0, v[74:77], s[2:3]
	global_store_dwordx4 v0, v[78:81], s[2:3] offset:1024
	global_store_dwordx4 v0, v[82:85], s[2:3] offset:2048
	global_store_dwordx4 v0, v[86:89], s[2:3] offset:3072
	s_waitcnt vmcnt(12)
; DI float shx(float v, int m, int lane) { return __int_as_float(__builtin_amdgcn_ds_bpermute((lane ^ m) << 2, __float_as_int(v))); }
; DI void wave_sum2(float& a, float& b, int lane) {
; #pragma unroll
;     for (int o = 1; o < 64; o <<= 1) { const float ta = shx(a, o, lane), tb = shx(b, o, lane); a += ta; b += tb; }
; }
; DI void ln_row_v(const Frame& F, f32x4 (&v)[4], float* xout, const float* g, const float* b, const float* sh, const float* sc, bf16_t* hout, const float* slab, const float* gres, float* stat = nullptr) {
;     ...
;     if (g) {
;         float s = 0.f, s2 = 0.f;
; #pragma unroll
;         for (int j = 0; j < 4; ++j) { s += (v[j][0] + v[j][1]) + (v[j][2] + v[j][3]); s2 += (v[j][0] * v[j][0] + v[j][1] * v[j][1]) + (v[j][2] * v[j][2] + v[j][3] * v[j][3]); }
;         wave_sum2(s, s2, F.lane);
;         const float mean = s * (1.f / D); const float rstd = 1.f / sqrtf(fmaxf(s2 * (1.f / D) - mean * mean, 0.f) + EPS);
;         if (stat && F.lane == 0) { f32x2 sv = {mean, rstd}; *(f32x2*)stat = sv; }
; #pragma unroll
;         for (int j = 0; j < 4; ++j) { const f32x4 gg = ((const f32x4*)g)[F.lane + 64 * j], bb = ((const f32x4*)b)[F.lane + 64 * j];
;             v[j] = (v[j] - mean) * rstd * gg + bb; if (xout) ((f32x4*)xout)[F.lane + 64 * j] = v[j]; }
;     }
	v_add_f32_e32 v9, v98, v99
	v_add_f32_e32 v91, v100, v101
	v_mul_f32_e32 v90, v98, v98
	v_mul_f32_e32 v92, v99, v99
	v_add_f32_e32 v9, v9, v102
	v_add_f32_e32 v91, v91, v103
	v_add_f32_e32 v9, v9, v104
	v_add_f32_e32 v91, v91, v105
	v_add_f32_e32 v9, v9, v106
	v_add_f32_e32 v91, v91, v107
	v_add_f32_e32 v9, v9, v108
	v_add_f32_e32 v91, v91, v109
	v_add_f32_e32 v9, v9, v110
	v_add_f32_e32 v91, v91, v111
	v_add_f32_e32 v9, v9, v112
	v_add_f32_e32 v91, v91, v113
	v_fmac_f32_e32 v90, v100, v100
	v_fmac_f32_e32 v92, v101, v101
	v_fmac_f32_e32 v90, v102, v102
	v_fmac_f32_e32 v92, v103, v103
	v_fmac_f32_e32 v90, v104, v104
	v_fmac_f32_e32 v92, v105, v105
	v_fmac_f32_e32 v90, v106, v106
	v_fmac_f32_e32 v92, v107, v107
	v_fmac_f32_e32 v90, v108, v108
	v_fmac_f32_e32 v92, v109, v109
	v_fmac_f32_e32 v90, v110, v110
	v_fmac_f32_e32 v92, v111, v111
	v_fmac_f32_e32 v90, v112, v112
	v_fmac_f32_e32 v92, v113, v113
	v_add_f32_e32 v9, v9, v91
	v_add_f32_e32 v90, v90, v92
	s_nop 1
	v_add_f32_dpp v9, v9, v9 quad_perm:[1,0,3,2] row_mask:0xf bank_mask:0xf
	v_add_f32_dpp v90, v90, v90 quad_perm:[1,0,3,2] row_mask:0xf bank_mask:0xf
	s_nop 0
	v_add_f32_dpp v9, v9, v9 quad_perm:[2,3,0,1] row_mask:0xf bank_mask:0xf
	v_add_f32_dpp v90, v90, v90 quad_perm:[2,3,0,1] row_mask:0xf bank_mask:0xf
	s_nop 0
	v_add_f32_dpp v9, v9, v9 row_half_mirror row_mask:0xf bank_mask:0xf
	v_add_f32_dpp v90, v90, v90 row_half_mirror row_mask:0xf bank_mask:0xf
	s_nop 0
	v_add_f32_dpp v9, v9, v9 row_mirror row_mask:0xf bank_mask:0xf
	v_add_f32_dpp v90, v90, v90 row_mirror row_mask:0xf bank_mask:0xf
	s_nop 0
	v_add_f32_dpp v9, v9, v9 row_bcast:15 row_mask:0xa bank_mask:0xf
	v_add_f32_dpp v90, v90, v90 row_bcast:15 row_mask:0xa bank_mask:0xf
	s_nop 0
	v_add_f32_dpp v9, v9, v9 row_bcast:31 row_mask:0xc bank_mask:0xf
	v_add_f32_dpp v90, v90, v90 row_bcast:31 row_mask:0xc bank_mask:0xf
	s_nop 0
	v_readlane_b32 s2, v9, 63
	v_readlane_b32 s3, v90, 63
	s_nop 1
	v_mov_b32_e32 v9, s2
	v_mov_b32_e32 v90, s3
	v_mul_f32_e32 v93, 0x3a800000, v9
	v_mul_f32_e32 v91, 0x3a800000, v90
	v_fma_f32 v91, -v93, v93, v91
	v_max_f32_e32 v91, 0, v91
	v_add_f32_e32 v91, 0x358637bd, v91
	v_rsq_f32_e32 v94, v91
	v_mul_f32_e32 v91, 0.5, v91
	v_mul_f32_e32 v92, v94, v94
	v_fma_f32 v92, -v91, v92, 0.5
	v_fma_f32 v94, v94, v92, v94
	v_sub_f32_e32 v98, v98, v93
	v_sub_f32_e32 v99, v99, v93
	v_sub_f32_e32 v100, v100, v93
	v_sub_f32_e32 v101, v101, v93
	v_sub_f32_e32 v102, v102, v93
	v_sub_f32_e32 v103, v103, v93
	v_sub_f32_e32 v104, v104, v93
	v_sub_f32_e32 v105, v105, v93
	v_sub_f32_e32 v106, v106, v93
	v_sub_f32_e32 v107, v107, v93
	v_sub_f32_e32 v108, v108, v93
	v_sub_f32_e32 v109, v109, v93
	v_sub_f32_e32 v110, v110, v93
	v_sub_f32_e32 v111, v111, v93
	v_sub_f32_e32 v112, v112, v93
	v_sub_f32_e32 v113, v113, v93
	v_mul_f32_e32 v98, v94, v98
	v_mul_f32_e32 v99, v94, v99
	v_mul_f32_e32 v100, v94, v100
	v_mul_f32_e32 v101, v94, v101
	v_mul_f32_e32 v102, v94, v102
	v_mul_f32_e32 v103, v94, v103
	v_mul_f32_e32 v104, v94, v104
	v_mul_f32_e32 v105, v94, v105
	v_mul_f32_e32 v106, v94, v106
	v_mul_f32_e32 v107, v94, v107
	v_mul_f32_e32 v108, v94, v108
	v_mul_f32_e32 v109, v94, v109
	v_mul_f32_e32 v110, v94, v110
	v_mul_f32_e32 v111, v94, v111
	v_mul_f32_e32 v112, v94, v112
	v_mul_f32_e32 v113, v94, v113
	v_fma_f32 v98, v98, v10, v26
	v_fma_f32 v99, v99, v11, v27
	v_fma_f32 v100, v100, v12, v28
	v_fma_f32 v101, v101, v13, v29
	v_fma_f32 v102, v102, v14, v30
	v_fma_f32 v103, v103, v15, v31
	v_fma_f32 v104, v104, v16, v32
	v_fma_f32 v105, v105, v17, v33
	v_fma_f32 v106, v106, v18, v34
	v_fma_f32 v107, v107, v19, v35
	v_fma_f32 v108, v108, v20, v36
	v_fma_f32 v109, v109, v21, v37
	v_fma_f32 v110, v110, v22, v38
	v_fma_f32 v111, v111, v23, v39
	v_fma_f32 v112, v112, v24, v40
	v_fma_f32 v113, v113, v25, v41
	s_add_u32 s2, s8, 0x7000
	s_addc_u32 s3, s9, 0
	global_store_dwordx4 v0, v[98:101], s[2:3]
	global_store_dwordx4 v0, v[102:105], s[2:3] offset:1024
	global_store_dwordx4 v0, v[106:109], s[2:3] offset:2048
	global_store_dwordx4 v0, v[110:113], s[2:3] offset:3072
	s_waitcnt vmcnt(0)

; DI unsigned pk2(float lo, float hi) { f32x2 v = {lo, hi}; bf16x2_t b = __builtin_convertvector(v, bf16x2_t); return __builtin_bit_cast(unsigned, b); }
; DI const float* modp(const Frame& F, int l, int mr, int which) { return (const float*)(F.ws + WS_MOD) + ((size_t)(l * 9 + mr) * 6 + which) * 1024; }
; DI void ln_row_v(const Frame& F, f32x4 (&v)[4], float* xout, const float* g, const float* b, const float* sh, const float* sc, bf16_t* hout, const float* slab, const float* gres, float* stat = nullptr) {
;     ...
;     if (hout) {
;         float s = 0.f, s2 = 0.f;
; #pragma unroll
;         for (int j = 0; j < 4; ++j) { s += (v[j][0] + v[j][1]) + (v[j][2] + v[j][3]); s2 += (v[j][0] * v[j][0] + v[j][1] * v[j][1]) + (v[j][2] * v[j][2] + v[j][3] * v[j][3]); }
;         wave_sum2(s, s2, F.lane);
;         const float mean = s * (1.f / D); const float rstd = 1.f / sqrtf(fmaxf(s2 * (1.f / D) - mean * mean, 0.f) + EPS);
; #pragma unroll
;         for (int j = 0; j < 4; ++j) { const f32x4 hh = ((const f32x4*)sh)[F.lane + 64 * j], cc = ((const f32x4*)sc)[F.lane + 64 * j];
;             const f32x4 o = (v[j] - mean) * rstd * (cc + 1.f) + hh; u32x2 wv; wv.x = pk2(o[0], o[1]); wv.y = pk2(o[2], o[3]);
;             ((u32x2*)hout)[F.lane + 64 * j] = wv; }
;     }
; DI void prologue_b(const Frame& F) {
;     const int gw = F.vcu * 8 + F.wave, NGW = F.G * 8;
;     bf16_t* H = (bf16_t*)(F.ws + WS_HB);
;     for (int row = gw; row < MT; row += NGW) {
;         const int mr = row < ML ? (row >> 11) : 8;
;         const float* xi = row < ML ? pin(F, I_X) + (size_t)row * D : pin(F, I_CTX) + (size_t)(row - ML) * D;
;         ln_row(F, xi, nullptr, nullptr, nullptr, modp(F, 0, mr, 0), modp(F, 0, mr, 1), H + (size_t)row * D);
;     }
; }
.LBB0_663:
	s_and_b64 vcc, exec, s[2:3]
	s_cbranch_vccz .LBB0_671
	v_readlane_b32 s2, v255, 29
	s_lshl_b32 s2, s2, 3
	v_readlane_b32 s3, v255, 31
	s_add_i32 s16, s3, s2
	v_lshlrev_b32_e32 v0, 4, v186
	v_lshlrev_b32_e32 v1, 3, v186
	v_lshlrev_b32_e32 v96, 2, v186
	v_xor_b32_e32 v3, 4, v96
	v_xor_b32_e32 v4, 8, v96
	v_xor_b32_e32 v5, 16, v96
	v_xor_b32_e32 v6, 32, v96
	v_xor_b32_e32 v7, 64, v96
	v_xor_b32_e32 v8, 128, v96
	s_load_dwordx2 s[8:9], s[62:63], 0x0
	s_load_dwordx2 s[20:21], s[62:63], 0x10
	s_mov_b32 s22, 0
	s_lshl_b32 s2, s16, 12
	s_lshl_b32 s3, s16, 15
	s_waitcnt lgkmcnt(0)
	s_add_u32 s8, s8, s3
	s_addc_u32 s9, s9, 0
	s_add_u32 s20, s20, s2
	s_addc_u32 s21, s21, 0
	s_lshl_b32 s2, s16, 14
	s_add_u32 s10, s94, s2
	s_addc_u32 s11, s95, 0
	s_add_u32 s10, s10, 0x3e00000
	s_addc_u32 s11, s11, 0
	s_lshl_b32 s2, s16, 6
	s_add_u32 s12, s94, s2
	s_addc_u32 s13, s95, 0
	s_add_u32 s12, s12, 0x4c0000
	s_addc_u32 s13, s13, 0
	s_mov_b32 s3, 0
	s_mul_i32 s3, s3, 0x36000
	s_add_u32 s14, s94, s3
	s_addc_u32 s15, s95, 0
	s_add_u32 s14, s14, 0x100000
	s_addc_u32 s15, s15, 0
	s_add_u32 s18, s14, 0x1000
	s_addc_u32 s19, s15, 0
	s_add_u32 s2, s8, 0x0
	s_addc_u32 s3, s9, 0
	global_load_dwordx4 v[42:45], v0, s[2:3]
	global_load_dwordx4 v[46:49], v0, s[2:3] offset:1024
	global_load_dwordx4 v[50:53], v0, s[2:3] offset:2048
	global_load_dwordx4 v[54:57], v0, s[2:3] offset:3072
	s_lshr_b32 s23, s16, 8
	s_mul_i32 s23, s23, 0x6000
	s_add_u32 s2, s14, s23
	s_addc_u32 s3, s15, 0
	global_load_dwordx4 v[114:117], v0, s[2:3]
	global_load_dwordx4 v[118:121], v0, s[2:3] offset:1024
	global_load_dwordx4 v[122:125], v0, s[2:3] offset:2048
	global_load_dwordx4 v[126:129], v0, s[2:3] offset:3072
	s_add_u32 s2, s18, s23
	s_addc_u32 s3, s19, 0
	global_load_dwordx4 v[130:133], v0, s[2:3]
	global_load_dwordx4 v[134:137], v0, s[2:3] offset:1024
	global_load_dwordx4 v[138:141], v0, s[2:3] offset:2048
	global_load_dwordx4 v[142:145], v0, s[2:3] offset:3072
	s_add_u32 s2, s8, 0x1000
	s_addc_u32 s3, s9, 0
	global_load_dwordx4 v[58:61], v0, s[2:3]
	global_load_dwordx4 v[62:65], v0, s[2:3] offset:1024
	global_load_dwordx4 v[66:69], v0, s[2:3] offset:2048
	global_load_dwordx4 v[70:73], v0, s[2:3] offset:3072
	s_mov_b32 s23, 0x30000
	s_add_u32 s2, s14, s23
	s_addc_u32 s3, s15, 0
	global_load_dwordx4 v[146:149], v0, s[2:3]
	global_load_dwordx4 v[150:153], v0, s[2:3] offset:1024
	global_load_dwordx4 v[154:157], v0, s[2:3] offset:2048
	global_load_dwordx4 v[158:161], v0, s[2:3] offset:3072
	s_add_u32 s2, s18, s23
	s_addc_u32 s3, s19, 0
	global_load_dwordx4 v[162:165], v0, s[2:3]
	global_load_dwordx4 v[166:169], v0, s[2:3] offset:1024
	global_load_dwordx4 v[170:173], v0, s[2:3] offset:2048
	global_load_dwordx4 v[174:177], v0, s[2:3] offset:3072
	s_add_u32 s2, s8, 0x2000
	s_addc_u32 s3, s9, 0
	global_load_dwordx4 v[74:77], v0, s[2:3]
	global_load_dwordx4 v[78:81], v0, s[2:3] offset:1024
	global_load_dwordx4 v[82:85], v0, s[2:3] offset:2048
	global_load_dwordx4 v[86:89], v0, s[2:3] offset:3072
	s_add_u32 s2, s8, 0x3000
	s_addc_u32 s3, s9, 0
	global_load_dwordx4 v[98:101], v0, s[2:3]
	global_load_dwordx4 v[102:105], v0, s[2:3] offset:1024
	global_load_dwordx4 v[106:109], v0, s[2:3] offset:2048
	global_load_dwordx4 v[110:113], v0, s[2:3] offset:3072
	s_waitcnt vmcnt(28)
	v_add_f32_e32 v9, v42, v43
	v_add_f32_e32 v91, v44, v45
	v_mul_f32_e32 v90, v42, v42
	v_mul_f32_e32 v92, v43, v43
	v_add_f32_e32 v9, v9, v46
	v_add_f32_e32 v91, v91, v47
	v_add_f32_e32 v9, v9, v48
	v_add_f32_e32 v91, v91, v49
	v_add_f32_e32 v9, v9, v50
	v_add_f32_e32 v91, v91, v51
	v_add_f32_e32 v9, v9, v52
	v_add_f32_e32 v91, v91, v53
	v_add_f32_e32 v9, v9, v54
	v_add_f32_e32 v91, v91, v55
	v_add_f32_e32 v9, v9, v56
	v_add_f32_e32 v91, v91, v57
	v_fmac_f32_e32 v90, v44, v44
	v_fmac_f32_e32 v92, v45, v45
	v_fmac_f32_e32 v90, v46, v46
	v_fmac_f32_e32 v92, v47, v47
	v_fmac_f32_e32 v90, v48, v48
	v_fmac_f32_e32 v92, v49, v49
	v_fmac_f32_e32 v90, v50, v50
	v_fmac_f32_e32 v92, v51, v51
	v_fmac_f32_e32 v90, v52, v52
	v_fmac_f32_e32 v92, v53, v53
	v_fmac_f32_e32 v90, v54, v54
	v_fmac_f32_e32 v92, v55, v55
	v_fmac_f32_e32 v90, v56, v56
	v_fmac_f32_e32 v92, v57, v57
	v_add_f32_e32 v9, v9, v91
	v_add_f32_e32 v90, v90, v92
	s_nop 1
	v_add_f32_dpp v9, v9, v9 quad_perm:[1,0,3,2] row_mask:0xf bank_mask:0xf
	v_add_f32_dpp v90, v90, v90 quad_perm:[1,0,3,2] row_mask:0xf bank_mask:0xf
	s_nop 0
	v_add_f32_dpp v9, v9, v9 quad_perm:[2,3,0,1] row_mask:0xf bank_mask:0xf
	v_add_f32_dpp v90, v90, v90 quad_perm:[2,3,0,1] row_mask:0xf bank_mask:0xf
	s_nop 0
	v_add_f32_dpp v9, v9, v9 row_half_mirror row_mask:0xf bank_mask:0xf
	v_add_f32_dpp v90, v90, v90 row_half_mirror row_mask:0xf bank_mask:0xf
	s_nop 0
	v_add_f32_dpp v9, v9, v9 row_mirror row_mask:0xf bank_mask:0xf
	v_add_f32_dpp v90, v90, v90 row_mirror row_mask:0xf bank_mask:0xf
	s_nop 0
	v_add_f32_dpp v9, v9, v9 row_bcast:15 row_mask:0xa bank_mask:0xf
	v_add_f32_dpp v90, v90, v90 row_bcast:15 row_mask:0xa bank_mask:0xf
	s_nop 0
	v_add_f32_dpp v9, v9, v9 row_bcast:31 row_mask:0xc bank_mask:0xf
	v_add_f32_dpp v90, v90, v90 row_bcast:31 row_mask:0xc bank_mask:0xf
	s_nop 0
	v_readlane_b32 s2, v9, 63
	v_readlane_b32 s3, v90, 63
	s_nop 1
	v_mov_b32_e32 v9, s2
	v_mov_b32_e32 v90, s3
	v_mul_f32_e32 v93, 0x3a800000, v9
	v_mul_f32_e32 v91, 0x3a800000, v90
	v_fma_f32 v91, -v93, v93, v91
	v_max_f32_e32 v91, 0, v91
	v_add_f32_e32 v91, 0x358637bd, v91
	v_rsq_f32_e32 v94, v91
	v_mul_f32_e32 v91, 0.5, v91
	v_mul_f32_e32 v92, v94, v94
	v_fma_f32 v92, -v91, v92, 0.5
	v_fma_f32 v94, v94, v92, v94
	s_waitcnt vmcnt(20)
; DI unsigned pk2(float lo, float hi) { f32x2 v = {lo, hi}; bf16x2_t b = __builtin_convertvector(v, bf16x2_t); return __builtin_bit_cast(unsigned, b); }
; DI float shx(float v, int m, int lane) { return __int_as_float(__builtin_amdgcn_ds_bpermute((lane ^ m) << 2, __float_as_int(v))); }
; DI void wave_sum2(float& a, float& b, int lane) {
; #pragma unroll
;     for (int o = 1; o < 64; o <<= 1) { const float ta = shx(a, o, lane), tb = shx(b, o, lane); a += ta; b += tb; }
; }
; DI void ln_row_v(const Frame& F, f32x4 (&v)[4], float* xout, const float* g, const float* b, const float* sh, const float* sc, bf16_t* hout, const float* slab, const float* gres, float* stat = nullptr) {
;     ...
;     if (hout) {
;         float s = 0.f, s2 = 0.f;
; #pragma unroll
;         for (int j = 0; j < 4; ++j) { s += (v[j][0] + v[j][1]) + (v[j][2] + v[j][3]); s2 += (v[j][0] * v[j][0] + v[j][1] * v[j][1]) + (v[j][2] * v[j][2] + v[j][3] * v[j][3]); }
;         wave_sum2(s, s2, F.lane);
;         const float mean = s * (1.f / D); const float rstd = 1.f / sqrtf(fmaxf(s2 * (1.f / D) - mean * mean, 0.f) + EPS);
; #pragma unroll
;         for (int j = 0; j < 4; ++j) { const f32x4 hh = ((const f32x4*)sh)[F.lane + 64 * j], cc = ((const f32x4*)sc)[F.lane + 64 * j];
;             const f32x4 o = (v[j] - mean) * rstd * (cc + 1.f) + hh; u32x2 wv; wv.x = pk2(o[0], o[1]); wv.y = pk2(o[2], o[3]);
;             ((u32x2*)hout)[F.lane + 64 * j] = wv; }
;     }
	v_sub_f32_e32 v42, v42, v93
	v_sub_f32_e32 v43, v43, v93
	v_sub_f32_e32 v44, v44, v93
	v_sub_f32_e32 v45, v45, v93
	v_sub_f32_e32 v46, v46, v93
	v_sub_f32_e32 v47, v47, v93
	v_sub_f32_e32 v48, v48, v93
	v_sub_f32_e32 v49, v49, v93
	v_sub_f32_e32 v50, v50, v93
	v_sub_f32_e32 v51, v51, v93
	v_sub_f32_e32 v52, v52, v93
	v_sub_f32_e32 v53, v53, v93
	v_sub_f32_e32 v54, v54, v93
	v_sub_f32_e32 v55, v55, v93
	v_sub_f32_e32 v56, v56, v93
	v_sub_f32_e32 v57, v57, v93
	v_add_f32_e32 v130, 1.0, v130
	v_add_f32_e32 v131, 1.0, v131
	v_add_f32_e32 v132, 1.0, v132
	v_add_f32_e32 v133, 1.0, v133
	v_add_f32_e32 v134, 1.0, v134
	v_add_f32_e32 v135, 1.0, v135
	v_add_f32_e32 v136, 1.0, v136
	v_add_f32_e32 v137, 1.0, v137
	v_add_f32_e32 v138, 1.0, v138
	v_add_f32_e32 v139, 1.0, v139
	v_add_f32_e32 v140, 1.0, v140
	v_add_f32_e32 v141, 1.0, v141
	v_add_f32_e32 v142, 1.0, v142
	v_add_f32_e32 v143, 1.0, v143
	v_add_f32_e32 v144, 1.0, v144
	v_add_f32_e32 v145, 1.0, v145
	v_mul_f32_e32 v42, v94, v42
	v_mul_f32_e32 v43, v94, v43
	v_mul_f32_e32 v44, v94, v44
	v_mul_f32_e32 v45, v94, v45
	v_mul_f32_e32 v46, v94, v46
	v_mul_f32_e32 v47, v94, v47
	v_mul_f32_e32 v48, v94, v48
	v_mul_f32_e32 v49, v94, v49
	v_mul_f32_e32 v50, v94, v50
	v_mul_f32_e32 v51, v94, v51
	v_mul_f32_e32 v52, v94, v52
	v_mul_f32_e32 v53, v94, v53
	v_mul_f32_e32 v54, v94, v54
	v_mul_f32_e32 v55, v94, v55
	v_mul_f32_e32 v56, v94, v56
	v_mul_f32_e32 v57, v94, v57
	v_fma_f32 v42, v42, v130, v114
	v_fma_f32 v43, v43, v131, v115
	v_fma_f32 v44, v44, v132, v116
	v_fma_f32 v45, v45, v133, v117
	v_fma_f32 v46, v46, v134, v118
	v_fma_f32 v47, v47, v135, v119
	v_fma_f32 v48, v48, v136, v120
	v_fma_f32 v49, v49, v137, v121
	v_fma_f32 v50, v50, v138, v122
	v_fma_f32 v51, v51, v139, v123
	v_fma_f32 v52, v52, v140, v124
	v_fma_f32 v53, v53, v141, v125
	v_fma_f32 v54, v54, v142, v126
	v_fma_f32 v55, v55, v143, v127
	v_fma_f32 v56, v56, v144, v128
	v_fma_f32 v57, v57, v145, v129
	v_cvt_pk_bf16_f32 v190, v42, v43
	v_cvt_pk_bf16_f32 v191, v44, v45
	v_cvt_pk_bf16_f32 v192, v46, v47
	v_cvt_pk_bf16_f32 v193, v48, v49
	v_cvt_pk_bf16_f32 v194, v50, v51
	v_cvt_pk_bf16_f32 v195, v52, v53
	v_cvt_pk_bf16_f32 v196, v54, v55
	v_cvt_pk_bf16_f32 v197, v56, v57
	s_add_u32 s2, s10, 0x0
	s_addc_u32 s3, s11, 0
	global_store_dwordx2 v1, v[190:191], s[2:3]
	global_store_dwordx2 v1, v[192:193], s[2:3] offset:512
	global_store_dwordx2 v1, v[194:195], s[2:3] offset:1024
	global_store_dwordx2 v1, v[196:197], s[2:3] offset:1536
	s_add_u32 s2, s8, 0x4000
	s_addc_u32 s3, s9, 0
	global_load_dwordx4 v[42:45], v0, s[2:3]
	global_load_dwordx4 v[46:49], v0, s[2:3] offset:1024
	global_load_dwordx4 v[50:53], v0, s[2:3] offset:2048
	global_load_dwordx4 v[54:57], v0, s[2:3] offset:3072
	s_waitcnt vmcnt(24)
	v_add_f32_e32 v9, v58, v59
	v_add_f32_e32 v91, v60, v61
	v_mul_f32_e32 v90, v58, v58
	v_mul_f32_e32 v92, v59, v59
	v_add_f32_e32 v9, v9, v62
	v_add_f32_e32 v91, v91, v63
	v_add_f32_e32 v9, v9, v64
	v_add_f32_e32 v91, v91, v65
	v_add_f32_e32 v9, v9, v66
	v_add_f32_e32 v91, v91, v67
	v_add_f32_e32 v9, v9, v68
	v_add_f32_e32 v91, v91, v69
	v_add_f32_e32 v9, v9, v70
	v_add_f32_e32 v91, v91, v71
	v_add_f32_e32 v9, v9, v72
	v_add_f32_e32 v91, v91, v73
	v_fmac_f32_e32 v90, v60, v60
	v_fmac_f32_e32 v92, v61, v61
	v_fmac_f32_e32 v90, v62, v62
	v_fmac_f32_e32 v92, v63, v63
	v_fmac_f32_e32 v90, v64, v64
	v_fmac_f32_e32 v92, v65, v65
	v_fmac_f32_e32 v90, v66, v66
	v_fmac_f32_e32 v92, v67, v67
	v_fmac_f32_e32 v90, v68, v68
	v_fmac_f32_e32 v92, v69, v69
	v_fmac_f32_e32 v90, v70, v70
	v_fmac_f32_e32 v92, v71, v71
	v_fmac_f32_e32 v90, v72, v72
	v_fmac_f32_e32 v92, v73, v73
	v_add_f32_e32 v9, v9, v91
	v_add_f32_e32 v90, v90, v92
	s_nop 1
	v_add_f32_dpp v9, v9, v9 quad_perm:[1,0,3,2] row_mask:0xf bank_mask:0xf
	v_add_f32_dpp v90, v90, v90 quad_perm:[1,0,3,2] row_mask:0xf bank_mask:0xf
	s_nop 0
	v_add_f32_dpp v9, v9, v9 quad_perm:[2,3,0,1] row_mask:0xf bank_mask:0xf
	v_add_f32_dpp v90, v90, v90 quad_perm:[2,3,0,1] row_mask:0xf bank_mask:0xf
	s_nop 0
	v_add_f32_dpp v9, v9, v9 row_half_mirror row_mask:0xf bank_mask:0xf
	v_add_f32_dpp v90, v90, v90 row_half_mirror row_mask:0xf bank_mask:0xf
	s_nop 0
	v_add_f32_dpp v9, v9, v9 row_mirror row_mask:0xf bank_mask:0xf
	v_add_f32_dpp v90, v90, v90 row_mirror row_mask:0xf bank_mask:0xf
	s_nop 0
	v_add_f32_dpp v9, v9, v9 row_bcast:15 row_mask:0xa bank_mask:0xf
	v_add_f32_dpp v90, v90, v90 row_bcast:15 row_mask:0xa bank_mask:0xf
	s_nop 0
	v_add_f32_dpp v9, v9, v9 row_bcast:31 row_mask:0xc bank_mask:0xf
	v_add_f32_dpp v90, v90, v90 row_bcast:31 row_mask:0xc bank_mask:0xf
	s_nop 0
	v_readlane_b32 s2, v9, 63
	v_readlane_b32 s3, v90, 63
	s_nop 1
	v_mov_b32_e32 v9, s2
	v_mov_b32_e32 v90, s3
	v_mul_f32_e32 v93, 0x3a800000, v9
	v_mul_f32_e32 v91, 0x3a800000, v90
	v_fma_f32 v91, -v93, v93, v91
	v_max_f32_e32 v91, 0, v91
	v_add_f32_e32 v91, 0x358637bd, v91
	v_rsq_f32_e32 v94, v91
	v_mul_f32_e32 v91, 0.5, v91
	v_mul_f32_e32 v92, v94, v94
	v_fma_f32 v92, -v91, v92, 0.5
	v_fma_f32 v94, v94, v92, v94
	v_sub_f32_e32 v58, v58, v93
	v_sub_f32_e32 v59, v59, v93
	v_sub_f32_e32 v60, v60, v93
	v_sub_f32_e32 v61, v61, v93
	v_sub_f32_e32 v62, v62, v93
	v_sub_f32_e32 v63, v63, v93
	v_sub_f32_e32 v64, v64, v93
	v_sub_f32_e32 v65, v65, v93
	v_sub_f32_e32 v66, v66, v93
	v_sub_f32_e32 v67, v67, v93
	v_sub_f32_e32 v68, v68, v93
	v_sub_f32_e32 v69, v69, v93
	v_sub_f32_e32 v70, v70, v93
	v_sub_f32_e32 v71, v71, v93
	v_sub_f32_e32 v72, v72, v93
	v_sub_f32_e32 v73, v73, v93
	v_mul_f32_e32 v58, v94, v58
	v_mul_f32_e32 v59, v94, v59
	v_mul_f32_e32 v60, v94, v60
	v_mul_f32_e32 v61, v94, v61
	v_mul_f32_e32 v62, v94, v62
	v_mul_f32_e32 v63, v94, v63
; DI unsigned pk2(float lo, float hi) { f32x2 v = {lo, hi}; bf16x2_t b = __builtin_convertvector(v, bf16x2_t); return __builtin_bit_cast(unsigned, b); }
; DI float shx(float v, int m, int lane) { return __int_as_float(__builtin_amdgcn_ds_bpermute((lane ^ m) << 2, __float_as_int(v))); }
; DI void wave_sum2(float& a, float& b, int lane) {
; #pragma unroll
;     for (int o = 1; o < 64; o <<= 1) { const float ta = shx(a, o, lane), tb = shx(b, o, lane); a += ta; b += tb; }
; }
; DI void ln_row_v(const Frame& F, f32x4 (&v)[4], float* xout, const float* g, const float* b, const float* sh, const float* sc, bf16_t* hout, const float* slab, const float* gres, float* stat = nullptr) {
;     ...
;     if (hout) {
;         float s = 0.f, s2 = 0.f;
; #pragma unroll
;         for (int j = 0; j < 4; ++j) { s += (v[j][0] + v[j][1]) + (v[j][2] + v[j][3]); s2 += (v[j][0] * v[j][0] + v[j][1] * v[j][1]) + (v[j][2] * v[j][2] + v[j][3] * v[j][3]); }
;         wave_sum2(s, s2, F.lane);
;         const float mean = s * (1.f / D); const float rstd = 1.f / sqrtf(fmaxf(s2 * (1.f / D) - mean * mean, 0.f) + EPS);
; #pragma unroll
;         for (int j = 0; j < 4; ++j) { const f32x4 hh = ((const f32x4*)sh)[F.lane + 64 * j], cc = ((const f32x4*)sc)[F.lane + 64 * j];
;             const f32x4 o = (v[j] - mean) * rstd * (cc + 1.f) + hh; u32x2 wv; wv.x = pk2(o[0], o[1]); wv.y = pk2(o[2], o[3]);
;             ((u32x2*)hout)[F.lane + 64 * j] = wv; }
;     }
	v_mul_f32_e32 v64, v94, v64
	v_mul_f32_e32 v65, v94, v65
	v_mul_f32_e32 v66, v94, v66
	v_mul_f32_e32 v67, v94, v67
	v_mul_f32_e32 v68, v94, v68
	v_mul_f32_e32 v69, v94, v69
	v_mul_f32_e32 v70, v94, v70
	v_mul_f32_e32 v71, v94, v71
	v_mul_f32_e32 v72, v94, v72
	v_mul_f32_e32 v73, v94, v73
	v_fma_f32 v58, v58, v130, v114
	v_fma_f32 v59, v59, v131, v115
	v_fma_f32 v60, v60, v132, v116
	v_fma_f32 v61, v61, v133, v117
	v_fma_f32 v62, v62, v134, v118
	v_fma_f32 v63, v63, v135, v119
	v_fma_f32 v64, v64, v136, v120
	v_fma_f32 v65, v65, v137, v121
	v_fma_f32 v66, v66, v138, v122
	v_fma_f32 v67, v67, v139, v123
	v_fma_f32 v68, v68, v140, v124
	v_fma_f32 v69, v69, v141, v125
	v_fma_f32 v70, v70, v142, v126
	v_fma_f32 v71, v71, v143, v127
	v_fma_f32 v72, v72, v144, v128
	v_fma_f32 v73, v73, v145, v129
	v_cvt_pk_bf16_f32 v190, v58, v59
	v_cvt_pk_bf16_f32 v191, v60, v61
	v_cvt_pk_bf16_f32 v192, v62, v63
	v_cvt_pk_bf16_f32 v193, v64, v65
	v_cvt_pk_bf16_f32 v194, v66, v67
	v_cvt_pk_bf16_f32 v195, v68, v69
	v_cvt_pk_bf16_f32 v196, v70, v71
	v_cvt_pk_bf16_f32 v197, v72, v73
	s_add_u32 s2, s10, 0x800
	s_addc_u32 s3, s11, 0
	global_store_dwordx2 v1, v[190:191], s[2:3]
	global_store_dwordx2 v1, v[192:193], s[2:3] offset:512
	global_store_dwordx2 v1, v[194:195], s[2:3] offset:1024
	global_store_dwordx2 v1, v[196:197], s[2:3] offset:1536
	s_add_u32 s2, s8, 0x5000
	s_addc_u32 s3, s9, 0
	global_load_dwordx4 v[58:61], v0, s[2:3]
	global_load_dwordx4 v[62:65], v0, s[2:3] offset:1024
	global_load_dwordx4 v[66:69], v0, s[2:3] offset:2048
	global_load_dwordx4 v[70:73], v0, s[2:3] offset:3072
	s_waitcnt vmcnt(20)
	v_add_f32_e32 v9, v74, v75
	v_add_f32_e32 v91, v76, v77
	v_mul_f32_e32 v90, v74, v74
	v_mul_f32_e32 v92, v75, v75
	v_add_f32_e32 v9, v9, v78
	v_add_f32_e32 v91, v91, v79
	v_add_f32_e32 v9, v9, v80
	v_add_f32_e32 v91, v91, v81
	v_add_f32_e32 v9, v9, v82
	v_add_f32_e32 v91, v91, v83
	v_add_f32_e32 v9, v9, v84
	v_add_f32_e32 v91, v91, v85
	v_add_f32_e32 v9, v9, v86
	v_add_f32_e32 v91, v91, v87
	v_add_f32_e32 v9, v9, v88
	v_add_f32_e32 v91, v91, v89
	v_fmac_f32_e32 v90, v76, v76
	v_fmac_f32_e32 v92, v77, v77
	v_fmac_f32_e32 v90, v78, v78
	v_fmac_f32_e32 v92, v79, v79
	v_fmac_f32_e32 v90, v80, v80
	v_fmac_f32_e32 v92, v81, v81
	v_fmac_f32_e32 v90, v82, v82
	v_fmac_f32_e32 v92, v83, v83
	v_fmac_f32_e32 v90, v84, v84
	v_fmac_f32_e32 v92, v85, v85
	v_fmac_f32_e32 v90, v86, v86
	v_fmac_f32_e32 v92, v87, v87
	v_fmac_f32_e32 v90, v88, v88
	v_fmac_f32_e32 v92, v89, v89
	v_add_f32_e32 v9, v9, v91
	v_add_f32_e32 v90, v90, v92
	s_nop 1
	v_add_f32_dpp v9, v9, v9 quad_perm:[1,0,3,2] row_mask:0xf bank_mask:0xf
	v_add_f32_dpp v90, v90, v90 quad_perm:[1,0,3,2] row_mask:0xf bank_mask:0xf
	s_nop 0
	v_add_f32_dpp v9, v9, v9 quad_perm:[2,3,0,1] row_mask:0xf bank_mask:0xf
	v_add_f32_dpp v90, v90, v90 quad_perm:[2,3,0,1] row_mask:0xf bank_mask:0xf
	s_nop 0
	v_add_f32_dpp v9, v9, v9 row_half_mirror row_mask:0xf bank_mask:0xf
	v_add_f32_dpp v90, v90, v90 row_half_mirror row_mask:0xf bank_mask:0xf
	s_nop 0
	v_add_f32_dpp v9, v9, v9 row_mirror row_mask:0xf bank_mask:0xf
	v_add_f32_dpp v90, v90, v90 row_mirror row_mask:0xf bank_mask:0xf
	s_nop 0
	v_add_f32_dpp v9, v9, v9 row_bcast:15 row_mask:0xa bank_mask:0xf
	v_add_f32_dpp v90, v90, v90 row_bcast:15 row_mask:0xa bank_mask:0xf
	s_nop 0
	v_add_f32_dpp v9, v9, v9 row_bcast:31 row_mask:0xc bank_mask:0xf
	v_add_f32_dpp v90, v90, v90 row_bcast:31 row_mask:0xc bank_mask:0xf
	s_nop 0
	v_readlane_b32 s2, v9, 63
	v_readlane_b32 s3, v90, 63
	s_nop 1
	v_mov_b32_e32 v9, s2
	v_mov_b32_e32 v90, s3
	v_mul_f32_e32 v93, 0x3a800000, v9
	v_mul_f32_e32 v91, 0x3a800000, v90
	v_fma_f32 v91, -v93, v93, v91
	v_max_f32_e32 v91, 0, v91
	v_add_f32_e32 v91, 0x358637bd, v91
	v_rsq_f32_e32 v94, v91
	v_mul_f32_e32 v91, 0.5, v91
	v_mul_f32_e32 v92, v94, v94
	v_fma_f32 v92, -v91, v92, 0.5
	v_fma_f32 v94, v94, v92, v94
	v_sub_f32_e32 v74, v74, v93
	v_sub_f32_e32 v75, v75, v93
	v_sub_f32_e32 v76, v76, v93
	v_sub_f32_e32 v77, v77, v93
	v_sub_f32_e32 v78, v78, v93
	v_sub_f32_e32 v79, v79, v93
	v_sub_f32_e32 v80, v80, v93
	v_sub_f32_e32 v81, v81, v93
	v_sub_f32_e32 v82, v82, v93
	v_sub_f32_e32 v83, v83, v93
	v_sub_f32_e32 v84, v84, v93
	v_sub_f32_e32 v85, v85, v93
	v_sub_f32_e32 v86, v86, v93
	v_sub_f32_e32 v87, v87, v93
	v_sub_f32_e32 v88, v88, v93
	v_sub_f32_e32 v89, v89, v93
	v_mul_f32_e32 v74, v94, v74
	v_mul_f32_e32 v75, v94, v75
	v_mul_f32_e32 v76, v94, v76
	v_mul_f32_e32 v77, v94, v77
	v_mul_f32_e32 v78, v94, v78
	v_mul_f32_e32 v79, v94, v79
	v_mul_f32_e32 v80, v94, v80
	v_mul_f32_e32 v81, v94, v81
	v_mul_f32_e32 v82, v94, v82
	v_mul_f32_e32 v83, v94, v83
	v_mul_f32_e32 v84, v94, v84
	v_mul_f32_e32 v85, v94, v85
	v_mul_f32_e32 v86, v94, v86
	v_mul_f32_e32 v87, v94, v87
	v_mul_f32_e32 v88, v94, v88
	v_mul_f32_e32 v89, v94, v89
	v_fma_f32 v74, v74, v130, v114
	v_fma_f32 v75, v75, v131, v115
	v_fma_f32 v76, v76, v132, v116
	v_fma_f32 v77, v77, v133, v117
	v_fma_f32 v78, v78, v134, v118
	v_fma_f32 v79, v79, v135, v119
	v_fma_f32 v80, v80, v136, v120
	v_fma_f32 v81, v81, v137, v121
	v_fma_f32 v82, v82, v138, v122
	v_fma_f32 v83, v83, v139, v123
	v_fma_f32 v84, v84, v140, v124
	v_fma_f32 v85, v85, v141, v125
	v_fma_f32 v86, v86, v142, v126
	v_fma_f32 v87, v87, v143, v127
	v_fma_f32 v88, v88, v144, v128
	v_fma_f32 v89, v89, v145, v129
	v_cvt_pk_bf16_f32 v190, v74, v75
	v_cvt_pk_bf16_f32 v191, v76, v77
	v_cvt_pk_bf16_f32 v192, v78, v79
	v_cvt_pk_bf16_f32 v193, v80, v81
	v_cvt_pk_bf16_f32 v194, v82, v83
	v_cvt_pk_bf16_f32 v195, v84, v85
	v_cvt_pk_bf16_f32 v196, v86, v87
	v_cvt_pk_bf16_f32 v197, v88, v89
	s_add_u32 s2, s10, 0x1000
	s_addc_u32 s3, s11, 0
	global_store_dwordx2 v1, v[190:191], s[2:3]
	global_store_dwordx2 v1, v[192:193], s[2:3] offset:512
	global_store_dwordx2 v1, v[194:195], s[2:3] offset:1024
	global_store_dwordx2 v1, v[196:197], s[2:3] offset:1536
	s_add_u32 s2, s8, 0x6000
	s_addc_u32 s3, s9, 0
	global_load_dwordx4 v[74:77], v0, s[2:3]
	global_load_dwordx4 v[78:81], v0, s[2:3] offset:1024
	global_load_dwordx4 v[82:85], v0, s[2:3] offset:2048
	global_load_dwordx4 v[86:89], v0, s[2:3] offset:3072
	s_waitcnt vmcnt(24)
; DI unsigned pk2(float lo, float hi) { f32x2 v = {lo, hi}; bf16x2_t b = __builtin_convertvector(v, bf16x2_t); return __builtin_bit_cast(unsigned, b); }
; DI float shx(float v, int m, int lane) { return __int_as_float(__builtin_amdgcn_ds_bpermute((lane ^ m) << 2, __float_as_int(v))); }
; DI void wave_sum2(float& a, float& b, int lane) {
; #pragma unroll
;     for (int o = 1; o < 64; o <<= 1) { const float ta = shx(a, o, lane), tb = shx(b, o, lane); a += ta; b += tb; }
; }
; DI void ln_row_v(const Frame& F, f32x4 (&v)[4], float* xout, const float* g, const float* b, const float* sh, const float* sc, bf16_t* hout, const float* slab, const float* gres, float* stat = nullptr) {
;     ...
;     if (hout) {
;         float s = 0.f, s2 = 0.f;
; #pragma unroll
;         for (int j = 0; j < 4; ++j) { s += (v[j][0] + v[j][1]) + (v[j][2] + v[j][3]); s2 += (v[j][0] * v[j][0] + v[j][1] * v[j][1]) + (v[j][2] * v[j][2] + v[j][3] * v[j][3]); }
;         wave_sum2(s, s2, F.lane);
;         const float mean = s * (1.f / D); const float rstd = 1.f / sqrtf(fmaxf(s2 * (1.f / D) - mean * mean, 0.f) + EPS);
; #pragma unroll
;         for (int j = 0; j < 4; ++j) { const f32x4 hh = ((const f32x4*)sh)[F.lane + 64 * j], cc = ((const f32x4*)sc)[F.lane + 64 * j];
;             const f32x4 o = (v[j] - mean) * rstd * (cc + 1.f) + hh; u32x2 wv; wv.x = pk2(o[0], o[1]); wv.y = pk2(o[2], o[3]);
;             ((u32x2*)hout)[F.lane + 64 * j] = wv; }
;     }
	v_add_f32_e32 v9, v98, v99
	v_add_f32_e32 v91, v100, v101
	v_mul_f32_e32 v90, v98, v98
	v_mul_f32_e32 v92, v99, v99
	v_add_f32_e32 v9, v9, v102
	v_add_f32_e32 v91, v91, v103
	v_add_f32_e32 v9, v9, v104
	v_add_f32_e32 v91, v91, v105
	v_add_f32_e32 v9, v9, v106
	v_add_f32_e32 v91, v91, v107
	v_add_f32_e32 v9, v9, v108
	v_add_f32_e32 v91, v91, v109
	v_add_f32_e32 v9, v9, v110
	v_add_f32_e32 v91, v91, v111
	v_add_f32_e32 v9, v9, v112
	v_add_f32_e32 v91, v91, v113
	v_fmac_f32_e32 v90, v100, v100
	v_fmac_f32_e32 v92, v101, v101
	v_fmac_f32_e32 v90, v102, v102
	v_fmac_f32_e32 v92, v103, v103
	v_fmac_f32_e32 v90, v104, v104
	v_fmac_f32_e32 v92, v105, v105
	v_fmac_f32_e32 v90, v106, v106
	v_fmac_f32_e32 v92, v107, v107
	v_fmac_f32_e32 v90, v108, v108
	v_fmac_f32_e32 v92, v109, v109
	v_fmac_f32_e32 v90, v110, v110
	v_fmac_f32_e32 v92, v111, v111
	v_fmac_f32_e32 v90, v112, v112
	v_fmac_f32_e32 v92, v113, v113
	v_add_f32_e32 v9, v9, v91
	v_add_f32_e32 v90, v90, v92
	s_nop 1
	v_add_f32_dpp v9, v9, v9 quad_perm:[1,0,3,2] row_mask:0xf bank_mask:0xf
	v_add_f32_dpp v90, v90, v90 quad_perm:[1,0,3,2] row_mask:0xf bank_mask:0xf
	s_nop 0
	v_add_f32_dpp v9, v9, v9 quad_perm:[2,3,0,1] row_mask:0xf bank_mask:0xf
	v_add_f32_dpp v90, v90, v90 quad_perm:[2,3,0,1] row_mask:0xf bank_mask:0xf
	s_nop 0
	v_add_f32_dpp v9, v9, v9 row_half_mirror row_mask:0xf bank_mask:0xf
	v_add_f32_dpp v90, v90, v90 row_half_mirror row_mask:0xf bank_mask:0xf
	s_nop 0
	v_add_f32_dpp v9, v9, v9 row_mirror row_mask:0xf bank_mask:0xf
	v_add_f32_dpp v90, v90, v90 row_mirror row_mask:0xf bank_mask:0xf
	s_nop 0
	v_add_f32_dpp v9, v9, v9 row_bcast:15 row_mask:0xa bank_mask:0xf
	v_add_f32_dpp v90, v90, v90 row_bcast:15 row_mask:0xa bank_mask:0xf
	s_nop 0
	v_add_f32_dpp v9, v9, v9 row_bcast:31 row_mask:0xc bank_mask:0xf
	v_add_f32_dpp v90, v90, v90 row_bcast:31 row_mask:0xc bank_mask:0xf
	s_nop 0
	v_readlane_b32 s2, v9, 63
	v_readlane_b32 s3, v90, 63
	s_nop 1
	v_mov_b32_e32 v9, s2
	v_mov_b32_e32 v90, s3
	v_mul_f32_e32 v93, 0x3a800000, v9
	v_mul_f32_e32 v91, 0x3a800000, v90
	v_fma_f32 v91, -v93, v93, v91
	v_max_f32_e32 v91, 0, v91
	v_add_f32_e32 v91, 0x358637bd, v91
	v_rsq_f32_e32 v94, v91
	v_mul_f32_e32 v91, 0.5, v91
	v_mul_f32_e32 v92, v94, v94
	v_fma_f32 v92, -v91, v92, 0.5
	v_fma_f32 v94, v94, v92, v94
	v_sub_f32_e32 v98, v98, v93
	v_sub_f32_e32 v99, v99, v93
	v_sub_f32_e32 v100, v100, v93
	v_sub_f32_e32 v101, v101, v93
	v_sub_f32_e32 v102, v102, v93
	v_sub_f32_e32 v103, v103, v93
	v_sub_f32_e32 v104, v104, v93
	v_sub_f32_e32 v105, v105, v93
	v_sub_f32_e32 v106, v106, v93
	v_sub_f32_e32 v107, v107, v93
	v_sub_f32_e32 v108, v108, v93
	v_sub_f32_e32 v109, v109, v93
	v_sub_f32_e32 v110, v110, v93
	v_sub_f32_e32 v111, v111, v93
	v_sub_f32_e32 v112, v112, v93
	v_sub_f32_e32 v113, v113, v93
	v_mul_f32_e32 v98, v94, v98
	v_mul_f32_e32 v99, v94, v99
	v_mul_f32_e32 v100, v94, v100
	v_mul_f32_e32 v101, v94, v101
	v_mul_f32_e32 v102, v94, v102
	v_mul_f32_e32 v103, v94, v103
	v_mul_f32_e32 v104, v94, v104
	v_mul_f32_e32 v105, v94, v105
	v_mul_f32_e32 v106, v94, v106
	v_mul_f32_e32 v107, v94, v107
	v_mul_f32_e32 v108, v94, v108
	v_mul_f32_e32 v109, v94, v109
	v_mul_f32_e32 v110, v94, v110
	v_mul_f32_e32 v111, v94, v111
	v_mul_f32_e32 v112, v94, v112
	v_mul_f32_e32 v113, v94, v113
	v_fma_f32 v98, v98, v130, v114
	v_fma_f32 v99, v99, v131, v115
	v_fma_f32 v100, v100, v132, v116
	v_fma_f32 v101, v101, v133, v117
	v_fma_f32 v102, v102, v134, v118
	v_fma_f32 v103, v103, v135, v119
	v_fma_f32 v104, v104, v136, v120
	v_fma_f32 v105, v105, v137, v121
	v_fma_f32 v106, v106, v138, v122
	v_fma_f32 v107, v107, v139, v123
	v_fma_f32 v108, v108, v140, v124
	v_fma_f32 v109, v109, v141, v125
	v_fma_f32 v110, v110, v142, v126
	v_fma_f32 v111, v111, v143, v127
	v_fma_f32 v112, v112, v144, v128
	v_fma_f32 v113, v113, v145, v129
	v_cvt_pk_bf16_f32 v190, v98, v99
	v_cvt_pk_bf16_f32 v191, v100, v101
	v_cvt_pk_bf16_f32 v192, v102, v103
	v_cvt_pk_bf16_f32 v193, v104, v105
	v_cvt_pk_bf16_f32 v194, v106, v107
	v_cvt_pk_bf16_f32 v195, v108, v109
	v_cvt_pk_bf16_f32 v196, v110, v111
	v_cvt_pk_bf16_f32 v197, v112, v113
	s_add_u32 s2, s10, 0x1800
	s_addc_u32 s3, s11, 0
	global_store_dwordx2 v1, v[190:191], s[2:3]
	global_store_dwordx2 v1, v[192:193], s[2:3] offset:512
	global_store_dwordx2 v1, v[194:195], s[2:3] offset:1024
	global_store_dwordx2 v1, v[196:197], s[2:3] offset:1536
	s_add_u32 s2, s8, 0x7000
	s_addc_u32 s3, s9, 0
	global_load_dwordx4 v[98:101], v0, s[2:3]
	global_load_dwordx4 v[102:105], v0, s[2:3] offset:1024
	global_load_dwordx4 v[106:109], v0, s[2:3] offset:2048
	global_load_dwordx4 v[110:113], v0, s[2:3] offset:3072
	s_waitcnt vmcnt(24)
; DI unsigned pk2(float lo, float hi) { f32x2 v = {lo, hi}; bf16x2_t b = __builtin_convertvector(v, bf16x2_t); return __builtin_bit_cast(unsigned, b); }
; DI float shx(float v, int m, int lane) { return __int_as_float(__builtin_amdgcn_ds_bpermute((lane ^ m) << 2, __float_as_int(v))); }
; DI void wave_sum2(float& a, float& b, int lane) {
; #pragma unroll
;     for (int o = 1; o < 64; o <<= 1) { const float ta = shx(a, o, lane), tb = shx(b, o, lane); a += ta; b += tb; }
; }
; DI void ln_row_v(const Frame& F, f32x4 (&v)[4], float* xout, const float* g, const float* b, const float* sh, const float* sc, bf16_t* hout, const float* slab, const float* gres, float* stat = nullptr) {
;     ...
;     if (hout) {
;         float s = 0.f, s2 = 0.f;
; #pragma unroll
;         for (int j = 0; j < 4; ++j) { s += (v[j][0] + v[j][1]) + (v[j][2] + v[j][3]); s2 += (v[j][0] * v[j][0] + v[j][1] * v[j][1]) + (v[j][2] * v[j][2] + v[j][3] * v[j][3]); }
;         wave_sum2(s, s2, F.lane);
;         const float mean = s * (1.f / D); const float rstd = 1.f / sqrtf(fmaxf(s2 * (1.f / D) - mean * mean, 0.f) + EPS);
; #pragma unroll
;         for (int j = 0; j < 4; ++j) { const f32x4 hh = ((const f32x4*)sh)[F.lane + 64 * j], cc = ((const f32x4*)sc)[F.lane + 64 * j];
;             const f32x4 o = (v[j] - mean) * rstd * (cc + 1.f) + hh; u32x2 wv; wv.x = pk2(o[0], o[1]); wv.y = pk2(o[2], o[3]);
;             ((u32x2*)hout)[F.lane + 64 * j] = wv; }
;     }
	v_add_f32_e32 v9, v42, v43
	v_add_f32_e32 v91, v44, v45
	v_mul_f32_e32 v90, v42, v42
	v_mul_f32_e32 v92, v43, v43
	v_add_f32_e32 v9, v9, v46
	v_add_f32_e32 v91, v91, v47
	v_add_f32_e32 v9, v9, v48
	v_add_f32_e32 v91, v91, v49
	v_add_f32_e32 v9, v9, v50
	v_add_f32_e32 v91, v91, v51
	v_add_f32_e32 v9, v9, v52
	v_add_f32_e32 v91, v91, v53
	v_add_f32_e32 v9, v9, v54
	v_add_f32_e32 v91, v91, v55
	v_add_f32_e32 v9, v9, v56
	v_add_f32_e32 v91, v91, v57
	v_fmac_f32_e32 v90, v44, v44
	v_fmac_f32_e32 v92, v45, v45
	v_fmac_f32_e32 v90, v46, v46
	v_fmac_f32_e32 v92, v47, v47
	v_fmac_f32_e32 v90, v48, v48
	v_fmac_f32_e32 v92, v49, v49
	v_fmac_f32_e32 v90, v50, v50
	v_fmac_f32_e32 v92, v51, v51
	v_fmac_f32_e32 v90, v52, v52
	v_fmac_f32_e32 v92, v53, v53
	v_fmac_f32_e32 v90, v54, v54
	v_fmac_f32_e32 v92, v55, v55
	v_fmac_f32_e32 v90, v56, v56
	v_fmac_f32_e32 v92, v57, v57
	v_add_f32_e32 v9, v9, v91
	v_add_f32_e32 v90, v90, v92
	s_nop 1
	v_add_f32_dpp v9, v9, v9 quad_perm:[1,0,3,2] row_mask:0xf bank_mask:0xf
	v_add_f32_dpp v90, v90, v90 quad_perm:[1,0,3,2] row_mask:0xf bank_mask:0xf
	s_nop 0
	v_add_f32_dpp v9, v9, v9 quad_perm:[2,3,0,1] row_mask:0xf bank_mask:0xf
	v_add_f32_dpp v90, v90, v90 quad_perm:[2,3,0,1] row_mask:0xf bank_mask:0xf
	s_nop 0
	v_add_f32_dpp v9, v9, v9 row_half_mirror row_mask:0xf bank_mask:0xf
	v_add_f32_dpp v90, v90, v90 row_half_mirror row_mask:0xf bank_mask:0xf
	s_nop 0
	v_add_f32_dpp v9, v9, v9 row_mirror row_mask:0xf bank_mask:0xf
	v_add_f32_dpp v90, v90, v90 row_mirror row_mask:0xf bank_mask:0xf
	s_nop 0
	v_add_f32_dpp v9, v9, v9 row_bcast:15 row_mask:0xa bank_mask:0xf
	v_add_f32_dpp v90, v90, v90 row_bcast:15 row_mask:0xa bank_mask:0xf
	s_nop 0
	v_add_f32_dpp v9, v9, v9 row_bcast:31 row_mask:0xc bank_mask:0xf
	v_add_f32_dpp v90, v90, v90 row_bcast:31 row_mask:0xc bank_mask:0xf
	s_nop 0
	v_readlane_b32 s2, v9, 63
	v_readlane_b32 s3, v90, 63
	s_nop 1
	v_mov_b32_e32 v9, s2
	v_mov_b32_e32 v90, s3
	v_mul_f32_e32 v93, 0x3a800000, v9
	v_mul_f32_e32 v91, 0x3a800000, v90
	v_fma_f32 v91, -v93, v93, v91
	v_max_f32_e32 v91, 0, v91
	v_add_f32_e32 v91, 0x358637bd, v91
	v_rsq_f32_e32 v94, v91
	v_mul_f32_e32 v91, 0.5, v91
	v_mul_f32_e32 v92, v94, v94
	v_fma_f32 v92, -v91, v92, 0.5
	v_fma_f32 v94, v94, v92, v94
	v_sub_f32_e32 v42, v42, v93
	v_sub_f32_e32 v43, v43, v93
	v_sub_f32_e32 v44, v44, v93
	v_sub_f32_e32 v45, v45, v93
	v_sub_f32_e32 v46, v46, v93
	v_sub_f32_e32 v47, v47, v93
	v_sub_f32_e32 v48, v48, v93
	v_sub_f32_e32 v49, v49, v93
	v_sub_f32_e32 v50, v50, v93
	v_sub_f32_e32 v51, v51, v93
	v_sub_f32_e32 v52, v52, v93
	v_sub_f32_e32 v53, v53, v93
	v_sub_f32_e32 v54, v54, v93
	v_sub_f32_e32 v55, v55, v93
	v_sub_f32_e32 v56, v56, v93
	v_sub_f32_e32 v57, v57, v93
	v_mul_f32_e32 v42, v94, v42
	v_mul_f32_e32 v43, v94, v43
	v_mul_f32_e32 v44, v94, v44
	v_mul_f32_e32 v45, v94, v45
	v_mul_f32_e32 v46, v94, v46
	v_mul_f32_e32 v47, v94, v47
	v_mul_f32_e32 v48, v94, v48
	v_mul_f32_e32 v49, v94, v49
	v_mul_f32_e32 v50, v94, v50
	v_mul_f32_e32 v51, v94, v51
	v_mul_f32_e32 v52, v94, v52
	v_mul_f32_e32 v53, v94, v53
	v_mul_f32_e32 v54, v94, v54
	v_mul_f32_e32 v55, v94, v55
	v_mul_f32_e32 v56, v94, v56
	v_mul_f32_e32 v57, v94, v57
	v_fma_f32 v42, v42, v130, v114
	v_fma_f32 v43, v43, v131, v115
	v_fma_f32 v44, v44, v132, v116
	v_fma_f32 v45, v45, v133, v117
	v_fma_f32 v46, v46, v134, v118
	v_fma_f32 v47, v47, v135, v119
	v_fma_f32 v48, v48, v136, v120
	v_fma_f32 v49, v49, v137, v121
	v_fma_f32 v50, v50, v138, v122
	v_fma_f32 v51, v51, v139, v123
	v_fma_f32 v52, v52, v140, v124
	v_fma_f32 v53, v53, v141, v125
	v_fma_f32 v54, v54, v142, v126
	v_fma_f32 v55, v55, v143, v127
	v_fma_f32 v56, v56, v144, v128
	v_fma_f32 v57, v57, v145, v129
	v_cvt_pk_bf16_f32 v190, v42, v43
	v_cvt_pk_bf16_f32 v191, v44, v45
	v_cvt_pk_bf16_f32 v192, v46, v47
	v_cvt_pk_bf16_f32 v193, v48, v49
	v_cvt_pk_bf16_f32 v194, v50, v51
	v_cvt_pk_bf16_f32 v195, v52, v53
	v_cvt_pk_bf16_f32 v196, v54, v55
	v_cvt_pk_bf16_f32 v197, v56, v57
	s_add_u32 s2, s10, 0x2000
	s_addc_u32 s3, s11, 0
	global_store_dwordx2 v1, v[190:191], s[2:3]
	global_store_dwordx2 v1, v[192:193], s[2:3] offset:512
	global_store_dwordx2 v1, v[194:195], s[2:3] offset:1024
	global_store_dwordx2 v1, v[196:197], s[2:3] offset:1536
	s_mov_b64 s[2:3], s[20:21]
	global_load_dwordx4 v[42:45], v0, s[2:3]
	global_load_dwordx4 v[46:49], v0, s[2:3] offset:1024
	global_load_dwordx4 v[50:53], v0, s[2:3] offset:2048
	global_load_dwordx4 v[54:57], v0, s[2:3] offset:3072
	s_waitcnt vmcnt(24)
; DI unsigned pk2(float lo, float hi) { f32x2 v = {lo, hi}; bf16x2_t b = __builtin_convertvector(v, bf16x2_t); return __builtin_bit_cast(unsigned, b); }
; DI float shx(float v, int m, int lane) { return __int_as_float(__builtin_amdgcn_ds_bpermute((lane ^ m) << 2, __float_as_int(v))); }
; DI void wave_sum2(float& a, float& b, int lane) {
; #pragma unroll
;     for (int o = 1; o < 64; o <<= 1) { const float ta = shx(a, o, lane), tb = shx(b, o, lane); a += ta; b += tb; }
; }
; DI void ln_row_v(const Frame& F, f32x4 (&v)[4], float* xout, const float* g, const float* b, const float* sh, const float* sc, bf16_t* hout, const float* slab, const float* gres, float* stat = nullptr) {
;     ...
;     if (hout) {
;         float s = 0.f, s2 = 0.f;
; #pragma unroll
;         for (int j = 0; j < 4; ++j) { s += (v[j][0] + v[j][1]) + (v[j][2] + v[j][3]); s2 += (v[j][0] * v[j][0] + v[j][1] * v[j][1]) + (v[j][2] * v[j][2] + v[j][3] * v[j][3]); }
;         wave_sum2(s, s2, F.lane);
;         const float mean = s * (1.f / D); const float rstd = 1.f / sqrtf(fmaxf(s2 * (1.f / D) - mean * mean, 0.f) + EPS);
; #pragma unroll
;         for (int j = 0; j < 4; ++j) { const f32x4 hh = ((const f32x4*)sh)[F.lane + 64 * j], cc = ((const f32x4*)sc)[F.lane + 64 * j];
;             const f32x4 o = (v[j] - mean) * rstd * (cc + 1.f) + hh; u32x2 wv; wv.x = pk2(o[0], o[1]); wv.y = pk2(o[2], o[3]);
;             ((u32x2*)hout)[F.lane + 64 * j] = wv; }
;     }
	v_add_f32_e32 v9, v58, v59
	v_add_f32_e32 v91, v60, v61
	v_mul_f32_e32 v90, v58, v58
	v_mul_f32_e32 v92, v59, v59
	v_add_f32_e32 v9, v9, v62
	v_add_f32_e32 v91, v91, v63
	v_add_f32_e32 v9, v9, v64
	v_add_f32_e32 v91, v91, v65
	v_add_f32_e32 v9, v9, v66
	v_add_f32_e32 v91, v91, v67
	v_add_f32_e32 v9, v9, v68
	v_add_f32_e32 v91, v91, v69
	v_add_f32_e32 v9, v9, v70
	v_add_f32_e32 v91, v91, v71
	v_add_f32_e32 v9, v9, v72
	v_add_f32_e32 v91, v91, v73
	v_fmac_f32_e32 v90, v60, v60
	v_fmac_f32_e32 v92, v61, v61
	v_fmac_f32_e32 v90, v62, v62
	v_fmac_f32_e32 v92, v63, v63
	v_fmac_f32_e32 v90, v64, v64
	v_fmac_f32_e32 v92, v65, v65
	v_fmac_f32_e32 v90, v66, v66
	v_fmac_f32_e32 v92, v67, v67
	v_fmac_f32_e32 v90, v68, v68
	v_fmac_f32_e32 v92, v69, v69
	v_fmac_f32_e32 v90, v70, v70
	v_fmac_f32_e32 v92, v71, v71
	v_fmac_f32_e32 v90, v72, v72
	v_fmac_f32_e32 v92, v73, v73
	v_add_f32_e32 v9, v9, v91
	v_add_f32_e32 v90, v90, v92
	s_nop 1
	v_add_f32_dpp v9, v9, v9 quad_perm:[1,0,3,2] row_mask:0xf bank_mask:0xf
	v_add_f32_dpp v90, v90, v90 quad_perm:[1,0,3,2] row_mask:0xf bank_mask:0xf
	s_nop 0
	v_add_f32_dpp v9, v9, v9 quad_perm:[2,3,0,1] row_mask:0xf bank_mask:0xf
	v_add_f32_dpp v90, v90, v90 quad_perm:[2,3,0,1] row_mask:0xf bank_mask:0xf
	s_nop 0
	v_add_f32_dpp v9, v9, v9 row_half_mirror row_mask:0xf bank_mask:0xf
	v_add_f32_dpp v90, v90, v90 row_half_mirror row_mask:0xf bank_mask:0xf
	s_nop 0
	v_add_f32_dpp v9, v9, v9 row_mirror row_mask:0xf bank_mask:0xf
	v_add_f32_dpp v90, v90, v90 row_mirror row_mask:0xf bank_mask:0xf
	s_nop 0
	v_add_f32_dpp v9, v9, v9 row_bcast:15 row_mask:0xa bank_mask:0xf
	v_add_f32_dpp v90, v90, v90 row_bcast:15 row_mask:0xa bank_mask:0xf
	s_nop 0
	v_add_f32_dpp v9, v9, v9 row_bcast:31 row_mask:0xc bank_mask:0xf
	v_add_f32_dpp v90, v90, v90 row_bcast:31 row_mask:0xc bank_mask:0xf
	s_nop 0
	v_readlane_b32 s2, v9, 63
	v_readlane_b32 s3, v90, 63
	s_nop 1
	v_mov_b32_e32 v9, s2
	v_mov_b32_e32 v90, s3
	v_mul_f32_e32 v93, 0x3a800000, v9
	v_mul_f32_e32 v91, 0x3a800000, v90
	v_fma_f32 v91, -v93, v93, v91
	v_max_f32_e32 v91, 0, v91
	v_add_f32_e32 v91, 0x358637bd, v91
	v_rsq_f32_e32 v94, v91
	v_mul_f32_e32 v91, 0.5, v91
	v_mul_f32_e32 v92, v94, v94
	v_fma_f32 v92, -v91, v92, 0.5
	v_fma_f32 v94, v94, v92, v94
	v_sub_f32_e32 v58, v58, v93
	v_sub_f32_e32 v59, v59, v93
	v_sub_f32_e32 v60, v60, v93
	v_sub_f32_e32 v61, v61, v93
	v_sub_f32_e32 v62, v62, v93
	v_sub_f32_e32 v63, v63, v93
	v_sub_f32_e32 v64, v64, v93
	v_sub_f32_e32 v65, v65, v93
	v_sub_f32_e32 v66, v66, v93
	v_sub_f32_e32 v67, v67, v93
	v_sub_f32_e32 v68, v68, v93
	v_sub_f32_e32 v69, v69, v93
	v_sub_f32_e32 v70, v70, v93
	v_sub_f32_e32 v71, v71, v93
	v_sub_f32_e32 v72, v72, v93
	v_sub_f32_e32 v73, v73, v93
	v_mul_f32_e32 v58, v94, v58
	v_mul_f32_e32 v59, v94, v59
	v_mul_f32_e32 v60, v94, v60
	v_mul_f32_e32 v61, v94, v61
	v_mul_f32_e32 v62, v94, v62
	v_mul_f32_e32 v63, v94, v63
	v_mul_f32_e32 v64, v94, v64
	v_mul_f32_e32 v65, v94, v65
	v_mul_f32_e32 v66, v94, v66
	v_mul_f32_e32 v67, v94, v67
	v_mul_f32_e32 v68, v94, v68
	v_mul_f32_e32 v69, v94, v69
	v_mul_f32_e32 v70, v94, v70
	v_mul_f32_e32 v71, v94, v71
	v_mul_f32_e32 v72, v94, v72
	v_mul_f32_e32 v73, v94, v73
	v_fma_f32 v58, v58, v130, v114
	v_fma_f32 v59, v59, v131, v115
	v_fma_f32 v60, v60, v132, v116
	v_fma_f32 v61, v61, v133, v117
	v_fma_f32 v62, v62, v134, v118
	v_fma_f32 v63, v63, v135, v119
	v_fma_f32 v64, v64, v136, v120
	v_fma_f32 v65, v65, v137, v121
	v_fma_f32 v66, v66, v138, v122
	v_fma_f32 v67, v67, v139, v123
	v_fma_f32 v68, v68, v140, v124
	v_fma_f32 v69, v69, v141, v125
	v_fma_f32 v70, v70, v142, v126
	v_fma_f32 v71, v71, v143, v127
	v_fma_f32 v72, v72, v144, v128
	v_fma_f32 v73, v73, v145, v129
	v_cvt_pk_bf16_f32 v190, v58, v59
	v_cvt_pk_bf16_f32 v191, v60, v61
	v_cvt_pk_bf16_f32 v192, v62, v63
	v_cvt_pk_bf16_f32 v193, v64, v65
	v_cvt_pk_bf16_f32 v194, v66, v67
	v_cvt_pk_bf16_f32 v195, v68, v69
	v_cvt_pk_bf16_f32 v196, v70, v71
	v_cvt_pk_bf16_f32 v197, v72, v73
	s_add_u32 s2, s10, 0x2800
	s_addc_u32 s3, s11, 0
	global_store_dwordx2 v1, v[190:191], s[2:3]
	global_store_dwordx2 v1, v[192:193], s[2:3] offset:512
	global_store_dwordx2 v1, v[194:195], s[2:3] offset:1024
	global_store_dwordx2 v1, v[196:197], s[2:3] offset:1536
	s_waitcnt vmcnt(20)
; DI unsigned pk2(float lo, float hi) { f32x2 v = {lo, hi}; bf16x2_t b = __builtin_convertvector(v, bf16x2_t); return __builtin_bit_cast(unsigned, b); }
; DI float shx(float v, int m, int lane) { return __int_as_float(__builtin_amdgcn_ds_bpermute((lane ^ m) << 2, __float_as_int(v))); }
; DI void wave_sum2(float& a, float& b, int lane) {
; #pragma unroll
;     for (int o = 1; o < 64; o <<= 1) { const float ta = shx(a, o, lane), tb = shx(b, o, lane); a += ta; b += tb; }
; }
; DI void ln_row_v(const Frame& F, f32x4 (&v)[4], float* xout, const float* g, const float* b, const float* sh, const float* sc, bf16_t* hout, const float* slab, const float* gres, float* stat = nullptr) {
;     ...
;     if (hout) {
;         float s = 0.f, s2 = 0.f;
; #pragma unroll
;         for (int j = 0; j < 4; ++j) { s += (v[j][0] + v[j][1]) + (v[j][2] + v[j][3]); s2 += (v[j][0] * v[j][0] + v[j][1] * v[j][1]) + (v[j][2] * v[j][2] + v[j][3] * v[j][3]); }
;         wave_sum2(s, s2, F.lane);
;         const float mean = s * (1.f / D); const float rstd = 1.f / sqrtf(fmaxf(s2 * (1.f / D) - mean * mean, 0.f) + EPS);
; #pragma unroll
;         for (int j = 0; j < 4; ++j) { const f32x4 hh = ((const f32x4*)sh)[F.lane + 64 * j], cc = ((const f32x4*)sc)[F.lane + 64 * j];
;             const f32x4 o = (v[j] - mean) * rstd * (cc + 1.f) + hh; u32x2 wv; wv.x = pk2(o[0], o[1]); wv.y = pk2(o[2], o[3]);
;             ((u32x2*)hout)[F.lane + 64 * j] = wv; }
;     }
	v_add_f32_e32 v9, v74, v75
	v_add_f32_e32 v91, v76, v77
	v_mul_f32_e32 v90, v74, v74
	v_mul_f32_e32 v92, v75, v75
	v_add_f32_e32 v9, v9, v78
	v_add_f32_e32 v91, v91, v79
	v_add_f32_e32 v9, v9, v80
	v_add_f32_e32 v91, v91, v81
	v_add_f32_e32 v9, v9, v82
	v_add_f32_e32 v91, v91, v83
	v_add_f32_e32 v9, v9, v84
	v_add_f32_e32 v91, v91, v85
	v_add_f32_e32 v9, v9, v86
	v_add_f32_e32 v91, v91, v87
	v_add_f32_e32 v9, v9, v88
	v_add_f32_e32 v91, v91, v89
	v_fmac_f32_e32 v90, v76, v76
	v_fmac_f32_e32 v92, v77, v77
	v_fmac_f32_e32 v90, v78, v78
	v_fmac_f32_e32 v92, v79, v79
	v_fmac_f32_e32 v90, v80, v80
	v_fmac_f32_e32 v92, v81, v81
	v_fmac_f32_e32 v90, v82, v82
	v_fmac_f32_e32 v92, v83, v83
	v_fmac_f32_e32 v90, v84, v84
	v_fmac_f32_e32 v92, v85, v85
	v_fmac_f32_e32 v90, v86, v86
	v_fmac_f32_e32 v92, v87, v87
	v_fmac_f32_e32 v90, v88, v88
	v_fmac_f32_e32 v92, v89, v89
	v_add_f32_e32 v9, v9, v91
	v_add_f32_e32 v90, v90, v92
	s_nop 1
	v_add_f32_dpp v9, v9, v9 quad_perm:[1,0,3,2] row_mask:0xf bank_mask:0xf
	v_add_f32_dpp v90, v90, v90 quad_perm:[1,0,3,2] row_mask:0xf bank_mask:0xf
	s_nop 0
	v_add_f32_dpp v9, v9, v9 quad_perm:[2,3,0,1] row_mask:0xf bank_mask:0xf
	v_add_f32_dpp v90, v90, v90 quad_perm:[2,3,0,1] row_mask:0xf bank_mask:0xf
	s_nop 0
	v_add_f32_dpp v9, v9, v9 row_half_mirror row_mask:0xf bank_mask:0xf
	v_add_f32_dpp v90, v90, v90 row_half_mirror row_mask:0xf bank_mask:0xf
	s_nop 0
	v_add_f32_dpp v9, v9, v9 row_mirror row_mask:0xf bank_mask:0xf
	v_add_f32_dpp v90, v90, v90 row_mirror row_mask:0xf bank_mask:0xf
	s_nop 0
	v_add_f32_dpp v9, v9, v9 row_bcast:15 row_mask:0xa bank_mask:0xf
	v_add_f32_dpp v90, v90, v90 row_bcast:15 row_mask:0xa bank_mask:0xf
	s_nop 0
	v_add_f32_dpp v9, v9, v9 row_bcast:31 row_mask:0xc bank_mask:0xf
	v_add_f32_dpp v90, v90, v90 row_bcast:31 row_mask:0xc bank_mask:0xf
	s_nop 0
	v_readlane_b32 s2, v9, 63
	v_readlane_b32 s3, v90, 63
	s_nop 1
	v_mov_b32_e32 v9, s2
	v_mov_b32_e32 v90, s3
	v_mul_f32_e32 v93, 0x3a800000, v9
	v_mul_f32_e32 v91, 0x3a800000, v90
	v_fma_f32 v91, -v93, v93, v91
	v_max_f32_e32 v91, 0, v91
	v_add_f32_e32 v91, 0x358637bd, v91
	v_rsq_f32_e32 v94, v91
	v_mul_f32_e32 v91, 0.5, v91
	v_mul_f32_e32 v92, v94, v94
	v_fma_f32 v92, -v91, v92, 0.5
	v_fma_f32 v94, v94, v92, v94
	v_sub_f32_e32 v74, v74, v93
	v_sub_f32_e32 v75, v75, v93
	v_sub_f32_e32 v76, v76, v93
	v_sub_f32_e32 v77, v77, v93
	v_sub_f32_e32 v78, v78, v93
	v_sub_f32_e32 v79, v79, v93
	v_sub_f32_e32 v80, v80, v93
	v_sub_f32_e32 v81, v81, v93
	v_sub_f32_e32 v82, v82, v93
	v_sub_f32_e32 v83, v83, v93
	v_sub_f32_e32 v84, v84, v93
	v_sub_f32_e32 v85, v85, v93
	v_sub_f32_e32 v86, v86, v93
	v_sub_f32_e32 v87, v87, v93
	v_sub_f32_e32 v88, v88, v93
	v_sub_f32_e32 v89, v89, v93
	v_mul_f32_e32 v74, v94, v74
	v_mul_f32_e32 v75, v94, v75
	v_mul_f32_e32 v76, v94, v76
	v_mul_f32_e32 v77, v94, v77
	v_mul_f32_e32 v78, v94, v78
	v_mul_f32_e32 v79, v94, v79
	v_mul_f32_e32 v80, v94, v80
	v_mul_f32_e32 v81, v94, v81
	v_mul_f32_e32 v82, v94, v82
	v_mul_f32_e32 v83, v94, v83
	v_mul_f32_e32 v84, v94, v84
	v_mul_f32_e32 v85, v94, v85
	v_mul_f32_e32 v86, v94, v86
	v_mul_f32_e32 v87, v94, v87
	v_mul_f32_e32 v88, v94, v88
	v_mul_f32_e32 v89, v94, v89
	v_fma_f32 v74, v74, v130, v114
	v_fma_f32 v75, v75, v131, v115
	v_fma_f32 v76, v76, v132, v116
	v_fma_f32 v77, v77, v133, v117
	v_fma_f32 v78, v78, v134, v118
	v_fma_f32 v79, v79, v135, v119
	v_fma_f32 v80, v80, v136, v120
	v_fma_f32 v81, v81, v137, v121
	v_fma_f32 v82, v82, v138, v122
	v_fma_f32 v83, v83, v139, v123
	v_fma_f32 v84, v84, v140, v124
	v_fma_f32 v85, v85, v141, v125
	v_fma_f32 v86, v86, v142, v126
	v_fma_f32 v87, v87, v143, v127
	v_fma_f32 v88, v88, v144, v128
	v_fma_f32 v89, v89, v145, v129
	v_cvt_pk_bf16_f32 v190, v74, v75
	v_cvt_pk_bf16_f32 v191, v76, v77
	v_cvt_pk_bf16_f32 v192, v78, v79
	v_cvt_pk_bf16_f32 v193, v80, v81
	v_cvt_pk_bf16_f32 v194, v82, v83
	v_cvt_pk_bf16_f32 v195, v84, v85
	v_cvt_pk_bf16_f32 v196, v86, v87
	v_cvt_pk_bf16_f32 v197, v88, v89
	s_add_u32 s2, s10, 0x3000
	s_addc_u32 s3, s11, 0
	global_store_dwordx2 v1, v[190:191], s[2:3]
	global_store_dwordx2 v1, v[192:193], s[2:3] offset:512
	global_store_dwordx2 v1, v[194:195], s[2:3] offset:1024
	global_store_dwordx2 v1, v[196:197], s[2:3] offset:1536
	s_waitcnt vmcnt(16)
; DI unsigned pk2(float lo, float hi) { f32x2 v = {lo, hi}; bf16x2_t b = __builtin_convertvector(v, bf16x2_t); return __builtin_bit_cast(unsigned, b); }
; DI float shx(float v, int m, int lane) { return __int_as_float(__builtin_amdgcn_ds_bpermute((lane ^ m) << 2, __float_as_int(v))); }
; DI void wave_sum2(float& a, float& b, int lane) {
; #pragma unroll
;     for (int o = 1; o < 64; o <<= 1) { const float ta = shx(a, o, lane), tb = shx(b, o, lane); a += ta; b += tb; }
; }
; DI void ln_row_v(const Frame& F, f32x4 (&v)[4], float* xout, const float* g, const float* b, const float* sh, const float* sc, bf16_t* hout, const float* slab, const float* gres, float* stat = nullptr) {
;     ...
;     if (hout) {
;         float s = 0.f, s2 = 0.f;
; #pragma unroll
;         for (int j = 0; j < 4; ++j) { s += (v[j][0] + v[j][1]) + (v[j][2] + v[j][3]); s2 += (v[j][0] * v[j][0] + v[j][1] * v[j][1]) + (v[j][2] * v[j][2] + v[j][3] * v[j][3]); }
;         wave_sum2(s, s2, F.lane);
;         const float mean = s * (1.f / D); const float rstd = 1.f / sqrtf(fmaxf(s2 * (1.f / D) - mean * mean, 0.f) + EPS);
; #pragma unroll
;         for (int j = 0; j < 4; ++j) { const f32x4 hh = ((const f32x4*)sh)[F.lane + 64 * j], cc = ((const f32x4*)sc)[F.lane + 64 * j];
;             const f32x4 o = (v[j] - mean) * rstd * (cc + 1.f) + hh; u32x2 wv; wv.x = pk2(o[0], o[1]); wv.y = pk2(o[2], o[3]);
;             ((u32x2*)hout)[F.lane + 64 * j] = wv; }
;     }
	v_add_f32_e32 v9, v98, v99
	v_add_f32_e32 v91, v100, v101
	v_mul_f32_e32 v90, v98, v98
	v_mul_f32_e32 v92, v99, v99
	v_add_f32_e32 v9, v9, v102
	v_add_f32_e32 v91, v91, v103
	v_add_f32_e32 v9, v9, v104
	v_add_f32_e32 v91, v91, v105
	v_add_f32_e32 v9, v9, v106
	v_add_f32_e32 v91, v91, v107
	v_add_f32_e32 v9, v9, v108
	v_add_f32_e32 v91, v91, v109
	v_add_f32_e32 v9, v9, v110
	v_add_f32_e32 v91, v91, v111
	v_add_f32_e32 v9, v9, v112
	v_add_f32_e32 v91, v91, v113
	v_fmac_f32_e32 v90, v100, v100
	v_fmac_f32_e32 v92, v101, v101
	v_fmac_f32_e32 v90, v102, v102
	v_fmac_f32_e32 v92, v103, v103
	v_fmac_f32_e32 v90, v104, v104
	v_fmac_f32_e32 v92, v105, v105
	v_fmac_f32_e32 v90, v106, v106
	v_fmac_f32_e32 v92, v107, v107
	v_fmac_f32_e32 v90, v108, v108
	v_fmac_f32_e32 v92, v109, v109
	v_fmac_f32_e32 v90, v110, v110
	v_fmac_f32_e32 v92, v111, v111
	v_fmac_f32_e32 v90, v112, v112
	v_fmac_f32_e32 v92, v113, v113
	v_add_f32_e32 v9, v9, v91
	v_add_f32_e32 v90, v90, v92
	s_nop 1
	v_add_f32_dpp v9, v9, v9 quad_perm:[1,0,3,2] row_mask:0xf bank_mask:0xf
	v_add_f32_dpp v90, v90, v90 quad_perm:[1,0,3,2] row_mask:0xf bank_mask:0xf
	s_nop 0
	v_add_f32_dpp v9, v9, v9 quad_perm:[2,3,0,1] row_mask:0xf bank_mask:0xf
	v_add_f32_dpp v90, v90, v90 quad_perm:[2,3,0,1] row_mask:0xf bank_mask:0xf
	s_nop 0
	v_add_f32_dpp v9, v9, v9 row_half_mirror row_mask:0xf bank_mask:0xf
	v_add_f32_dpp v90, v90, v90 row_half_mirror row_mask:0xf bank_mask:0xf
	s_nop 0
	v_add_f32_dpp v9, v9, v9 row_mirror row_mask:0xf bank_mask:0xf
	v_add_f32_dpp v90, v90, v90 row_mirror row_mask:0xf bank_mask:0xf
	s_nop 0
	v_add_f32_dpp v9, v9, v9 row_bcast:15 row_mask:0xa bank_mask:0xf
	v_add_f32_dpp v90, v90, v90 row_bcast:15 row_mask:0xa bank_mask:0xf
	s_nop 0
	v_add_f32_dpp v9, v9, v9 row_bcast:31 row_mask:0xc bank_mask:0xf
	v_add_f32_dpp v90, v90, v90 row_bcast:31 row_mask:0xc bank_mask:0xf
	s_nop 0
	v_readlane_b32 s2, v9, 63
	v_readlane_b32 s3, v90, 63
	s_nop 1
	v_mov_b32_e32 v9, s2
	v_mov_b32_e32 v90, s3
	v_mul_f32_e32 v93, 0x3a800000, v9
	v_mul_f32_e32 v91, 0x3a800000, v90
	v_fma_f32 v91, -v93, v93, v91
	v_max_f32_e32 v91, 0, v91
	v_add_f32_e32 v91, 0x358637bd, v91
	v_rsq_f32_e32 v94, v91
	v_mul_f32_e32 v91, 0.5, v91
	v_mul_f32_e32 v92, v94, v94
	v_fma_f32 v92, -v91, v92, 0.5
	v_fma_f32 v94, v94, v92, v94
	v_sub_f32_e32 v98, v98, v93
	v_sub_f32_e32 v99, v99, v93
	v_sub_f32_e32 v100, v100, v93
	v_sub_f32_e32 v101, v101, v93
	v_sub_f32_e32 v102, v102, v93
	v_sub_f32_e32 v103, v103, v93
	v_sub_f32_e32 v104, v104, v93
	v_sub_f32_e32 v105, v105, v93
	v_sub_f32_e32 v106, v106, v93
	v_sub_f32_e32 v107, v107, v93
	v_sub_f32_e32 v108, v108, v93
	v_sub_f32_e32 v109, v109, v93
	v_sub_f32_e32 v110, v110, v93
	v_sub_f32_e32 v111, v111, v93
	v_sub_f32_e32 v112, v112, v93
	v_sub_f32_e32 v113, v113, v93
	v_mul_f32_e32 v98, v94, v98
	v_mul_f32_e32 v99, v94, v99
	v_mul_f32_e32 v100, v94, v100
	v_mul_f32_e32 v101, v94, v101
	v_mul_f32_e32 v102, v94, v102
	v_mul_f32_e32 v103, v94, v103
	v_mul_f32_e32 v104, v94, v104
	v_mul_f32_e32 v105, v94, v105
	v_mul_f32_e32 v106, v94, v106
	v_mul_f32_e32 v107, v94, v107
	v_mul_f32_e32 v108, v94, v108
	v_mul_f32_e32 v109, v94, v109
	v_mul_f32_e32 v110, v94, v110
	v_mul_f32_e32 v111, v94, v111
	v_mul_f32_e32 v112, v94, v112
	v_mul_f32_e32 v113, v94, v113
	v_fma_f32 v98, v98, v130, v114
	v_fma_f32 v99, v99, v131, v115
	v_fma_f32 v100, v100, v132, v116
	v_fma_f32 v101, v101, v133, v117
	v_fma_f32 v102, v102, v134, v118
	v_fma_f32 v103, v103, v135, v119
	v_fma_f32 v104, v104, v136, v120
	v_fma_f32 v105, v105, v137, v121
	v_fma_f32 v106, v106, v138, v122
	v_fma_f32 v107, v107, v139, v123
	v_fma_f32 v108, v108, v140, v124
	v_fma_f32 v109, v109, v141, v125
	v_fma_f32 v110, v110, v142, v126
	v_fma_f32 v111, v111, v143, v127
	v_fma_f32 v112, v112, v144, v128
	v_fma_f32 v113, v113, v145, v129
	v_cvt_pk_bf16_f32 v190, v98, v99
	v_cvt_pk_bf16_f32 v191, v100, v101
	v_cvt_pk_bf16_f32 v192, v102, v103
	v_cvt_pk_bf16_f32 v193, v104, v105
	v_cvt_pk_bf16_f32 v194, v106, v107
	v_cvt_pk_bf16_f32 v195, v108, v109
	v_cvt_pk_bf16_f32 v196, v110, v111
	v_cvt_pk_bf16_f32 v197, v112, v113
	s_add_u32 s2, s10, 0x3800
	s_addc_u32 s3, s11, 0
	global_store_dwordx2 v1, v[190:191], s[2:3]
	global_store_dwordx2 v1, v[192:193], s[2:3] offset:512
	global_store_dwordx2 v1, v[194:195], s[2:3] offset:1024
	global_store_dwordx2 v1, v[196:197], s[2:3] offset:1536
	s_waitcnt vmcnt(12)
; DI unsigned pk2(float lo, float hi) { f32x2 v = {lo, hi}; bf16x2_t b = __builtin_convertvector(v, bf16x2_t); return __builtin_bit_cast(unsigned, b); }
; DI const float* modp(const Frame& F, int l, int mr, int which) { return (const float*)(F.ws + WS_MOD) + ((size_t)(l * 9 + mr) * 6 + which) * 1024; }
; DI void ln_row_v(const Frame& F, f32x4 (&v)[4], float* xout, const float* g, const float* b, const float* sh, const float* sc, bf16_t* hout, const float* slab, const float* gres, float* stat = nullptr) {
;     ...
;     if (hout) {
;         float s = 0.f, s2 = 0.f;
; #pragma unroll
;         for (int j = 0; j < 4; ++j) { s += (v[j][0] + v[j][1]) + (v[j][2] + v[j][3]); s2 += (v[j][0] * v[j][0] + v[j][1] * v[j][1]) + (v[j][2] * v[j][2] + v[j][3] * v[j][3]); }
;         wave_sum2(s, s2, F.lane);
;         const float mean = s * (1.f / D); const float rstd = 1.f / sqrtf(fmaxf(s2 * (1.f / D) - mean * mean, 0.f) + EPS);
; #pragma unroll
;         for (int j = 0; j < 4; ++j) { const f32x4 hh = ((const f32x4*)sh)[F.lane + 64 * j], cc = ((const f32x4*)sc)[F.lane + 64 * j];
;             const f32x4 o = (v[j] - mean) * rstd * (cc + 1.f) + hh; u32x2 wv; wv.x = pk2(o[0], o[1]); wv.y = pk2(o[2], o[3]);
;             ((u32x2*)hout)[F.lane + 64 * j] = wv; }
;     }
; DI void prologue_b(const Frame& F) {
;     const int gw = F.vcu * 8 + F.wave, NGW = F.G * 8;
;     bf16_t* H = (bf16_t*)(F.ws + WS_HB);
;     for (int row = gw; row < MT; row += NGW) {
;         const int mr = row < ML ? (row >> 11) : 8;
;         const float* xi = row < ML ? pin(F, I_X) + (size_t)row * D : pin(F, I_CTX) + (size_t)(row - ML) * D;
;         ln_row(F, xi, nullptr, nullptr, nullptr, modp(F, 0, mr, 0), modp(F, 0, mr, 1), H + (size_t)row * D);
;     }
; }
	v_add_f32_e32 v9, v42, v43
	v_add_f32_e32 v91, v44, v45
	v_mul_f32_e32 v90, v42, v42
	v_mul_f32_e32 v92, v43, v43
	v_add_f32_e32 v9, v9, v46
	v_add_f32_e32 v91, v91, v47
	v_add_f32_e32 v9, v9, v48
	v_add_f32_e32 v91, v91, v49
	v_add_f32_e32 v9, v9, v50
	v_add_f32_e32 v91, v91, v51
	v_add_f32_e32 v9, v9, v52
	v_add_f32_e32 v91, v91, v53
	v_add_f32_e32 v9, v9, v54
	v_add_f32_e32 v91, v91, v55
	v_add_f32_e32 v9, v9, v56
	v_add_f32_e32 v91, v91, v57
	v_fmac_f32_e32 v90, v44, v44
	v_fmac_f32_e32 v92, v45, v45
	v_fmac_f32_e32 v90, v46, v46
	v_fmac_f32_e32 v92, v47, v47
	v_fmac_f32_e32 v90, v48, v48
	v_fmac_f32_e32 v92, v49, v49
	v_fmac_f32_e32 v90, v50, v50
	v_fmac_f32_e32 v92, v51, v51
	v_fmac_f32_e32 v90, v52, v52
	v_fmac_f32_e32 v92, v53, v53
	v_fmac_f32_e32 v90, v54, v54
	v_fmac_f32_e32 v92, v55, v55
	v_fmac_f32_e32 v90, v56, v56
	v_fmac_f32_e32 v92, v57, v57
	v_add_f32_e32 v9, v9, v91
	v_add_f32_e32 v90, v90, v92
	s_nop 1
	v_add_f32_dpp v9, v9, v9 quad_perm:[1,0,3,2] row_mask:0xf bank_mask:0xf
	v_add_f32_dpp v90, v90, v90 quad_perm:[1,0,3,2] row_mask:0xf bank_mask:0xf
	s_nop 0
	v_add_f32_dpp v9, v9, v9 quad_perm:[2,3,0,1] row_mask:0xf bank_mask:0xf
	v_add_f32_dpp v90, v90, v90 quad_perm:[2,3,0,1] row_mask:0xf bank_mask:0xf
	s_nop 0
	v_add_f32_dpp v9, v9, v9 row_half_mirror row_mask:0xf bank_mask:0xf
	v_add_f32_dpp v90, v90, v90 row_half_mirror row_mask:0xf bank_mask:0xf
	s_nop 0
	v_add_f32_dpp v9, v9, v9 row_mirror row_mask:0xf bank_mask:0xf
	v_add_f32_dpp v90, v90, v90 row_mirror row_mask:0xf bank_mask:0xf
	s_nop 0
	v_add_f32_dpp v9, v9, v9 row_bcast:15 row_mask:0xa bank_mask:0xf
	v_add_f32_dpp v90, v90, v90 row_bcast:15 row_mask:0xa bank_mask:0xf
	s_nop 0
	v_add_f32_dpp v9, v9, v9 row_bcast:31 row_mask:0xc bank_mask:0xf
	v_add_f32_dpp v90, v90, v90 row_bcast:31 row_mask:0xc bank_mask:0xf
	s_nop 0
	v_readlane_b32 s2, v9, 63
	v_readlane_b32 s3, v90, 63
	s_nop 1
	v_mov_b32_e32 v9, s2
	v_mov_b32_e32 v90, s3
	v_mul_f32_e32 v93, 0x3a800000, v9
	v_mul_f32_e32 v91, 0x3a800000, v90
	v_fma_f32 v91, -v93, v93, v91
	v_max_f32_e32 v91, 0, v91
	v_add_f32_e32 v91, 0x358637bd, v91
	v_rsq_f32_e32 v94, v91
	v_mul_f32_e32 v91, 0.5, v91
	v_mul_f32_e32 v92, v94, v94
	v_fma_f32 v92, -v91, v92, 0.5
	v_fma_f32 v94, v94, v92, v94
	v_sub_f32_e32 v42, v42, v93
	v_sub_f32_e32 v43, v43, v93
	v_sub_f32_e32 v44, v44, v93
	v_sub_f32_e32 v45, v45, v93
	v_sub_f32_e32 v46, v46, v93
	v_sub_f32_e32 v47, v47, v93
	v_sub_f32_e32 v48, v48, v93
	v_sub_f32_e32 v49, v49, v93
	v_sub_f32_e32 v50, v50, v93
	v_sub_f32_e32 v51, v51, v93
	v_sub_f32_e32 v52, v52, v93
	v_sub_f32_e32 v53, v53, v93
	v_sub_f32_e32 v54, v54, v93
	v_sub_f32_e32 v55, v55, v93
	v_sub_f32_e32 v56, v56, v93
	v_sub_f32_e32 v57, v57, v93
	v_add_f32_e32 v162, 1.0, v162
	v_add_f32_e32 v163, 1.0, v163
	v_add_f32_e32 v164, 1.0, v164
	v_add_f32_e32 v165, 1.0, v165
	v_add_f32_e32 v166, 1.0, v166
	v_add_f32_e32 v167, 1.0, v167
	v_add_f32_e32 v168, 1.0, v168
	v_add_f32_e32 v169, 1.0, v169
	v_add_f32_e32 v170, 1.0, v170
	v_add_f32_e32 v171, 1.0, v171
	v_add_f32_e32 v172, 1.0, v172
	v_add_f32_e32 v173, 1.0, v173
	v_add_f32_e32 v174, 1.0, v174
	v_add_f32_e32 v175, 1.0, v175
	v_add_f32_e32 v176, 1.0, v176
	v_add_f32_e32 v177, 1.0, v177
	v_mul_f32_e32 v42, v94, v42
	v_mul_f32_e32 v43, v94, v43
	v_mul_f32_e32 v44, v94, v44
	v_mul_f32_e32 v45, v94, v45
	v_mul_f32_e32 v46, v94, v46
	v_mul_f32_e32 v47, v94, v47
	v_mul_f32_e32 v48, v94, v48
	v_mul_f32_e32 v49, v94, v49
	v_mul_f32_e32 v50, v94, v50
	v_mul_f32_e32 v51, v94, v51
	v_mul_f32_e32 v52, v94, v52
	v_mul_f32_e32 v53, v94, v53
	v_mul_f32_e32 v54, v94, v54
	v_mul_f32_e32 v55, v94, v55
	v_mul_f32_e32 v56, v94, v56
	v_mul_f32_e32 v57, v94, v57
	v_fma_f32 v42, v42, v162, v146
	v_fma_f32 v43, v43, v163, v147
	v_fma_f32 v44, v44, v164, v148
	v_fma_f32 v45, v45, v165, v149
	v_fma_f32 v46, v46, v166, v150
	v_fma_f32 v47, v47, v167, v151
	v_fma_f32 v48, v48, v168, v152
	v_fma_f32 v49, v49, v169, v153
	v_fma_f32 v50, v50, v170, v154
	v_fma_f32 v51, v51, v171, v155
	v_fma_f32 v52, v52, v172, v156
	v_fma_f32 v53, v53, v173, v157
	v_fma_f32 v54, v54, v174, v158
	v_fma_f32 v55, v55, v175, v159
	v_fma_f32 v56, v56, v176, v160
	v_fma_f32 v57, v57, v177, v161
	v_cvt_pk_bf16_f32 v190, v42, v43
	v_cvt_pk_bf16_f32 v191, v44, v45
	v_cvt_pk_bf16_f32 v192, v46, v47
	v_cvt_pk_bf16_f32 v193, v48, v49
	v_cvt_pk_bf16_f32 v194, v50, v51
	v_cvt_pk_bf16_f32 v195, v52, v53
	v_cvt_pk_bf16_f32 v196, v54, v55
	v_cvt_pk_bf16_f32 v197, v56, v57
	s_lshl_b32 s2, s16, 11
	s_add_u32 s2, s94, s2
	s_addc_u32 s3, s95, 0
	s_add_u32 s2, s2, 0x5e00000
	s_addc_u32 s3, s3, 0
	global_store_dwordx2 v1, v[190:191], s[2:3]
	global_store_dwordx2 v1, v[192:193], s[2:3] offset:512
	global_store_dwordx2 v1, v[194:195], s[2:3] offset:1024
	global_store_dwordx2 v1, v[196:197], s[2:3] offset:1536
	s_waitcnt vmcnt(0)
	s_add_i32 s16, s16, 0x4800
	s_cmpk_gt_u32 s16, 0x47ff
	s_cbranch_scc1 .LBB0_671
	s_lshl_b64 s[2:3], s[44:45], 3
	s_add_u32 s4, s62, s2
	s_addc_u32 s5, s63, s3
	v_lshlrev_b32_e32 v0, 2, v186
	v_lshlrev_b32_e32 v96, 3, v186
	s_add_u32 s18, s94, 0x100000
	v_xor_b32_e32 v18, 4, v0
	v_xor_b32_e32 v19, 8, v0
	v_xor_b32_e32 v20, 16, v0
	v_xor_b32_e32 v21, 32, v0
	v_xor_b32_e32 v22, 64, v0
	v_xor_b32_e32 v23, 0x80, v0
	v_or_b32_e32 v0, 64, v186
	v_or_b32_e32 v2, 0x80, v186
	v_or_b32_e32 v4, 0xc0, v186
	v_lshl_add_u64 v[6:7], s[94:95], 0, v[96:97]
	s_mov_b64 s[2:3], 0x3e00000
	s_addc_u32 s19, s95, 0
	v_lshl_add_u64 v[16:17], v[6:7], 0, s[2:3]
	s_lshl_b32 s20, s93, 3
	s_lshl_b64 s[6:7], s[16:17], 12
	s_lshl_b32 s21, s93, 15
	v_lshlrev_b32_e32 v24, 4, v186
	v_lshlrev_b32_e32 v25, 4, v0
	v_lshlrev_b32_e32 v26, 4, v2
	v_lshlrev_b32_e32 v27, 4, v4
	s_mov_b64 s[8:9], s[16:17]
	s_branch .LBB0_668
